# GEMM K-loops: per-cluster s_setprio raise/drop deleted (no priority flips in the 8-phase loops)
# speedup vs baseline: 1.0047x; 1.0023x over previous
; #define PG8_STAGE(bufoff, gbase, voff) do { _Pragma("unroll") for (int _i = 0; _i < 2; ++_i) \
;         __builtin_amdgcn_global_load_lds((const unsigned*)((const char*)(gbase) + (voff)[_i]), (LAS unsigned*)(lds + (bufoff) + ldsw + _i * 8192), 16, 0, 0); } while (0)
; #define PG8_STAGEB(bufoff, gbase, perm) do { _Pragma("unroll") for (int _i = 0; _i < 2; ++_i) \
;         __builtin_amdgcn_global_load_lds((const unsigned*)((const char*)(gbase) + ((BSEL && (perm)) ? voffBp[_i] : voffB[_i])), (LAS unsigned*)(lds + (bufoff) + ldsw + _i * 8192), 16, 0, 0); } while (0)
; #define PG8_LDA(dst, b, h) do { _Pragma("unroll") for (int m = 0; m < 4; ++m) _Pragma("unroll") for (int k = 0; k < 2; ++k) dst[m][k] = *(const LAS bf16x8*)(lds + PG8_SA(b, h) + aoff + m * 2048 + k * 1024); } while (0)
; #define PG8_LDB(dst, b, h) do { _Pragma("unroll") for (int n = 0; n < 2; ++n) _Pragma("unroll") for (int k = 0; k < 2; ++k) dst[n][k] = *(const LAS bf16x8*)(lds + PG8_SB(b, h) + boff + n * 2048 + k * 1024); } while (0)
; #define PG8_WAIT_V(n) asm volatile("s_waitcnt vmcnt(" #n ")" ::: "memory")
; #define PG8_WAIT_L(n) asm volatile("s_waitcnt lgkmcnt(" #n ")" ::: "memory")
; #define PG8_BAR __builtin_amdgcn_s_barrier()
; #define PG8_SCHED __builtin_amdgcn_sched_barrier(0)
; template <class Epi, bool BSEL = false>
; __device__ __forceinline__ void gemm_phase(LAS unsigned char* lds, const Gemm g, const Order& S, const Epi& E, const int tid) {
;     ...
;             const bool last = (t == nt - 2);
;             const char* a1 = cA + (size_t)(t + 1) * kstep;
;             const char* a2 = last ? nA : cA + (size_t)(t + 2) * kstep; const char* b2 = last ? nB : cB + (size_t)(t + 2) * kstep;
;             const char* a3 = a2 + kstep; const char* b3 = b2 + kstep;
;             const bool p2 = last ? nP : cP; const size_t h2 = last ? nhB : chB;
;             PG8_LDB(B0, 0, 0); PG8_LDB(B1, 0, 1); PG8_SCHED; PG8_LDA(At, 0, 0); PG8_STAGE(PG8_SA(1, 1), a1 + hstepA, voffA);
;             PG8_WAIT_V(8); PG8_WAIT_L(0); PG8_BAR; PG8_MMA(0, 0, At, B0); PG8_MMA(0, 1, At, B1); PG8_BAR; PG8_SCHED;
;             PG8_LDA(At, 0, 1); PG8_STAGEB(PG8_SB(0, 0), b2, p2); PG8_STAGEB(PG8_SB(0, 1), b2 + h2, p2); PG8_STAGE(PG8_SA(0, 0), a2, voffA);
;             PG8_WAIT_V(8); PG8_WAIT_L(0); PG8_BAR; PG8_MMA(1, 0, At, B0); PG8_MMA(1, 1, At, B1); PG8_BAR; PG8_SCHED;
.LBB0_324:
	v_add_u32_e32 v162, s45, v147
	v_add_u32_e32 v178, s46, v147
	s_add_u32 s2, s8, s38
	ds_read_b128 v[150:153], v162
	ds_read_b128 v[154:157], v162 offset:1024
	ds_read_b128 v[158:161], v162 offset:2048
	ds_read_b128 v[162:165], v162 offset:3072
	ds_read_b128 v[166:169], v178
	ds_read_b128 v[170:173], v178 offset:1024
	ds_read_b128 v[174:177], v178 offset:2048
	ds_read_b128 v[178:181], v178 offset:3072
	s_addc_u32 s3, s9, s39
	s_add_u32 s2, s2, 0x100
	s_addc_u32 s3, s3, 0
	s_add_u32 s57, s25, s38
	s_addc_u32 s58, s51, s39
	s_cmpk_eq_i32 s38, 0x700
	s_cselect_b32 s35, s52, s3
	s_cselect_b32 s34, s53, s2
	s_cselect_b32 s3, s54, s58
	s_cselect_b32 s2, s55, s57
	v_lshl_add_u64 v[198:199], v[142:143], 0, s[38:39]
	s_add_i32 m0, s7, 0xc000
	ds_read_b128 v[182:185], v149
	ds_read_b128 v[186:189], v149 offset:1024
	ds_read_b128 v[190:193], v149 offset:2048
	ds_read_b128 v[194:197], v149 offset:3072
	ds_read_b128 v[202:205], v149 offset:4096
	ds_read_b128 v[206:209], v149 offset:5120
	ds_read_b128 v[210:213], v149 offset:6144
	ds_read_b128 v[214:217], v149 offset:7168
	global_load_lds_dwordx4 v[198:199], off
	v_lshl_add_u64 v[198:199], v[144:145], 0, s[38:39]
	s_add_i32 m0, s7, 0xe000
	s_nop 0
	global_load_lds_dwordx4 v[198:199], off
	s_waitcnt vmcnt(8)
	s_waitcnt lgkmcnt(0)
	s_barrier
	v_mfma_f32_16x16x32_bf16 v[124:127], v[150:153], v[182:185], v[124:127]
	v_mfma_f32_16x16x32_bf16 v[120:123], v[158:161], v[182:185], v[120:123]
	v_mfma_f32_16x16x32_bf16 v[116:119], v[150:153], v[190:193], v[116:119]
	v_mfma_f32_16x16x32_bf16 v[112:115], v[158:161], v[190:193], v[112:115]
	v_mfma_f32_16x16x32_bf16 v[108:111], v[150:153], v[202:205], v[108:111]
	v_mfma_f32_16x16x32_bf16 v[104:107], v[158:161], v[202:205], v[104:107]
	v_mfma_f32_16x16x32_bf16 v[100:103], v[150:153], v[210:213], v[100:103]
	v_mfma_f32_16x16x32_bf16 v[96:99], v[158:161], v[210:213], v[96:99]
	v_mfma_f32_16x16x32_bf16 v[124:127], v[154:157], v[186:189], v[124:127]
	v_mfma_f32_16x16x32_bf16 v[120:123], v[162:165], v[186:189], v[120:123]
	v_mfma_f32_16x16x32_bf16 v[116:119], v[154:157], v[194:197], v[116:119]
	v_mfma_f32_16x16x32_bf16 v[112:115], v[162:165], v[194:197], v[112:115]
	v_mfma_f32_16x16x32_bf16 v[108:111], v[154:157], v[206:209], v[108:111]
	v_mfma_f32_16x16x32_bf16 v[104:107], v[162:165], v[206:209], v[104:107]
	v_mfma_f32_16x16x32_bf16 v[100:103], v[154:157], v[214:217], v[100:103]
	v_mfma_f32_16x16x32_bf16 v[96:99], v[162:165], v[214:217], v[96:99]
	v_mfma_f32_16x16x32_bf16 v[92:95], v[166:169], v[182:185], v[92:95]
	v_mfma_f32_16x16x32_bf16 v[88:91], v[174:177], v[182:185], v[88:91]
	v_mfma_f32_16x16x32_bf16 v[84:87], v[166:169], v[190:193], v[84:87]
	v_mfma_f32_16x16x32_bf16 v[80:83], v[174:177], v[190:193], v[80:83]
	v_mfma_f32_16x16x32_bf16 v[76:79], v[166:169], v[202:205], v[76:79]
	v_mfma_f32_16x16x32_bf16 v[72:75], v[174:177], v[202:205], v[72:75]
	v_mfma_f32_16x16x32_bf16 v[68:71], v[166:169], v[210:213], v[68:71]
	v_mfma_f32_16x16x32_bf16 v[64:67], v[174:177], v[210:213], v[64:67]
	v_mfma_f32_16x16x32_bf16 v[92:95], v[170:173], v[186:189], v[92:95]
	v_mfma_f32_16x16x32_bf16 v[88:91], v[178:181], v[186:189], v[88:91]
	v_mfma_f32_16x16x32_bf16 v[84:87], v[170:173], v[194:197], v[84:87]
	v_mfma_f32_16x16x32_bf16 v[80:83], v[178:181], v[194:197], v[80:83]
	v_mfma_f32_16x16x32_bf16 v[76:79], v[170:173], v[206:209], v[76:79]
	v_mfma_f32_16x16x32_bf16 v[72:75], v[178:181], v[206:209], v[72:75]
	v_mfma_f32_16x16x32_bf16 v[68:71], v[170:173], v[214:217], v[68:71]
	v_mfma_f32_16x16x32_bf16 v[64:67], v[178:181], v[214:217], v[64:67]
	s_barrier
	s_add_i32 s57, s45, s12
	v_lshl_add_u64 v[198:199], s[2:3], 0, v[132:133]
	s_mov_b32 m0, s57
	ds_read_b128 v[182:185], v149 offset:16384
	ds_read_b128 v[186:189], v149 offset:17408
	ds_read_b128 v[190:193], v149 offset:18432
	ds_read_b128 v[194:197], v149 offset:19456
	ds_read_b128 v[202:205], v149 offset:20480
	ds_read_b128 v[206:209], v149 offset:21504
	ds_read_b128 v[210:213], v149 offset:22528
	ds_read_b128 v[214:217], v149 offset:23552
	global_load_lds_dwordx4 v[198:199], off
	s_add_i32 m0, s57, 0x2000
	s_add_u32 s58, s2, 0x40000
	v_lshl_add_u64 v[218:219], s[2:3], 0, v[128:129]
	s_addc_u32 s59, s3, 0
	s_add_i32 s57, s46, s12
	global_load_lds_dwordx4 v[218:219], off
	v_lshl_add_u64 v[220:221], s[58:59], 0, v[132:133]
	s_mov_b32 m0, s57
	v_lshl_add_u64 v[222:223], s[34:35], 0, v[130:131]
	global_load_lds_dwordx4 v[220:221], off
	v_lshl_add_u64 v[220:221], s[58:59], 0, v[128:129]
	s_add_i32 m0, s57, 0x2000
	s_nop 0
	global_load_lds_dwordx4 v[220:221], off
	v_lshl_add_u64 v[220:221], s[34:35], 0, v[134:135]
	s_mov_b32 m0, s7
	s_nop 0
	global_load_lds_dwordx4 v[220:221], off
	s_mov_b32 m0, s15
	s_nop 0
	global_load_lds_dwordx4 v[222:223], off
	s_waitcnt vmcnt(8)
	s_waitcnt lgkmcnt(0)
	s_barrier
; #define PG8_STAGE(bufoff, gbase, voff) do { _Pragma("unroll") for (int _i = 0; _i < 2; ++_i) \
;         __builtin_amdgcn_global_load_lds((const unsigned*)((const char*)(gbase) + (voff)[_i]), (LAS unsigned*)(lds + (bufoff) + ldsw + _i * 8192), 16, 0, 0); } while (0)
; #define PG8_LDA(dst, b, h) do { _Pragma("unroll") for (int m = 0; m < 4; ++m) _Pragma("unroll") for (int k = 0; k < 2; ++k) dst[m][k] = *(const LAS bf16x8*)(lds + PG8_SA(b, h) + aoff + m * 2048 + k * 1024); } while (0)
; #define PG8_LDB(dst, b, h) do { _Pragma("unroll") for (int n = 0; n < 2; ++n) _Pragma("unroll") for (int k = 0; k < 2; ++k) dst[n][k] = *(const LAS bf16x8*)(lds + PG8_SB(b, h) + boff + n * 2048 + k * 1024); } while (0)
; #define PG8_MMA(ai, bj, At, Bt) do { __builtin_amdgcn_s_setprio(1); _Pragma("unroll") for (int m = 0; m < 4; ++m) _Pragma("unroll") for (int n = 0; n < 2; ++n) _Pragma("unroll") for (int k = 0; k < 2; ++k) \
;         acc[ai][bj][m][n] = __builtin_amdgcn_mfma_f32_16x16x32_bf16(Bt[n][k], At[m][k], acc[ai][bj][m][n], 0, 0, 0); __builtin_amdgcn_s_setprio(0); } while (0)
; #define PG8_WAIT_V(n) asm volatile("s_waitcnt vmcnt(" #n ")" ::: "memory")
; #define PG8_WAIT_L(n) asm volatile("s_waitcnt lgkmcnt(" #n ")" ::: "memory")
; #define PG8_BAR __builtin_amdgcn_s_barrier()
; #define PG8_SCHED __builtin_amdgcn_sched_barrier(0)
; template <class Epi, bool BSEL = false>
; __device__ __forceinline__ void gemm_phase(LAS unsigned char* lds, const Gemm g, const Order& S, const Epi& E, const int tid) {
;     ...
;             PG8_WAIT_V(8); PG8_WAIT_L(0); PG8_BAR; PG8_MMA(1, 0, At, B0); PG8_MMA(1, 1, At, B1); PG8_BAR; PG8_SCHED;
;             PG8_LDB(B0, 1, 0); PG8_LDB(B1, 1, 1); PG8_SCHED; PG8_LDA(At, 1, 0); PG8_STAGE(PG8_SA(0, 1), a2 + hstepA, voffA);
;             PG8_WAIT_V(8); PG8_WAIT_L(0); PG8_BAR; PG8_MMA(0, 0, At, B0); PG8_MMA(0, 1, At, B1); PG8_BAR; PG8_SCHED;
	v_mfma_f32_16x16x32_bf16 v[60:63], v[150:153], v[182:185], v[60:63]
	v_mfma_f32_16x16x32_bf16 v[56:59], v[158:161], v[182:185], v[56:59]
	v_mfma_f32_16x16x32_bf16 v[52:55], v[150:153], v[190:193], v[52:55]
	v_mfma_f32_16x16x32_bf16 v[48:51], v[158:161], v[190:193], v[48:51]
	v_mfma_f32_16x16x32_bf16 v[44:47], v[150:153], v[202:205], v[44:47]
	v_mfma_f32_16x16x32_bf16 v[40:43], v[158:161], v[202:205], v[40:43]
	v_mfma_f32_16x16x32_bf16 v[36:39], v[150:153], v[210:213], v[36:39]
	v_mfma_f32_16x16x32_bf16 v[32:35], v[158:161], v[210:213], v[32:35]
	v_mfma_f32_16x16x32_bf16 v[60:63], v[154:157], v[186:189], v[60:63]
	v_mfma_f32_16x16x32_bf16 v[56:59], v[162:165], v[186:189], v[56:59]
	v_mfma_f32_16x16x32_bf16 v[52:55], v[154:157], v[194:197], v[52:55]
	v_mfma_f32_16x16x32_bf16 v[48:51], v[162:165], v[194:197], v[48:51]
	v_mfma_f32_16x16x32_bf16 v[44:47], v[154:157], v[206:209], v[44:47]
	v_mfma_f32_16x16x32_bf16 v[40:43], v[162:165], v[206:209], v[40:43]
	v_mfma_f32_16x16x32_bf16 v[36:39], v[154:157], v[214:217], v[36:39]
	v_mfma_f32_16x16x32_bf16 v[32:35], v[162:165], v[214:217], v[32:35]
	v_mfma_f32_16x16x32_bf16 v[28:31], v[166:169], v[182:185], v[28:31]
	v_mfma_f32_16x16x32_bf16 v[24:27], v[174:177], v[182:185], v[24:27]
	v_mfma_f32_16x16x32_bf16 v[20:23], v[166:169], v[190:193], v[20:23]
	v_mfma_f32_16x16x32_bf16 v[16:19], v[174:177], v[190:193], v[16:19]
	v_mfma_f32_16x16x32_bf16 v[12:15], v[166:169], v[202:205], v[12:15]
	v_mfma_f32_16x16x32_bf16 v[8:11], v[174:177], v[202:205], v[8:11]
	v_mfma_f32_16x16x32_bf16 v[4:7], v[166:169], v[210:213], v[4:7]
	v_mfma_f32_16x16x32_bf16 v[0:3], v[174:177], v[210:213], v[0:3]
	v_mfma_f32_16x16x32_bf16 v[28:31], v[170:173], v[186:189], v[28:31]
	v_mfma_f32_16x16x32_bf16 v[24:27], v[178:181], v[186:189], v[24:27]
	v_mfma_f32_16x16x32_bf16 v[20:23], v[170:173], v[194:197], v[20:23]
	v_mfma_f32_16x16x32_bf16 v[16:19], v[178:181], v[194:197], v[16:19]
	v_mfma_f32_16x16x32_bf16 v[12:15], v[170:173], v[206:209], v[12:15]
	v_mfma_f32_16x16x32_bf16 v[8:11], v[178:181], v[206:209], v[8:11]
	v_mfma_f32_16x16x32_bf16 v[4:7], v[170:173], v[214:217], v[4:7]
	v_mfma_f32_16x16x32_bf16 v[0:3], v[178:181], v[214:217], v[0:3]
	s_barrier
	s_add_i32 s57, 0, 0x18000
	s_add_i32 s58, 0, 0x1c000
	v_add_u32_e32 v162, s57, v147
	v_add_u32_e32 v178, s58, v147
	ds_read_b128 v[150:153], v162
	ds_read_b128 v[154:157], v162 offset:1024
	ds_read_b128 v[158:161], v162 offset:2048
	ds_read_b128 v[162:165], v162 offset:3072
	ds_read_b128 v[166:169], v178
	ds_read_b128 v[170:173], v178 offset:1024
	ds_read_b128 v[174:177], v178 offset:2048
	ds_read_b128 v[178:181], v178 offset:3072
	s_add_u32 s34, s34, 0x40000
	s_addc_u32 s35, s35, 0
	s_mov_b32 m0, s40
	v_lshl_add_u64 v[224:225], s[34:35], 0, v[134:135]
	ds_read_b128 v[182:185], v149 offset:32768
	ds_read_b128 v[186:189], v149 offset:33792
	ds_read_b128 v[190:193], v149 offset:34816
	ds_read_b128 v[194:197], v149 offset:35840
	ds_read_b128 v[202:205], v149 offset:36864
	ds_read_b128 v[206:209], v149 offset:37888
	ds_read_b128 v[210:213], v149 offset:38912
	ds_read_b128 v[214:217], v149 offset:39936
	global_load_lds_dwordx4 v[224:225], off
	v_lshl_add_u64 v[224:225], s[34:35], 0, v[130:131]
	s_mov_b32 m0, s41
	s_nop 0
	global_load_lds_dwordx4 v[224:225], off
	s_waitcnt vmcnt(8)
	s_waitcnt lgkmcnt(0)
	s_barrier
	v_mfma_f32_16x16x32_bf16 v[124:127], v[150:153], v[182:185], v[124:127]
	v_mfma_f32_16x16x32_bf16 v[120:123], v[158:161], v[182:185], v[120:123]
	v_mfma_f32_16x16x32_bf16 v[116:119], v[150:153], v[190:193], v[116:119]
	v_mfma_f32_16x16x32_bf16 v[112:115], v[158:161], v[190:193], v[112:115]
	v_mfma_f32_16x16x32_bf16 v[108:111], v[150:153], v[202:205], v[108:111]
	v_mfma_f32_16x16x32_bf16 v[104:107], v[158:161], v[202:205], v[104:107]
	v_mfma_f32_16x16x32_bf16 v[100:103], v[150:153], v[210:213], v[100:103]
	v_mfma_f32_16x16x32_bf16 v[96:99], v[158:161], v[210:213], v[96:99]
	v_mfma_f32_16x16x32_bf16 v[124:127], v[154:157], v[186:189], v[124:127]
	v_mfma_f32_16x16x32_bf16 v[120:123], v[162:165], v[186:189], v[120:123]
	v_mfma_f32_16x16x32_bf16 v[116:119], v[154:157], v[194:197], v[116:119]
	v_mfma_f32_16x16x32_bf16 v[112:115], v[162:165], v[194:197], v[112:115]
	v_mfma_f32_16x16x32_bf16 v[108:111], v[154:157], v[206:209], v[108:111]
	v_mfma_f32_16x16x32_bf16 v[104:107], v[162:165], v[206:209], v[104:107]
	v_mfma_f32_16x16x32_bf16 v[100:103], v[154:157], v[214:217], v[100:103]
	v_mfma_f32_16x16x32_bf16 v[96:99], v[162:165], v[214:217], v[96:99]
	v_mfma_f32_16x16x32_bf16 v[92:95], v[166:169], v[182:185], v[92:95]
	v_mfma_f32_16x16x32_bf16 v[88:91], v[174:177], v[182:185], v[88:91]
	v_mfma_f32_16x16x32_bf16 v[84:87], v[166:169], v[190:193], v[84:87]
	v_mfma_f32_16x16x32_bf16 v[80:83], v[174:177], v[190:193], v[80:83]
	v_mfma_f32_16x16x32_bf16 v[76:79], v[166:169], v[202:205], v[76:79]
	v_mfma_f32_16x16x32_bf16 v[72:75], v[174:177], v[202:205], v[72:75]
	v_mfma_f32_16x16x32_bf16 v[68:71], v[166:169], v[210:213], v[68:71]
	v_mfma_f32_16x16x32_bf16 v[64:67], v[174:177], v[210:213], v[64:67]
	v_mfma_f32_16x16x32_bf16 v[92:95], v[170:173], v[186:189], v[92:95]
	v_mfma_f32_16x16x32_bf16 v[88:91], v[178:181], v[186:189], v[88:91]
	v_mfma_f32_16x16x32_bf16 v[84:87], v[170:173], v[194:197], v[84:87]
	v_mfma_f32_16x16x32_bf16 v[80:83], v[178:181], v[194:197], v[80:83]
	v_mfma_f32_16x16x32_bf16 v[76:79], v[170:173], v[206:209], v[76:79]
	v_mfma_f32_16x16x32_bf16 v[72:75], v[178:181], v[206:209], v[72:75]
	v_mfma_f32_16x16x32_bf16 v[68:71], v[170:173], v[214:217], v[68:71]
	v_mfma_f32_16x16x32_bf16 v[64:67], v[178:181], v[214:217], v[64:67]
	s_barrier
; #define PG8_STAGE(bufoff, gbase, voff) do { _Pragma("unroll") for (int _i = 0; _i < 2; ++_i) \
;         __builtin_amdgcn_global_load_lds((const unsigned*)((const char*)(gbase) + (voff)[_i]), (LAS unsigned*)(lds + (bufoff) + ldsw + _i * 8192), 16, 0, 0); } while (0)
; #define PG8_STAGEB(bufoff, gbase, perm) do { _Pragma("unroll") for (int _i = 0; _i < 2; ++_i) \
;         __builtin_amdgcn_global_load_lds((const unsigned*)((const char*)(gbase) + ((BSEL && (perm)) ? voffBp[_i] : voffB[_i])), (LAS unsigned*)(lds + (bufoff) + ldsw + _i * 8192), 16, 0, 0); } while (0)
; #define PG8_LDA(dst, b, h) do { _Pragma("unroll") for (int m = 0; m < 4; ++m) _Pragma("unroll") for (int k = 0; k < 2; ++k) dst[m][k] = *(const LAS bf16x8*)(lds + PG8_SA(b, h) + aoff + m * 2048 + k * 1024); } while (0)
; #define PG8_MMA(ai, bj, At, Bt) do { __builtin_amdgcn_s_setprio(1); _Pragma("unroll") for (int m = 0; m < 4; ++m) _Pragma("unroll") for (int n = 0; n < 2; ++n) _Pragma("unroll") for (int k = 0; k < 2; ++k) \
;         acc[ai][bj][m][n] = __builtin_amdgcn_mfma_f32_16x16x32_bf16(Bt[n][k], At[m][k], acc[ai][bj][m][n], 0, 0, 0); __builtin_amdgcn_s_setprio(0); } while (0)
; #define PG8_WAIT_V(n) asm volatile("s_waitcnt vmcnt(" #n ")" ::: "memory")
; #define PG8_WAIT_L(n) asm volatile("s_waitcnt lgkmcnt(" #n ")" ::: "memory")
; #define PG8_BAR __builtin_amdgcn_s_barrier()
; #define PG8_SCHED __builtin_amdgcn_sched_barrier(0)
; template <class Epi, bool BSEL = false>
; __device__ __forceinline__ void gemm_phase(LAS unsigned char* lds, const Gemm g, const Order& S, const Epi& E, const int tid) {
;     ...
;             PG8_LDA(At, 1, 1); PG8_STAGEB(PG8_SB(1, 0), b3, p2); PG8_STAGEB(PG8_SB(1, 1), b3 + h2, p2); PG8_STAGE(PG8_SA(1, 0), a3, voffA);
;             PG8_WAIT_V(8); PG8_WAIT_L(0); PG8_BAR; PG8_MMA(1, 0, At, B0); PG8_MMA(1, 1, At, B1); PG8_BAR; PG8_SCHED;
;         }
	s_add_i32 s34, s57, s12
	v_lshl_add_u64 v[198:199], v[198:199], 0, s[20:21]
	s_mov_b32 m0, s34
	ds_read_b128 v[182:185], v149 offset:49152
	ds_read_b128 v[186:189], v149 offset:50176
	ds_read_b128 v[190:193], v149 offset:51200
	ds_read_b128 v[194:197], v149 offset:52224
	ds_read_b128 v[202:205], v149 offset:53248
	ds_read_b128 v[206:209], v149 offset:54272
	ds_read_b128 v[210:213], v149 offset:55296
	ds_read_b128 v[214:217], v149 offset:56320
	global_load_lds_dwordx4 v[198:199], off
	s_add_i32 m0, s34, 0x2000
	s_add_u32 s2, s2, 0x40080
	v_lshl_add_u64 v[198:199], v[218:219], 0, s[20:21]
	s_addc_u32 s3, s3, 0
	s_add_i32 s34, s58, s12
	global_load_lds_dwordx4 v[198:199], off
	v_lshl_add_u64 v[198:199], s[2:3], 0, v[132:133]
	s_mov_b32 m0, s34
	s_nop 0
	global_load_lds_dwordx4 v[198:199], off
	v_lshl_add_u64 v[198:199], s[2:3], 0, v[128:129]
	s_add_i32 m0, s34, 0x2000
	s_nop 0
	global_load_lds_dwordx4 v[198:199], off
	v_lshl_add_u64 v[198:199], v[220:221], 0, s[20:21]
	s_mov_b32 m0, s43
	s_nop 0
	global_load_lds_dwordx4 v[198:199], off
	v_lshl_add_u64 v[198:199], v[222:223], 0, s[20:21]
	s_mov_b32 m0, s44
	s_nop 0
	global_load_lds_dwordx4 v[198:199], off
	s_waitcnt vmcnt(8)
	s_waitcnt lgkmcnt(0)
	s_barrier
	v_mfma_f32_16x16x32_bf16 v[60:63], v[150:153], v[182:185], v[60:63]
	v_mfma_f32_16x16x32_bf16 v[56:59], v[158:161], v[182:185], v[56:59]
	v_mfma_f32_16x16x32_bf16 v[52:55], v[150:153], v[190:193], v[52:55]
	v_mfma_f32_16x16x32_bf16 v[48:51], v[158:161], v[190:193], v[48:51]
	v_mfma_f32_16x16x32_bf16 v[44:47], v[150:153], v[202:205], v[44:47]
	v_mfma_f32_16x16x32_bf16 v[40:43], v[158:161], v[202:205], v[40:43]
	v_mfma_f32_16x16x32_bf16 v[36:39], v[150:153], v[210:213], v[36:39]
	v_mfma_f32_16x16x32_bf16 v[32:35], v[158:161], v[210:213], v[32:35]
	v_mfma_f32_16x16x32_bf16 v[60:63], v[154:157], v[186:189], v[60:63]
	v_mfma_f32_16x16x32_bf16 v[56:59], v[162:165], v[186:189], v[56:59]
	v_mfma_f32_16x16x32_bf16 v[52:55], v[154:157], v[194:197], v[52:55]
	v_mfma_f32_16x16x32_bf16 v[48:51], v[162:165], v[194:197], v[48:51]
	v_mfma_f32_16x16x32_bf16 v[44:47], v[154:157], v[206:209], v[44:47]
	v_mfma_f32_16x16x32_bf16 v[40:43], v[162:165], v[206:209], v[40:43]
	v_mfma_f32_16x16x32_bf16 v[36:39], v[154:157], v[214:217], v[36:39]
	v_mfma_f32_16x16x32_bf16 v[32:35], v[162:165], v[214:217], v[32:35]
	v_mfma_f32_16x16x32_bf16 v[28:31], v[166:169], v[182:185], v[28:31]
	v_mfma_f32_16x16x32_bf16 v[24:27], v[174:177], v[182:185], v[24:27]
	v_mfma_f32_16x16x32_bf16 v[20:23], v[166:169], v[190:193], v[20:23]
	v_mfma_f32_16x16x32_bf16 v[16:19], v[174:177], v[190:193], v[16:19]
	v_mfma_f32_16x16x32_bf16 v[12:15], v[166:169], v[202:205], v[12:15]
	v_mfma_f32_16x16x32_bf16 v[8:11], v[174:177], v[202:205], v[8:11]
	v_mfma_f32_16x16x32_bf16 v[4:7], v[166:169], v[210:213], v[4:7]
	v_mfma_f32_16x16x32_bf16 v[0:3], v[174:177], v[210:213], v[0:3]
	v_mfma_f32_16x16x32_bf16 v[28:31], v[170:173], v[186:189], v[28:31]
	v_mfma_f32_16x16x32_bf16 v[24:27], v[178:181], v[186:189], v[24:27]
	v_mfma_f32_16x16x32_bf16 v[20:23], v[170:173], v[194:197], v[20:23]
	v_mfma_f32_16x16x32_bf16 v[16:19], v[178:181], v[194:197], v[16:19]
	v_mfma_f32_16x16x32_bf16 v[12:15], v[170:173], v[206:209], v[12:15]
	v_mfma_f32_16x16x32_bf16 v[8:11], v[178:181], v[206:209], v[8:11]
	v_mfma_f32_16x16x32_bf16 v[4:7], v[170:173], v[214:217], v[4:7]
	v_mfma_f32_16x16x32_bf16 v[0:3], v[178:181], v[214:217], v[0:3]
	s_barrier
	s_add_i32 s56, s56, 2
	s_add_u32 s38, s38, 0x100
	s_addc_u32 s39, s39, 0
	s_cmp_gt_u32 s56, 13
	s_cbranch_scc0 .LBB0_324
	s_and_b64 vcc, exec, s[22:23]
	s_cbranch_vccz .LBB0_327
	s_barrier

; #define PG8_STAGE(bufoff, gbase, voff) do { _Pragma("unroll") for (int _i = 0; _i < 2; ++_i) \
;         __builtin_amdgcn_global_load_lds((const unsigned*)((const char*)(gbase) + (voff)[_i]), (LAS unsigned*)(lds + (bufoff) + ldsw + _i * 8192), 16, 0, 0); } while (0)
; #define PG8_STAGEB(bufoff, gbase, perm) do { _Pragma("unroll") for (int _i = 0; _i < 2; ++_i) \
;         __builtin_amdgcn_global_load_lds((const unsigned*)((const char*)(gbase) + ((BSEL && (perm)) ? voffBp[_i] : voffB[_i])), (LAS unsigned*)(lds + (bufoff) + ldsw + _i * 8192), 16, 0, 0); } while (0)
; #define PG8_LDA(dst, b, h) do { _Pragma("unroll") for (int m = 0; m < 4; ++m) _Pragma("unroll") for (int k = 0; k < 2; ++k) dst[m][k] = *(const LAS bf16x8*)(lds + PG8_SA(b, h) + aoff + m * 2048 + k * 1024); } while (0)
; #define PG8_LDB(dst, b, h) do { _Pragma("unroll") for (int n = 0; n < 2; ++n) _Pragma("unroll") for (int k = 0; k < 2; ++k) dst[n][k] = *(const LAS bf16x8*)(lds + PG8_SB(b, h) + boff + n * 2048 + k * 1024); } while (0)
; #define PG8_MMA(ai, bj, At, Bt) do { __builtin_amdgcn_s_setprio(1); _Pragma("unroll") for (int m = 0; m < 4; ++m) _Pragma("unroll") for (int n = 0; n < 2; ++n) _Pragma("unroll") for (int k = 0; k < 2; ++k) \
;         acc[ai][bj][m][n] = __builtin_amdgcn_mfma_f32_16x16x32_bf16(Bt[n][k], At[m][k], acc[ai][bj][m][n], 0, 0, 0); __builtin_amdgcn_s_setprio(0); } while (0)
; #define PG8_WAIT_V(n) asm volatile("s_waitcnt vmcnt(" #n ")" ::: "memory")
; #define PG8_WAIT_L(n) asm volatile("s_waitcnt lgkmcnt(" #n ")" ::: "memory")
; template <class Epi, bool BSEL = false>
; __device__ __forceinline__ void gemm_phase(LAS unsigned char* lds, const Gemm g, const Order& S, const Epi& E, const int tid) {
;     ...
;             const char* a2 = last ? nA : cA + (size_t)(t + 2) * kstep; const char* b2 = last ? nB : cB + (size_t)(t + 2) * kstep;
;             const char* a3 = a2 + kstep; const char* b3 = b2 + kstep;
;             const bool p2 = last ? nP : cP; const size_t h2 = last ? nhB : chB;
;             PG8_LDB(B0, 0, 0); PG8_LDB(B1, 0, 1); PG8_SCHED; PG8_LDA(At, 0, 0); PG8_STAGE(PG8_SA(1, 1), a1 + hstepA, voffA);
;             PG8_WAIT_V(8); PG8_WAIT_L(0); PG8_BAR; PG8_MMA(0, 0, At, B0); PG8_MMA(0, 1, At, B1); PG8_BAR; PG8_SCHED;
;             PG8_LDA(At, 0, 1); PG8_STAGEB(PG8_SB(0, 0), b2, p2); PG8_STAGEB(PG8_SB(0, 1), b2 + h2, p2); PG8_STAGE(PG8_SA(0, 0), a2, voffA);
.LBB0_417:
	v_add_u32_e32 v167, s55, v156
	v_add_u32_e32 v201, s56, v156
	ds_read_b128 v[140:143], v167
	ds_read_b128 v[144:147], v167 offset:1024
	ds_read_b128 v[148:151], v167 offset:2048
	ds_read_b128 v[152:155], v167 offset:3072
	ds_read_b128 v[168:171], v201
	ds_read_b128 v[172:175], v201 offset:1024
	ds_read_b128 v[190:193], v201 offset:2048
	ds_read_b128 v[194:197], v201 offset:3072
	s_and_b64 s[2:3], s[46:47], exec
	s_cselect_b32 s45, s41, s5
	s_cselect_b32 s44, s40, s4
	s_cselect_b32 s3, s43, s23
	s_cselect_b32 s2, s42, s22
	s_add_u32 s64, s4, 0xb0080
	s_addc_u32 s65, s5, 0
	s_add_i32 s68, s1, 0xc000
	v_lshl_add_u64 v[176:177], s[64:65], 0, v[130:131]
	s_mov_b32 m0, s68
	s_add_i32 s39, s1, 0xe000
	ds_read_b128 v[202:205], v166
	ds_read_b128 v[206:209], v166 offset:1024
	ds_read_b128 v[210:213], v166 offset:2048
	ds_read_b128 v[214:217], v166 offset:3072
	ds_read_b128 v[218:221], v166 offset:4096
	ds_read_b128 v[222:225], v166 offset:5120
	ds_read_b128 v[226:229], v166 offset:6144
	ds_read_b128 v[230:233], v166 offset:7168
	global_load_lds_dwordx4 v[176:177], off
	v_lshl_add_u64 v[176:177], s[64:65], 0, v[134:135]
	s_mov_b32 m0, s39
	s_nop 0
	global_load_lds_dwordx4 v[176:177], off
	s_waitcnt vmcnt(8)
	s_waitcnt lgkmcnt(0)
	s_barrier
	v_mfma_f32_16x16x32_bf16 v[124:127], v[140:143], v[202:205], v[124:127]
	v_mfma_f32_16x16x32_bf16 v[120:123], v[148:151], v[202:205], v[120:123]
	v_mfma_f32_16x16x32_bf16 v[116:119], v[140:143], v[210:213], v[116:119]
	v_mfma_f32_16x16x32_bf16 v[112:115], v[148:151], v[210:213], v[112:115]
	v_mfma_f32_16x16x32_bf16 v[108:111], v[140:143], v[218:221], v[108:111]
	v_mfma_f32_16x16x32_bf16 v[104:107], v[148:151], v[218:221], v[104:107]
	v_mfma_f32_16x16x32_bf16 v[100:103], v[140:143], v[226:229], v[100:103]
	v_mfma_f32_16x16x32_bf16 v[96:99], v[148:151], v[226:229], v[96:99]
	v_mfma_f32_16x16x32_bf16 v[124:127], v[144:147], v[206:209], v[124:127]
	v_mfma_f32_16x16x32_bf16 v[120:123], v[152:155], v[206:209], v[120:123]
	v_mfma_f32_16x16x32_bf16 v[116:119], v[144:147], v[214:217], v[116:119]
	v_mfma_f32_16x16x32_bf16 v[112:115], v[152:155], v[214:217], v[112:115]
	v_mfma_f32_16x16x32_bf16 v[108:111], v[144:147], v[222:225], v[108:111]
	v_mfma_f32_16x16x32_bf16 v[104:107], v[152:155], v[222:225], v[104:107]
	v_mfma_f32_16x16x32_bf16 v[100:103], v[144:147], v[230:233], v[100:103]
	v_mfma_f32_16x16x32_bf16 v[96:99], v[152:155], v[230:233], v[96:99]
	v_mfma_f32_16x16x32_bf16 v[92:95], v[168:171], v[202:205], v[92:95]
	v_mfma_f32_16x16x32_bf16 v[88:91], v[190:193], v[202:205], v[88:91]
	v_mfma_f32_16x16x32_bf16 v[84:87], v[168:171], v[210:213], v[84:87]
	v_mfma_f32_16x16x32_bf16 v[80:83], v[190:193], v[210:213], v[80:83]
	v_mfma_f32_16x16x32_bf16 v[76:79], v[168:171], v[218:221], v[76:79]
	v_mfma_f32_16x16x32_bf16 v[72:75], v[190:193], v[218:221], v[72:75]
	v_mfma_f32_16x16x32_bf16 v[68:71], v[168:171], v[226:229], v[68:71]
	v_mfma_f32_16x16x32_bf16 v[64:67], v[190:193], v[226:229], v[64:67]
	v_mfma_f32_16x16x32_bf16 v[92:95], v[172:175], v[206:209], v[92:95]
	v_mfma_f32_16x16x32_bf16 v[88:91], v[194:197], v[206:209], v[88:91]
	v_mfma_f32_16x16x32_bf16 v[84:87], v[172:175], v[214:217], v[84:87]
	v_mfma_f32_16x16x32_bf16 v[80:83], v[194:197], v[214:217], v[80:83]
	v_mfma_f32_16x16x32_bf16 v[76:79], v[172:175], v[222:225], v[76:79]
	v_mfma_f32_16x16x32_bf16 v[72:75], v[194:197], v[222:225], v[72:75]
	v_mfma_f32_16x16x32_bf16 v[68:71], v[172:175], v[230:233], v[68:71]
	v_mfma_f32_16x16x32_bf16 v[64:67], v[194:197], v[230:233], v[64:67]
	s_barrier
	v_lshl_add_u64 v[176:177], s[22:23], 0, v[132:133]
	s_add_i32 s66, s55, s20
	v_lshl_add_u64 v[198:199], v[176:177], 0, s[34:35]
	s_mov_b32 m0, s66
	s_add_i32 s63, s66, 0x2000
	ds_read_b128 v[202:205], v166 offset:16384
	ds_read_b128 v[206:209], v166 offset:17408
	ds_read_b128 v[210:213], v166 offset:18432
	ds_read_b128 v[214:217], v166 offset:19456
	ds_read_b128 v[218:221], v166 offset:20480
	ds_read_b128 v[222:225], v166 offset:21504
	ds_read_b128 v[226:229], v166 offset:22528
	ds_read_b128 v[230:233], v166 offset:23552
	global_load_lds_dwordx4 v[198:199], off
	v_lshl_add_u64 v[198:199], s[22:23], 0, v[136:137]
	s_add_u32 s70, s22, 0xb0100
	v_lshl_add_u64 v[234:235], v[198:199], 0, s[34:35]
	s_mov_b32 m0, s63
	s_addc_u32 s71, s23, 0
	s_add_i32 s64, s56, s20
	global_load_lds_dwordx4 v[234:235], off
	v_lshl_add_u64 v[234:235], s[70:71], 0, v[132:133]
	s_mov_b32 m0, s64
	s_add_i32 s65, s64, 0x2000
	global_load_lds_dwordx4 v[234:235], off
	v_lshl_add_u64 v[234:235], s[70:71], 0, v[136:137]
	s_mov_b32 m0, s65
	s_nop 0
	global_load_lds_dwordx4 v[234:235], off
	v_lshl_add_u64 v[234:235], s[4:5], 0, v[130:131]
	v_lshl_add_u64 v[236:237], v[234:235], 0, s[34:35]
	s_mov_b32 m0, s1
	s_nop 0
	global_load_lds_dwordx4 v[236:237], off
	v_lshl_add_u64 v[236:237], s[4:5], 0, v[134:135]
	v_lshl_add_u64 v[238:239], v[236:237], 0, s[34:35]
	s_mov_b32 m0, s49
	s_nop 0
	global_load_lds_dwordx4 v[238:239], off
	s_waitcnt vmcnt(8)
	s_waitcnt lgkmcnt(0)
	s_barrier
; #define PG8_STAGE(bufoff, gbase, voff) do { _Pragma("unroll") for (int _i = 0; _i < 2; ++_i) \
;         __builtin_amdgcn_global_load_lds((const unsigned*)((const char*)(gbase) + (voff)[_i]), (LAS unsigned*)(lds + (bufoff) + ldsw + _i * 8192), 16, 0, 0); } while (0)
; #define PG8_LDA(dst, b, h) do { _Pragma("unroll") for (int m = 0; m < 4; ++m) _Pragma("unroll") for (int k = 0; k < 2; ++k) dst[m][k] = *(const LAS bf16x8*)(lds + PG8_SA(b, h) + aoff + m * 2048 + k * 1024); } while (0)
; #define PG8_LDB(dst, b, h) do { _Pragma("unroll") for (int n = 0; n < 2; ++n) _Pragma("unroll") for (int k = 0; k < 2; ++k) dst[n][k] = *(const LAS bf16x8*)(lds + PG8_SB(b, h) + boff + n * 2048 + k * 1024); } while (0)
; #define PG8_MMA(ai, bj, At, Bt) do { __builtin_amdgcn_s_setprio(1); _Pragma("unroll") for (int m = 0; m < 4; ++m) _Pragma("unroll") for (int n = 0; n < 2; ++n) _Pragma("unroll") for (int k = 0; k < 2; ++k) \
;         acc[ai][bj][m][n] = __builtin_amdgcn_mfma_f32_16x16x32_bf16(Bt[n][k], At[m][k], acc[ai][bj][m][n], 0, 0, 0); __builtin_amdgcn_s_setprio(0); } while (0)
; #define PG8_WAIT_V(n) asm volatile("s_waitcnt vmcnt(" #n ")" ::: "memory")
; #define PG8_WAIT_L(n) asm volatile("s_waitcnt lgkmcnt(" #n ")" ::: "memory")
; #define PG8_BAR __builtin_amdgcn_s_barrier()
; #define PG8_SCHED __builtin_amdgcn_sched_barrier(0)
; template <class Epi, bool BSEL = false>
; __device__ __forceinline__ void gemm_phase(LAS unsigned char* lds, const Gemm g, const Order& S, const Epi& E, const int tid) {
;     ...
;             PG8_WAIT_V(8); PG8_WAIT_L(0); PG8_BAR; PG8_MMA(1, 0, At, B0); PG8_MMA(1, 1, At, B1); PG8_BAR; PG8_SCHED;
;             PG8_LDB(B0, 1, 0); PG8_LDB(B1, 1, 1); PG8_SCHED; PG8_LDA(At, 1, 0); PG8_STAGE(PG8_SA(0, 1), a2 + hstepA, voffA);
;             PG8_WAIT_V(8); PG8_WAIT_L(0); PG8_BAR; PG8_MMA(0, 0, At, B0); PG8_MMA(0, 1, At, B1); PG8_BAR; PG8_SCHED;
	v_mfma_f32_16x16x32_bf16 v[60:63], v[140:143], v[202:205], v[60:63]
	v_mfma_f32_16x16x32_bf16 v[56:59], v[148:151], v[202:205], v[56:59]
	v_mfma_f32_16x16x32_bf16 v[52:55], v[140:143], v[210:213], v[52:55]
	v_mfma_f32_16x16x32_bf16 v[48:51], v[148:151], v[210:213], v[48:51]
	v_mfma_f32_16x16x32_bf16 v[44:47], v[140:143], v[218:221], v[44:47]
	v_mfma_f32_16x16x32_bf16 v[40:43], v[148:151], v[218:221], v[40:43]
	v_mfma_f32_16x16x32_bf16 v[36:39], v[140:143], v[226:229], v[36:39]
	v_mfma_f32_16x16x32_bf16 v[32:35], v[148:151], v[226:229], v[32:35]
	v_mfma_f32_16x16x32_bf16 v[60:63], v[144:147], v[206:209], v[60:63]
	v_mfma_f32_16x16x32_bf16 v[56:59], v[152:155], v[206:209], v[56:59]
	v_mfma_f32_16x16x32_bf16 v[52:55], v[144:147], v[214:217], v[52:55]
	v_mfma_f32_16x16x32_bf16 v[48:51], v[152:155], v[214:217], v[48:51]
	v_mfma_f32_16x16x32_bf16 v[44:47], v[144:147], v[222:225], v[44:47]
	v_mfma_f32_16x16x32_bf16 v[40:43], v[152:155], v[222:225], v[40:43]
	v_mfma_f32_16x16x32_bf16 v[36:39], v[144:147], v[230:233], v[36:39]
	v_mfma_f32_16x16x32_bf16 v[32:35], v[152:155], v[230:233], v[32:35]
	v_mfma_f32_16x16x32_bf16 v[28:31], v[168:171], v[202:205], v[28:31]
	v_mfma_f32_16x16x32_bf16 v[24:27], v[190:193], v[202:205], v[24:27]
	v_mfma_f32_16x16x32_bf16 v[20:23], v[168:171], v[210:213], v[20:23]
	v_mfma_f32_16x16x32_bf16 v[16:19], v[190:193], v[210:213], v[16:19]
	v_mfma_f32_16x16x32_bf16 v[12:15], v[168:171], v[218:221], v[12:15]
	v_mfma_f32_16x16x32_bf16 v[8:11], v[190:193], v[218:221], v[8:11]
	v_mfma_f32_16x16x32_bf16 v[4:7], v[168:171], v[226:229], v[4:7]
	v_mfma_f32_16x16x32_bf16 v[0:3], v[190:193], v[226:229], v[0:3]
	v_mfma_f32_16x16x32_bf16 v[28:31], v[172:175], v[206:209], v[28:31]
	v_mfma_f32_16x16x32_bf16 v[24:27], v[194:197], v[206:209], v[24:27]
	v_mfma_f32_16x16x32_bf16 v[20:23], v[172:175], v[214:217], v[20:23]
	v_mfma_f32_16x16x32_bf16 v[16:19], v[194:197], v[214:217], v[16:19]
	v_mfma_f32_16x16x32_bf16 v[12:15], v[172:175], v[222:225], v[12:15]
	v_mfma_f32_16x16x32_bf16 v[8:11], v[194:197], v[222:225], v[8:11]
	v_mfma_f32_16x16x32_bf16 v[4:7], v[172:175], v[230:233], v[4:7]
	v_mfma_f32_16x16x32_bf16 v[0:3], v[194:197], v[230:233], v[0:3]
	s_barrier
	s_add_i32 s67, 0, 0x18000
	s_add_i32 s69, 0, 0x1c000
	v_add_u32_e32 v240, s67, v156
	v_add_u32_e32 v241, s69, v156
	ds_read_b128 v[140:143], v240
	ds_read_b128 v[144:147], v240 offset:1024
	ds_read_b128 v[148:151], v240 offset:2048
	ds_read_b128 v[152:155], v240 offset:3072
	ds_read_b128 v[168:171], v241
	ds_read_b128 v[172:175], v241 offset:1024
	ds_read_b128 v[190:193], v241 offset:2048
	ds_read_b128 v[194:197], v241 offset:3072
	s_add_u32 s70, s4, 0xb0100
	s_addc_u32 s71, s5, 0
	s_mov_b32 m0, s50
	v_lshl_add_u64 v[238:239], s[70:71], 0, v[130:131]
	ds_read_b128 v[202:205], v166 offset:32768
	ds_read_b128 v[206:209], v166 offset:33792
	ds_read_b128 v[210:213], v166 offset:34816
	ds_read_b128 v[214:217], v166 offset:35840
	ds_read_b128 v[218:221], v166 offset:36864
	ds_read_b128 v[222:225], v166 offset:37888
	ds_read_b128 v[226:229], v166 offset:38912
	ds_read_b128 v[230:233], v166 offset:39936
	global_load_lds_dwordx4 v[238:239], off
	v_lshl_add_u64 v[238:239], s[70:71], 0, v[134:135]
	s_mov_b32 m0, s51
	s_nop 0
	global_load_lds_dwordx4 v[238:239], off
	s_waitcnt vmcnt(8)
	s_waitcnt lgkmcnt(0)
	s_barrier
	v_mfma_f32_16x16x32_bf16 v[124:127], v[140:143], v[202:205], v[124:127]
	v_mfma_f32_16x16x32_bf16 v[120:123], v[148:151], v[202:205], v[120:123]
	v_mfma_f32_16x16x32_bf16 v[116:119], v[140:143], v[210:213], v[116:119]
	v_mfma_f32_16x16x32_bf16 v[112:115], v[148:151], v[210:213], v[112:115]
	v_mfma_f32_16x16x32_bf16 v[108:111], v[140:143], v[218:221], v[108:111]
	v_mfma_f32_16x16x32_bf16 v[104:107], v[148:151], v[218:221], v[104:107]
	v_mfma_f32_16x16x32_bf16 v[100:103], v[140:143], v[226:229], v[100:103]
	v_mfma_f32_16x16x32_bf16 v[96:99], v[148:151], v[226:229], v[96:99]
	v_mfma_f32_16x16x32_bf16 v[124:127], v[144:147], v[206:209], v[124:127]
	v_mfma_f32_16x16x32_bf16 v[120:123], v[152:155], v[206:209], v[120:123]
	v_mfma_f32_16x16x32_bf16 v[116:119], v[144:147], v[214:217], v[116:119]
	v_mfma_f32_16x16x32_bf16 v[112:115], v[152:155], v[214:217], v[112:115]
	v_mfma_f32_16x16x32_bf16 v[108:111], v[144:147], v[222:225], v[108:111]
	v_mfma_f32_16x16x32_bf16 v[104:107], v[152:155], v[222:225], v[104:107]
	v_mfma_f32_16x16x32_bf16 v[100:103], v[144:147], v[230:233], v[100:103]
	v_mfma_f32_16x16x32_bf16 v[96:99], v[152:155], v[230:233], v[96:99]
	v_mfma_f32_16x16x32_bf16 v[92:95], v[168:171], v[202:205], v[92:95]
	v_mfma_f32_16x16x32_bf16 v[88:91], v[190:193], v[202:205], v[88:91]
	v_mfma_f32_16x16x32_bf16 v[84:87], v[168:171], v[210:213], v[84:87]
	v_mfma_f32_16x16x32_bf16 v[80:83], v[190:193], v[210:213], v[80:83]
	v_mfma_f32_16x16x32_bf16 v[76:79], v[168:171], v[218:221], v[76:79]
	v_mfma_f32_16x16x32_bf16 v[72:75], v[190:193], v[218:221], v[72:75]
	v_mfma_f32_16x16x32_bf16 v[68:71], v[168:171], v[226:229], v[68:71]
	v_mfma_f32_16x16x32_bf16 v[64:67], v[190:193], v[226:229], v[64:67]
	v_mfma_f32_16x16x32_bf16 v[92:95], v[172:175], v[206:209], v[92:95]
	v_mfma_f32_16x16x32_bf16 v[88:91], v[194:197], v[206:209], v[88:91]
	v_mfma_f32_16x16x32_bf16 v[84:87], v[172:175], v[214:217], v[84:87]
	v_mfma_f32_16x16x32_bf16 v[80:83], v[194:197], v[214:217], v[80:83]
	v_mfma_f32_16x16x32_bf16 v[76:79], v[172:175], v[222:225], v[76:79]
	v_mfma_f32_16x16x32_bf16 v[72:75], v[194:197], v[222:225], v[72:75]
	v_mfma_f32_16x16x32_bf16 v[68:71], v[172:175], v[230:233], v[68:71]
	v_mfma_f32_16x16x32_bf16 v[64:67], v[194:197], v[230:233], v[64:67]
	s_barrier
; #define PG8_STAGE(bufoff, gbase, voff) do { _Pragma("unroll") for (int _i = 0; _i < 2; ++_i) \
;         __builtin_amdgcn_global_load_lds((const unsigned*)((const char*)(gbase) + (voff)[_i]), (LAS unsigned*)(lds + (bufoff) + ldsw + _i * 8192), 16, 0, 0); } while (0)
; #define PG8_STAGEB(bufoff, gbase, perm) do { _Pragma("unroll") for (int _i = 0; _i < 2; ++_i) \
;         __builtin_amdgcn_global_load_lds((const unsigned*)((const char*)(gbase) + ((BSEL && (perm)) ? voffBp[_i] : voffB[_i])), (LAS unsigned*)(lds + (bufoff) + ldsw + _i * 8192), 16, 0, 0); } while (0)
; #define PG8_LDA(dst, b, h) do { _Pragma("unroll") for (int m = 0; m < 4; ++m) _Pragma("unroll") for (int k = 0; k < 2; ++k) dst[m][k] = *(const LAS bf16x8*)(lds + PG8_SA(b, h) + aoff + m * 2048 + k * 1024); } while (0)
; #define PG8_LDB(dst, b, h) do { _Pragma("unroll") for (int n = 0; n < 2; ++n) _Pragma("unroll") for (int k = 0; k < 2; ++k) dst[n][k] = *(const LAS bf16x8*)(lds + PG8_SB(b, h) + boff + n * 2048 + k * 1024); } while (0)
; #define PG8_WAIT_V(n) asm volatile("s_waitcnt vmcnt(" #n ")" ::: "memory")
; #define PG8_WAIT_L(n) asm volatile("s_waitcnt lgkmcnt(" #n ")" ::: "memory")
; template <class Epi, bool BSEL = false>
; __device__ __forceinline__ void gemm_phase(LAS unsigned char* lds, const Gemm g, const Order& S, const Epi& E, const int tid) {
;     ...
;             PG8_LDB(B0, 0, 0); PG8_LDB(B1, 0, 1); PG8_SCHED; PG8_LDA(At, 0, 0); PG8_STAGE(PG8_SA(1, 1), a1 + hstepA, voffA);
;             PG8_WAIT_V(8); PG8_WAIT_L(0); PG8_BAR; PG8_MMA(0, 0, At, B0); PG8_MMA(0, 1, At, B1); PG8_BAR; PG8_SCHED;
;             PG8_LDA(At, 0, 1); PG8_STAGEB(PG8_SB(0, 0), b2, p2); PG8_STAGEB(PG8_SB(0, 1), b2 + h2, p2); PG8_STAGE(PG8_SA(0, 0), a2, voffA);
;             PG8_WAIT_V(8); PG8_WAIT_L(0); PG8_BAR; PG8_MMA(1, 0, At, B0); PG8_MMA(1, 1, At, B1); PG8_BAR; PG8_SCHED;
;             PG8_LDB(B0, 1, 0); PG8_LDB(B1, 1, 1); PG8_SCHED; PG8_LDA(At, 1, 0); PG8_STAGE(PG8_SA(0, 1), a2 + hstepA, voffA);
;             PG8_WAIT_V(8); PG8_WAIT_L(0); PG8_BAR; PG8_MMA(0, 0, At, B0); PG8_MMA(0, 1, At, B1); PG8_BAR; PG8_SCHED;
;             PG8_LDA(At, 1, 1); PG8_STAGEB(PG8_SB(1, 0), b3, p2); PG8_STAGEB(PG8_SB(1, 1), b3 + h2, p2); PG8_STAGE(PG8_SA(1, 0), a3, voffA);
;             PG8_WAIT_V(8); PG8_WAIT_L(0); PG8_BAR; PG8_MMA(1, 0, At, B0); PG8_MMA(1, 1, At, B1); PG8_BAR; PG8_SCHED;
	s_add_i32 s71, s67, s20
	s_add_i32 s67, s71, 0x2000
	v_lshl_add_u64 v[176:177], v[176:177], 0, s[36:37]
	s_mov_b32 m0, s71
	s_add_u32 s72, s22, 0xb0180
	ds_read_b128 v[202:205], v166 offset:49152
	ds_read_b128 v[206:209], v166 offset:50176
	ds_read_b128 v[210:213], v166 offset:51200
	ds_read_b128 v[214:217], v166 offset:52224
	ds_read_b128 v[218:221], v166 offset:53248
	ds_read_b128 v[222:225], v166 offset:54272
	ds_read_b128 v[226:229], v166 offset:55296
	ds_read_b128 v[230:233], v166 offset:56320
	global_load_lds_dwordx4 v[176:177], off
	v_lshl_add_u64 v[176:177], v[198:199], 0, s[36:37]
	s_mov_b32 m0, s67
	s_addc_u32 s73, s23, 0
	s_add_i32 s69, s69, s20
	global_load_lds_dwordx4 v[176:177], off
	v_lshl_add_u64 v[176:177], s[72:73], 0, v[132:133]
	s_mov_b32 m0, s69
	s_add_i32 s70, s69, 0x2000
	global_load_lds_dwordx4 v[176:177], off
	v_lshl_add_u64 v[176:177], s[72:73], 0, v[136:137]
	s_mov_b32 m0, s70
	s_nop 0
	global_load_lds_dwordx4 v[176:177], off
	v_lshl_add_u64 v[176:177], v[234:235], 0, s[36:37]
	s_mov_b32 m0, s53
	s_nop 0
	global_load_lds_dwordx4 v[176:177], off
	v_lshl_add_u64 v[176:177], v[236:237], 0, s[36:37]
	s_mov_b32 m0, s54
	s_nop 0
	global_load_lds_dwordx4 v[176:177], off
	s_waitcnt vmcnt(8)
	s_waitcnt lgkmcnt(0)
	s_barrier
	v_mfma_f32_16x16x32_bf16 v[60:63], v[140:143], v[202:205], v[60:63]
	v_mfma_f32_16x16x32_bf16 v[56:59], v[148:151], v[202:205], v[56:59]
	v_mfma_f32_16x16x32_bf16 v[52:55], v[140:143], v[210:213], v[52:55]
	v_mfma_f32_16x16x32_bf16 v[48:51], v[148:151], v[210:213], v[48:51]
	v_mfma_f32_16x16x32_bf16 v[44:47], v[140:143], v[218:221], v[44:47]
	v_mfma_f32_16x16x32_bf16 v[40:43], v[148:151], v[218:221], v[40:43]
	v_mfma_f32_16x16x32_bf16 v[36:39], v[140:143], v[226:229], v[36:39]
	v_mfma_f32_16x16x32_bf16 v[32:35], v[148:151], v[226:229], v[32:35]
	v_mfma_f32_16x16x32_bf16 v[60:63], v[144:147], v[206:209], v[60:63]
	v_mfma_f32_16x16x32_bf16 v[56:59], v[152:155], v[206:209], v[56:59]
	v_mfma_f32_16x16x32_bf16 v[52:55], v[144:147], v[214:217], v[52:55]
	v_mfma_f32_16x16x32_bf16 v[48:51], v[152:155], v[214:217], v[48:51]
	v_mfma_f32_16x16x32_bf16 v[44:47], v[144:147], v[222:225], v[44:47]
	v_mfma_f32_16x16x32_bf16 v[40:43], v[152:155], v[222:225], v[40:43]
	v_mfma_f32_16x16x32_bf16 v[36:39], v[144:147], v[230:233], v[36:39]
	v_mfma_f32_16x16x32_bf16 v[32:35], v[152:155], v[230:233], v[32:35]
	v_mfma_f32_16x16x32_bf16 v[28:31], v[168:171], v[202:205], v[28:31]
	v_mfma_f32_16x16x32_bf16 v[24:27], v[190:193], v[202:205], v[24:27]
	v_mfma_f32_16x16x32_bf16 v[20:23], v[168:171], v[210:213], v[20:23]
	v_mfma_f32_16x16x32_bf16 v[16:19], v[190:193], v[210:213], v[16:19]
	v_mfma_f32_16x16x32_bf16 v[12:15], v[168:171], v[218:221], v[12:15]
	v_mfma_f32_16x16x32_bf16 v[8:11], v[190:193], v[218:221], v[8:11]
	v_mfma_f32_16x16x32_bf16 v[4:7], v[168:171], v[226:229], v[4:7]
	v_mfma_f32_16x16x32_bf16 v[0:3], v[190:193], v[226:229], v[0:3]
	v_mfma_f32_16x16x32_bf16 v[28:31], v[172:175], v[206:209], v[28:31]
	v_mfma_f32_16x16x32_bf16 v[24:27], v[194:197], v[206:209], v[24:27]
	v_mfma_f32_16x16x32_bf16 v[20:23], v[172:175], v[214:217], v[20:23]
	v_mfma_f32_16x16x32_bf16 v[16:19], v[194:197], v[214:217], v[16:19]
	v_mfma_f32_16x16x32_bf16 v[12:15], v[172:175], v[222:225], v[12:15]
	v_mfma_f32_16x16x32_bf16 v[8:11], v[194:197], v[222:225], v[8:11]
	v_mfma_f32_16x16x32_bf16 v[4:7], v[172:175], v[230:233], v[4:7]
	v_mfma_f32_16x16x32_bf16 v[0:3], v[194:197], v[230:233], v[0:3]
	s_barrier
	ds_read_b128 v[140:143], v167
	ds_read_b128 v[144:147], v167 offset:1024
	ds_read_b128 v[148:151], v167 offset:2048
	ds_read_b128 v[152:155], v167 offset:3072
	ds_read_b128 v[168:171], v201
	ds_read_b128 v[172:175], v201 offset:1024
	ds_read_b128 v[190:193], v201 offset:2048
	ds_read_b128 v[194:197], v201 offset:3072
	s_add_u32 s72, s4, 0xb0180
	s_addc_u32 s73, s5, 0
	s_mov_b32 m0, s68
	v_lshl_add_u64 v[176:177], s[72:73], 0, v[130:131]
	ds_read_b128 v[202:205], v166
	ds_read_b128 v[206:209], v166 offset:1024
	ds_read_b128 v[210:213], v166 offset:2048
	ds_read_b128 v[214:217], v166 offset:3072
	ds_read_b128 v[218:221], v166 offset:4096
	ds_read_b128 v[222:225], v166 offset:5120
	ds_read_b128 v[226:229], v166 offset:6144
	ds_read_b128 v[230:233], v166 offset:7168
	global_load_lds_dwordx4 v[176:177], off
	v_lshl_add_u64 v[176:177], s[72:73], 0, v[134:135]
	s_mov_b32 m0, s39
	s_nop 0
	global_load_lds_dwordx4 v[176:177], off
	s_waitcnt vmcnt(8)
	s_waitcnt lgkmcnt(0)
	s_barrier
	v_mfma_f32_16x16x32_bf16 v[124:127], v[140:143], v[202:205], v[124:127]
	v_mfma_f32_16x16x32_bf16 v[120:123], v[148:151], v[202:205], v[120:123]
	v_mfma_f32_16x16x32_bf16 v[116:119], v[140:143], v[210:213], v[116:119]
	v_mfma_f32_16x16x32_bf16 v[112:115], v[148:151], v[210:213], v[112:115]
	v_mfma_f32_16x16x32_bf16 v[108:111], v[140:143], v[218:221], v[108:111]
	v_mfma_f32_16x16x32_bf16 v[104:107], v[148:151], v[218:221], v[104:107]
	v_mfma_f32_16x16x32_bf16 v[100:103], v[140:143], v[226:229], v[100:103]
	v_mfma_f32_16x16x32_bf16 v[96:99], v[148:151], v[226:229], v[96:99]
	v_mfma_f32_16x16x32_bf16 v[124:127], v[144:147], v[206:209], v[124:127]
	v_mfma_f32_16x16x32_bf16 v[120:123], v[152:155], v[206:209], v[120:123]
	v_mfma_f32_16x16x32_bf16 v[116:119], v[144:147], v[214:217], v[116:119]
	v_mfma_f32_16x16x32_bf16 v[112:115], v[152:155], v[214:217], v[112:115]
	v_mfma_f32_16x16x32_bf16 v[108:111], v[144:147], v[222:225], v[108:111]
	v_mfma_f32_16x16x32_bf16 v[104:107], v[152:155], v[222:225], v[104:107]
	v_mfma_f32_16x16x32_bf16 v[100:103], v[144:147], v[230:233], v[100:103]
	v_mfma_f32_16x16x32_bf16 v[96:99], v[152:155], v[230:233], v[96:99]
	v_mfma_f32_16x16x32_bf16 v[92:95], v[168:171], v[202:205], v[92:95]
	v_mfma_f32_16x16x32_bf16 v[88:91], v[190:193], v[202:205], v[88:91]
	v_mfma_f32_16x16x32_bf16 v[84:87], v[168:171], v[210:213], v[84:87]
	v_mfma_f32_16x16x32_bf16 v[80:83], v[190:193], v[210:213], v[80:83]
	v_mfma_f32_16x16x32_bf16 v[76:79], v[168:171], v[218:221], v[76:79]
	v_mfma_f32_16x16x32_bf16 v[72:75], v[190:193], v[218:221], v[72:75]
	v_mfma_f32_16x16x32_bf16 v[68:71], v[168:171], v[226:229], v[68:71]
	v_mfma_f32_16x16x32_bf16 v[64:67], v[190:193], v[226:229], v[64:67]
	v_mfma_f32_16x16x32_bf16 v[92:95], v[172:175], v[206:209], v[92:95]
	v_mfma_f32_16x16x32_bf16 v[88:91], v[194:197], v[206:209], v[88:91]
	v_mfma_f32_16x16x32_bf16 v[84:87], v[172:175], v[214:217], v[84:87]
	v_mfma_f32_16x16x32_bf16 v[80:83], v[194:197], v[214:217], v[80:83]
	v_mfma_f32_16x16x32_bf16 v[76:79], v[172:175], v[222:225], v[76:79]
	v_mfma_f32_16x16x32_bf16 v[72:75], v[194:197], v[222:225], v[72:75]
	v_mfma_f32_16x16x32_bf16 v[68:71], v[172:175], v[230:233], v[68:71]
	v_mfma_f32_16x16x32_bf16 v[64:67], v[194:197], v[230:233], v[64:67]
	s_barrier
; #define PG8_STAGE(bufoff, gbase, voff) do { _Pragma("unroll") for (int _i = 0; _i < 2; ++_i) \
;         __builtin_amdgcn_global_load_lds((const unsigned*)((const char*)(gbase) + (voff)[_i]), (LAS unsigned*)(lds + (bufoff) + ldsw + _i * 8192), 16, 0, 0); } while (0)
; #define PG8_STAGEB(bufoff, gbase, perm) do { _Pragma("unroll") for (int _i = 0; _i < 2; ++_i) \
;         __builtin_amdgcn_global_load_lds((const unsigned*)((const char*)(gbase) + ((BSEL && (perm)) ? voffBp[_i] : voffB[_i])), (LAS unsigned*)(lds + (bufoff) + ldsw + _i * 8192), 16, 0, 0); } while (0)
; #define PG8_LDA(dst, b, h) do { _Pragma("unroll") for (int m = 0; m < 4; ++m) _Pragma("unroll") for (int k = 0; k < 2; ++k) dst[m][k] = *(const LAS bf16x8*)(lds + PG8_SA(b, h) + aoff + m * 2048 + k * 1024); } while (0)
; #define PG8_LDB(dst, b, h) do { _Pragma("unroll") for (int n = 0; n < 2; ++n) _Pragma("unroll") for (int k = 0; k < 2; ++k) dst[n][k] = *(const LAS bf16x8*)(lds + PG8_SB(b, h) + boff + n * 2048 + k * 1024); } while (0)
; #define PG8_MMA(ai, bj, At, Bt) do { __builtin_amdgcn_s_setprio(1); _Pragma("unroll") for (int m = 0; m < 4; ++m) _Pragma("unroll") for (int n = 0; n < 2; ++n) _Pragma("unroll") for (int k = 0; k < 2; ++k) \
;         acc[ai][bj][m][n] = __builtin_amdgcn_mfma_f32_16x16x32_bf16(Bt[n][k], At[m][k], acc[ai][bj][m][n], 0, 0, 0); __builtin_amdgcn_s_setprio(0); } while (0)
; #define PG8_WAIT_V(n) asm volatile("s_waitcnt vmcnt(" #n ")" ::: "memory")
; #define PG8_WAIT_L(n) asm volatile("s_waitcnt lgkmcnt(" #n ")" ::: "memory")
; #define PG8_BAR __builtin_amdgcn_s_barrier()
; #define PG8_SCHED __builtin_amdgcn_sched_barrier(0)
; template <class Epi, bool BSEL = false>
; __device__ __forceinline__ void gemm_phase(LAS unsigned char* lds, const Gemm g, const Order& S, const Epi& E, const int tid) {
;     ...
;             PG8_LDA(At, 0, 1); PG8_STAGEB(PG8_SB(0, 0), b2, p2); PG8_STAGEB(PG8_SB(0, 1), b2 + h2, p2); PG8_STAGE(PG8_SA(0, 0), a2, voffA);
;             PG8_WAIT_V(8); PG8_WAIT_L(0); PG8_BAR; PG8_MMA(1, 0, At, B0); PG8_MMA(1, 1, At, B1); PG8_BAR; PG8_SCHED;
;             PG8_LDB(B0, 1, 0); PG8_LDB(B1, 1, 1); PG8_SCHED; PG8_LDA(At, 1, 0); PG8_STAGE(PG8_SA(0, 1), a2 + hstepA, voffA);
;             PG8_WAIT_V(8); PG8_WAIT_L(0); PG8_BAR; PG8_MMA(0, 0, At, B0); PG8_MMA(0, 1, At, B1); PG8_BAR; PG8_SCHED;
	s_mov_b32 m0, s66
	v_lshl_add_u64 v[176:177], s[2:3], 0, v[132:133]
	s_add_u32 s72, s2, 0xb0000
	ds_read_b128 v[202:205], v166 offset:16384
	ds_read_b128 v[206:209], v166 offset:17408
	ds_read_b128 v[210:213], v166 offset:18432
	ds_read_b128 v[214:217], v166 offset:19456
	ds_read_b128 v[218:221], v166 offset:20480
	ds_read_b128 v[222:225], v166 offset:21504
	ds_read_b128 v[226:229], v166 offset:22528
	ds_read_b128 v[230:233], v166 offset:23552
	global_load_lds_dwordx4 v[176:177], off
	v_lshl_add_u64 v[198:199], s[2:3], 0, v[136:137]
	s_mov_b32 m0, s63
	s_addc_u32 s73, s3, 0
	global_load_lds_dwordx4 v[198:199], off
	v_lshl_add_u64 v[234:235], s[72:73], 0, v[132:133]
	s_mov_b32 m0, s64
	v_lshl_add_u64 v[236:237], s[44:45], 0, v[134:135]
	global_load_lds_dwordx4 v[234:235], off
	v_lshl_add_u64 v[234:235], s[72:73], 0, v[136:137]
	s_mov_b32 m0, s65
	s_nop 0
	global_load_lds_dwordx4 v[234:235], off
	v_lshl_add_u64 v[234:235], s[44:45], 0, v[130:131]
	s_mov_b32 m0, s1
	s_nop 0
	global_load_lds_dwordx4 v[234:235], off
	s_mov_b32 m0, s49
	s_nop 0
	global_load_lds_dwordx4 v[236:237], off
	s_waitcnt vmcnt(8)
	s_waitcnt lgkmcnt(0)
	s_barrier
	v_mfma_f32_16x16x32_bf16 v[60:63], v[140:143], v[202:205], v[60:63]
	v_mfma_f32_16x16x32_bf16 v[56:59], v[148:151], v[202:205], v[56:59]
	v_mfma_f32_16x16x32_bf16 v[52:55], v[140:143], v[210:213], v[52:55]
	v_mfma_f32_16x16x32_bf16 v[48:51], v[148:151], v[210:213], v[48:51]
	v_mfma_f32_16x16x32_bf16 v[44:47], v[140:143], v[218:221], v[44:47]
	v_mfma_f32_16x16x32_bf16 v[40:43], v[148:151], v[218:221], v[40:43]
	v_mfma_f32_16x16x32_bf16 v[36:39], v[140:143], v[226:229], v[36:39]
	v_mfma_f32_16x16x32_bf16 v[32:35], v[148:151], v[226:229], v[32:35]
	v_mfma_f32_16x16x32_bf16 v[60:63], v[144:147], v[206:209], v[60:63]
	v_mfma_f32_16x16x32_bf16 v[56:59], v[152:155], v[206:209], v[56:59]
	v_mfma_f32_16x16x32_bf16 v[52:55], v[144:147], v[214:217], v[52:55]
	v_mfma_f32_16x16x32_bf16 v[48:51], v[152:155], v[214:217], v[48:51]
	v_mfma_f32_16x16x32_bf16 v[44:47], v[144:147], v[222:225], v[44:47]
	v_mfma_f32_16x16x32_bf16 v[40:43], v[152:155], v[222:225], v[40:43]
	v_mfma_f32_16x16x32_bf16 v[36:39], v[144:147], v[230:233], v[36:39]
	v_mfma_f32_16x16x32_bf16 v[32:35], v[152:155], v[230:233], v[32:35]
	v_mfma_f32_16x16x32_bf16 v[28:31], v[168:171], v[202:205], v[28:31]
	v_mfma_f32_16x16x32_bf16 v[24:27], v[190:193], v[202:205], v[24:27]
	v_mfma_f32_16x16x32_bf16 v[20:23], v[168:171], v[210:213], v[20:23]
	v_mfma_f32_16x16x32_bf16 v[16:19], v[190:193], v[210:213], v[16:19]
	v_mfma_f32_16x16x32_bf16 v[12:15], v[168:171], v[218:221], v[12:15]
	v_mfma_f32_16x16x32_bf16 v[8:11], v[190:193], v[218:221], v[8:11]
	v_mfma_f32_16x16x32_bf16 v[4:7], v[168:171], v[226:229], v[4:7]
	v_mfma_f32_16x16x32_bf16 v[0:3], v[190:193], v[226:229], v[0:3]
	v_mfma_f32_16x16x32_bf16 v[28:31], v[172:175], v[206:209], v[28:31]
	v_mfma_f32_16x16x32_bf16 v[24:27], v[194:197], v[206:209], v[24:27]
	v_mfma_f32_16x16x32_bf16 v[20:23], v[172:175], v[214:217], v[20:23]
	v_mfma_f32_16x16x32_bf16 v[16:19], v[194:197], v[214:217], v[16:19]
	v_mfma_f32_16x16x32_bf16 v[12:15], v[172:175], v[222:225], v[12:15]
	v_mfma_f32_16x16x32_bf16 v[8:11], v[194:197], v[222:225], v[8:11]
	v_mfma_f32_16x16x32_bf16 v[4:7], v[172:175], v[230:233], v[4:7]
	v_mfma_f32_16x16x32_bf16 v[0:3], v[194:197], v[230:233], v[0:3]
	s_barrier
	ds_read_b128 v[140:143], v240
	ds_read_b128 v[144:147], v240 offset:1024
	ds_read_b128 v[148:151], v240 offset:2048
	ds_read_b128 v[152:155], v240 offset:3072
	ds_read_b128 v[168:171], v241
	ds_read_b128 v[172:175], v241 offset:1024
	ds_read_b128 v[190:193], v241 offset:2048
	ds_read_b128 v[194:197], v241 offset:3072
	s_add_u32 s44, s44, 0xb0000
	s_addc_u32 s45, s45, 0
	s_mov_b32 m0, s50
	v_lshl_add_u64 v[238:239], s[44:45], 0, v[130:131]
	ds_read_b128 v[202:205], v166 offset:32768
	ds_read_b128 v[206:209], v166 offset:33792
	ds_read_b128 v[210:213], v166 offset:34816
	ds_read_b128 v[214:217], v166 offset:35840
	ds_read_b128 v[218:221], v166 offset:36864
	ds_read_b128 v[222:225], v166 offset:37888
	ds_read_b128 v[226:229], v166 offset:38912
	ds_read_b128 v[230:233], v166 offset:39936
	global_load_lds_dwordx4 v[238:239], off
	v_lshl_add_u64 v[238:239], s[44:45], 0, v[134:135]
	s_mov_b32 m0, s51
	s_nop 0
	global_load_lds_dwordx4 v[238:239], off
	s_waitcnt vmcnt(8)
	s_waitcnt lgkmcnt(0)
	s_barrier
; #define PG8_STAGE(bufoff, gbase, voff) do { _Pragma("unroll") for (int _i = 0; _i < 2; ++_i) \
;         __builtin_amdgcn_global_load_lds((const unsigned*)((const char*)(gbase) + (voff)[_i]), (LAS unsigned*)(lds + (bufoff) + ldsw + _i * 8192), 16, 0, 0); } while (0)
; #define PG8_STAGEB(bufoff, gbase, perm) do { _Pragma("unroll") for (int _i = 0; _i < 2; ++_i) \
;         __builtin_amdgcn_global_load_lds((const unsigned*)((const char*)(gbase) + ((BSEL && (perm)) ? voffBp[_i] : voffB[_i])), (LAS unsigned*)(lds + (bufoff) + ldsw + _i * 8192), 16, 0, 0); } while (0)
; #define PG8_LDA(dst, b, h) do { _Pragma("unroll") for (int m = 0; m < 4; ++m) _Pragma("unroll") for (int k = 0; k < 2; ++k) dst[m][k] = *(const LAS bf16x8*)(lds + PG8_SA(b, h) + aoff + m * 2048 + k * 1024); } while (0)
; #define PG8_MMA(ai, bj, At, Bt) do { __builtin_amdgcn_s_setprio(1); _Pragma("unroll") for (int m = 0; m < 4; ++m) _Pragma("unroll") for (int n = 0; n < 2; ++n) _Pragma("unroll") for (int k = 0; k < 2; ++k) \
;         acc[ai][bj][m][n] = __builtin_amdgcn_mfma_f32_16x16x32_bf16(Bt[n][k], At[m][k], acc[ai][bj][m][n], 0, 0, 0); __builtin_amdgcn_s_setprio(0); } while (0)
; #define PG8_WAIT_V(n) asm volatile("s_waitcnt vmcnt(" #n ")" ::: "memory")
; #define PG8_WAIT_L(n) asm volatile("s_waitcnt lgkmcnt(" #n ")" ::: "memory")
; #define PG8_BAR __builtin_amdgcn_s_barrier()
; #define PG8_SCHED __builtin_amdgcn_sched_barrier(0)
; template <class Epi, bool BSEL = false>
; __device__ __forceinline__ void gemm_phase(LAS unsigned char* lds, const Gemm g, const Order& S, const Epi& E, const int tid) {
;     ...
;             PG8_WAIT_V(8); PG8_WAIT_L(0); PG8_BAR; PG8_MMA(0, 0, At, B0); PG8_MMA(0, 1, At, B1); PG8_BAR; PG8_SCHED;
;             PG8_LDA(At, 1, 1); PG8_STAGEB(PG8_SB(1, 0), b3, p2); PG8_STAGEB(PG8_SB(1, 1), b3 + h2, p2); PG8_STAGE(PG8_SA(1, 0), a3, voffA);
;             PG8_WAIT_V(8); PG8_WAIT_L(0); PG8_BAR; PG8_MMA(1, 0, At, B0); PG8_MMA(1, 1, At, B1); PG8_BAR; PG8_SCHED;
;         }
;         if constexpr (ALIGN_EPI) { if (wr == 0) PG8_BAR; }
	v_mfma_f32_16x16x32_bf16 v[124:127], v[140:143], v[202:205], v[124:127]
	v_mfma_f32_16x16x32_bf16 v[120:123], v[148:151], v[202:205], v[120:123]
	v_mfma_f32_16x16x32_bf16 v[116:119], v[140:143], v[210:213], v[116:119]
	v_mfma_f32_16x16x32_bf16 v[112:115], v[148:151], v[210:213], v[112:115]
	v_mfma_f32_16x16x32_bf16 v[108:111], v[140:143], v[218:221], v[108:111]
	v_mfma_f32_16x16x32_bf16 v[104:107], v[148:151], v[218:221], v[104:107]
	v_mfma_f32_16x16x32_bf16 v[100:103], v[140:143], v[226:229], v[100:103]
	v_mfma_f32_16x16x32_bf16 v[96:99], v[148:151], v[226:229], v[96:99]
	v_mfma_f32_16x16x32_bf16 v[124:127], v[144:147], v[206:209], v[124:127]
	v_mfma_f32_16x16x32_bf16 v[120:123], v[152:155], v[206:209], v[120:123]
	v_mfma_f32_16x16x32_bf16 v[116:119], v[144:147], v[214:217], v[116:119]
	v_mfma_f32_16x16x32_bf16 v[112:115], v[152:155], v[214:217], v[112:115]
	v_mfma_f32_16x16x32_bf16 v[108:111], v[144:147], v[222:225], v[108:111]
	v_mfma_f32_16x16x32_bf16 v[104:107], v[152:155], v[222:225], v[104:107]
	v_mfma_f32_16x16x32_bf16 v[100:103], v[144:147], v[230:233], v[100:103]
	v_mfma_f32_16x16x32_bf16 v[96:99], v[152:155], v[230:233], v[96:99]
	v_mfma_f32_16x16x32_bf16 v[92:95], v[168:171], v[202:205], v[92:95]
	v_mfma_f32_16x16x32_bf16 v[88:91], v[190:193], v[202:205], v[88:91]
	v_mfma_f32_16x16x32_bf16 v[84:87], v[168:171], v[210:213], v[84:87]
	v_mfma_f32_16x16x32_bf16 v[80:83], v[190:193], v[210:213], v[80:83]
	v_mfma_f32_16x16x32_bf16 v[76:79], v[168:171], v[218:221], v[76:79]
	v_mfma_f32_16x16x32_bf16 v[72:75], v[190:193], v[218:221], v[72:75]
	v_mfma_f32_16x16x32_bf16 v[68:71], v[168:171], v[226:229], v[68:71]
	v_mfma_f32_16x16x32_bf16 v[64:67], v[190:193], v[226:229], v[64:67]
	v_mfma_f32_16x16x32_bf16 v[92:95], v[172:175], v[206:209], v[92:95]
	v_mfma_f32_16x16x32_bf16 v[88:91], v[194:197], v[206:209], v[88:91]
	v_mfma_f32_16x16x32_bf16 v[84:87], v[172:175], v[214:217], v[84:87]
	v_mfma_f32_16x16x32_bf16 v[80:83], v[194:197], v[214:217], v[80:83]
	v_mfma_f32_16x16x32_bf16 v[76:79], v[172:175], v[222:225], v[76:79]
	v_mfma_f32_16x16x32_bf16 v[72:75], v[194:197], v[222:225], v[72:75]
	v_mfma_f32_16x16x32_bf16 v[68:71], v[172:175], v[230:233], v[68:71]
	v_mfma_f32_16x16x32_bf16 v[64:67], v[194:197], v[230:233], v[64:67]
	s_barrier
	s_mov_b32 m0, s71
	v_lshl_add_u64 v[176:177], v[176:177], 0, s[26:27]
	s_add_u32 s2, s2, 0xb0080
	ds_read_b128 v[202:205], v166 offset:49152
	ds_read_b128 v[206:209], v166 offset:50176
	ds_read_b128 v[210:213], v166 offset:51200
	ds_read_b128 v[214:217], v166 offset:52224
	ds_read_b128 v[218:221], v166 offset:53248
	ds_read_b128 v[222:225], v166 offset:54272
	ds_read_b128 v[226:229], v166 offset:55296
	ds_read_b128 v[230:233], v166 offset:56320
	global_load_lds_dwordx4 v[176:177], off
	v_lshl_add_u64 v[176:177], v[198:199], 0, s[26:27]
	s_mov_b32 m0, s67
	s_addc_u32 s3, s3, 0
	global_load_lds_dwordx4 v[176:177], off
	v_lshl_add_u64 v[176:177], s[2:3], 0, v[132:133]
	s_mov_b32 m0, s69
	s_nop 0
	global_load_lds_dwordx4 v[176:177], off
	v_lshl_add_u64 v[176:177], s[2:3], 0, v[136:137]
	s_mov_b32 m0, s70
	s_nop 0
	global_load_lds_dwordx4 v[176:177], off
	v_lshl_add_u64 v[176:177], v[234:235], 0, s[26:27]
	s_mov_b32 m0, s53
	s_nop 0
	global_load_lds_dwordx4 v[176:177], off
	v_lshl_add_u64 v[176:177], v[236:237], 0, s[26:27]
	s_mov_b32 m0, s54
	s_nop 0
	global_load_lds_dwordx4 v[176:177], off
	s_waitcnt vmcnt(8)
	s_waitcnt lgkmcnt(0)
	s_barrier
	v_mfma_f32_16x16x32_bf16 v[60:63], v[140:143], v[202:205], v[60:63]
	v_mfma_f32_16x16x32_bf16 v[56:59], v[148:151], v[202:205], v[56:59]
	v_mfma_f32_16x16x32_bf16 v[52:55], v[140:143], v[210:213], v[52:55]
	v_mfma_f32_16x16x32_bf16 v[48:51], v[148:151], v[210:213], v[48:51]
	v_mfma_f32_16x16x32_bf16 v[44:47], v[140:143], v[218:221], v[44:47]
	v_mfma_f32_16x16x32_bf16 v[40:43], v[148:151], v[218:221], v[40:43]
	v_mfma_f32_16x16x32_bf16 v[36:39], v[140:143], v[226:229], v[36:39]
	v_mfma_f32_16x16x32_bf16 v[32:35], v[148:151], v[226:229], v[32:35]
	v_mfma_f32_16x16x32_bf16 v[60:63], v[144:147], v[206:209], v[60:63]
	v_mfma_f32_16x16x32_bf16 v[56:59], v[152:155], v[206:209], v[56:59]
	v_mfma_f32_16x16x32_bf16 v[52:55], v[144:147], v[214:217], v[52:55]
	v_mfma_f32_16x16x32_bf16 v[48:51], v[152:155], v[214:217], v[48:51]
	v_mfma_f32_16x16x32_bf16 v[44:47], v[144:147], v[222:225], v[44:47]
	v_mfma_f32_16x16x32_bf16 v[40:43], v[152:155], v[222:225], v[40:43]
	v_mfma_f32_16x16x32_bf16 v[36:39], v[144:147], v[230:233], v[36:39]
	v_mfma_f32_16x16x32_bf16 v[32:35], v[152:155], v[230:233], v[32:35]
	v_mfma_f32_16x16x32_bf16 v[28:31], v[168:171], v[202:205], v[28:31]
	v_mfma_f32_16x16x32_bf16 v[24:27], v[190:193], v[202:205], v[24:27]
	v_mfma_f32_16x16x32_bf16 v[20:23], v[168:171], v[210:213], v[20:23]
	v_mfma_f32_16x16x32_bf16 v[16:19], v[190:193], v[210:213], v[16:19]
	v_mfma_f32_16x16x32_bf16 v[12:15], v[168:171], v[218:221], v[12:15]
	v_mfma_f32_16x16x32_bf16 v[8:11], v[190:193], v[218:221], v[8:11]
	v_mfma_f32_16x16x32_bf16 v[4:7], v[168:171], v[226:229], v[4:7]
	v_mfma_f32_16x16x32_bf16 v[0:3], v[190:193], v[226:229], v[0:3]
	v_mfma_f32_16x16x32_bf16 v[28:31], v[172:175], v[206:209], v[28:31]
	v_mfma_f32_16x16x32_bf16 v[24:27], v[194:197], v[206:209], v[24:27]
	v_mfma_f32_16x16x32_bf16 v[20:23], v[172:175], v[214:217], v[20:23]
	v_mfma_f32_16x16x32_bf16 v[16:19], v[194:197], v[214:217], v[16:19]
	v_mfma_f32_16x16x32_bf16 v[12:15], v[172:175], v[222:225], v[12:15]
	v_mfma_f32_16x16x32_bf16 v[8:11], v[194:197], v[222:225], v[8:11]
	v_mfma_f32_16x16x32_bf16 v[4:7], v[172:175], v[230:233], v[4:7]
	v_mfma_f32_16x16x32_bf16 v[0:3], v[194:197], v[230:233], v[0:3]
	s_barrier
	s_andn2_b64 vcc, exec, s[28:29]
	s_cbranch_vccnz .LBB0_419
	s_barrier

; #define PG8_STAGE(bufoff, gbase, voff) do { _Pragma("unroll") for (int _i = 0; _i < 2; ++_i) \
;         __builtin_amdgcn_global_load_lds((const unsigned*)((const char*)(gbase) + (voff)[_i]), (LAS unsigned*)(lds + (bufoff) + ldsw + _i * 8192), 16, 0, 0); } while (0)
; #define PG8_STAGEB(bufoff, gbase, perm) do { _Pragma("unroll") for (int _i = 0; _i < 2; ++_i) \
;         __builtin_amdgcn_global_load_lds((const unsigned*)((const char*)(gbase) + ((BSEL && (perm)) ? voffBp[_i] : voffB[_i])), (LAS unsigned*)(lds + (bufoff) + ldsw + _i * 8192), 16, 0, 0); } while (0)
; #define PG8_LDA(dst, b, h) do { _Pragma("unroll") for (int m = 0; m < 4; ++m) _Pragma("unroll") for (int k = 0; k < 2; ++k) dst[m][k] = *(const LAS bf16x8*)(lds + PG8_SA(b, h) + aoff + m * 2048 + k * 1024); } while (0)
; #define PG8_LDB(dst, b, h) do { _Pragma("unroll") for (int n = 0; n < 2; ++n) _Pragma("unroll") for (int k = 0; k < 2; ++k) dst[n][k] = *(const LAS bf16x8*)(lds + PG8_SB(b, h) + boff + n * 2048 + k * 1024); } while (0)
; #define PG8_MMA(ai, bj, At, Bt) do { __builtin_amdgcn_s_setprio(1); _Pragma("unroll") for (int m = 0; m < 4; ++m) _Pragma("unroll") for (int n = 0; n < 2; ++n) _Pragma("unroll") for (int k = 0; k < 2; ++k) \
;         acc[ai][bj][m][n] = __builtin_amdgcn_mfma_f32_16x16x32_bf16(Bt[n][k], At[m][k], acc[ai][bj][m][n], 0, 0, 0); __builtin_amdgcn_s_setprio(0); } while (0)
; #define PG8_BAR __builtin_amdgcn_s_barrier()
; template <class Epi, bool BSEL = false>
; __device__ __forceinline__ void gemm_phase(LAS unsigned char* lds, const Gemm g, const Order& S, const Epi& E, const int tid) {
;     ...
;             const bool last = (t == nt - 2);
;             const char* a1 = cA + (size_t)(t + 1) * kstep;
;             const char* a2 = last ? nA : cA + (size_t)(t + 2) * kstep; const char* b2 = last ? nB : cB + (size_t)(t + 2) * kstep;
;             const char* a3 = a2 + kstep; const char* b3 = b2 + kstep;
;             const bool p2 = last ? nP : cP; const size_t h2 = last ? nhB : chB;
;             PG8_LDB(B0, 0, 0); PG8_LDB(B1, 0, 1); PG8_SCHED; PG8_LDA(At, 0, 0); PG8_STAGE(PG8_SA(1, 1), a1 + hstepA, voffA);
;             PG8_WAIT_V(8); PG8_WAIT_L(0); PG8_BAR; PG8_MMA(0, 0, At, B0); PG8_MMA(0, 1, At, B1); PG8_BAR; PG8_SCHED;
;             PG8_LDA(At, 0, 1); PG8_STAGEB(PG8_SB(0, 0), b2, p2); PG8_STAGEB(PG8_SB(0, 1), b2 + h2, p2); PG8_STAGE(PG8_SA(0, 0), a2, voffA);
.LBB0_440:
	v_add_u32_e32 v176, s46, v133
	ds_read_b128 v[164:167], v176
	ds_read_b128 v[168:171], v176 offset:1024
	ds_read_b128 v[172:175], v176 offset:2048
	ds_read_b128 v[192:195], v176 offset:3072
	v_add_u32_e32 v176, s47, v133
	s_add_u32 s36, s10, s2
	ds_read_b128 v[196:199], v176
	ds_read_b128 v[202:205], v176 offset:1024
	ds_read_b128 v[206:209], v176 offset:2048
	ds_read_b128 v[210:213], v176 offset:3072
	s_addc_u32 s37, s11, s3
	s_add_u32 s36, s36, 0x100
	s_addc_u32 s37, s37, 0
	s_add_u32 s58, s1, s2
	s_addc_u32 s59, s52, s3
	s_cmpk_eq_i32 s2, 0x1500
	s_cselect_b32 s41, s53, s37
	s_cselect_b32 s40, s54, s36
	s_cselect_b32 s37, s55, s59
	s_cselect_b32 s36, s56, s58
	v_lshl_add_u64 v[176:177], v[160:161], 0, s[2:3]
	s_add_i32 m0, s15, 0xc000
	ds_read_b128 v[214:217], v190
	ds_read_b128 v[218:221], v190 offset:1024
	ds_read_b128 v[222:225], v190 offset:2048
	ds_read_b128 v[226:229], v190 offset:3072
	ds_read_b128 v[230:233], v190 offset:4096
	ds_read_b128 v[234:237], v190 offset:5120
	ds_read_b128 v[238:241], v190 offset:6144
	ds_read_b128 v[242:245], v190 offset:7168
	global_load_lds_dwordx4 v[176:177], off
	v_lshl_add_u64 v[176:177], v[162:163], 0, s[2:3]
	s_add_i32 m0, s15, 0xe000
	s_nop 0
	global_load_lds_dwordx4 v[176:177], off
	s_waitcnt vmcnt(8)
	s_waitcnt lgkmcnt(0)
	s_barrier
	v_mfma_f32_16x16x32_bf16 v[124:127], v[164:167], v[214:217], v[124:127]
	v_mfma_f32_16x16x32_bf16 v[120:123], v[172:175], v[214:217], v[120:123]
	v_mfma_f32_16x16x32_bf16 v[116:119], v[164:167], v[222:225], v[116:119]
	v_mfma_f32_16x16x32_bf16 v[112:115], v[172:175], v[222:225], v[112:115]
	v_mfma_f32_16x16x32_bf16 v[108:111], v[164:167], v[230:233], v[108:111]
	v_mfma_f32_16x16x32_bf16 v[104:107], v[172:175], v[230:233], v[104:107]
	v_mfma_f32_16x16x32_bf16 v[100:103], v[164:167], v[238:241], v[100:103]
	v_mfma_f32_16x16x32_bf16 v[96:99], v[172:175], v[238:241], v[96:99]
	v_mfma_f32_16x16x32_bf16 v[124:127], v[168:171], v[218:221], v[124:127]
	v_mfma_f32_16x16x32_bf16 v[120:123], v[192:195], v[218:221], v[120:123]
	v_mfma_f32_16x16x32_bf16 v[116:119], v[168:171], v[226:229], v[116:119]
	v_mfma_f32_16x16x32_bf16 v[112:115], v[192:195], v[226:229], v[112:115]
	v_mfma_f32_16x16x32_bf16 v[108:111], v[168:171], v[234:237], v[108:111]
	v_mfma_f32_16x16x32_bf16 v[104:107], v[192:195], v[234:237], v[104:107]
	v_mfma_f32_16x16x32_bf16 v[100:103], v[168:171], v[242:245], v[100:103]
	v_mfma_f32_16x16x32_bf16 v[96:99], v[192:195], v[242:245], v[96:99]
	v_mfma_f32_16x16x32_bf16 v[92:95], v[196:199], v[214:217], v[92:95]
	v_mfma_f32_16x16x32_bf16 v[88:91], v[206:209], v[214:217], v[88:91]
	v_mfma_f32_16x16x32_bf16 v[84:87], v[196:199], v[222:225], v[84:87]
	v_mfma_f32_16x16x32_bf16 v[80:83], v[206:209], v[222:225], v[80:83]
	v_mfma_f32_16x16x32_bf16 v[76:79], v[196:199], v[230:233], v[76:79]
	v_mfma_f32_16x16x32_bf16 v[72:75], v[206:209], v[230:233], v[72:75]
	v_mfma_f32_16x16x32_bf16 v[68:71], v[196:199], v[238:241], v[68:71]
	v_mfma_f32_16x16x32_bf16 v[64:67], v[206:209], v[238:241], v[64:67]
	v_mfma_f32_16x16x32_bf16 v[92:95], v[202:205], v[218:221], v[92:95]
	v_mfma_f32_16x16x32_bf16 v[88:91], v[210:213], v[218:221], v[88:91]
	v_mfma_f32_16x16x32_bf16 v[84:87], v[202:205], v[226:229], v[84:87]
	v_mfma_f32_16x16x32_bf16 v[80:83], v[210:213], v[226:229], v[80:83]
	v_mfma_f32_16x16x32_bf16 v[76:79], v[202:205], v[234:237], v[76:79]
	v_mfma_f32_16x16x32_bf16 v[72:75], v[210:213], v[234:237], v[72:75]
	v_mfma_f32_16x16x32_bf16 v[68:71], v[202:205], v[242:245], v[68:71]
	v_mfma_f32_16x16x32_bf16 v[64:67], v[210:213], v[242:245], v[64:67]
	s_barrier
	s_add_i32 s58, s46, s14
	v_lshl_add_u64 v[176:177], s[36:37], 0, v[130:131]
	s_mov_b32 m0, s58
	ds_read_b128 v[214:217], v190 offset:16384
	ds_read_b128 v[218:221], v190 offset:17408
	ds_read_b128 v[222:225], v190 offset:18432
	ds_read_b128 v[226:229], v190 offset:19456
	ds_read_b128 v[230:233], v190 offset:20480
	ds_read_b128 v[234:237], v190 offset:21504
	ds_read_b128 v[238:241], v190 offset:22528
	ds_read_b128 v[242:245], v190 offset:23552
	global_load_lds_dwordx4 v[176:177], off
	s_add_i32 m0, s58, 0x2000
	s_add_u32 s58, s36, 0xb0000
	v_lshl_add_u64 v[246:247], s[36:37], 0, v[134:135]
	s_addc_u32 s59, s37, 0
	s_add_i32 s62, s47, s14
	global_load_lds_dwordx4 v[246:247], off
	v_lshl_add_u64 v[248:249], s[58:59], 0, v[130:131]
	s_mov_b32 m0, s62
	v_lshl_add_u64 v[250:251], s[40:41], 0, v[134:135]
	global_load_lds_dwordx4 v[248:249], off
	v_lshl_add_u64 v[248:249], s[58:59], 0, v[134:135]
	s_add_i32 m0, s62, 0x2000
	s_nop 0
	global_load_lds_dwordx4 v[248:249], off
	v_lshl_add_u64 v[248:249], s[40:41], 0, v[130:131]
	s_mov_b32 m0, s15
	s_nop 0
	global_load_lds_dwordx4 v[248:249], off
	s_mov_b32 m0, s20
	s_nop 0
	global_load_lds_dwordx4 v[250:251], off
	s_waitcnt vmcnt(8)
	s_waitcnt lgkmcnt(0)
	s_barrier
; #define PG8_STAGE(bufoff, gbase, voff) do { _Pragma("unroll") for (int _i = 0; _i < 2; ++_i) \
;         __builtin_amdgcn_global_load_lds((const unsigned*)((const char*)(gbase) + (voff)[_i]), (LAS unsigned*)(lds + (bufoff) + ldsw + _i * 8192), 16, 0, 0); } while (0)
; #define PG8_LDA(dst, b, h) do { _Pragma("unroll") for (int m = 0; m < 4; ++m) _Pragma("unroll") for (int k = 0; k < 2; ++k) dst[m][k] = *(const LAS bf16x8*)(lds + PG8_SA(b, h) + aoff + m * 2048 + k * 1024); } while (0)
; #define PG8_LDB(dst, b, h) do { _Pragma("unroll") for (int n = 0; n < 2; ++n) _Pragma("unroll") for (int k = 0; k < 2; ++k) dst[n][k] = *(const LAS bf16x8*)(lds + PG8_SB(b, h) + boff + n * 2048 + k * 1024); } while (0)
; #define PG8_MMA(ai, bj, At, Bt) do { __builtin_amdgcn_s_setprio(1); _Pragma("unroll") for (int m = 0; m < 4; ++m) _Pragma("unroll") for (int n = 0; n < 2; ++n) _Pragma("unroll") for (int k = 0; k < 2; ++k) \
;         acc[ai][bj][m][n] = __builtin_amdgcn_mfma_f32_16x16x32_bf16(Bt[n][k], At[m][k], acc[ai][bj][m][n], 0, 0, 0); __builtin_amdgcn_s_setprio(0); } while (0)
; #define PG8_WAIT_V(n) asm volatile("s_waitcnt vmcnt(" #n ")" ::: "memory")
; #define PG8_WAIT_L(n) asm volatile("s_waitcnt lgkmcnt(" #n ")" ::: "memory")
; #define PG8_BAR __builtin_amdgcn_s_barrier()
; #define PG8_SCHED __builtin_amdgcn_sched_barrier(0)
; template <class Epi, bool BSEL = false>
; __device__ __forceinline__ void gemm_phase(LAS unsigned char* lds, const Gemm g, const Order& S, const Epi& E, const int tid) {
;     ...
;             PG8_WAIT_V(8); PG8_WAIT_L(0); PG8_BAR; PG8_MMA(1, 0, At, B0); PG8_MMA(1, 1, At, B1); PG8_BAR; PG8_SCHED;
;             PG8_LDB(B0, 1, 0); PG8_LDB(B1, 1, 1); PG8_SCHED; PG8_LDA(At, 1, 0); PG8_STAGE(PG8_SA(0, 1), a2 + hstepA, voffA);
;             PG8_WAIT_V(8); PG8_WAIT_L(0); PG8_BAR; PG8_MMA(0, 0, At, B0); PG8_MMA(0, 1, At, B1); PG8_BAR; PG8_SCHED;
	v_mfma_f32_16x16x32_bf16 v[60:63], v[164:167], v[214:217], v[60:63]
	v_mfma_f32_16x16x32_bf16 v[56:59], v[172:175], v[214:217], v[56:59]
	v_mfma_f32_16x16x32_bf16 v[52:55], v[164:167], v[222:225], v[52:55]
	v_mfma_f32_16x16x32_bf16 v[48:51], v[172:175], v[222:225], v[48:51]
	v_mfma_f32_16x16x32_bf16 v[44:47], v[164:167], v[230:233], v[44:47]
	v_mfma_f32_16x16x32_bf16 v[40:43], v[172:175], v[230:233], v[40:43]
	v_mfma_f32_16x16x32_bf16 v[36:39], v[164:167], v[238:241], v[36:39]
	v_mfma_f32_16x16x32_bf16 v[32:35], v[172:175], v[238:241], v[32:35]
	v_mfma_f32_16x16x32_bf16 v[60:63], v[168:171], v[218:221], v[60:63]
	v_mfma_f32_16x16x32_bf16 v[56:59], v[192:195], v[218:221], v[56:59]
	v_mfma_f32_16x16x32_bf16 v[52:55], v[168:171], v[226:229], v[52:55]
	v_mfma_f32_16x16x32_bf16 v[48:51], v[192:195], v[226:229], v[48:51]
	v_mfma_f32_16x16x32_bf16 v[44:47], v[168:171], v[234:237], v[44:47]
	v_mfma_f32_16x16x32_bf16 v[40:43], v[192:195], v[234:237], v[40:43]
	v_mfma_f32_16x16x32_bf16 v[36:39], v[168:171], v[242:245], v[36:39]
	v_mfma_f32_16x16x32_bf16 v[32:35], v[192:195], v[242:245], v[32:35]
	v_mfma_f32_16x16x32_bf16 v[28:31], v[196:199], v[214:217], v[28:31]
	v_mfma_f32_16x16x32_bf16 v[24:27], v[206:209], v[214:217], v[24:27]
	v_mfma_f32_16x16x32_bf16 v[20:23], v[196:199], v[222:225], v[20:23]
	v_mfma_f32_16x16x32_bf16 v[16:19], v[206:209], v[222:225], v[16:19]
	v_mfma_f32_16x16x32_bf16 v[12:15], v[196:199], v[230:233], v[12:15]
	v_mfma_f32_16x16x32_bf16 v[8:11], v[206:209], v[230:233], v[8:11]
	v_mfma_f32_16x16x32_bf16 v[4:7], v[196:199], v[238:241], v[4:7]
	v_mfma_f32_16x16x32_bf16 v[0:3], v[206:209], v[238:241], v[0:3]
	v_mfma_f32_16x16x32_bf16 v[28:31], v[202:205], v[218:221], v[28:31]
	v_mfma_f32_16x16x32_bf16 v[24:27], v[210:213], v[218:221], v[24:27]
	v_mfma_f32_16x16x32_bf16 v[20:23], v[202:205], v[226:229], v[20:23]
	v_mfma_f32_16x16x32_bf16 v[16:19], v[210:213], v[226:229], v[16:19]
	v_mfma_f32_16x16x32_bf16 v[12:15], v[202:205], v[234:237], v[12:15]
	v_mfma_f32_16x16x32_bf16 v[8:11], v[210:213], v[234:237], v[8:11]
	v_mfma_f32_16x16x32_bf16 v[4:7], v[202:205], v[242:245], v[4:7]
	v_mfma_f32_16x16x32_bf16 v[0:3], v[210:213], v[242:245], v[0:3]
	s_barrier
	s_add_i32 s58, 0, 0x18000
	v_add_u32_e32 v191, s58, v133
	s_add_i32 s59, 0, 0x1c000
	ds_read_b128 v[164:167], v191
	ds_read_b128 v[168:171], v191 offset:1024
	ds_read_b128 v[172:175], v191 offset:2048
	ds_read_b128 v[192:195], v191 offset:3072
	v_add_u32_e32 v191, s59, v133
	ds_read_b128 v[196:199], v191
	ds_read_b128 v[202:205], v191 offset:1024
	ds_read_b128 v[206:209], v191 offset:2048
	ds_read_b128 v[210:213], v191 offset:3072
	s_add_u32 s40, s40, 0xb0000
	s_addc_u32 s41, s41, 0
	s_mov_b32 m0, s21
	v_lshl_add_u64 v[252:253], s[40:41], 0, v[130:131]
	ds_read_b128 v[214:217], v190 offset:32768
	ds_read_b128 v[218:221], v190 offset:33792
	ds_read_b128 v[222:225], v190 offset:34816
	ds_read_b128 v[226:229], v190 offset:35840
	ds_read_b128 v[230:233], v190 offset:36864
	ds_read_b128 v[234:237], v190 offset:37888
	ds_read_b128 v[238:241], v190 offset:38912
	ds_read_b128 v[242:245], v190 offset:39936
	global_load_lds_dwordx4 v[252:253], off
	v_lshl_add_u64 v[252:253], s[40:41], 0, v[134:135]
	s_mov_b32 m0, s42
	s_nop 0
	global_load_lds_dwordx4 v[252:253], off
	s_waitcnt vmcnt(8)
	s_waitcnt lgkmcnt(0)
	s_barrier
	v_mfma_f32_16x16x32_bf16 v[124:127], v[164:167], v[214:217], v[124:127]
	v_mfma_f32_16x16x32_bf16 v[120:123], v[172:175], v[214:217], v[120:123]
	v_mfma_f32_16x16x32_bf16 v[116:119], v[164:167], v[222:225], v[116:119]
	v_mfma_f32_16x16x32_bf16 v[112:115], v[172:175], v[222:225], v[112:115]
	v_mfma_f32_16x16x32_bf16 v[108:111], v[164:167], v[230:233], v[108:111]
	v_mfma_f32_16x16x32_bf16 v[104:107], v[172:175], v[230:233], v[104:107]
	v_mfma_f32_16x16x32_bf16 v[100:103], v[164:167], v[238:241], v[100:103]
	v_mfma_f32_16x16x32_bf16 v[96:99], v[172:175], v[238:241], v[96:99]
	v_mfma_f32_16x16x32_bf16 v[124:127], v[168:171], v[218:221], v[124:127]
	v_mfma_f32_16x16x32_bf16 v[120:123], v[192:195], v[218:221], v[120:123]
	v_mfma_f32_16x16x32_bf16 v[116:119], v[168:171], v[226:229], v[116:119]
	v_mfma_f32_16x16x32_bf16 v[112:115], v[192:195], v[226:229], v[112:115]
	v_mfma_f32_16x16x32_bf16 v[108:111], v[168:171], v[234:237], v[108:111]
	v_mfma_f32_16x16x32_bf16 v[104:107], v[192:195], v[234:237], v[104:107]
	v_mfma_f32_16x16x32_bf16 v[100:103], v[168:171], v[242:245], v[100:103]
	v_mfma_f32_16x16x32_bf16 v[96:99], v[192:195], v[242:245], v[96:99]
	v_mfma_f32_16x16x32_bf16 v[92:95], v[196:199], v[214:217], v[92:95]
	v_mfma_f32_16x16x32_bf16 v[88:91], v[206:209], v[214:217], v[88:91]
	v_mfma_f32_16x16x32_bf16 v[84:87], v[196:199], v[222:225], v[84:87]
	v_mfma_f32_16x16x32_bf16 v[80:83], v[206:209], v[222:225], v[80:83]
	v_mfma_f32_16x16x32_bf16 v[76:79], v[196:199], v[230:233], v[76:79]
	v_mfma_f32_16x16x32_bf16 v[72:75], v[206:209], v[230:233], v[72:75]
	v_mfma_f32_16x16x32_bf16 v[68:71], v[196:199], v[238:241], v[68:71]
	v_mfma_f32_16x16x32_bf16 v[64:67], v[206:209], v[238:241], v[64:67]
	v_mfma_f32_16x16x32_bf16 v[92:95], v[202:205], v[218:221], v[92:95]
	v_mfma_f32_16x16x32_bf16 v[88:91], v[210:213], v[218:221], v[88:91]
	v_mfma_f32_16x16x32_bf16 v[84:87], v[202:205], v[226:229], v[84:87]
	v_mfma_f32_16x16x32_bf16 v[80:83], v[210:213], v[226:229], v[80:83]
	v_mfma_f32_16x16x32_bf16 v[76:79], v[202:205], v[234:237], v[76:79]
	v_mfma_f32_16x16x32_bf16 v[72:75], v[210:213], v[234:237], v[72:75]
	v_mfma_f32_16x16x32_bf16 v[68:71], v[202:205], v[242:245], v[68:71]
	v_mfma_f32_16x16x32_bf16 v[64:67], v[210:213], v[242:245], v[64:67]
	s_barrier
; #define PG8_STAGE(bufoff, gbase, voff) do { _Pragma("unroll") for (int _i = 0; _i < 2; ++_i) \
;         __builtin_amdgcn_global_load_lds((const unsigned*)((const char*)(gbase) + (voff)[_i]), (LAS unsigned*)(lds + (bufoff) + ldsw + _i * 8192), 16, 0, 0); } while (0)
; #define PG8_STAGEB(bufoff, gbase, perm) do { _Pragma("unroll") for (int _i = 0; _i < 2; ++_i) \
;         __builtin_amdgcn_global_load_lds((const unsigned*)((const char*)(gbase) + ((BSEL && (perm)) ? voffBp[_i] : voffB[_i])), (LAS unsigned*)(lds + (bufoff) + ldsw + _i * 8192), 16, 0, 0); } while (0)
; #define PG8_LDA(dst, b, h) do { _Pragma("unroll") for (int m = 0; m < 4; ++m) _Pragma("unroll") for (int k = 0; k < 2; ++k) dst[m][k] = *(const LAS bf16x8*)(lds + PG8_SA(b, h) + aoff + m * 2048 + k * 1024); } while (0)
; #define PG8_MMA(ai, bj, At, Bt) do { __builtin_amdgcn_s_setprio(1); _Pragma("unroll") for (int m = 0; m < 4; ++m) _Pragma("unroll") for (int n = 0; n < 2; ++n) _Pragma("unroll") for (int k = 0; k < 2; ++k) \
;         acc[ai][bj][m][n] = __builtin_amdgcn_mfma_f32_16x16x32_bf16(Bt[n][k], At[m][k], acc[ai][bj][m][n], 0, 0, 0); __builtin_amdgcn_s_setprio(0); } while (0)
; #define PG8_WAIT_V(n) asm volatile("s_waitcnt vmcnt(" #n ")" ::: "memory")
; #define PG8_WAIT_L(n) asm volatile("s_waitcnt lgkmcnt(" #n ")" ::: "memory")
; #define PG8_BAR __builtin_amdgcn_s_barrier()
; #define PG8_SCHED __builtin_amdgcn_sched_barrier(0)
; template <class Epi, bool BSEL = false>
; __device__ __forceinline__ void gemm_phase(LAS unsigned char* lds, const Gemm g, const Order& S, const Epi& E, const int tid) {
;     ...
;             PG8_LDA(At, 1, 1); PG8_STAGEB(PG8_SB(1, 0), b3, p2); PG8_STAGEB(PG8_SB(1, 1), b3 + h2, p2); PG8_STAGE(PG8_SA(1, 0), a3, voffA);
;             PG8_WAIT_V(8); PG8_WAIT_L(0); PG8_BAR; PG8_MMA(1, 0, At, B0); PG8_MMA(1, 1, At, B1); PG8_BAR; PG8_SCHED;
;         }
;         if constexpr (ALIGN_EPI) { if (wr == 0) PG8_BAR; }
	s_add_i32 s40, s58, s14
	v_lshl_add_u64 v[176:177], v[176:177], 0, s[24:25]
	s_mov_b32 m0, s40
	ds_read_b128 v[214:217], v190 offset:49152
	ds_read_b128 v[218:221], v190 offset:50176
	ds_read_b128 v[222:225], v190 offset:51200
	ds_read_b128 v[226:229], v190 offset:52224
	ds_read_b128 v[230:233], v190 offset:53248
	ds_read_b128 v[234:237], v190 offset:54272
	ds_read_b128 v[238:241], v190 offset:55296
	ds_read_b128 v[242:245], v190 offset:56320
	global_load_lds_dwordx4 v[176:177], off
	s_add_i32 m0, s40, 0x2000
	s_add_u32 s36, s36, 0xb0080
	v_lshl_add_u64 v[176:177], v[246:247], 0, s[24:25]
	s_addc_u32 s37, s37, 0
	s_add_i32 s40, s59, s14
	global_load_lds_dwordx4 v[176:177], off
	v_lshl_add_u64 v[176:177], s[36:37], 0, v[130:131]
	s_mov_b32 m0, s40
	s_nop 0
	global_load_lds_dwordx4 v[176:177], off
	v_lshl_add_u64 v[176:177], s[36:37], 0, v[134:135]
	s_add_i32 m0, s40, 0x2000
	s_nop 0
	global_load_lds_dwordx4 v[176:177], off
	v_lshl_add_u64 v[176:177], v[248:249], 0, s[24:25]
	s_mov_b32 m0, s44
	s_nop 0
	global_load_lds_dwordx4 v[176:177], off
	v_lshl_add_u64 v[176:177], v[250:251], 0, s[24:25]
	s_mov_b32 m0, s45
	s_nop 0
	global_load_lds_dwordx4 v[176:177], off
	s_waitcnt vmcnt(8)
	s_waitcnt lgkmcnt(0)
	s_barrier
	v_mfma_f32_16x16x32_bf16 v[60:63], v[164:167], v[214:217], v[60:63]
	v_mfma_f32_16x16x32_bf16 v[56:59], v[172:175], v[214:217], v[56:59]
	v_mfma_f32_16x16x32_bf16 v[52:55], v[164:167], v[222:225], v[52:55]
	v_mfma_f32_16x16x32_bf16 v[48:51], v[172:175], v[222:225], v[48:51]
	v_mfma_f32_16x16x32_bf16 v[44:47], v[164:167], v[230:233], v[44:47]
	v_mfma_f32_16x16x32_bf16 v[40:43], v[172:175], v[230:233], v[40:43]
	v_mfma_f32_16x16x32_bf16 v[36:39], v[164:167], v[238:241], v[36:39]
	v_mfma_f32_16x16x32_bf16 v[32:35], v[172:175], v[238:241], v[32:35]
	v_mfma_f32_16x16x32_bf16 v[60:63], v[168:171], v[218:221], v[60:63]
	v_mfma_f32_16x16x32_bf16 v[56:59], v[192:195], v[218:221], v[56:59]
	v_mfma_f32_16x16x32_bf16 v[52:55], v[168:171], v[226:229], v[52:55]
	v_mfma_f32_16x16x32_bf16 v[48:51], v[192:195], v[226:229], v[48:51]
	v_mfma_f32_16x16x32_bf16 v[44:47], v[168:171], v[234:237], v[44:47]
	v_mfma_f32_16x16x32_bf16 v[40:43], v[192:195], v[234:237], v[40:43]
	v_mfma_f32_16x16x32_bf16 v[36:39], v[168:171], v[242:245], v[36:39]
	v_mfma_f32_16x16x32_bf16 v[32:35], v[192:195], v[242:245], v[32:35]
	v_mfma_f32_16x16x32_bf16 v[28:31], v[196:199], v[214:217], v[28:31]
	v_mfma_f32_16x16x32_bf16 v[24:27], v[206:209], v[214:217], v[24:27]
	v_mfma_f32_16x16x32_bf16 v[20:23], v[196:199], v[222:225], v[20:23]
	v_mfma_f32_16x16x32_bf16 v[16:19], v[206:209], v[222:225], v[16:19]
	v_mfma_f32_16x16x32_bf16 v[12:15], v[196:199], v[230:233], v[12:15]
	v_mfma_f32_16x16x32_bf16 v[8:11], v[206:209], v[230:233], v[8:11]
	v_mfma_f32_16x16x32_bf16 v[4:7], v[196:199], v[238:241], v[4:7]
	v_mfma_f32_16x16x32_bf16 v[0:3], v[206:209], v[238:241], v[0:3]
	v_mfma_f32_16x16x32_bf16 v[28:31], v[202:205], v[218:221], v[28:31]
	v_mfma_f32_16x16x32_bf16 v[24:27], v[210:213], v[218:221], v[24:27]
	v_mfma_f32_16x16x32_bf16 v[20:23], v[202:205], v[226:229], v[20:23]
	v_mfma_f32_16x16x32_bf16 v[16:19], v[210:213], v[226:229], v[16:19]
	v_mfma_f32_16x16x32_bf16 v[12:15], v[202:205], v[234:237], v[12:15]
	v_mfma_f32_16x16x32_bf16 v[8:11], v[210:213], v[234:237], v[8:11]
	v_mfma_f32_16x16x32_bf16 v[4:7], v[202:205], v[242:245], v[4:7]
	v_mfma_f32_16x16x32_bf16 v[0:3], v[210:213], v[242:245], v[0:3]
	s_barrier
	s_add_i32 s57, s57, 2
	s_add_u32 s2, s2, 0x100
	s_addc_u32 s3, s3, 0
	s_cmp_gt_u32 s57, 41
	s_cbranch_scc0 .LBB0_440
	s_and_b64 vcc, exec, s[26:27]
	s_cbranch_vccz .LBB0_443
	s_barrier

; #define PG8_STAGE(bufoff, gbase, voff) do { _Pragma("unroll") for (int _i = 0; _i < 2; ++_i) \
;         __builtin_amdgcn_global_load_lds((const unsigned*)((const char*)(gbase) + (voff)[_i]), (LAS unsigned*)(lds + (bufoff) + ldsw + _i * 8192), 16, 0, 0); } while (0)
; #define PG8_STAGEB(bufoff, gbase, perm) do { _Pragma("unroll") for (int _i = 0; _i < 2; ++_i) \
;         __builtin_amdgcn_global_load_lds((const unsigned*)((const char*)(gbase) + ((BSEL && (perm)) ? voffBp[_i] : voffB[_i])), (LAS unsigned*)(lds + (bufoff) + ldsw + _i * 8192), 16, 0, 0); } while (0)
; #define PG8_LDA(dst, b, h) do { _Pragma("unroll") for (int m = 0; m < 4; ++m) _Pragma("unroll") for (int k = 0; k < 2; ++k) dst[m][k] = *(const LAS bf16x8*)(lds + PG8_SA(b, h) + aoff + m * 2048 + k * 1024); } while (0)
; #define PG8_LDB(dst, b, h) do { _Pragma("unroll") for (int n = 0; n < 2; ++n) _Pragma("unroll") for (int k = 0; k < 2; ++k) dst[n][k] = *(const LAS bf16x8*)(lds + PG8_SB(b, h) + boff + n * 2048 + k * 1024); } while (0)
; #define PG8_WAIT_V(n) asm volatile("s_waitcnt vmcnt(" #n ")" ::: "memory")
; #define PG8_WAIT_L(n) asm volatile("s_waitcnt lgkmcnt(" #n ")" ::: "memory")
; #define PG8_BAR __builtin_amdgcn_s_barrier()
; #define PG8_SCHED __builtin_amdgcn_sched_barrier(0)
; template <class Epi, bool BSEL = false>
; __device__ __forceinline__ void gemm_phase(LAS unsigned char* lds, const Gemm g, const Order& S, const Epi& E, const int tid) {
;     ...
;             const bool last = (t == nt - 2);
;             const char* a1 = cA + (size_t)(t + 1) * kstep;
;             const char* a2 = last ? nA : cA + (size_t)(t + 2) * kstep; const char* b2 = last ? nB : cB + (size_t)(t + 2) * kstep;
;             const char* a3 = a2 + kstep; const char* b3 = b2 + kstep;
;             const bool p2 = last ? nP : cP; const size_t h2 = last ? nhB : chB;
;             PG8_LDB(B0, 0, 0); PG8_LDB(B1, 0, 1); PG8_SCHED; PG8_LDA(At, 0, 0); PG8_STAGE(PG8_SA(1, 1), a1 + hstepA, voffA);
;             PG8_WAIT_V(8); PG8_WAIT_L(0); PG8_BAR; PG8_MMA(0, 0, At, B0); PG8_MMA(0, 1, At, B1); PG8_BAR; PG8_SCHED;
;             PG8_LDA(At, 0, 1); PG8_STAGEB(PG8_SB(0, 0), b2, p2); PG8_STAGEB(PG8_SB(0, 1), b2 + h2, p2); PG8_STAGE(PG8_SA(0, 0), a2, voffA);
;             PG8_WAIT_V(8); PG8_WAIT_L(0); PG8_BAR; PG8_MMA(1, 0, At, B0); PG8_MMA(1, 1, At, B1); PG8_BAR; PG8_SCHED;
.LBB0_472:
	v_add_u32_e32 v164, s52, v139
	v_add_u32_e32 v176, s53, v139
	s_add_u32 s46, s26, s44
	ds_read_b128 v[152:155], v164
	ds_read_b128 v[156:159], v164 offset:1024
	ds_read_b128 v[160:163], v164 offset:2048
	ds_read_b128 v[164:167], v164 offset:3072
	ds_read_b128 v[168:171], v176
	ds_read_b128 v[172:175], v176 offset:1024
	ds_read_b128 v[180:183], v176 offset:2048
	ds_read_b128 v[184:187], v176 offset:3072
	s_addc_u32 s47, s27, s45
	s_add_u32 s46, s46, 0x100
	s_addc_u32 s47, s47, 0
	s_add_u32 s65, s41, s44
	s_addc_u32 s66, s57, s45
	s_cmpk_eq_i32 s44, 0x1500
	s_cselect_b32 s49, s58, s47
	s_cselect_b32 s48, s59, s46
	s_cselect_b32 s47, s62, s66
	s_cselect_b32 s46, s63, s65
	v_lshl_add_u64 v[176:177], v[146:147], 0, s[44:45]
	s_add_i32 m0, s20, 0xc000
	ds_read_b128 v[188:191], v151
	ds_read_b128 v[192:195], v151 offset:1024
	ds_read_b128 v[196:199], v151 offset:2048
	ds_read_b128 v[202:205], v151 offset:3072
	ds_read_b128 v[206:209], v151 offset:4096
	ds_read_b128 v[210:213], v151 offset:5120
	ds_read_b128 v[214:217], v151 offset:6144
	ds_read_b128 v[218:221], v151 offset:7168
	global_load_lds_dwordx4 v[176:177], off
	v_lshl_add_u64 v[176:177], v[148:149], 0, s[44:45]
	s_add_i32 m0, s20, 0xe000
	s_nop 0
	global_load_lds_dwordx4 v[176:177], off
	s_waitcnt vmcnt(8)
	s_waitcnt lgkmcnt(0)
	s_barrier
	v_mfma_f32_16x16x32_bf16 v[124:127], v[152:155], v[188:191], v[124:127]
	v_mfma_f32_16x16x32_bf16 v[120:123], v[160:163], v[188:191], v[120:123]
	v_mfma_f32_16x16x32_bf16 v[108:111], v[152:155], v[196:199], v[108:111]
	v_mfma_f32_16x16x32_bf16 v[104:107], v[160:163], v[196:199], v[104:107]
	v_mfma_f32_16x16x32_bf16 v[92:95], v[152:155], v[206:209], v[92:95]
	v_mfma_f32_16x16x32_bf16 v[88:91], v[160:163], v[206:209], v[88:91]
	v_mfma_f32_16x16x32_bf16 v[76:79], v[152:155], v[214:217], v[76:79]
	v_mfma_f32_16x16x32_bf16 v[72:75], v[160:163], v[214:217], v[72:75]
	v_mfma_f32_16x16x32_bf16 v[124:127], v[156:159], v[192:195], v[124:127]
	v_mfma_f32_16x16x32_bf16 v[120:123], v[164:167], v[192:195], v[120:123]
	v_mfma_f32_16x16x32_bf16 v[108:111], v[156:159], v[202:205], v[108:111]
	v_mfma_f32_16x16x32_bf16 v[104:107], v[164:167], v[202:205], v[104:107]
	v_mfma_f32_16x16x32_bf16 v[92:95], v[156:159], v[210:213], v[92:95]
	v_mfma_f32_16x16x32_bf16 v[88:91], v[164:167], v[210:213], v[88:91]
	v_mfma_f32_16x16x32_bf16 v[76:79], v[156:159], v[218:221], v[76:79]
	v_mfma_f32_16x16x32_bf16 v[72:75], v[164:167], v[218:221], v[72:75]
	v_mfma_f32_16x16x32_bf16 v[116:119], v[168:171], v[188:191], v[116:119]
	v_mfma_f32_16x16x32_bf16 v[112:115], v[180:183], v[188:191], v[112:115]
	v_mfma_f32_16x16x32_bf16 v[100:103], v[168:171], v[196:199], v[100:103]
	v_mfma_f32_16x16x32_bf16 v[96:99], v[180:183], v[196:199], v[96:99]
	v_mfma_f32_16x16x32_bf16 v[84:87], v[168:171], v[206:209], v[84:87]
	v_mfma_f32_16x16x32_bf16 v[80:83], v[180:183], v[206:209], v[80:83]
	v_mfma_f32_16x16x32_bf16 v[68:71], v[168:171], v[214:217], v[68:71]
	v_mfma_f32_16x16x32_bf16 v[64:67], v[180:183], v[214:217], v[64:67]
	v_mfma_f32_16x16x32_bf16 v[116:119], v[172:175], v[192:195], v[116:119]
	v_mfma_f32_16x16x32_bf16 v[112:115], v[184:187], v[192:195], v[112:115]
	v_mfma_f32_16x16x32_bf16 v[100:103], v[172:175], v[202:205], v[100:103]
	v_mfma_f32_16x16x32_bf16 v[96:99], v[184:187], v[202:205], v[96:99]
	v_mfma_f32_16x16x32_bf16 v[84:87], v[172:175], v[210:213], v[84:87]
	v_mfma_f32_16x16x32_bf16 v[80:83], v[184:187], v[210:213], v[80:83]
	v_mfma_f32_16x16x32_bf16 v[68:71], v[172:175], v[218:221], v[68:71]
	v_mfma_f32_16x16x32_bf16 v[64:67], v[184:187], v[218:221], v[64:67]
	s_barrier
	s_add_i32 s65, s52, s15
	v_lshl_add_u64 v[176:177], s[46:47], 0, v[132:133]
	s_mov_b32 m0, s65
	ds_read_b128 v[188:191], v151 offset:16384
	ds_read_b128 v[192:195], v151 offset:17408
	ds_read_b128 v[196:199], v151 offset:18432
	ds_read_b128 v[202:205], v151 offset:19456
	ds_read_b128 v[206:209], v151 offset:20480
	ds_read_b128 v[210:213], v151 offset:21504
	ds_read_b128 v[214:217], v151 offset:22528
	ds_read_b128 v[218:221], v151 offset:23552
	global_load_lds_dwordx4 v[176:177], off
	s_add_i32 m0, s65, 0x2000
	s_add_u32 s66, s46, 0xb0000
	v_lshl_add_u64 v[222:223], s[46:47], 0, v[136:137]
	s_addc_u32 s67, s47, 0
	s_add_i32 s65, s53, s15
	global_load_lds_dwordx4 v[222:223], off
	v_lshl_add_u64 v[224:225], s[66:67], 0, v[132:133]
	s_mov_b32 m0, s65
	v_lshl_add_u64 v[226:227], s[48:49], 0, v[134:135]
	global_load_lds_dwordx4 v[224:225], off
	v_lshl_add_u64 v[224:225], s[66:67], 0, v[136:137]
	s_add_i32 m0, s65, 0x2000
	s_nop 0
	global_load_lds_dwordx4 v[224:225], off
	v_lshl_add_u64 v[224:225], s[48:49], 0, v[130:131]
	s_mov_b32 m0, s20
	s_nop 0
	global_load_lds_dwordx4 v[224:225], off
	s_mov_b32 m0, s21
	s_nop 0
	global_load_lds_dwordx4 v[226:227], off
	s_waitcnt vmcnt(8)
	s_waitcnt lgkmcnt(0)
	s_barrier
; #define PG8_STAGE(bufoff, gbase, voff) do { _Pragma("unroll") for (int _i = 0; _i < 2; ++_i) \
;         __builtin_amdgcn_global_load_lds((const unsigned*)((const char*)(gbase) + (voff)[_i]), (LAS unsigned*)(lds + (bufoff) + ldsw + _i * 8192), 16, 0, 0); } while (0)
; #define PG8_LDA(dst, b, h) do { _Pragma("unroll") for (int m = 0; m < 4; ++m) _Pragma("unroll") for (int k = 0; k < 2; ++k) dst[m][k] = *(const LAS bf16x8*)(lds + PG8_SA(b, h) + aoff + m * 2048 + k * 1024); } while (0)
; #define PG8_LDB(dst, b, h) do { _Pragma("unroll") for (int n = 0; n < 2; ++n) _Pragma("unroll") for (int k = 0; k < 2; ++k) dst[n][k] = *(const LAS bf16x8*)(lds + PG8_SB(b, h) + boff + n * 2048 + k * 1024); } while (0)
; #define PG8_MMA(ai, bj, At, Bt) do { __builtin_amdgcn_s_setprio(1); _Pragma("unroll") for (int m = 0; m < 4; ++m) _Pragma("unroll") for (int n = 0; n < 2; ++n) _Pragma("unroll") for (int k = 0; k < 2; ++k) \
;         acc[ai][bj][m][n] = __builtin_amdgcn_mfma_f32_16x16x32_bf16(Bt[n][k], At[m][k], acc[ai][bj][m][n], 0, 0, 0); __builtin_amdgcn_s_setprio(0); } while (0)
; #define PG8_WAIT_V(n) asm volatile("s_waitcnt vmcnt(" #n ")" ::: "memory")
; #define PG8_WAIT_L(n) asm volatile("s_waitcnt lgkmcnt(" #n ")" ::: "memory")
; #define PG8_BAR __builtin_amdgcn_s_barrier()
; #define PG8_SCHED __builtin_amdgcn_sched_barrier(0)
; template <class Epi, bool BSEL = false>
; __device__ __forceinline__ void gemm_phase(LAS unsigned char* lds, const Gemm g, const Order& S, const Epi& E, const int tid) {
;     ...
;             PG8_WAIT_V(8); PG8_WAIT_L(0); PG8_BAR; PG8_MMA(1, 0, At, B0); PG8_MMA(1, 1, At, B1); PG8_BAR; PG8_SCHED;
;             PG8_LDB(B0, 1, 0); PG8_LDB(B1, 1, 1); PG8_SCHED; PG8_LDA(At, 1, 0); PG8_STAGE(PG8_SA(0, 1), a2 + hstepA, voffA);
;             PG8_WAIT_V(8); PG8_WAIT_L(0); PG8_BAR; PG8_MMA(0, 0, At, B0); PG8_MMA(0, 1, At, B1); PG8_BAR; PG8_SCHED;
	v_mfma_f32_16x16x32_bf16 v[60:63], v[152:155], v[188:191], v[60:63]
	v_mfma_f32_16x16x32_bf16 v[56:59], v[160:163], v[188:191], v[56:59]
	v_mfma_f32_16x16x32_bf16 v[44:47], v[152:155], v[196:199], v[44:47]
	v_mfma_f32_16x16x32_bf16 v[40:43], v[160:163], v[196:199], v[40:43]
	v_mfma_f32_16x16x32_bf16 v[28:31], v[152:155], v[206:209], v[28:31]
	v_mfma_f32_16x16x32_bf16 v[24:27], v[160:163], v[206:209], v[24:27]
	v_mfma_f32_16x16x32_bf16 v[12:15], v[152:155], v[214:217], v[12:15]
	v_mfma_f32_16x16x32_bf16 v[8:11], v[160:163], v[214:217], v[8:11]
	v_mfma_f32_16x16x32_bf16 v[60:63], v[156:159], v[192:195], v[60:63]
	v_mfma_f32_16x16x32_bf16 v[56:59], v[164:167], v[192:195], v[56:59]
	v_mfma_f32_16x16x32_bf16 v[44:47], v[156:159], v[202:205], v[44:47]
	v_mfma_f32_16x16x32_bf16 v[40:43], v[164:167], v[202:205], v[40:43]
	v_mfma_f32_16x16x32_bf16 v[28:31], v[156:159], v[210:213], v[28:31]
	v_mfma_f32_16x16x32_bf16 v[24:27], v[164:167], v[210:213], v[24:27]
	v_mfma_f32_16x16x32_bf16 v[12:15], v[156:159], v[218:221], v[12:15]
	v_mfma_f32_16x16x32_bf16 v[8:11], v[164:167], v[218:221], v[8:11]
	v_mfma_f32_16x16x32_bf16 v[52:55], v[168:171], v[188:191], v[52:55]
	v_mfma_f32_16x16x32_bf16 v[48:51], v[180:183], v[188:191], v[48:51]
	v_mfma_f32_16x16x32_bf16 v[36:39], v[168:171], v[196:199], v[36:39]
	v_mfma_f32_16x16x32_bf16 v[32:35], v[180:183], v[196:199], v[32:35]
	v_mfma_f32_16x16x32_bf16 v[20:23], v[168:171], v[206:209], v[20:23]
	v_mfma_f32_16x16x32_bf16 v[16:19], v[180:183], v[206:209], v[16:19]
	v_mfma_f32_16x16x32_bf16 v[4:7], v[168:171], v[214:217], v[4:7]
	v_mfma_f32_16x16x32_bf16 v[0:3], v[180:183], v[214:217], v[0:3]
	v_mfma_f32_16x16x32_bf16 v[52:55], v[172:175], v[192:195], v[52:55]
	v_mfma_f32_16x16x32_bf16 v[48:51], v[184:187], v[192:195], v[48:51]
	v_mfma_f32_16x16x32_bf16 v[36:39], v[172:175], v[202:205], v[36:39]
	v_mfma_f32_16x16x32_bf16 v[32:35], v[184:187], v[202:205], v[32:35]
	v_mfma_f32_16x16x32_bf16 v[20:23], v[172:175], v[210:213], v[20:23]
	v_mfma_f32_16x16x32_bf16 v[16:19], v[184:187], v[210:213], v[16:19]
	v_mfma_f32_16x16x32_bf16 v[4:7], v[172:175], v[218:221], v[4:7]
	v_mfma_f32_16x16x32_bf16 v[0:3], v[184:187], v[218:221], v[0:3]
	s_barrier
	s_add_i32 s65, 0, 0x18000
	s_add_i32 s66, 0, 0x1c000
	v_add_u32_e32 v164, s65, v139
	v_add_u32_e32 v179, s66, v139
	ds_read_b128 v[152:155], v164
	ds_read_b128 v[156:159], v164 offset:1024
	ds_read_b128 v[160:163], v164 offset:2048
	ds_read_b128 v[164:167], v164 offset:3072
	ds_read_b128 v[168:171], v179
	ds_read_b128 v[172:175], v179 offset:1024
	ds_read_b128 v[180:183], v179 offset:2048
	ds_read_b128 v[184:187], v179 offset:3072
	s_add_u32 s48, s48, 0xb0000
	s_addc_u32 s49, s49, 0
	s_mov_b32 m0, s23
	v_lshl_add_u64 v[228:229], s[48:49], 0, v[130:131]
	ds_read_b128 v[188:191], v151 offset:32768
	ds_read_b128 v[192:195], v151 offset:33792
	ds_read_b128 v[196:199], v151 offset:34816
	ds_read_b128 v[202:205], v151 offset:35840
	ds_read_b128 v[206:209], v151 offset:36864
	ds_read_b128 v[210:213], v151 offset:37888
	ds_read_b128 v[214:217], v151 offset:38912
	ds_read_b128 v[218:221], v151 offset:39936
	global_load_lds_dwordx4 v[228:229], off
	v_lshl_add_u64 v[228:229], s[48:49], 0, v[134:135]
	s_mov_b32 m0, s25
	s_nop 0
	global_load_lds_dwordx4 v[228:229], off
	s_waitcnt vmcnt(8)
	s_waitcnt lgkmcnt(0)
	s_barrier
	v_mfma_f32_16x16x32_bf16 v[124:127], v[152:155], v[188:191], v[124:127]
	v_mfma_f32_16x16x32_bf16 v[120:123], v[160:163], v[188:191], v[120:123]
	v_mfma_f32_16x16x32_bf16 v[108:111], v[152:155], v[196:199], v[108:111]
	v_mfma_f32_16x16x32_bf16 v[104:107], v[160:163], v[196:199], v[104:107]
	v_mfma_f32_16x16x32_bf16 v[92:95], v[152:155], v[206:209], v[92:95]
	v_mfma_f32_16x16x32_bf16 v[88:91], v[160:163], v[206:209], v[88:91]
	v_mfma_f32_16x16x32_bf16 v[76:79], v[152:155], v[214:217], v[76:79]
	v_mfma_f32_16x16x32_bf16 v[72:75], v[160:163], v[214:217], v[72:75]
	v_mfma_f32_16x16x32_bf16 v[124:127], v[156:159], v[192:195], v[124:127]
	v_mfma_f32_16x16x32_bf16 v[120:123], v[164:167], v[192:195], v[120:123]
	v_mfma_f32_16x16x32_bf16 v[108:111], v[156:159], v[202:205], v[108:111]
	v_mfma_f32_16x16x32_bf16 v[104:107], v[164:167], v[202:205], v[104:107]
	v_mfma_f32_16x16x32_bf16 v[92:95], v[156:159], v[210:213], v[92:95]
	v_mfma_f32_16x16x32_bf16 v[88:91], v[164:167], v[210:213], v[88:91]
	v_mfma_f32_16x16x32_bf16 v[76:79], v[156:159], v[218:221], v[76:79]
	v_mfma_f32_16x16x32_bf16 v[72:75], v[164:167], v[218:221], v[72:75]
	v_mfma_f32_16x16x32_bf16 v[116:119], v[168:171], v[188:191], v[116:119]
	v_mfma_f32_16x16x32_bf16 v[112:115], v[180:183], v[188:191], v[112:115]
	v_mfma_f32_16x16x32_bf16 v[100:103], v[168:171], v[196:199], v[100:103]
	v_mfma_f32_16x16x32_bf16 v[96:99], v[180:183], v[196:199], v[96:99]
	v_mfma_f32_16x16x32_bf16 v[84:87], v[168:171], v[206:209], v[84:87]
	v_mfma_f32_16x16x32_bf16 v[80:83], v[180:183], v[206:209], v[80:83]
	v_mfma_f32_16x16x32_bf16 v[68:71], v[168:171], v[214:217], v[68:71]
	v_mfma_f32_16x16x32_bf16 v[64:67], v[180:183], v[214:217], v[64:67]
	v_mfma_f32_16x16x32_bf16 v[116:119], v[172:175], v[192:195], v[116:119]
	v_mfma_f32_16x16x32_bf16 v[112:115], v[184:187], v[192:195], v[112:115]
	v_mfma_f32_16x16x32_bf16 v[100:103], v[172:175], v[202:205], v[100:103]
	v_mfma_f32_16x16x32_bf16 v[96:99], v[184:187], v[202:205], v[96:99]
	v_mfma_f32_16x16x32_bf16 v[84:87], v[172:175], v[210:213], v[84:87]
	v_mfma_f32_16x16x32_bf16 v[80:83], v[184:187], v[210:213], v[80:83]
	v_mfma_f32_16x16x32_bf16 v[68:71], v[172:175], v[218:221], v[68:71]
	v_mfma_f32_16x16x32_bf16 v[64:67], v[184:187], v[218:221], v[64:67]
	s_barrier
; #define PG8_STAGE(bufoff, gbase, voff) do { _Pragma("unroll") for (int _i = 0; _i < 2; ++_i) \
;         __builtin_amdgcn_global_load_lds((const unsigned*)((const char*)(gbase) + (voff)[_i]), (LAS unsigned*)(lds + (bufoff) + ldsw + _i * 8192), 16, 0, 0); } while (0)
; #define PG8_STAGEB(bufoff, gbase, perm) do { _Pragma("unroll") for (int _i = 0; _i < 2; ++_i) \
;         __builtin_amdgcn_global_load_lds((const unsigned*)((const char*)(gbase) + ((BSEL && (perm)) ? voffBp[_i] : voffB[_i])), (LAS unsigned*)(lds + (bufoff) + ldsw + _i * 8192), 16, 0, 0); } while (0)
; #define PG8_LDA(dst, b, h) do { _Pragma("unroll") for (int m = 0; m < 4; ++m) _Pragma("unroll") for (int k = 0; k < 2; ++k) dst[m][k] = *(const LAS bf16x8*)(lds + PG8_SA(b, h) + aoff + m * 2048 + k * 1024); } while (0)
; #define PG8_MMA(ai, bj, At, Bt) do { __builtin_amdgcn_s_setprio(1); _Pragma("unroll") for (int m = 0; m < 4; ++m) _Pragma("unroll") for (int n = 0; n < 2; ++n) _Pragma("unroll") for (int k = 0; k < 2; ++k) \
;         acc[ai][bj][m][n] = __builtin_amdgcn_mfma_f32_16x16x32_bf16(Bt[n][k], At[m][k], acc[ai][bj][m][n], 0, 0, 0); __builtin_amdgcn_s_setprio(0); } while (0)
; #define PG8_WAIT_V(n) asm volatile("s_waitcnt vmcnt(" #n ")" ::: "memory")
; #define PG8_WAIT_L(n) asm volatile("s_waitcnt lgkmcnt(" #n ")" ::: "memory")
; #define PG8_BAR __builtin_amdgcn_s_barrier()
; #define PG8_SCHED __builtin_amdgcn_sched_barrier(0)
; template <class Epi, bool BSEL = false>
; __device__ __forceinline__ void gemm_phase(LAS unsigned char* lds, const Gemm g, const Order& S, const Epi& E, const int tid) {
;     ...
;             PG8_LDA(At, 1, 1); PG8_STAGEB(PG8_SB(1, 0), b3, p2); PG8_STAGEB(PG8_SB(1, 1), b3 + h2, p2); PG8_STAGE(PG8_SA(1, 0), a3, voffA);
;             PG8_WAIT_V(8); PG8_WAIT_L(0); PG8_BAR; PG8_MMA(1, 0, At, B0); PG8_MMA(1, 1, At, B1); PG8_BAR; PG8_SCHED;
;         }
;         if constexpr (ALIGN_EPI) { if (wr == 0) PG8_BAR; }
	s_add_i32 s48, s65, s15
	v_lshl_add_u64 v[176:177], v[176:177], 0, s[30:31]
	s_mov_b32 m0, s48
	ds_read_b128 v[188:191], v151 offset:49152
	ds_read_b128 v[192:195], v151 offset:50176
	ds_read_b128 v[196:199], v151 offset:51200
	ds_read_b128 v[202:205], v151 offset:52224
	ds_read_b128 v[206:209], v151 offset:53248
	ds_read_b128 v[210:213], v151 offset:54272
	ds_read_b128 v[214:217], v151 offset:55296
	ds_read_b128 v[218:221], v151 offset:56320
	global_load_lds_dwordx4 v[176:177], off
	s_add_i32 m0, s48, 0x2000
	s_add_u32 s46, s46, 0xb0080
	v_lshl_add_u64 v[176:177], v[222:223], 0, s[30:31]
	s_addc_u32 s47, s47, 0
	s_add_i32 s48, s66, s15
	global_load_lds_dwordx4 v[176:177], off
	v_lshl_add_u64 v[176:177], s[46:47], 0, v[132:133]
	s_mov_b32 m0, s48
	s_nop 0
	global_load_lds_dwordx4 v[176:177], off
	v_lshl_add_u64 v[176:177], s[46:47], 0, v[136:137]
	s_add_i32 m0, s48, 0x2000
	s_nop 0
	global_load_lds_dwordx4 v[176:177], off
	v_lshl_add_u64 v[176:177], v[224:225], 0, s[30:31]
	s_mov_b32 m0, s50
	s_nop 0
	global_load_lds_dwordx4 v[176:177], off
	v_lshl_add_u64 v[176:177], v[226:227], 0, s[30:31]
	s_mov_b32 m0, s51
	s_nop 0
	global_load_lds_dwordx4 v[176:177], off
	s_waitcnt vmcnt(8)
	s_waitcnt lgkmcnt(0)
	s_barrier
	v_mfma_f32_16x16x32_bf16 v[60:63], v[152:155], v[188:191], v[60:63]
	v_mfma_f32_16x16x32_bf16 v[56:59], v[160:163], v[188:191], v[56:59]
	v_mfma_f32_16x16x32_bf16 v[44:47], v[152:155], v[196:199], v[44:47]
	v_mfma_f32_16x16x32_bf16 v[40:43], v[160:163], v[196:199], v[40:43]
	v_mfma_f32_16x16x32_bf16 v[28:31], v[152:155], v[206:209], v[28:31]
	v_mfma_f32_16x16x32_bf16 v[24:27], v[160:163], v[206:209], v[24:27]
	v_mfma_f32_16x16x32_bf16 v[12:15], v[152:155], v[214:217], v[12:15]
	v_mfma_f32_16x16x32_bf16 v[8:11], v[160:163], v[214:217], v[8:11]
	v_mfma_f32_16x16x32_bf16 v[60:63], v[156:159], v[192:195], v[60:63]
	v_mfma_f32_16x16x32_bf16 v[56:59], v[164:167], v[192:195], v[56:59]
	v_mfma_f32_16x16x32_bf16 v[44:47], v[156:159], v[202:205], v[44:47]
	v_mfma_f32_16x16x32_bf16 v[40:43], v[164:167], v[202:205], v[40:43]
	v_mfma_f32_16x16x32_bf16 v[28:31], v[156:159], v[210:213], v[28:31]
	v_mfma_f32_16x16x32_bf16 v[24:27], v[164:167], v[210:213], v[24:27]
	v_mfma_f32_16x16x32_bf16 v[12:15], v[156:159], v[218:221], v[12:15]
	v_mfma_f32_16x16x32_bf16 v[8:11], v[164:167], v[218:221], v[8:11]
	v_mfma_f32_16x16x32_bf16 v[52:55], v[168:171], v[188:191], v[52:55]
	v_mfma_f32_16x16x32_bf16 v[48:51], v[180:183], v[188:191], v[48:51]
	v_mfma_f32_16x16x32_bf16 v[36:39], v[168:171], v[196:199], v[36:39]
	v_mfma_f32_16x16x32_bf16 v[32:35], v[180:183], v[196:199], v[32:35]
	v_mfma_f32_16x16x32_bf16 v[20:23], v[168:171], v[206:209], v[20:23]
	v_mfma_f32_16x16x32_bf16 v[16:19], v[180:183], v[206:209], v[16:19]
	v_mfma_f32_16x16x32_bf16 v[4:7], v[168:171], v[214:217], v[4:7]
	v_mfma_f32_16x16x32_bf16 v[0:3], v[180:183], v[214:217], v[0:3]
	v_mfma_f32_16x16x32_bf16 v[52:55], v[172:175], v[192:195], v[52:55]
	v_mfma_f32_16x16x32_bf16 v[48:51], v[184:187], v[192:195], v[48:51]
	v_mfma_f32_16x16x32_bf16 v[36:39], v[172:175], v[202:205], v[36:39]
	v_mfma_f32_16x16x32_bf16 v[32:35], v[184:187], v[202:205], v[32:35]
	v_mfma_f32_16x16x32_bf16 v[20:23], v[172:175], v[210:213], v[20:23]
	v_mfma_f32_16x16x32_bf16 v[16:19], v[184:187], v[210:213], v[16:19]
	v_mfma_f32_16x16x32_bf16 v[4:7], v[172:175], v[218:221], v[4:7]
	v_mfma_f32_16x16x32_bf16 v[0:3], v[184:187], v[218:221], v[0:3]
	s_barrier
	s_add_i32 s64, s64, 2
	s_add_u32 s44, s44, 0x100
	s_addc_u32 s45, s45, 0
	s_cmp_gt_u32 s64, 41
	s_cbranch_scc0 .LBB0_472
	s_and_b64 vcc, exec, s[34:35]
	s_cbranch_vccz .LBB0_475
	s_barrier

; #define PG8_STAGE(bufoff, gbase, voff) do { _Pragma("unroll") for (int _i = 0; _i < 2; ++_i) \
;         __builtin_amdgcn_global_load_lds((const unsigned*)((const char*)(gbase) + (voff)[_i]), (LAS unsigned*)(lds + (bufoff) + ldsw + _i * 8192), 16, 0, 0); } while (0)
; #define PG8_STAGEB(bufoff, gbase, perm) do { _Pragma("unroll") for (int _i = 0; _i < 2; ++_i) \
;         __builtin_amdgcn_global_load_lds((const unsigned*)((const char*)(gbase) + ((BSEL && (perm)) ? voffBp[_i] : voffB[_i])), (LAS unsigned*)(lds + (bufoff) + ldsw + _i * 8192), 16, 0, 0); } while (0)
; #define PG8_LDA(dst, b, h) do { _Pragma("unroll") for (int m = 0; m < 4; ++m) _Pragma("unroll") for (int k = 0; k < 2; ++k) dst[m][k] = *(const LAS bf16x8*)(lds + PG8_SA(b, h) + aoff + m * 2048 + k * 1024); } while (0)
; #define PG8_LDB(dst, b, h) do { _Pragma("unroll") for (int n = 0; n < 2; ++n) _Pragma("unroll") for (int k = 0; k < 2; ++k) dst[n][k] = *(const LAS bf16x8*)(lds + PG8_SB(b, h) + boff + n * 2048 + k * 1024); } while (0)
; #define PG8_WAIT_V(n) asm volatile("s_waitcnt vmcnt(" #n ")" ::: "memory")
; #define PG8_WAIT_L(n) asm volatile("s_waitcnt lgkmcnt(" #n ")" ::: "memory")
; template <class Epi, bool BSEL = false>
; __device__ __forceinline__ void gemm_phase(LAS unsigned char* lds, const Gemm g, const Order& S, const Epi& E, const int tid) {
;     ...
;         const bool nP = has_next ? (BSEL && nxt.kind == 3) : cP; const size_t nhB = nP ? hstepBp : hstepBn;
;         for (int t = 0; t < nt; t += 2) {
;             const bool last = (t == nt - 2);
;             const char* a1 = cA + (size_t)(t + 1) * kstep;
;             const char* a2 = last ? nA : cA + (size_t)(t + 2) * kstep; const char* b2 = last ? nB : cB + (size_t)(t + 2) * kstep;
;             const char* a3 = a2 + kstep; const char* b3 = b2 + kstep;
;             const bool p2 = last ? nP : cP; const size_t h2 = last ? nhB : chB;
;             PG8_LDB(B0, 0, 0); PG8_LDB(B1, 0, 1); PG8_SCHED; PG8_LDA(At, 0, 0); PG8_STAGE(PG8_SA(1, 1), a1 + hstepA, voffA);
;             PG8_WAIT_V(8); PG8_WAIT_L(0); PG8_BAR; PG8_MMA(0, 0, At, B0); PG8_MMA(0, 1, At, B1); PG8_BAR; PG8_SCHED;
;             PG8_LDA(At, 0, 1); PG8_STAGEB(PG8_SB(0, 0), b2, p2); PG8_STAGEB(PG8_SB(0, 1), b2 + h2, p2); PG8_STAGE(PG8_SA(0, 0), a2, voffA);
;             PG8_WAIT_V(8); PG8_WAIT_L(0); PG8_BAR; PG8_MMA(1, 0, At, B0); PG8_MMA(1, 1, At, B1); PG8_BAR; PG8_SCHED;
.LBB0_670:
	s_add_u32 s2, s26, s62
	s_addc_u32 s3, s27, s63
	s_add_u32 s2, s2, 0x100
	s_addc_u32 s3, s3, 0
	s_add_u32 s44, s15, s62
	s_addc_u32 s45, s47, s63
	s_cmpk_eq_i32 s62, 0x700
	v_cndmask_b32_e64 v133, 0, 1, vcc
	s_cselect_b64 s[8:9], -1, 0
	v_cndmask_b32_e64 v133, v132, v133, s[8:9]
	v_and_b32_e32 v133, 1, v133
	v_cmp_eq_u32_e64 s[8:9], 1, v133
	v_add_u32_e32 v133, s94, v161
	ds_read_b128 v[134:137], v133
	ds_read_b128 v[138:141], v133 offset:1024
	ds_read_b128 v[178:181], v133 offset:2048
	ds_read_b128 v[182:185], v133 offset:3072
	v_add_u32_e32 v133, s96, v161
	ds_read_b128 v[186:189], v133
	ds_read_b128 v[190:193], v133 offset:1024
	ds_read_b128 v[194:197], v133 offset:2048
	ds_read_b128 v[202:205], v133 offset:3072
	s_cselect_b32 s3, s58, s3
	s_cselect_b32 s2, s59, s2
	s_cselect_b32 s45, s64, s45
	s_cselect_b32 s44, s65, s44
	s_cselect_b32 s93, 0, s51
	s_cselect_b32 s70, s28, s50
	v_lshl_add_u64 v[142:143], v[128:129], 0, s[62:63]
	s_add_i32 m0, s74, 0xc000
	ds_read_b128 v[206:209], v163
	ds_read_b128 v[210:213], v163 offset:1024
	ds_read_b128 v[214:217], v163 offset:2048
	ds_read_b128 v[218:221], v163 offset:3072
	ds_read_b128 v[222:225], v163 offset:4096
	ds_read_b128 v[226:229], v163 offset:5120
	ds_read_b128 v[230:233], v163 offset:6144
	ds_read_b128 v[234:237], v163 offset:7168
	global_load_lds_dwordx4 v[142:143], off
	v_lshl_add_u64 v[142:143], v[130:131], 0, s[62:63]
	s_add_i32 m0, s74, 0xe000
	s_nop 0
	global_load_lds_dwordx4 v[142:143], off
	s_waitcnt vmcnt(8)
	s_waitcnt lgkmcnt(0)
	s_barrier
	v_mfma_f32_16x16x32_bf16 v[124:127], v[134:137], v[206:209], v[124:127]
	v_mfma_f32_16x16x32_bf16 v[120:123], v[178:181], v[206:209], v[120:123]
	v_mfma_f32_16x16x32_bf16 v[116:119], v[134:137], v[214:217], v[116:119]
	v_mfma_f32_16x16x32_bf16 v[112:115], v[178:181], v[214:217], v[112:115]
	v_mfma_f32_16x16x32_bf16 v[108:111], v[134:137], v[222:225], v[108:111]
	v_mfma_f32_16x16x32_bf16 v[104:107], v[178:181], v[222:225], v[104:107]
	v_mfma_f32_16x16x32_bf16 v[100:103], v[134:137], v[230:233], v[100:103]
	v_mfma_f32_16x16x32_bf16 v[96:99], v[178:181], v[230:233], v[96:99]
	v_mfma_f32_16x16x32_bf16 v[124:127], v[138:141], v[210:213], v[124:127]
	v_mfma_f32_16x16x32_bf16 v[120:123], v[182:185], v[210:213], v[120:123]
	v_mfma_f32_16x16x32_bf16 v[116:119], v[138:141], v[218:221], v[116:119]
	v_mfma_f32_16x16x32_bf16 v[112:115], v[182:185], v[218:221], v[112:115]
	v_mfma_f32_16x16x32_bf16 v[108:111], v[138:141], v[226:229], v[108:111]
	v_mfma_f32_16x16x32_bf16 v[104:107], v[182:185], v[226:229], v[104:107]
	v_mfma_f32_16x16x32_bf16 v[100:103], v[138:141], v[234:237], v[100:103]
	v_mfma_f32_16x16x32_bf16 v[96:99], v[182:185], v[234:237], v[96:99]
	v_mfma_f32_16x16x32_bf16 v[92:95], v[186:189], v[206:209], v[92:95]
	v_mfma_f32_16x16x32_bf16 v[88:91], v[194:197], v[206:209], v[88:91]
	v_mfma_f32_16x16x32_bf16 v[84:87], v[186:189], v[214:217], v[84:87]
	v_mfma_f32_16x16x32_bf16 v[80:83], v[194:197], v[214:217], v[80:83]
	v_mfma_f32_16x16x32_bf16 v[76:79], v[186:189], v[222:225], v[76:79]
	v_mfma_f32_16x16x32_bf16 v[72:75], v[194:197], v[222:225], v[72:75]
	v_mfma_f32_16x16x32_bf16 v[68:71], v[186:189], v[230:233], v[68:71]
	v_mfma_f32_16x16x32_bf16 v[64:67], v[194:197], v[230:233], v[64:67]
	v_mfma_f32_16x16x32_bf16 v[92:95], v[190:193], v[210:213], v[92:95]
	v_mfma_f32_16x16x32_bf16 v[88:91], v[202:205], v[210:213], v[88:91]
	v_mfma_f32_16x16x32_bf16 v[84:87], v[190:193], v[218:221], v[84:87]
	v_mfma_f32_16x16x32_bf16 v[80:83], v[202:205], v[218:221], v[80:83]
	v_mfma_f32_16x16x32_bf16 v[76:79], v[190:193], v[226:229], v[76:79]
	v_mfma_f32_16x16x32_bf16 v[72:75], v[202:205], v[226:229], v[72:75]
	v_mfma_f32_16x16x32_bf16 v[68:71], v[190:193], v[234:237], v[68:71]
	v_mfma_f32_16x16x32_bf16 v[64:67], v[202:205], v[234:237], v[64:67]
	s_barrier
	s_add_i32 s71, s94, s25
	v_cndmask_b32_e64 v148, v151, v153, s[8:9]
	s_mov_b32 m0, s71
	ds_read_b128 v[206:209], v163 offset:16384
	ds_read_b128 v[210:213], v163 offset:17408
	ds_read_b128 v[214:217], v163 offset:18432
	ds_read_b128 v[218:221], v163 offset:19456
	ds_read_b128 v[222:225], v163 offset:20480
	ds_read_b128 v[226:229], v163 offset:21504
	ds_read_b128 v[230:233], v163 offset:22528
	ds_read_b128 v[234:237], v163 offset:23552
	global_load_lds_dwordx4 v148, s[44:45]
	s_add_i32 m0, s71, 0x2000
	v_cndmask_b32_e64 v198, v155, v157, s[8:9]
	v_mov_b32_e32 v199, v149
	s_add_u32 s8, s44, s70
	v_lshl_add_u64 v[142:143], s[44:45], 0, v[148:149]
	v_lshl_add_u64 v[238:239], s[44:45], 0, v[198:199]
	global_load_lds_dwordx4 v198, s[44:45]
	s_addc_u32 s9, s45, s93
	s_add_i32 s44, s96, s25
	s_mov_b32 m0, s44
	v_lshl_add_u64 v[242:243], s[8:9], 0, v[198:199]
	global_load_lds_dwordx4 v148, s[8:9]
	s_add_i32 m0, s44, 0x2000
	v_lshl_add_u64 v[244:245], s[2:3], 0, v[146:147]
	global_load_lds_dwordx4 v198, s[8:9]
	v_lshl_add_u64 v[198:199], s[2:3], 0, v[144:145]
	s_mov_b32 m0, s74
	v_lshl_add_u64 v[240:241], s[8:9], 0, v[148:149]
	global_load_lds_dwordx4 v[198:199], off
	s_mov_b32 m0, s76
	s_nop 0
	global_load_lds_dwordx4 v[244:245], off
	s_waitcnt vmcnt(8)
	s_waitcnt lgkmcnt(0)
	s_barrier
; #define PG8_STAGE(bufoff, gbase, voff) do { _Pragma("unroll") for (int _i = 0; _i < 2; ++_i) \
;         __builtin_amdgcn_global_load_lds((const unsigned*)((const char*)(gbase) + (voff)[_i]), (LAS unsigned*)(lds + (bufoff) + ldsw + _i * 8192), 16, 0, 0); } while (0)
; #define PG8_LDA(dst, b, h) do { _Pragma("unroll") for (int m = 0; m < 4; ++m) _Pragma("unroll") for (int k = 0; k < 2; ++k) dst[m][k] = *(const LAS bf16x8*)(lds + PG8_SA(b, h) + aoff + m * 2048 + k * 1024); } while (0)
; #define PG8_LDB(dst, b, h) do { _Pragma("unroll") for (int n = 0; n < 2; ++n) _Pragma("unroll") for (int k = 0; k < 2; ++k) dst[n][k] = *(const LAS bf16x8*)(lds + PG8_SB(b, h) + boff + n * 2048 + k * 1024); } while (0)
; #define PG8_MMA(ai, bj, At, Bt) do { __builtin_amdgcn_s_setprio(1); _Pragma("unroll") for (int m = 0; m < 4; ++m) _Pragma("unroll") for (int n = 0; n < 2; ++n) _Pragma("unroll") for (int k = 0; k < 2; ++k) \
;         acc[ai][bj][m][n] = __builtin_amdgcn_mfma_f32_16x16x32_bf16(Bt[n][k], At[m][k], acc[ai][bj][m][n], 0, 0, 0); __builtin_amdgcn_s_setprio(0); } while (0)
; #define PG8_WAIT_V(n) asm volatile("s_waitcnt vmcnt(" #n ")" ::: "memory")
; #define PG8_WAIT_L(n) asm volatile("s_waitcnt lgkmcnt(" #n ")" ::: "memory")
; #define PG8_BAR __builtin_amdgcn_s_barrier()
; #define PG8_SCHED __builtin_amdgcn_sched_barrier(0)
; template <class Epi, bool BSEL = false>
; __device__ __forceinline__ void gemm_phase(LAS unsigned char* lds, const Gemm g, const Order& S, const Epi& E, const int tid) {
;     ...
;             PG8_WAIT_V(8); PG8_WAIT_L(0); PG8_BAR; PG8_MMA(1, 0, At, B0); PG8_MMA(1, 1, At, B1); PG8_BAR; PG8_SCHED;
;             PG8_LDB(B0, 1, 0); PG8_LDB(B1, 1, 1); PG8_SCHED; PG8_LDA(At, 1, 0); PG8_STAGE(PG8_SA(0, 1), a2 + hstepA, voffA);
;             PG8_WAIT_V(8); PG8_WAIT_L(0); PG8_BAR; PG8_MMA(0, 0, At, B0); PG8_MMA(0, 1, At, B1); PG8_BAR; PG8_SCHED;
	v_mfma_f32_16x16x32_bf16 v[60:63], v[134:137], v[206:209], v[60:63]
	v_mfma_f32_16x16x32_bf16 v[56:59], v[178:181], v[206:209], v[56:59]
	v_mfma_f32_16x16x32_bf16 v[52:55], v[134:137], v[214:217], v[52:55]
	v_mfma_f32_16x16x32_bf16 v[48:51], v[178:181], v[214:217], v[48:51]
	v_mfma_f32_16x16x32_bf16 v[44:47], v[134:137], v[222:225], v[44:47]
	v_mfma_f32_16x16x32_bf16 v[40:43], v[178:181], v[222:225], v[40:43]
	v_mfma_f32_16x16x32_bf16 v[36:39], v[134:137], v[230:233], v[36:39]
	v_mfma_f32_16x16x32_bf16 v[32:35], v[178:181], v[230:233], v[32:35]
	v_mfma_f32_16x16x32_bf16 v[60:63], v[138:141], v[210:213], v[60:63]
	v_mfma_f32_16x16x32_bf16 v[56:59], v[182:185], v[210:213], v[56:59]
	v_mfma_f32_16x16x32_bf16 v[52:55], v[138:141], v[218:221], v[52:55]
	v_mfma_f32_16x16x32_bf16 v[48:51], v[182:185], v[218:221], v[48:51]
	v_mfma_f32_16x16x32_bf16 v[44:47], v[138:141], v[226:229], v[44:47]
	v_mfma_f32_16x16x32_bf16 v[40:43], v[182:185], v[226:229], v[40:43]
	v_mfma_f32_16x16x32_bf16 v[36:39], v[138:141], v[234:237], v[36:39]
	v_mfma_f32_16x16x32_bf16 v[32:35], v[182:185], v[234:237], v[32:35]
	v_mfma_f32_16x16x32_bf16 v[28:31], v[186:189], v[206:209], v[28:31]
	v_mfma_f32_16x16x32_bf16 v[24:27], v[194:197], v[206:209], v[24:27]
	v_mfma_f32_16x16x32_bf16 v[20:23], v[186:189], v[214:217], v[20:23]
	v_mfma_f32_16x16x32_bf16 v[16:19], v[194:197], v[214:217], v[16:19]
	v_mfma_f32_16x16x32_bf16 v[12:15], v[186:189], v[222:225], v[12:15]
	v_mfma_f32_16x16x32_bf16 v[8:11], v[194:197], v[222:225], v[8:11]
	v_mfma_f32_16x16x32_bf16 v[4:7], v[186:189], v[230:233], v[4:7]
	v_mfma_f32_16x16x32_bf16 v[0:3], v[194:197], v[230:233], v[0:3]
	v_mfma_f32_16x16x32_bf16 v[28:31], v[190:193], v[210:213], v[28:31]
	v_mfma_f32_16x16x32_bf16 v[24:27], v[202:205], v[210:213], v[24:27]
	v_mfma_f32_16x16x32_bf16 v[20:23], v[190:193], v[218:221], v[20:23]
	v_mfma_f32_16x16x32_bf16 v[16:19], v[202:205], v[218:221], v[16:19]
	v_mfma_f32_16x16x32_bf16 v[12:15], v[190:193], v[226:229], v[12:15]
	v_mfma_f32_16x16x32_bf16 v[8:11], v[202:205], v[226:229], v[8:11]
	v_mfma_f32_16x16x32_bf16 v[4:7], v[190:193], v[234:237], v[4:7]
	v_mfma_f32_16x16x32_bf16 v[0:3], v[202:205], v[234:237], v[0:3]
	s_barrier
	s_add_i32 s8, 0, 0x18000
	v_add_u32_e32 v133, s8, v161
	s_add_i32 s9, 0, 0x1c000
	ds_read_b128 v[134:137], v133
	ds_read_b128 v[138:141], v133 offset:1024
	ds_read_b128 v[178:181], v133 offset:2048
	ds_read_b128 v[182:185], v133 offset:3072
	v_add_u32_e32 v133, s9, v161
	ds_read_b128 v[186:189], v133
	ds_read_b128 v[190:193], v133 offset:1024
	ds_read_b128 v[194:197], v133 offset:2048
	ds_read_b128 v[202:205], v133 offset:3072
	s_add_u32 s2, s2, 0x40000
	s_addc_u32 s3, s3, 0
	s_mov_b32 m0, s77
	v_lshl_add_u64 v[246:247], s[2:3], 0, v[144:145]
	ds_read_b128 v[206:209], v163 offset:32768
	ds_read_b128 v[210:213], v163 offset:33792
	ds_read_b128 v[214:217], v163 offset:34816
	ds_read_b128 v[218:221], v163 offset:35840
	ds_read_b128 v[222:225], v163 offset:36864
	ds_read_b128 v[226:229], v163 offset:37888
	ds_read_b128 v[230:233], v163 offset:38912
	ds_read_b128 v[234:237], v163 offset:39936
	global_load_lds_dwordx4 v[246:247], off
	v_lshl_add_u64 v[246:247], s[2:3], 0, v[146:147]
	s_mov_b32 m0, s78
	s_nop 0
	global_load_lds_dwordx4 v[246:247], off
	s_waitcnt vmcnt(8)
	s_waitcnt lgkmcnt(0)
	s_barrier
	v_mfma_f32_16x16x32_bf16 v[124:127], v[134:137], v[206:209], v[124:127]
	v_mfma_f32_16x16x32_bf16 v[120:123], v[178:181], v[206:209], v[120:123]
	v_mfma_f32_16x16x32_bf16 v[116:119], v[134:137], v[214:217], v[116:119]
	v_mfma_f32_16x16x32_bf16 v[112:115], v[178:181], v[214:217], v[112:115]
	v_mfma_f32_16x16x32_bf16 v[108:111], v[134:137], v[222:225], v[108:111]
	v_mfma_f32_16x16x32_bf16 v[104:107], v[178:181], v[222:225], v[104:107]
	v_mfma_f32_16x16x32_bf16 v[100:103], v[134:137], v[230:233], v[100:103]
	v_mfma_f32_16x16x32_bf16 v[96:99], v[178:181], v[230:233], v[96:99]
	v_mfma_f32_16x16x32_bf16 v[124:127], v[138:141], v[210:213], v[124:127]
	v_mfma_f32_16x16x32_bf16 v[120:123], v[182:185], v[210:213], v[120:123]
	v_mfma_f32_16x16x32_bf16 v[116:119], v[138:141], v[218:221], v[116:119]
	v_mfma_f32_16x16x32_bf16 v[112:115], v[182:185], v[218:221], v[112:115]
	v_mfma_f32_16x16x32_bf16 v[108:111], v[138:141], v[226:229], v[108:111]
	v_mfma_f32_16x16x32_bf16 v[104:107], v[182:185], v[226:229], v[104:107]
	v_mfma_f32_16x16x32_bf16 v[100:103], v[138:141], v[234:237], v[100:103]
	v_mfma_f32_16x16x32_bf16 v[96:99], v[182:185], v[234:237], v[96:99]
	v_mfma_f32_16x16x32_bf16 v[92:95], v[186:189], v[206:209], v[92:95]
	v_mfma_f32_16x16x32_bf16 v[88:91], v[194:197], v[206:209], v[88:91]
	v_mfma_f32_16x16x32_bf16 v[84:87], v[186:189], v[214:217], v[84:87]
	v_mfma_f32_16x16x32_bf16 v[80:83], v[194:197], v[214:217], v[80:83]
	v_mfma_f32_16x16x32_bf16 v[76:79], v[186:189], v[222:225], v[76:79]
	v_mfma_f32_16x16x32_bf16 v[72:75], v[194:197], v[222:225], v[72:75]
	v_mfma_f32_16x16x32_bf16 v[68:71], v[186:189], v[230:233], v[68:71]
	v_mfma_f32_16x16x32_bf16 v[64:67], v[194:197], v[230:233], v[64:67]
	v_mfma_f32_16x16x32_bf16 v[92:95], v[190:193], v[210:213], v[92:95]
	v_mfma_f32_16x16x32_bf16 v[88:91], v[202:205], v[210:213], v[88:91]
	v_mfma_f32_16x16x32_bf16 v[84:87], v[190:193], v[218:221], v[84:87]
	v_mfma_f32_16x16x32_bf16 v[80:83], v[202:205], v[218:221], v[80:83]
	v_mfma_f32_16x16x32_bf16 v[76:79], v[190:193], v[226:229], v[76:79]
	v_mfma_f32_16x16x32_bf16 v[72:75], v[202:205], v[226:229], v[72:75]
	v_mfma_f32_16x16x32_bf16 v[68:71], v[190:193], v[234:237], v[68:71]
	v_mfma_f32_16x16x32_bf16 v[64:67], v[202:205], v[234:237], v[64:67]
	s_barrier
; #define PG8_STAGE(bufoff, gbase, voff) do { _Pragma("unroll") for (int _i = 0; _i < 2; ++_i) \
;         __builtin_amdgcn_global_load_lds((const unsigned*)((const char*)(gbase) + (voff)[_i]), (LAS unsigned*)(lds + (bufoff) + ldsw + _i * 8192), 16, 0, 0); } while (0)
; #define PG8_STAGEB(bufoff, gbase, perm) do { _Pragma("unroll") for (int _i = 0; _i < 2; ++_i) \
;         __builtin_amdgcn_global_load_lds((const unsigned*)((const char*)(gbase) + ((BSEL && (perm)) ? voffBp[_i] : voffB[_i])), (LAS unsigned*)(lds + (bufoff) + ldsw + _i * 8192), 16, 0, 0); } while (0)
; #define PG8_LDA(dst, b, h) do { _Pragma("unroll") for (int m = 0; m < 4; ++m) _Pragma("unroll") for (int k = 0; k < 2; ++k) dst[m][k] = *(const LAS bf16x8*)(lds + PG8_SA(b, h) + aoff + m * 2048 + k * 1024); } while (0)
; #define PG8_MMA(ai, bj, At, Bt) do { __builtin_amdgcn_s_setprio(1); _Pragma("unroll") for (int m = 0; m < 4; ++m) _Pragma("unroll") for (int n = 0; n < 2; ++n) _Pragma("unroll") for (int k = 0; k < 2; ++k) \
;         acc[ai][bj][m][n] = __builtin_amdgcn_mfma_f32_16x16x32_bf16(Bt[n][k], At[m][k], acc[ai][bj][m][n], 0, 0, 0); __builtin_amdgcn_s_setprio(0); } while (0)
; #define PG8_WAIT_V(n) asm volatile("s_waitcnt vmcnt(" #n ")" ::: "memory")
; #define PG8_WAIT_L(n) asm volatile("s_waitcnt lgkmcnt(" #n ")" ::: "memory")
; #define PG8_BAR __builtin_amdgcn_s_barrier()
; #define PG8_SCHED __builtin_amdgcn_sched_barrier(0)
; template <class Epi, bool BSEL = false>
; __device__ __forceinline__ void gemm_phase(LAS unsigned char* lds, const Gemm g, const Order& S, const Epi& E, const int tid) {
;     ...
;             PG8_LDA(At, 1, 1); PG8_STAGEB(PG8_SB(1, 0), b3, p2); PG8_STAGEB(PG8_SB(1, 1), b3 + h2, p2); PG8_STAGE(PG8_SA(1, 0), a3, voffA);
;             PG8_WAIT_V(8); PG8_WAIT_L(0); PG8_BAR; PG8_MMA(1, 0, At, B0); PG8_MMA(1, 1, At, B1); PG8_BAR; PG8_SCHED;
;         }
;         if constexpr (ALIGN_EPI) { if (wr == 0) PG8_BAR; }
;         if constexpr (!Epi::AFTER_DRAIN) E(acc, cur, wr, wc, fr, fq);
;         if (!has_next) break;
;     __device__ __forceinline__ void operator()(const f32x4 (&acc)[2][2][4][2], const Unit& u, int wr, int wc, int fr, int fq) const {
;         if (u.kind <= 1) {
	s_add_i32 s2, s8, s25
	v_lshl_add_u64 v[142:143], v[142:143], 0, s[36:37]
	s_mov_b32 m0, s2
	ds_read_b128 v[206:209], v163 offset:49152
	ds_read_b128 v[210:213], v163 offset:50176
	ds_read_b128 v[214:217], v163 offset:51200
	ds_read_b128 v[218:221], v163 offset:52224
	ds_read_b128 v[222:225], v163 offset:53248
	ds_read_b128 v[226:229], v163 offset:54272
	ds_read_b128 v[230:233], v163 offset:55296
	ds_read_b128 v[234:237], v163 offset:56320
	global_load_lds_dwordx4 v[142:143], off
	v_lshl_add_u64 v[142:143], v[238:239], 0, s[36:37]
	s_add_i32 m0, s2, 0x2000
	s_add_i32 s2, s9, s25
	global_load_lds_dwordx4 v[142:143], off
	v_lshl_add_u64 v[142:143], v[240:241], 0, s[36:37]
	s_mov_b32 m0, s2
	s_nop 0
	global_load_lds_dwordx4 v[142:143], off
	v_lshl_add_u64 v[142:143], v[242:243], 0, s[36:37]
	s_add_i32 m0, s2, 0x2000
	s_nop 0
	global_load_lds_dwordx4 v[142:143], off
	v_lshl_add_u64 v[142:143], v[198:199], 0, s[36:37]
	s_mov_b32 m0, s89
	s_nop 0
	global_load_lds_dwordx4 v[142:143], off
	v_lshl_add_u64 v[142:143], v[244:245], 0, s[36:37]
	s_mov_b32 m0, s90
	s_nop 0
	global_load_lds_dwordx4 v[142:143], off
	s_waitcnt vmcnt(8)
	s_waitcnt lgkmcnt(0)
	s_barrier
	v_mfma_f32_16x16x32_bf16 v[60:63], v[134:137], v[206:209], v[60:63]
	v_mfma_f32_16x16x32_bf16 v[56:59], v[178:181], v[206:209], v[56:59]
	v_mfma_f32_16x16x32_bf16 v[52:55], v[134:137], v[214:217], v[52:55]
	v_mfma_f32_16x16x32_bf16 v[48:51], v[178:181], v[214:217], v[48:51]
	v_mfma_f32_16x16x32_bf16 v[44:47], v[134:137], v[222:225], v[44:47]
	v_mfma_f32_16x16x32_bf16 v[40:43], v[178:181], v[222:225], v[40:43]
	v_mfma_f32_16x16x32_bf16 v[36:39], v[134:137], v[230:233], v[36:39]
	v_mfma_f32_16x16x32_bf16 v[32:35], v[178:181], v[230:233], v[32:35]
	v_mfma_f32_16x16x32_bf16 v[60:63], v[138:141], v[210:213], v[60:63]
	v_mfma_f32_16x16x32_bf16 v[56:59], v[182:185], v[210:213], v[56:59]
	v_mfma_f32_16x16x32_bf16 v[52:55], v[138:141], v[218:221], v[52:55]
	v_mfma_f32_16x16x32_bf16 v[48:51], v[182:185], v[218:221], v[48:51]
	v_mfma_f32_16x16x32_bf16 v[44:47], v[138:141], v[226:229], v[44:47]
	v_mfma_f32_16x16x32_bf16 v[40:43], v[182:185], v[226:229], v[40:43]
	v_mfma_f32_16x16x32_bf16 v[36:39], v[138:141], v[234:237], v[36:39]
	v_mfma_f32_16x16x32_bf16 v[32:35], v[182:185], v[234:237], v[32:35]
	v_mfma_f32_16x16x32_bf16 v[28:31], v[186:189], v[206:209], v[28:31]
	v_mfma_f32_16x16x32_bf16 v[24:27], v[194:197], v[206:209], v[24:27]
	v_mfma_f32_16x16x32_bf16 v[20:23], v[186:189], v[214:217], v[20:23]
	v_mfma_f32_16x16x32_bf16 v[16:19], v[194:197], v[214:217], v[16:19]
	v_mfma_f32_16x16x32_bf16 v[12:15], v[186:189], v[222:225], v[12:15]
	v_mfma_f32_16x16x32_bf16 v[8:11], v[194:197], v[222:225], v[8:11]
	v_mfma_f32_16x16x32_bf16 v[4:7], v[186:189], v[230:233], v[4:7]
	v_mfma_f32_16x16x32_bf16 v[0:3], v[194:197], v[230:233], v[0:3]
	v_mfma_f32_16x16x32_bf16 v[28:31], v[190:193], v[210:213], v[28:31]
	v_mfma_f32_16x16x32_bf16 v[24:27], v[202:205], v[210:213], v[24:27]
	v_mfma_f32_16x16x32_bf16 v[20:23], v[190:193], v[218:221], v[20:23]
	v_mfma_f32_16x16x32_bf16 v[16:19], v[202:205], v[218:221], v[16:19]
	v_mfma_f32_16x16x32_bf16 v[12:15], v[190:193], v[226:229], v[12:15]
	v_mfma_f32_16x16x32_bf16 v[8:11], v[202:205], v[226:229], v[8:11]
	v_mfma_f32_16x16x32_bf16 v[4:7], v[190:193], v[234:237], v[4:7]
	v_mfma_f32_16x16x32_bf16 v[0:3], v[202:205], v[234:237], v[0:3]
	s_barrier
	s_add_i32 s95, s95, 2
	s_add_u32 s62, s62, 0x100
	s_addc_u32 s63, s63, 0
	s_cmp_gt_u32 s95, 13
	s_cbranch_scc0 .LBB0_670
	s_and_b64 vcc, exec, s[38:39]
	s_cbranch_vccz .LBB0_696
	s_barrier
	s_cmp_gt_i32 s73, 1
	s_mov_b64 s[2:3], -1
	s_cbranch_scc1 .LBB0_697

; #define PG8_STAGE(bufoff, gbase, voff) do { _Pragma("unroll") for (int _i = 0; _i < 2; ++_i) \
;         __builtin_amdgcn_global_load_lds((const unsigned*)((const char*)(gbase) + (voff)[_i]), (LAS unsigned*)(lds + (bufoff) + ldsw + _i * 8192), 16, 0, 0); } while (0)
; #define PG8_STAGEB(bufoff, gbase, perm) do { _Pragma("unroll") for (int _i = 0; _i < 2; ++_i) \
;         __builtin_amdgcn_global_load_lds((const unsigned*)((const char*)(gbase) + ((BSEL && (perm)) ? voffBp[_i] : voffB[_i])), (LAS unsigned*)(lds + (bufoff) + ldsw + _i * 8192), 16, 0, 0); } while (0)
; #define PG8_LDA(dst, b, h) do { _Pragma("unroll") for (int m = 0; m < 4; ++m) _Pragma("unroll") for (int k = 0; k < 2; ++k) dst[m][k] = *(const LAS bf16x8*)(lds + PG8_SA(b, h) + aoff + m * 2048 + k * 1024); } while (0)
; #define PG8_LDB(dst, b, h) do { _Pragma("unroll") for (int n = 0; n < 2; ++n) _Pragma("unroll") for (int k = 0; k < 2; ++k) dst[n][k] = *(const LAS bf16x8*)(lds + PG8_SB(b, h) + boff + n * 2048 + k * 1024); } while (0)
; #define PG8_WAIT_V(n) asm volatile("s_waitcnt vmcnt(" #n ")" ::: "memory")
; #define PG8_WAIT_L(n) asm volatile("s_waitcnt lgkmcnt(" #n ")" ::: "memory")
; #define PG8_BAR __builtin_amdgcn_s_barrier()
; #define PG8_SCHED __builtin_amdgcn_sched_barrier(0)
; template <class Epi, bool BSEL = false>
; __device__ __forceinline__ void gemm_phase(LAS unsigned char* lds, const Gemm g, const Order& S, const Epi& E, const int tid) {
;     ...
;         for (int t = 0; t < nt; t += 2) {
;             const bool last = (t == nt - 2);
;             const char* a1 = cA + (size_t)(t + 1) * kstep;
;             const char* a2 = last ? nA : cA + (size_t)(t + 2) * kstep; const char* b2 = last ? nB : cB + (size_t)(t + 2) * kstep;
;             const char* a3 = a2 + kstep; const char* b3 = b2 + kstep;
;             const bool p2 = last ? nP : cP; const size_t h2 = last ? nhB : chB;
;             PG8_LDB(B0, 0, 0); PG8_LDB(B1, 0, 1); PG8_SCHED; PG8_LDA(At, 0, 0); PG8_STAGE(PG8_SA(1, 1), a1 + hstepA, voffA);
;             PG8_WAIT_V(8); PG8_WAIT_L(0); PG8_BAR; PG8_MMA(0, 0, At, B0); PG8_MMA(0, 1, At, B1); PG8_BAR; PG8_SCHED;
;             PG8_LDA(At, 0, 1); PG8_STAGEB(PG8_SB(0, 0), b2, p2); PG8_STAGEB(PG8_SB(0, 1), b2 + h2, p2); PG8_STAGE(PG8_SA(0, 0), a2, voffA);
;             PG8_WAIT_V(8); PG8_WAIT_L(0); PG8_BAR; PG8_MMA(1, 0, At, B0); PG8_MMA(1, 1, At, B1); PG8_BAR; PG8_SCHED;
.LBB0_826:
	s_xor_b64 s[38:39], s[40:41], -1
	v_add_u32_e32 v145, s53, v139
	s_and_b64 s[2:3], s[40:41], exec
	ds_read_b128 v[146:149], v145
	ds_read_b128 v[150:153], v145 offset:1024
	ds_read_b128 v[154:157], v145 offset:2048
	ds_read_b128 v[158:161], v145 offset:3072
	v_add_u32_e32 v145, s54, v139
	s_cselect_b32 s45, s1, s1
	s_cselect_b32 s44, s0, s0
	s_add_u32 s58, s0, 0x8080
	ds_read_b128 v[162:165], v145
	ds_read_b128 v[166:169], v145 offset:1024
	ds_read_b128 v[170:173], v145 offset:2048
	ds_read_b128 v[174:177], v145 offset:3072
	s_addc_u32 s59, s1, 0
	s_add_u32 s42, s44, 0x8000
	s_addc_u32 s43, s45, 0
	s_and_b64 s[2:3], s[40:41], exec
	s_cselect_b32 s2, s36, s4
	s_cselect_b32 s3, s37, s5
	s_add_u32 s60, s2, 0x8000
	s_addc_u32 s61, s3, 0
	v_lshl_add_u64 v[198:199], s[58:59], 0, v[128:129]
	s_add_i32 m0, s20, 0xc000
	ds_read_b128 v[178:181], v144
	ds_read_b128 v[182:185], v144 offset:1024
	ds_read_b128 v[186:189], v144 offset:2048
	ds_read_b128 v[190:193], v144 offset:3072
	ds_read_b128 v[194:197], v144 offset:4096
	ds_read_b128 v[202:205], v144 offset:5120
	ds_read_b128 v[206:209], v144 offset:6144
	ds_read_b128 v[210:213], v144 offset:7168
	global_load_lds_dwordx4 v[198:199], off
	v_lshl_add_u64 v[198:199], s[58:59], 0, v[132:133]
	s_add_i32 m0, s20, 0xe000
	s_nop 0
	global_load_lds_dwordx4 v[198:199], off
	s_waitcnt vmcnt(8)
	s_waitcnt lgkmcnt(0)
	s_barrier
	v_mfma_f32_16x16x32_bf16 v[124:127], v[146:149], v[178:181], v[124:127]
	v_mfma_f32_16x16x32_bf16 v[120:123], v[154:157], v[178:181], v[120:123]
	v_mfma_f32_16x16x32_bf16 v[116:119], v[146:149], v[186:189], v[116:119]
	v_mfma_f32_16x16x32_bf16 v[112:115], v[154:157], v[186:189], v[112:115]
	v_mfma_f32_16x16x32_bf16 v[108:111], v[146:149], v[194:197], v[108:111]
	v_mfma_f32_16x16x32_bf16 v[104:107], v[154:157], v[194:197], v[104:107]
	v_mfma_f32_16x16x32_bf16 v[100:103], v[146:149], v[206:209], v[100:103]
	v_mfma_f32_16x16x32_bf16 v[96:99], v[154:157], v[206:209], v[96:99]
	v_mfma_f32_16x16x32_bf16 v[124:127], v[150:153], v[182:185], v[124:127]
	v_mfma_f32_16x16x32_bf16 v[120:123], v[158:161], v[182:185], v[120:123]
	v_mfma_f32_16x16x32_bf16 v[116:119], v[150:153], v[190:193], v[116:119]
	v_mfma_f32_16x16x32_bf16 v[112:115], v[158:161], v[190:193], v[112:115]
	v_mfma_f32_16x16x32_bf16 v[108:111], v[150:153], v[202:205], v[108:111]
	v_mfma_f32_16x16x32_bf16 v[104:107], v[158:161], v[202:205], v[104:107]
	v_mfma_f32_16x16x32_bf16 v[100:103], v[150:153], v[210:213], v[100:103]
	v_mfma_f32_16x16x32_bf16 v[96:99], v[158:161], v[210:213], v[96:99]
	v_mfma_f32_16x16x32_bf16 v[92:95], v[162:165], v[178:181], v[92:95]
	v_mfma_f32_16x16x32_bf16 v[88:91], v[170:173], v[178:181], v[88:91]
	v_mfma_f32_16x16x32_bf16 v[84:87], v[162:165], v[186:189], v[84:87]
	v_mfma_f32_16x16x32_bf16 v[80:83], v[170:173], v[186:189], v[80:83]
	v_mfma_f32_16x16x32_bf16 v[76:79], v[162:165], v[194:197], v[76:79]
	v_mfma_f32_16x16x32_bf16 v[72:75], v[170:173], v[194:197], v[72:75]
	v_mfma_f32_16x16x32_bf16 v[68:71], v[162:165], v[206:209], v[68:71]
	v_mfma_f32_16x16x32_bf16 v[64:67], v[170:173], v[206:209], v[64:67]
	v_mfma_f32_16x16x32_bf16 v[92:95], v[166:169], v[182:185], v[92:95]
	v_mfma_f32_16x16x32_bf16 v[88:91], v[174:177], v[182:185], v[88:91]
	v_mfma_f32_16x16x32_bf16 v[84:87], v[166:169], v[190:193], v[84:87]
	v_mfma_f32_16x16x32_bf16 v[80:83], v[174:177], v[190:193], v[80:83]
	v_mfma_f32_16x16x32_bf16 v[76:79], v[166:169], v[202:205], v[76:79]
	v_mfma_f32_16x16x32_bf16 v[72:75], v[174:177], v[202:205], v[72:75]
	v_mfma_f32_16x16x32_bf16 v[68:71], v[166:169], v[210:213], v[68:71]
	v_mfma_f32_16x16x32_bf16 v[64:67], v[174:177], v[210:213], v[64:67]
	s_barrier
	s_add_i32 s35, s53, s15
	v_lshl_add_u64 v[198:199], s[2:3], 0, v[130:131]
	s_mov_b32 m0, s35
	ds_read_b128 v[178:181], v144 offset:16384
	ds_read_b128 v[182:185], v144 offset:17408
	ds_read_b128 v[186:189], v144 offset:18432
	ds_read_b128 v[190:193], v144 offset:19456
	ds_read_b128 v[194:197], v144 offset:20480
	ds_read_b128 v[202:205], v144 offset:21504
	ds_read_b128 v[206:209], v144 offset:22528
	ds_read_b128 v[210:213], v144 offset:23552
	global_load_lds_dwordx4 v[198:199], off
	v_lshl_add_u64 v[214:215], s[2:3], 0, v[134:135]
	s_add_i32 m0, s35, 0x2000
	s_add_i32 s35, s54, s15
	global_load_lds_dwordx4 v[214:215], off
	v_lshl_add_u64 v[216:217], s[60:61], 0, v[130:131]
	s_mov_b32 m0, s35
	v_lshl_add_u64 v[218:219], s[44:45], 0, v[132:133]
	global_load_lds_dwordx4 v[216:217], off
	v_lshl_add_u64 v[216:217], s[60:61], 0, v[134:135]
	s_add_i32 m0, s35, 0x2000
	s_nop 0
	global_load_lds_dwordx4 v[216:217], off
	v_lshl_add_u64 v[216:217], s[44:45], 0, v[128:129]
	s_mov_b32 m0, s20
	s_nop 0
	global_load_lds_dwordx4 v[216:217], off
	s_mov_b32 m0, s21
	s_nop 0
	global_load_lds_dwordx4 v[218:219], off
	s_waitcnt vmcnt(8)
	s_waitcnt lgkmcnt(0)
	s_barrier
; #define PG8_STAGE(bufoff, gbase, voff) do { _Pragma("unroll") for (int _i = 0; _i < 2; ++_i) \
;         __builtin_amdgcn_global_load_lds((const unsigned*)((const char*)(gbase) + (voff)[_i]), (LAS unsigned*)(lds + (bufoff) + ldsw + _i * 8192), 16, 0, 0); } while (0)
; #define PG8_LDA(dst, b, h) do { _Pragma("unroll") for (int m = 0; m < 4; ++m) _Pragma("unroll") for (int k = 0; k < 2; ++k) dst[m][k] = *(const LAS bf16x8*)(lds + PG8_SA(b, h) + aoff + m * 2048 + k * 1024); } while (0)
; #define PG8_LDB(dst, b, h) do { _Pragma("unroll") for (int n = 0; n < 2; ++n) _Pragma("unroll") for (int k = 0; k < 2; ++k) dst[n][k] = *(const LAS bf16x8*)(lds + PG8_SB(b, h) + boff + n * 2048 + k * 1024); } while (0)
; #define PG8_MMA(ai, bj, At, Bt) do { __builtin_amdgcn_s_setprio(1); _Pragma("unroll") for (int m = 0; m < 4; ++m) _Pragma("unroll") for (int n = 0; n < 2; ++n) _Pragma("unroll") for (int k = 0; k < 2; ++k) \
;         acc[ai][bj][m][n] = __builtin_amdgcn_mfma_f32_16x16x32_bf16(Bt[n][k], At[m][k], acc[ai][bj][m][n], 0, 0, 0); __builtin_amdgcn_s_setprio(0); } while (0)
; #define PG8_WAIT_V(n) asm volatile("s_waitcnt vmcnt(" #n ")" ::: "memory")
; #define PG8_WAIT_L(n) asm volatile("s_waitcnt lgkmcnt(" #n ")" ::: "memory")
; #define PG8_BAR __builtin_amdgcn_s_barrier()
; #define PG8_SCHED __builtin_amdgcn_sched_barrier(0)
; template <class Epi, bool BSEL = false>
; __device__ __forceinline__ void gemm_phase(LAS unsigned char* lds, const Gemm g, const Order& S, const Epi& E, const int tid) {
;     ...
;             PG8_WAIT_V(8); PG8_WAIT_L(0); PG8_BAR; PG8_MMA(1, 0, At, B0); PG8_MMA(1, 1, At, B1); PG8_BAR; PG8_SCHED;
;             PG8_LDB(B0, 1, 0); PG8_LDB(B1, 1, 1); PG8_SCHED; PG8_LDA(At, 1, 0); PG8_STAGE(PG8_SA(0, 1), a2 + hstepA, voffA);
;             PG8_WAIT_V(8); PG8_WAIT_L(0); PG8_BAR; PG8_MMA(0, 0, At, B0); PG8_MMA(0, 1, At, B1); PG8_BAR; PG8_SCHED;
	v_mfma_f32_16x16x32_bf16 v[60:63], v[146:149], v[178:181], v[60:63]
	v_mfma_f32_16x16x32_bf16 v[56:59], v[154:157], v[178:181], v[56:59]
	v_mfma_f32_16x16x32_bf16 v[52:55], v[146:149], v[186:189], v[52:55]
	v_mfma_f32_16x16x32_bf16 v[48:51], v[154:157], v[186:189], v[48:51]
	v_mfma_f32_16x16x32_bf16 v[44:47], v[146:149], v[194:197], v[44:47]
	v_mfma_f32_16x16x32_bf16 v[40:43], v[154:157], v[194:197], v[40:43]
	v_mfma_f32_16x16x32_bf16 v[36:39], v[146:149], v[206:209], v[36:39]
	v_mfma_f32_16x16x32_bf16 v[32:35], v[154:157], v[206:209], v[32:35]
	v_mfma_f32_16x16x32_bf16 v[60:63], v[150:153], v[182:185], v[60:63]
	v_mfma_f32_16x16x32_bf16 v[56:59], v[158:161], v[182:185], v[56:59]
	v_mfma_f32_16x16x32_bf16 v[52:55], v[150:153], v[190:193], v[52:55]
	v_mfma_f32_16x16x32_bf16 v[48:51], v[158:161], v[190:193], v[48:51]
	v_mfma_f32_16x16x32_bf16 v[44:47], v[150:153], v[202:205], v[44:47]
	v_mfma_f32_16x16x32_bf16 v[40:43], v[158:161], v[202:205], v[40:43]
	v_mfma_f32_16x16x32_bf16 v[36:39], v[150:153], v[210:213], v[36:39]
	v_mfma_f32_16x16x32_bf16 v[32:35], v[158:161], v[210:213], v[32:35]
	v_mfma_f32_16x16x32_bf16 v[28:31], v[162:165], v[178:181], v[28:31]
	v_mfma_f32_16x16x32_bf16 v[24:27], v[170:173], v[178:181], v[24:27]
	v_mfma_f32_16x16x32_bf16 v[20:23], v[162:165], v[186:189], v[20:23]
	v_mfma_f32_16x16x32_bf16 v[16:19], v[170:173], v[186:189], v[16:19]
	v_mfma_f32_16x16x32_bf16 v[12:15], v[162:165], v[194:197], v[12:15]
	v_mfma_f32_16x16x32_bf16 v[8:11], v[170:173], v[194:197], v[8:11]
	v_mfma_f32_16x16x32_bf16 v[4:7], v[162:165], v[206:209], v[4:7]
	v_mfma_f32_16x16x32_bf16 v[0:3], v[170:173], v[206:209], v[0:3]
	v_mfma_f32_16x16x32_bf16 v[28:31], v[166:169], v[182:185], v[28:31]
	v_mfma_f32_16x16x32_bf16 v[24:27], v[174:177], v[182:185], v[24:27]
	v_mfma_f32_16x16x32_bf16 v[20:23], v[166:169], v[190:193], v[20:23]
	v_mfma_f32_16x16x32_bf16 v[16:19], v[174:177], v[190:193], v[16:19]
	v_mfma_f32_16x16x32_bf16 v[12:15], v[166:169], v[202:205], v[12:15]
	v_mfma_f32_16x16x32_bf16 v[8:11], v[174:177], v[202:205], v[8:11]
	v_mfma_f32_16x16x32_bf16 v[4:7], v[166:169], v[210:213], v[4:7]
	v_mfma_f32_16x16x32_bf16 v[0:3], v[174:177], v[210:213], v[0:3]
	s_barrier
	s_add_i32 s35, 0, 0x18000
	v_add_u32_e32 v145, s35, v139
	s_add_i32 s44, 0, 0x1c000
	ds_read_b128 v[146:149], v145
	ds_read_b128 v[150:153], v145 offset:1024
	ds_read_b128 v[154:157], v145 offset:2048
	ds_read_b128 v[158:161], v145 offset:3072
	v_add_u32_e32 v145, s44, v139
	ds_read_b128 v[162:165], v145
	ds_read_b128 v[166:169], v145 offset:1024
	ds_read_b128 v[170:173], v145 offset:2048
	ds_read_b128 v[174:177], v145 offset:3072
	s_mov_b32 m0, s46
	v_lshl_add_u64 v[220:221], s[42:43], 0, v[128:129]
	ds_read_b128 v[178:181], v144 offset:32768
	ds_read_b128 v[182:185], v144 offset:33792
	ds_read_b128 v[186:189], v144 offset:34816
	ds_read_b128 v[190:193], v144 offset:35840
	ds_read_b128 v[194:197], v144 offset:36864
	ds_read_b128 v[202:205], v144 offset:37888
	ds_read_b128 v[206:209], v144 offset:38912
	ds_read_b128 v[210:213], v144 offset:39936
	global_load_lds_dwordx4 v[220:221], off
	v_lshl_add_u64 v[220:221], s[42:43], 0, v[132:133]
	s_mov_b32 m0, s47
	s_nop 0
	global_load_lds_dwordx4 v[220:221], off
	s_waitcnt vmcnt(8)
	s_waitcnt lgkmcnt(0)
	s_barrier
	v_mfma_f32_16x16x32_bf16 v[124:127], v[146:149], v[178:181], v[124:127]
	v_mfma_f32_16x16x32_bf16 v[120:123], v[154:157], v[178:181], v[120:123]
	v_mfma_f32_16x16x32_bf16 v[116:119], v[146:149], v[186:189], v[116:119]
	v_mfma_f32_16x16x32_bf16 v[112:115], v[154:157], v[186:189], v[112:115]
	v_mfma_f32_16x16x32_bf16 v[108:111], v[146:149], v[194:197], v[108:111]
	v_mfma_f32_16x16x32_bf16 v[104:107], v[154:157], v[194:197], v[104:107]
	v_mfma_f32_16x16x32_bf16 v[100:103], v[146:149], v[206:209], v[100:103]
	v_mfma_f32_16x16x32_bf16 v[96:99], v[154:157], v[206:209], v[96:99]
	v_mfma_f32_16x16x32_bf16 v[124:127], v[150:153], v[182:185], v[124:127]
	v_mfma_f32_16x16x32_bf16 v[120:123], v[158:161], v[182:185], v[120:123]
	v_mfma_f32_16x16x32_bf16 v[116:119], v[150:153], v[190:193], v[116:119]
	v_mfma_f32_16x16x32_bf16 v[112:115], v[158:161], v[190:193], v[112:115]
	v_mfma_f32_16x16x32_bf16 v[108:111], v[150:153], v[202:205], v[108:111]
	v_mfma_f32_16x16x32_bf16 v[104:107], v[158:161], v[202:205], v[104:107]
	v_mfma_f32_16x16x32_bf16 v[100:103], v[150:153], v[210:213], v[100:103]
	v_mfma_f32_16x16x32_bf16 v[96:99], v[158:161], v[210:213], v[96:99]
	v_mfma_f32_16x16x32_bf16 v[92:95], v[162:165], v[178:181], v[92:95]
	v_mfma_f32_16x16x32_bf16 v[88:91], v[170:173], v[178:181], v[88:91]
	v_mfma_f32_16x16x32_bf16 v[84:87], v[162:165], v[186:189], v[84:87]
	v_mfma_f32_16x16x32_bf16 v[80:83], v[170:173], v[186:189], v[80:83]
	v_mfma_f32_16x16x32_bf16 v[76:79], v[162:165], v[194:197], v[76:79]
	v_mfma_f32_16x16x32_bf16 v[72:75], v[170:173], v[194:197], v[72:75]
	v_mfma_f32_16x16x32_bf16 v[68:71], v[162:165], v[206:209], v[68:71]
	v_mfma_f32_16x16x32_bf16 v[64:67], v[170:173], v[206:209], v[64:67]
	v_mfma_f32_16x16x32_bf16 v[92:95], v[166:169], v[182:185], v[92:95]
	v_mfma_f32_16x16x32_bf16 v[88:91], v[174:177], v[182:185], v[88:91]
	v_mfma_f32_16x16x32_bf16 v[84:87], v[166:169], v[190:193], v[84:87]
	v_mfma_f32_16x16x32_bf16 v[80:83], v[174:177], v[190:193], v[80:83]
	v_mfma_f32_16x16x32_bf16 v[76:79], v[166:169], v[202:205], v[76:79]
	v_mfma_f32_16x16x32_bf16 v[72:75], v[174:177], v[202:205], v[72:75]
	v_mfma_f32_16x16x32_bf16 v[68:71], v[166:169], v[210:213], v[68:71]
	v_mfma_f32_16x16x32_bf16 v[64:67], v[174:177], v[210:213], v[64:67]
	s_barrier
; #define PG8_MMA(ai, bj, At, Bt) do { __builtin_amdgcn_s_setprio(1); _Pragma("unroll") for (int m = 0; m < 4; ++m) _Pragma("unroll") for (int n = 0; n < 2; ++n) _Pragma("unroll") for (int k = 0; k < 2; ++k) \
;         acc[ai][bj][m][n] = __builtin_amdgcn_mfma_f32_16x16x32_bf16(Bt[n][k], At[m][k], acc[ai][bj][m][n], 0, 0, 0); __builtin_amdgcn_s_setprio(0); } while (0)
; #define PG8_WAIT_V(n) asm volatile("s_waitcnt vmcnt(" #n ")" ::: "memory")
; #define PG8_WAIT_L(n) asm volatile("s_waitcnt lgkmcnt(" #n ")" ::: "memory")
; #define PG8_BAR __builtin_amdgcn_s_barrier()
; #define PG8_SCHED __builtin_amdgcn_sched_barrier(0)
; template <class Epi, bool BSEL = false>
; __device__ __forceinline__ void gemm_phase(LAS unsigned char* lds, const Gemm g, const Order& S, const Epi& E, const int tid) {
;     ...
;             PG8_WAIT_V(8); PG8_WAIT_L(0); PG8_BAR; PG8_MMA(1, 0, At, B0); PG8_MMA(1, 1, At, B1); PG8_BAR; PG8_SCHED;
;         }
;         if constexpr (ALIGN_EPI) { if (wr == 0) PG8_BAR; }
;     __device__ __forceinline__ void operator()(const f32x4 (&acc)[2][2][4][2], const Unit& u, int wr, int wc, int fr, int fq) const {
;         if (wr != 0) return;
;         const __amdgpu_buffer_rsrc_t rsrc = __builtin_amdgcn_make_buffer_rsrc(YT, 0, 65536 * 128 * 2, 0x00020000);
; #pragma unroll
;         for (int m = 0; m < 4; ++m) { const int k1 = 16 * m + fr;
; #pragma unroll
;             for (int bj = 0; bj < 2; ++bj) { const int col = 4 * u.pn + 2 * bj + (wc >> 1), b = col >> 8, ch = col & 255;
;                 const int n2 = 32 * (wc & 1) + 8 * fq;
;                 const unsigned rowo = (unsigned)((((size_t)(b * 64 + k1) * 256 + ch) * 128 + n2) * 2);
;                 int kk = k1; asm volatile("" : "+v"(kk));
;                 f32x4 pr[2], pi[2];
; #pragma unroll
;                 for (int n = 0; n < 2; ++n) { const f32x4 yr = acc[0][bj][m][n], yi = acc[1][bj][m][n];
; #pragma unroll
;                     for (int i = 0; i < 4; ++i) { const f32x2 cs = TW[(n2 + 4 * n + i) * kk]; pr[n][i] = yr[i] * cs.x + yi[i] * cs.y; pi[n][i] = yi[i] * cs.x - yr[i] * cs.y; } }
	s_add_i32 s35, s35, s15
	v_lshl_add_u64 v[198:199], v[198:199], 0, s[28:29]
	s_mov_b32 m0, s35
	ds_read_b128 v[178:181], v144 offset:49152
	ds_read_b128 v[182:185], v144 offset:50176
	ds_read_b128 v[186:189], v144 offset:51200
	ds_read_b128 v[190:193], v144 offset:52224
	ds_read_b128 v[194:197], v144 offset:53248
	ds_read_b128 v[202:205], v144 offset:54272
	ds_read_b128 v[206:209], v144 offset:55296
	ds_read_b128 v[210:213], v144 offset:56320
	global_load_lds_dwordx4 v[198:199], off
	s_add_i32 m0, s35, 0x2000
	s_add_u32 s2, s2, 0x8080
	v_lshl_add_u64 v[198:199], v[214:215], 0, s[28:29]
	s_addc_u32 s3, s3, 0
	s_add_i32 s35, s44, s15
	global_load_lds_dwordx4 v[198:199], off
	v_lshl_add_u64 v[198:199], s[2:3], 0, v[130:131]
	s_mov_b32 m0, s35
	s_nop 0
	global_load_lds_dwordx4 v[198:199], off
	v_lshl_add_u64 v[198:199], s[2:3], 0, v[134:135]
	s_add_i32 m0, s35, 0x2000
	s_nop 0
	global_load_lds_dwordx4 v[198:199], off
	v_lshl_add_u64 v[198:199], v[216:217], 0, s[28:29]
	s_mov_b32 m0, s49
	s_nop 0
	global_load_lds_dwordx4 v[198:199], off
	v_lshl_add_u64 v[198:199], v[218:219], 0, s[28:29]
	s_mov_b32 m0, s51
	s_nop 0
	global_load_lds_dwordx4 v[198:199], off
	s_waitcnt vmcnt(8)
	s_waitcnt lgkmcnt(0)
	s_barrier
	v_mfma_f32_16x16x32_bf16 v[60:63], v[146:149], v[178:181], v[60:63]
	v_mfma_f32_16x16x32_bf16 v[56:59], v[154:157], v[178:181], v[56:59]
	v_mfma_f32_16x16x32_bf16 v[52:55], v[146:149], v[186:189], v[52:55]
	v_mfma_f32_16x16x32_bf16 v[48:51], v[154:157], v[186:189], v[48:51]
	v_mfma_f32_16x16x32_bf16 v[44:47], v[146:149], v[194:197], v[44:47]
	v_mfma_f32_16x16x32_bf16 v[40:43], v[154:157], v[194:197], v[40:43]
	v_mfma_f32_16x16x32_bf16 v[36:39], v[146:149], v[206:209], v[36:39]
	v_mfma_f32_16x16x32_bf16 v[32:35], v[154:157], v[206:209], v[32:35]
	v_mfma_f32_16x16x32_bf16 v[60:63], v[150:153], v[182:185], v[60:63]
	v_mfma_f32_16x16x32_bf16 v[56:59], v[158:161], v[182:185], v[56:59]
	v_mfma_f32_16x16x32_bf16 v[52:55], v[150:153], v[190:193], v[52:55]
	v_mfma_f32_16x16x32_bf16 v[48:51], v[158:161], v[190:193], v[48:51]
	v_mfma_f32_16x16x32_bf16 v[44:47], v[150:153], v[202:205], v[44:47]
	v_mfma_f32_16x16x32_bf16 v[40:43], v[158:161], v[202:205], v[40:43]
	v_mfma_f32_16x16x32_bf16 v[36:39], v[150:153], v[210:213], v[36:39]
	v_mfma_f32_16x16x32_bf16 v[32:35], v[158:161], v[210:213], v[32:35]
	v_mfma_f32_16x16x32_bf16 v[28:31], v[162:165], v[178:181], v[28:31]
	v_mfma_f32_16x16x32_bf16 v[24:27], v[170:173], v[178:181], v[24:27]
	v_mfma_f32_16x16x32_bf16 v[20:23], v[162:165], v[186:189], v[20:23]
	v_mfma_f32_16x16x32_bf16 v[16:19], v[170:173], v[186:189], v[16:19]
	v_mfma_f32_16x16x32_bf16 v[12:15], v[162:165], v[194:197], v[12:15]
	v_mfma_f32_16x16x32_bf16 v[8:11], v[170:173], v[194:197], v[8:11]
	v_mfma_f32_16x16x32_bf16 v[4:7], v[162:165], v[206:209], v[4:7]
	v_mfma_f32_16x16x32_bf16 v[0:3], v[170:173], v[206:209], v[0:3]
	v_mfma_f32_16x16x32_bf16 v[28:31], v[166:169], v[182:185], v[28:31]
	v_mfma_f32_16x16x32_bf16 v[24:27], v[174:177], v[182:185], v[24:27]
	v_mfma_f32_16x16x32_bf16 v[20:23], v[166:169], v[190:193], v[20:23]
	v_mfma_f32_16x16x32_bf16 v[16:19], v[174:177], v[190:193], v[16:19]
	v_mfma_f32_16x16x32_bf16 v[12:15], v[166:169], v[202:205], v[12:15]
	v_mfma_f32_16x16x32_bf16 v[8:11], v[174:177], v[202:205], v[8:11]
	v_mfma_f32_16x16x32_bf16 v[4:7], v[166:169], v[210:213], v[4:7]
	v_mfma_f32_16x16x32_bf16 v[0:3], v[174:177], v[210:213], v[0:3]
	s_barrier
	s_andn2_b64 vcc, exec, s[30:31]
	s_cbranch_vccnz .LBB0_828
	v_mov_b32_e32 v145, v138
	s_barrier
	v_mov_b32_e32 v162, v124
	v_mul_lo_u32 v146, v145, v140
	v_ashrrev_i32_e32 v147, 31, v146
	v_lshl_add_u64 v[148:149], v[146:147], 3, s[26:27]
	v_add_u32_e32 v146, v146, v145
	v_ashrrev_i32_e32 v147, 31, v146
	v_lshl_add_u64 v[150:151], v[146:147], 3, s[26:27]
	v_add_u32_e32 v146, v146, v145
	v_ashrrev_i32_e32 v147, 31, v146
	v_lshl_add_u64 v[152:153], v[146:147], 3, s[26:27]
	v_add_u32_e32 v146, v146, v145
	v_ashrrev_i32_e32 v147, 31, v146
	v_lshl_add_u64 v[154:155], v[146:147], 3, s[26:27]
	v_add_u32_e32 v146, v146, v145
	global_load_dwordx2 v[148:149], v[148:149], off
	v_ashrrev_i32_e32 v147, 31, v146
	global_load_dwordx2 v[150:151], v[150:151], off
	v_lshl_add_u64 v[156:157], v[146:147], 3, s[26:27]
	v_add_u32_e32 v146, v146, v145
	global_load_dwordx2 v[152:153], v[152:153], off
	v_ashrrev_i32_e32 v147, 31, v146
	global_load_dwordx2 v[154:155], v[154:155], off
	v_lshl_add_u64 v[158:159], v[146:147], 3, s[26:27]
	v_add_u32_e32 v146, v146, v145
	global_load_dwordx2 v[156:157], v[156:157], off
	v_ashrrev_i32_e32 v147, 31, v146
	global_load_dwordx2 v[158:159], v[158:159], off
	v_lshl_add_u64 v[160:161], v[146:147], 3, s[26:27]
	global_load_dwordx2 v[160:161], v[160:161], off
	v_add_u32_e32 v146, v146, v145
	v_ashrrev_i32_e32 v147, 31, v146
	v_lshl_add_u64 v[146:147], v[146:147], 3, s[26:27]
	global_load_dwordx2 v[146:147], v[146:147], off
	v_mov_b32_e32 v163, v60
	v_mov_b32_e32 v164, v60
	v_mov_b32_e32 v165, v124
	v_mov_b32_e32 v166, v125
	v_mov_b32_e32 v167, v61
	v_mov_b32_e32 v168, v61
	v_mov_b32_e32 v169, v125
	v_mov_b32_e32 v170, v126
	v_mov_b32_e32 v171, v62
	v_mov_b32_e32 v172, v62
	v_mov_b32_e32 v173, v126
	v_mov_b32_e32 v174, v127
	v_mov_b32_e32 v175, v63
	v_mov_b32_e32 v176, v63
	v_mov_b32_e32 v177, v127
	v_mov_b32_e32 v178, v120
	v_mov_b32_e32 v179, v56
	v_mov_b32_e32 v180, v56
	v_mov_b32_e32 v181, v120
	v_mov_b32_e32 v182, v121
	v_mov_b32_e32 v183, v57
	v_mov_b32_e32 v184, v57
	v_mov_b32_e32 v185, v121
	v_mov_b32_e32 v186, v122
	v_mov_b32_e32 v187, v58
	s_lshl_b32 s3, s48, 2
	s_and_b32 s2, s48, 0xffc0
	s_and_b32 s3, s3, 0xfc
	v_or_b32_e32 v145, s2, v138
	s_or_b32 s3, s3, s52
	v_lshl_or_b32 v145, v145, 15, v140
	s_lshl_b32 s35, s3, 7
	v_or_b32_e32 v188, s35, v145
	s_or_b32 s3, s35, 0x100
	v_or_b32_e32 v145, s3, v145
	v_lshlrev_b32_e32 v145, 1, v145
	s_waitcnt vmcnt(0)
; __device__ __forceinline__ unsigned cvt_pk_bf16(float lo, float hi) { unsigned r; asm volatile("v_cvt_pk_bf16_f32 %0, %1, %2" : "=v"(r) : "v"(lo), "v"(hi)); return r; }
;     __device__ __forceinline__ void operator()(const f32x4 (&acc)[2][2][4][2], const Unit& u, int wr, int wc, int fr, int fq) const {
;     ...
;         for (int m = 0; m < 4; ++m) { const int k1 = 16 * m + fr;
; #pragma unroll
;             for (int bj = 0; bj < 2; ++bj) { const int col = 4 * u.pn + 2 * bj + (wc >> 1), b = col >> 8, ch = col & 255;
;                 const int n2 = 32 * (wc & 1) + 8 * fq;
;                 const unsigned rowo = (unsigned)((((size_t)(b * 64 + k1) * 256 + ch) * 128 + n2) * 2);
;                 int kk = k1; asm volatile("" : "+v"(kk));
;                 f32x4 pr[2], pi[2];
; #pragma unroll
;                 for (int n = 0; n < 2; ++n) { const f32x4 yr = acc[0][bj][m][n], yi = acc[1][bj][m][n];
; #pragma unroll
;                     for (int i = 0; i < 4; ++i) { const f32x2 cs = TW[(n2 + 4 * n + i) * kk]; pr[n][i] = yr[i] * cs.x + yi[i] * cs.y; pi[n][i] = yi[i] * cs.x - yr[i] * cs.y; } }
;                 u32x4 w; w.x = cvt_pk_bf16(pr[0][0], pr[0][1]); w.y = cvt_pk_bf16(pr[0][2], pr[0][3]); w.z = cvt_pk_bf16(pr[1][0], pr[1][1]); w.w = cvt_pk_bf16(pr[1][2], pr[1][3]);
;                 __builtin_amdgcn_raw_buffer_store_b128(w, rsrc, rowo, 0, 16);
;                 w.x = cvt_pk_bf16(pi[0][0], pi[0][1]); w.y = cvt_pk_bf16(pi[0][2], pi[0][3]); w.z = cvt_pk_bf16(pi[1][0], pi[1][1]); w.w = cvt_pk_bf16(pi[1][2], pi[1][3]);
;                 __builtin_amdgcn_raw_buffer_store_b128(w, rsrc, rowo + 128, 0, 16);
;                 asm volatile("" ::: "memory"); } }
	v_pk_mul_f32 v[162:163], v[162:163], v[148:149]
	v_pk_mul_f32 v[148:149], v[164:165], v[148:149]
	v_add_f32_e32 v162, v162, v163
	v_sub_f32_e32 v163, v148, v149
	v_pk_mul_f32 v[148:149], v[166:167], v[150:151]
	v_pk_mul_f32 v[150:151], v[168:169], v[150:151]
	v_add_f32_e32 v164, v148, v149
	v_pk_mul_f32 v[148:149], v[170:171], v[152:153]
	v_sub_f32_e32 v165, v150, v151
	v_pk_mul_f32 v[150:151], v[172:173], v[152:153]
	v_add_f32_e32 v152, v148, v149
	v_pk_mul_f32 v[148:149], v[174:175], v[154:155]
	v_sub_f32_e32 v153, v150, v151
	v_pk_mul_f32 v[150:151], v[176:177], v[154:155]
	v_add_f32_e32 v154, v148, v149
	v_pk_mul_f32 v[148:149], v[178:179], v[156:157]
	v_sub_f32_e32 v155, v150, v151
	v_pk_mul_f32 v[150:151], v[180:181], v[156:157]
	v_add_f32_e32 v156, v148, v149
	v_pk_mul_f32 v[148:149], v[182:183], v[158:159]
	v_sub_f32_e32 v157, v150, v151
	v_pk_mul_f32 v[150:151], v[184:185], v[158:159]
	v_add_f32_e32 v158, v148, v149
	v_pk_mul_f32 v[148:149], v[186:187], v[160:161]
	v_sub_f32_e32 v150, v150, v151
	v_add_f32_e32 v151, v148, v149
	v_mov_b32_e32 v148, v58
	v_mov_b32_e32 v149, v122
	v_pk_mul_f32 v[148:149], v[148:149], v[160:161]
	v_lshlrev_b32_e32 v166, 1, v188
	v_sub_f32_e32 v159, v148, v149
	v_mov_b32_e32 v148, v123
	v_mov_b32_e32 v149, v59
	v_pk_mul_f32 v[148:149], v[148:149], v[146:147]
	v_mov_b32_e32 v167, v29
	v_add_f32_e32 v160, v148, v149
	v_mov_b32_e32 v148, v59
	v_mov_b32_e32 v149, v123
	v_pk_mul_f32 v[146:147], v[148:149], v[146:147]
	v_mov_b32_e32 v168, v29
	v_sub_f32_e32 v161, v146, v147
	v_cvt_pk_bf16_f32 v146, v162, v164
	v_cvt_pk_bf16_f32 v147, v152, v154
	v_cvt_pk_bf16_f32 v148, v156, v158
	v_cvt_pk_bf16_f32 v149, v151, v160
	buffer_store_dwordx4 v[146:149], v166, s[8:11], 0 offen sc1
	v_mov_b32_e32 v162, v138
	v_mov_b32_e32 v164, v28
	v_cvt_pk_bf16_f32 v146, v163, v165
	v_cvt_pk_bf16_f32 v147, v153, v155
	v_cvt_pk_bf16_f32 v148, v157, v150
	v_cvt_pk_bf16_f32 v149, v159, v161
	buffer_store_dwordx4 v[146:149], v166, s[8:11], 0 offen offset:128 sc1
	v_mov_b32_e32 v163, v28
	v_mov_b32_e32 v165, v92
	v_mul_lo_u32 v146, v162, v140
	v_ashrrev_i32_e32 v147, 31, v146
	v_lshl_add_u64 v[148:149], v[146:147], 3, s[26:27]
	v_add_u32_e32 v146, v146, v162
	v_ashrrev_i32_e32 v147, 31, v146
	v_lshl_add_u64 v[150:151], v[146:147], 3, s[26:27]
	v_add_u32_e32 v146, v146, v162
	v_ashrrev_i32_e32 v147, 31, v146
	global_load_dwordx2 v[148:149], v[148:149], off
	v_lshl_add_u64 v[152:153], v[146:147], 3, s[26:27]
	v_add_u32_e32 v146, v146, v162
	global_load_dwordx2 v[150:151], v[150:151], off
	v_ashrrev_i32_e32 v147, 31, v146
	global_load_dwordx2 v[152:153], v[152:153], off
	v_lshl_add_u64 v[154:155], v[146:147], 3, s[26:27]
	v_add_u32_e32 v146, v146, v162
	global_load_dwordx2 v[154:155], v[154:155], off
	v_ashrrev_i32_e32 v147, 31, v146
	v_lshl_add_u64 v[156:157], v[146:147], 3, s[26:27]
	global_load_dwordx2 v[156:157], v[156:157], off
	v_add_u32_e32 v146, v146, v162
	v_ashrrev_i32_e32 v147, 31, v146
	v_lshl_add_u64 v[158:159], v[146:147], 3, s[26:27]
	global_load_dwordx2 v[158:159], v[158:159], off
	v_add_u32_e32 v146, v146, v162
	v_ashrrev_i32_e32 v147, 31, v146
	v_lshl_add_u64 v[160:161], v[146:147], 3, s[26:27]
	global_load_dwordx2 v[160:161], v[160:161], off
	v_add_u32_e32 v146, v146, v162
	v_ashrrev_i32_e32 v147, 31, v146
	v_lshl_add_u64 v[146:147], v[146:147], 3, s[26:27]
	global_load_dwordx2 v[146:147], v[146:147], off
	v_mov_b32_e32 v162, v92
	v_mov_b32_e32 v166, v93
	v_mov_b32_e32 v169, v93
	v_mov_b32_e32 v170, v94
	v_mov_b32_e32 v171, v30
	v_mov_b32_e32 v172, v30
	v_mov_b32_e32 v173, v94
	v_mov_b32_e32 v174, v95
	v_mov_b32_e32 v175, v31
	v_mov_b32_e32 v176, v31
	v_mov_b32_e32 v177, v95
	s_waitcnt vmcnt(7)
	v_pk_mul_f32 v[162:163], v[162:163], v[148:149]
	v_pk_mul_f32 v[148:149], v[164:165], v[148:149]
	v_add_f32_e32 v162, v162, v163
	v_sub_f32_e32 v163, v148, v149
	s_waitcnt vmcnt(6)
	v_pk_mul_f32 v[148:149], v[166:167], v[150:151]
	v_pk_mul_f32 v[150:151], v[168:169], v[150:151]
	v_add_f32_e32 v164, v148, v149
	s_waitcnt vmcnt(5)
	v_pk_mul_f32 v[148:149], v[170:171], v[152:153]
	v_sub_f32_e32 v165, v150, v151
	v_pk_mul_f32 v[150:151], v[172:173], v[152:153]
	v_add_f32_e32 v152, v148, v149
	s_waitcnt vmcnt(4)
	v_pk_mul_f32 v[148:149], v[174:175], v[154:155]
	v_sub_f32_e32 v153, v150, v151
	v_pk_mul_f32 v[150:151], v[176:177], v[154:155]
	v_add_f32_e32 v154, v148, v149
	v_mov_b32_e32 v148, v88
	v_mov_b32_e32 v149, v24
	s_waitcnt vmcnt(3)
	v_pk_mul_f32 v[148:149], v[148:149], v[156:157]
	v_sub_f32_e32 v150, v150, v151
	v_add_f32_e32 v151, v148, v149
	v_mov_b32_e32 v148, v24
	v_mov_b32_e32 v149, v88
	v_pk_mul_f32 v[148:149], v[148:149], v[156:157]
	v_mov_b32_e32 v166, v117
	v_sub_f32_e32 v155, v148, v149
	v_mov_b32_e32 v148, v89
	v_mov_b32_e32 v149, v25
	s_waitcnt vmcnt(2)
	v_pk_mul_f32 v[148:149], v[148:149], v[158:159]
	v_mov_b32_e32 v167, v53
	v_add_f32_e32 v156, v148, v149
	v_mov_b32_e32 v148, v25
	v_mov_b32_e32 v149, v89
	v_pk_mul_f32 v[148:149], v[148:149], v[158:159]
	s_nop 0
	v_sub_f32_e32 v157, v148, v149
	v_mov_b32_e32 v148, v90
	v_mov_b32_e32 v149, v26
	s_waitcnt vmcnt(1)
	v_pk_mul_f32 v[148:149], v[148:149], v[160:161]
	s_nop 0
	v_add_f32_e32 v158, v148, v149
	v_mov_b32_e32 v148, v26
	v_mov_b32_e32 v149, v90
	v_pk_mul_f32 v[148:149], v[148:149], v[160:161]
	s_nop 0
	v_sub_f32_e32 v159, v148, v149
	v_mov_b32_e32 v148, v91
	v_mov_b32_e32 v149, v27
	s_waitcnt vmcnt(0)
; __device__ __forceinline__ unsigned cvt_pk_bf16(float lo, float hi) { unsigned r; asm volatile("v_cvt_pk_bf16_f32 %0, %1, %2" : "=v"(r) : "v"(lo), "v"(hi)); return r; }
;     __device__ __forceinline__ void operator()(const f32x4 (&acc)[2][2][4][2], const Unit& u, int wr, int wc, int fr, int fq) const {
;     ...
;         for (int m = 0; m < 4; ++m) { const int k1 = 16 * m + fr;
; #pragma unroll
;             for (int bj = 0; bj < 2; ++bj) { const int col = 4 * u.pn + 2 * bj + (wc >> 1), b = col >> 8, ch = col & 255;
;                 const int n2 = 32 * (wc & 1) + 8 * fq;
;                 const unsigned rowo = (unsigned)((((size_t)(b * 64 + k1) * 256 + ch) * 128 + n2) * 2);
;                 int kk = k1; asm volatile("" : "+v"(kk));
;                 f32x4 pr[2], pi[2];
; #pragma unroll
;                 for (int n = 0; n < 2; ++n) { const f32x4 yr = acc[0][bj][m][n], yi = acc[1][bj][m][n];
; #pragma unroll
;                     for (int i = 0; i < 4; ++i) { const f32x2 cs = TW[(n2 + 4 * n + i) * kk]; pr[n][i] = yr[i] * cs.x + yi[i] * cs.y; pi[n][i] = yi[i] * cs.x - yr[i] * cs.y; } }
;                 u32x4 w; w.x = cvt_pk_bf16(pr[0][0], pr[0][1]); w.y = cvt_pk_bf16(pr[0][2], pr[0][3]); w.z = cvt_pk_bf16(pr[1][0], pr[1][1]); w.w = cvt_pk_bf16(pr[1][2], pr[1][3]);
;                 __builtin_amdgcn_raw_buffer_store_b128(w, rsrc, rowo, 0, 16);
;                 w.x = cvt_pk_bf16(pi[0][0], pi[0][1]); w.y = cvt_pk_bf16(pi[0][2], pi[0][3]); w.z = cvt_pk_bf16(pi[1][0], pi[1][1]); w.w = cvt_pk_bf16(pi[1][2], pi[1][3]);
;                 __builtin_amdgcn_raw_buffer_store_b128(w, rsrc, rowo + 128, 0, 16);
;                 asm volatile("" ::: "memory"); } }
	v_pk_mul_f32 v[148:149], v[148:149], v[146:147]
	s_nop 0
	v_add_f32_e32 v160, v148, v149
	v_mov_b32_e32 v148, v27
	v_mov_b32_e32 v149, v91
	v_pk_mul_f32 v[146:147], v[148:149], v[146:147]
	s_nop 0
	v_sub_f32_e32 v161, v146, v147
	v_cvt_pk_bf16_f32 v146, v162, v164
	v_cvt_pk_bf16_f32 v147, v152, v154
	v_cvt_pk_bf16_f32 v148, v151, v156
	v_cvt_pk_bf16_f32 v149, v158, v160
	buffer_store_dwordx4 v[146:149], v145, s[8:11], 0 offen sc1
	v_mov_b32_e32 v162, v116
	v_mov_b32_e32 v164, v52
	v_cvt_pk_bf16_f32 v146, v163, v165
	v_cvt_pk_bf16_f32 v147, v153, v150
	v_cvt_pk_bf16_f32 v148, v155, v157
	v_cvt_pk_bf16_f32 v149, v159, v161
	buffer_store_dwordx4 v[146:149], v145, s[8:11], 0 offen offset:128 sc1
	v_mov_b32_e32 v145, v141
	v_mov_b32_e32 v163, v52
	v_mul_lo_u32 v146, v145, v140
	v_ashrrev_i32_e32 v147, 31, v146
	v_lshl_add_u64 v[148:149], v[146:147], 3, s[26:27]
	v_add_u32_e32 v146, v146, v145
	v_ashrrev_i32_e32 v147, 31, v146
	global_load_dwordx2 v[148:149], v[148:149], off
	v_lshl_add_u64 v[150:151], v[146:147], 3, s[26:27]
	global_load_dwordx2 v[150:151], v[150:151], off
	v_add_u32_e32 v146, v146, v145
	v_ashrrev_i32_e32 v147, 31, v146
	v_lshl_add_u64 v[152:153], v[146:147], 3, s[26:27]
	global_load_dwordx2 v[152:153], v[152:153], off
	v_add_u32_e32 v146, v146, v145
	v_ashrrev_i32_e32 v147, 31, v146
	v_lshl_add_u64 v[154:155], v[146:147], 3, s[26:27]
	global_load_dwordx2 v[154:155], v[154:155], off
	v_add_u32_e32 v146, v146, v145
	v_ashrrev_i32_e32 v147, 31, v146
	v_lshl_add_u64 v[156:157], v[146:147], 3, s[26:27]
	global_load_dwordx2 v[156:157], v[156:157], off
	v_add_u32_e32 v146, v146, v145
	v_ashrrev_i32_e32 v147, 31, v146
	v_lshl_add_u64 v[158:159], v[146:147], 3, s[26:27]
	global_load_dwordx2 v[158:159], v[158:159], off
	v_add_u32_e32 v146, v146, v145
	v_ashrrev_i32_e32 v147, 31, v146
	v_lshl_add_u64 v[160:161], v[146:147], 3, s[26:27]
	global_load_dwordx2 v[160:161], v[160:161], off
	v_add_u32_e32 v146, v146, v145
	v_ashrrev_i32_e32 v147, 31, v146
	v_lshl_add_u64 v[146:147], v[146:147], 3, s[26:27]
	global_load_dwordx2 v[146:147], v[146:147], off
	v_mov_b32_e32 v165, v116
	v_or_b32_e32 v145, s2, v141
	v_lshl_or_b32 v145, v145, 15, v140
	v_or_b32_e32 v168, s35, v145
	v_or_b32_e32 v145, s3, v145
	v_lshlrev_b32_e32 v145, 1, v145
	s_waitcnt vmcnt(7)
	v_pk_mul_f32 v[162:163], v[162:163], v[148:149]
	v_pk_mul_f32 v[148:149], v[164:165], v[148:149]
	v_add_f32_e32 v162, v162, v163
	v_sub_f32_e32 v163, v148, v149
	s_waitcnt vmcnt(6)
	v_pk_mul_f32 v[148:149], v[166:167], v[150:151]
	v_lshlrev_b32_e32 v166, 1, v168
	v_add_f32_e32 v164, v148, v149
	v_mov_b32_e32 v148, v53
	v_mov_b32_e32 v149, v117
	v_pk_mul_f32 v[148:149], v[148:149], v[150:151]
	s_nop 0
	v_sub_f32_e32 v150, v148, v149
	v_mov_b32_e32 v148, v118
	v_mov_b32_e32 v149, v54
	s_waitcnt vmcnt(5)
	v_pk_mul_f32 v[148:149], v[148:149], v[152:153]
	s_nop 0
	v_add_f32_e32 v151, v148, v149
	v_mov_b32_e32 v148, v54
	v_mov_b32_e32 v149, v118
	v_pk_mul_f32 v[148:149], v[148:149], v[152:153]
	s_nop 0
	v_sub_f32_e32 v152, v148, v149
	v_mov_b32_e32 v148, v119
	v_mov_b32_e32 v149, v55
	s_waitcnt vmcnt(4)
	v_pk_mul_f32 v[148:149], v[148:149], v[154:155]
	s_nop 0
	v_add_f32_e32 v153, v148, v149
	v_mov_b32_e32 v148, v55
	v_mov_b32_e32 v149, v119
	v_pk_mul_f32 v[148:149], v[148:149], v[154:155]
	s_nop 0
	v_sub_f32_e32 v154, v148, v149
	v_mov_b32_e32 v148, v112
	v_mov_b32_e32 v149, v48
	s_waitcnt vmcnt(3)
	v_pk_mul_f32 v[148:149], v[148:149], v[156:157]
	s_nop 0
	v_add_f32_e32 v155, v148, v149
	v_mov_b32_e32 v148, v48
	v_mov_b32_e32 v149, v112
	v_pk_mul_f32 v[148:149], v[148:149], v[156:157]
	s_nop 0
	v_sub_f32_e32 v156, v148, v149
	v_mov_b32_e32 v148, v113
	v_mov_b32_e32 v149, v49
	s_waitcnt vmcnt(2)
	v_pk_mul_f32 v[148:149], v[148:149], v[158:159]
	s_nop 0
	v_add_f32_e32 v157, v148, v149
	v_mov_b32_e32 v148, v49
	v_mov_b32_e32 v149, v113
	v_pk_mul_f32 v[148:149], v[148:149], v[158:159]
	s_nop 0
	v_sub_f32_e32 v158, v148, v149
	v_mov_b32_e32 v148, v114
	v_mov_b32_e32 v149, v50
	s_waitcnt vmcnt(1)
	v_pk_mul_f32 v[148:149], v[148:149], v[160:161]
	s_nop 0
	v_add_f32_e32 v159, v148, v149
	v_mov_b32_e32 v148, v50
	v_mov_b32_e32 v149, v114
	v_pk_mul_f32 v[148:149], v[148:149], v[160:161]
	s_nop 0
	v_sub_f32_e32 v160, v148, v149
	v_mov_b32_e32 v148, v115
	v_mov_b32_e32 v149, v51
	s_waitcnt vmcnt(0)
	v_pk_mul_f32 v[148:149], v[148:149], v[146:147]
	s_nop 0
	v_add_f32_e32 v161, v148, v149
	v_mov_b32_e32 v148, v51
	v_mov_b32_e32 v149, v115
	v_pk_mul_f32 v[146:147], v[148:149], v[146:147]
	s_nop 0
	v_sub_f32_e32 v165, v146, v147
	v_cvt_pk_bf16_f32 v146, v162, v164
	v_cvt_pk_bf16_f32 v147, v151, v153
	v_cvt_pk_bf16_f32 v148, v155, v157
	v_cvt_pk_bf16_f32 v149, v159, v161
	buffer_store_dwordx4 v[146:149], v166, s[8:11], 0 offen sc1
	v_mov_b32_e32 v162, v141
	s_nop 0
	v_cvt_pk_bf16_f32 v146, v163, v150
	v_cvt_pk_bf16_f32 v147, v152, v154
	v_cvt_pk_bf16_f32 v148, v156, v158
	v_cvt_pk_bf16_f32 v149, v160, v165
	buffer_store_dwordx4 v[146:149], v166, s[8:11], 0 offen offset:128 sc1
	v_mov_b32_e32 v163, v20
	s_nop 0
	v_mul_lo_u32 v146, v162, v140
	v_ashrrev_i32_e32 v147, 31, v146
	v_lshl_add_u64 v[148:149], v[146:147], 3, s[26:27]
	global_load_dwordx2 v[148:149], v[148:149], off
	v_add_u32_e32 v146, v146, v162
	v_ashrrev_i32_e32 v147, 31, v146
	v_lshl_add_u64 v[150:151], v[146:147], 3, s[26:27]
	global_load_dwordx2 v[150:151], v[150:151], off
	v_add_u32_e32 v146, v146, v162
	v_ashrrev_i32_e32 v147, 31, v146
	v_lshl_add_u64 v[152:153], v[146:147], 3, s[26:27]
	global_load_dwordx2 v[152:153], v[152:153], off
	v_add_u32_e32 v146, v146, v162
	v_ashrrev_i32_e32 v147, 31, v146
	v_lshl_add_u64 v[154:155], v[146:147], 3, s[26:27]
	global_load_dwordx2 v[154:155], v[154:155], off
	v_add_u32_e32 v146, v146, v162
	v_ashrrev_i32_e32 v147, 31, v146
	v_lshl_add_u64 v[156:157], v[146:147], 3, s[26:27]
	global_load_dwordx2 v[156:157], v[156:157], off
	v_add_u32_e32 v146, v146, v162
	v_ashrrev_i32_e32 v147, 31, v146
	v_lshl_add_u64 v[158:159], v[146:147], 3, s[26:27]
	global_load_dwordx2 v[158:159], v[158:159], off
	v_add_u32_e32 v146, v146, v162
	v_ashrrev_i32_e32 v147, 31, v146
	v_lshl_add_u64 v[160:161], v[146:147], 3, s[26:27]
	global_load_dwordx2 v[160:161], v[160:161], off
	v_add_u32_e32 v146, v146, v162
	v_ashrrev_i32_e32 v147, 31, v146
	v_lshl_add_u64 v[146:147], v[146:147], 3, s[26:27]
	global_load_dwordx2 v[146:147], v[146:147], off
	v_mov_b32_e32 v162, v84
	s_waitcnt vmcnt(7)
; __device__ __forceinline__ unsigned cvt_pk_bf16(float lo, float hi) { unsigned r; asm volatile("v_cvt_pk_bf16_f32 %0, %1, %2" : "=v"(r) : "v"(lo), "v"(hi)); return r; }
;     __device__ __forceinline__ void operator()(const f32x4 (&acc)[2][2][4][2], const Unit& u, int wr, int wc, int fr, int fq) const {
;     ...
;         for (int m = 0; m < 4; ++m) { const int k1 = 16 * m + fr;
; #pragma unroll
;             for (int bj = 0; bj < 2; ++bj) { const int col = 4 * u.pn + 2 * bj + (wc >> 1), b = col >> 8, ch = col & 255;
;                 const int n2 = 32 * (wc & 1) + 8 * fq;
;                 const unsigned rowo = (unsigned)((((size_t)(b * 64 + k1) * 256 + ch) * 128 + n2) * 2);
;                 int kk = k1; asm volatile("" : "+v"(kk));
;                 f32x4 pr[2], pi[2];
; #pragma unroll
;                 for (int n = 0; n < 2; ++n) { const f32x4 yr = acc[0][bj][m][n], yi = acc[1][bj][m][n];
; #pragma unroll
;                     for (int i = 0; i < 4; ++i) { const f32x2 cs = TW[(n2 + 4 * n + i) * kk]; pr[n][i] = yr[i] * cs.x + yi[i] * cs.y; pi[n][i] = yi[i] * cs.x - yr[i] * cs.y; } }
;                 u32x4 w; w.x = cvt_pk_bf16(pr[0][0], pr[0][1]); w.y = cvt_pk_bf16(pr[0][2], pr[0][3]); w.z = cvt_pk_bf16(pr[1][0], pr[1][1]); w.w = cvt_pk_bf16(pr[1][2], pr[1][3]);
;                 __builtin_amdgcn_raw_buffer_store_b128(w, rsrc, rowo, 0, 16);
;                 w.x = cvt_pk_bf16(pi[0][0], pi[0][1]); w.y = cvt_pk_bf16(pi[0][2], pi[0][3]); w.z = cvt_pk_bf16(pi[1][0], pi[1][1]); w.w = cvt_pk_bf16(pi[1][2], pi[1][3]);
;                 __builtin_amdgcn_raw_buffer_store_b128(w, rsrc, rowo + 128, 0, 16);
;                 asm volatile("" ::: "memory"); } }
	v_pk_mul_f32 v[162:163], v[162:163], v[148:149]
	s_nop 0
	v_add_f32_e32 v164, v162, v163
	v_mov_b32_e32 v162, v20
	v_mov_b32_e32 v163, v84
	v_pk_mul_f32 v[148:149], v[162:163], v[148:149]
	s_nop 0
	v_sub_f32_e32 v162, v148, v149
	v_mov_b32_e32 v148, v85
	v_mov_b32_e32 v149, v21
	s_waitcnt vmcnt(6)
	v_pk_mul_f32 v[148:149], v[148:149], v[150:151]
	s_nop 0
	v_add_f32_e32 v163, v148, v149
	v_mov_b32_e32 v148, v21
	v_mov_b32_e32 v149, v85
	v_pk_mul_f32 v[148:149], v[148:149], v[150:151]
	s_nop 0
	v_sub_f32_e32 v150, v148, v149
	v_mov_b32_e32 v148, v86
	v_mov_b32_e32 v149, v22
	s_waitcnt vmcnt(5)
	v_pk_mul_f32 v[148:149], v[148:149], v[152:153]
	s_nop 0
	v_add_f32_e32 v151, v148, v149
	v_mov_b32_e32 v148, v22
	v_mov_b32_e32 v149, v86
	v_pk_mul_f32 v[148:149], v[148:149], v[152:153]
	s_nop 0
	v_sub_f32_e32 v152, v148, v149
	v_mov_b32_e32 v148, v87
	v_mov_b32_e32 v149, v23
	s_waitcnt vmcnt(4)
	v_pk_mul_f32 v[148:149], v[148:149], v[154:155]
	s_nop 0
	v_add_f32_e32 v153, v148, v149
	v_mov_b32_e32 v148, v23
	v_mov_b32_e32 v149, v87
	v_pk_mul_f32 v[148:149], v[148:149], v[154:155]
	s_nop 0
	v_sub_f32_e32 v154, v148, v149
	v_mov_b32_e32 v148, v80
	v_mov_b32_e32 v149, v16
	s_waitcnt vmcnt(3)
	v_pk_mul_f32 v[148:149], v[148:149], v[156:157]
	s_nop 0
	v_add_f32_e32 v155, v148, v149
	v_mov_b32_e32 v148, v16
	v_mov_b32_e32 v149, v80
	v_pk_mul_f32 v[148:149], v[148:149], v[156:157]
	s_nop 0
	v_sub_f32_e32 v156, v148, v149
	v_mov_b32_e32 v148, v81
	v_mov_b32_e32 v149, v17
	s_waitcnt vmcnt(2)
	v_pk_mul_f32 v[148:149], v[148:149], v[158:159]
	s_nop 0
	v_add_f32_e32 v157, v148, v149
	v_mov_b32_e32 v148, v17
	v_mov_b32_e32 v149, v81
	v_pk_mul_f32 v[148:149], v[148:149], v[158:159]
	s_nop 0
	v_sub_f32_e32 v158, v148, v149
	v_mov_b32_e32 v148, v82
	v_mov_b32_e32 v149, v18
	s_waitcnt vmcnt(1)
	v_pk_mul_f32 v[148:149], v[148:149], v[160:161]
	s_nop 0
	v_add_f32_e32 v159, v148, v149
	v_mov_b32_e32 v148, v18
	v_mov_b32_e32 v149, v82
	v_pk_mul_f32 v[148:149], v[148:149], v[160:161]
	s_nop 0
	v_sub_f32_e32 v160, v148, v149
	v_mov_b32_e32 v148, v83
	v_mov_b32_e32 v149, v19
	s_waitcnt vmcnt(0)
	v_pk_mul_f32 v[148:149], v[148:149], v[146:147]
	s_nop 0
	v_add_f32_e32 v161, v148, v149
	v_mov_b32_e32 v148, v19
	v_mov_b32_e32 v149, v83
	v_pk_mul_f32 v[146:147], v[148:149], v[146:147]
	s_nop 0
	v_sub_f32_e32 v165, v146, v147
	v_cvt_pk_bf16_f32 v146, v164, v163
	v_cvt_pk_bf16_f32 v147, v151, v153
	v_cvt_pk_bf16_f32 v148, v155, v157
	v_cvt_pk_bf16_f32 v149, v159, v161
	buffer_store_dwordx4 v[146:149], v145, s[8:11], 0 offen sc1
	v_mov_b32_e32 v163, v44
	s_nop 0
	v_cvt_pk_bf16_f32 v146, v162, v150
	v_cvt_pk_bf16_f32 v147, v152, v154
	v_cvt_pk_bf16_f32 v148, v156, v158
	v_cvt_pk_bf16_f32 v149, v160, v165
	buffer_store_dwordx4 v[146:149], v145, s[8:11], 0 offen offset:128 sc1
	v_mov_b32_e32 v145, v142
	v_mov_b32_e32 v162, v108
	v_mul_lo_u32 v146, v145, v140
	v_ashrrev_i32_e32 v147, 31, v146
	v_lshl_add_u64 v[148:149], v[146:147], 3, s[26:27]
	global_load_dwordx2 v[148:149], v[148:149], off
	v_add_u32_e32 v146, v146, v145
	v_ashrrev_i32_e32 v147, 31, v146
	v_lshl_add_u64 v[150:151], v[146:147], 3, s[26:27]
	global_load_dwordx2 v[150:151], v[150:151], off
	v_add_u32_e32 v146, v146, v145
	v_ashrrev_i32_e32 v147, 31, v146
	v_lshl_add_u64 v[152:153], v[146:147], 3, s[26:27]
	global_load_dwordx2 v[152:153], v[152:153], off
	v_add_u32_e32 v146, v146, v145
	v_ashrrev_i32_e32 v147, 31, v146
	v_lshl_add_u64 v[154:155], v[146:147], 3, s[26:27]
	global_load_dwordx2 v[154:155], v[154:155], off
	v_add_u32_e32 v146, v146, v145
	v_ashrrev_i32_e32 v147, 31, v146
	v_lshl_add_u64 v[156:157], v[146:147], 3, s[26:27]
	global_load_dwordx2 v[156:157], v[156:157], off
	v_add_u32_e32 v146, v146, v145
	v_ashrrev_i32_e32 v147, 31, v146
	v_lshl_add_u64 v[158:159], v[146:147], 3, s[26:27]
	global_load_dwordx2 v[158:159], v[158:159], off
	v_add_u32_e32 v146, v146, v145
	v_ashrrev_i32_e32 v147, 31, v146
	v_lshl_add_u64 v[160:161], v[146:147], 3, s[26:27]
	global_load_dwordx2 v[160:161], v[160:161], off
	v_add_u32_e32 v146, v146, v145
	v_ashrrev_i32_e32 v147, 31, v146
	v_lshl_add_u64 v[146:147], v[146:147], 3, s[26:27]
	global_load_dwordx2 v[146:147], v[146:147], off
	v_or_b32_e32 v145, s2, v142
	v_lshl_or_b32 v145, v145, 15, v140
	v_or_b32_e32 v164, s35, v145
	v_lshlrev_b32_e32 v164, 1, v164
	v_or_b32_e32 v145, s3, v145
	v_lshlrev_b32_e32 v145, 1, v145
	s_waitcnt vmcnt(7)
	v_pk_mul_f32 v[162:163], v[162:163], v[148:149]
	s_nop 0
	v_add_f32_e32 v165, v162, v163
	v_mov_b32_e32 v162, v44
	v_mov_b32_e32 v163, v108
	v_pk_mul_f32 v[148:149], v[162:163], v[148:149]
	s_nop 0
	v_sub_f32_e32 v162, v148, v149
	v_mov_b32_e32 v148, v109
	v_mov_b32_e32 v149, v45
	s_waitcnt vmcnt(6)
	v_pk_mul_f32 v[148:149], v[148:149], v[150:151]
	s_nop 0
	v_add_f32_e32 v163, v148, v149
	v_mov_b32_e32 v148, v45
	v_mov_b32_e32 v149, v109
	v_pk_mul_f32 v[148:149], v[148:149], v[150:151]
	s_nop 0
	v_sub_f32_e32 v150, v148, v149
	v_mov_b32_e32 v148, v110
	v_mov_b32_e32 v149, v46
	s_waitcnt vmcnt(5)
	v_pk_mul_f32 v[148:149], v[148:149], v[152:153]
	s_nop 0
	v_add_f32_e32 v151, v148, v149
	v_mov_b32_e32 v148, v46
	v_mov_b32_e32 v149, v110
	v_pk_mul_f32 v[148:149], v[148:149], v[152:153]
	s_nop 0
	v_sub_f32_e32 v152, v148, v149
	v_mov_b32_e32 v148, v111
	v_mov_b32_e32 v149, v47
	s_waitcnt vmcnt(4)
	v_pk_mul_f32 v[148:149], v[148:149], v[154:155]
	s_nop 0
	v_add_f32_e32 v153, v148, v149
	v_mov_b32_e32 v148, v47
	v_mov_b32_e32 v149, v111
	v_pk_mul_f32 v[148:149], v[148:149], v[154:155]
	s_nop 0
	v_sub_f32_e32 v154, v148, v149
	v_mov_b32_e32 v148, v104
	v_mov_b32_e32 v149, v40
	s_waitcnt vmcnt(3)
; __device__ __forceinline__ unsigned cvt_pk_bf16(float lo, float hi) { unsigned r; asm volatile("v_cvt_pk_bf16_f32 %0, %1, %2" : "=v"(r) : "v"(lo), "v"(hi)); return r; }
;     __device__ __forceinline__ void operator()(const f32x4 (&acc)[2][2][4][2], const Unit& u, int wr, int wc, int fr, int fq) const {
;     ...
;         for (int m = 0; m < 4; ++m) { const int k1 = 16 * m + fr;
; #pragma unroll
;             for (int bj = 0; bj < 2; ++bj) { const int col = 4 * u.pn + 2 * bj + (wc >> 1), b = col >> 8, ch = col & 255;
;                 const int n2 = 32 * (wc & 1) + 8 * fq;
;                 const unsigned rowo = (unsigned)((((size_t)(b * 64 + k1) * 256 + ch) * 128 + n2) * 2);
;                 int kk = k1; asm volatile("" : "+v"(kk));
;                 f32x4 pr[2], pi[2];
; #pragma unroll
;                 for (int n = 0; n < 2; ++n) { const f32x4 yr = acc[0][bj][m][n], yi = acc[1][bj][m][n];
; #pragma unroll
;                     for (int i = 0; i < 4; ++i) { const f32x2 cs = TW[(n2 + 4 * n + i) * kk]; pr[n][i] = yr[i] * cs.x + yi[i] * cs.y; pi[n][i] = yi[i] * cs.x - yr[i] * cs.y; } }
;                 u32x4 w; w.x = cvt_pk_bf16(pr[0][0], pr[0][1]); w.y = cvt_pk_bf16(pr[0][2], pr[0][3]); w.z = cvt_pk_bf16(pr[1][0], pr[1][1]); w.w = cvt_pk_bf16(pr[1][2], pr[1][3]);
;                 __builtin_amdgcn_raw_buffer_store_b128(w, rsrc, rowo, 0, 16);
;                 w.x = cvt_pk_bf16(pi[0][0], pi[0][1]); w.y = cvt_pk_bf16(pi[0][2], pi[0][3]); w.z = cvt_pk_bf16(pi[1][0], pi[1][1]); w.w = cvt_pk_bf16(pi[1][2], pi[1][3]);
;                 __builtin_amdgcn_raw_buffer_store_b128(w, rsrc, rowo + 128, 0, 16);
;                 asm volatile("" ::: "memory"); } }
	v_pk_mul_f32 v[148:149], v[148:149], v[156:157]
	s_nop 0
	v_add_f32_e32 v155, v148, v149
	v_mov_b32_e32 v148, v40
	v_mov_b32_e32 v149, v104
	v_pk_mul_f32 v[148:149], v[148:149], v[156:157]
	s_nop 0
	v_sub_f32_e32 v156, v148, v149
	v_mov_b32_e32 v148, v105
	v_mov_b32_e32 v149, v41
	s_waitcnt vmcnt(2)
	v_pk_mul_f32 v[148:149], v[148:149], v[158:159]
	s_nop 0
	v_add_f32_e32 v157, v148, v149
	v_mov_b32_e32 v148, v41
	v_mov_b32_e32 v149, v105
	v_pk_mul_f32 v[148:149], v[148:149], v[158:159]
	s_nop 0
	v_sub_f32_e32 v158, v148, v149
	v_mov_b32_e32 v148, v106
	v_mov_b32_e32 v149, v42
	s_waitcnt vmcnt(1)
	v_pk_mul_f32 v[148:149], v[148:149], v[160:161]
	s_nop 0
	v_add_f32_e32 v159, v148, v149
	v_mov_b32_e32 v148, v42
	v_mov_b32_e32 v149, v106
	v_pk_mul_f32 v[148:149], v[148:149], v[160:161]
	s_nop 0
	v_sub_f32_e32 v160, v148, v149
	v_mov_b32_e32 v148, v107
	v_mov_b32_e32 v149, v43
	s_waitcnt vmcnt(0)
	v_pk_mul_f32 v[148:149], v[148:149], v[146:147]
	s_nop 0
	v_add_f32_e32 v161, v148, v149
	v_mov_b32_e32 v148, v43
	v_mov_b32_e32 v149, v107
	v_pk_mul_f32 v[146:147], v[148:149], v[146:147]
	s_nop 0
	v_sub_f32_e32 v166, v146, v147
	v_cvt_pk_bf16_f32 v146, v165, v163
	v_cvt_pk_bf16_f32 v147, v151, v153
	v_cvt_pk_bf16_f32 v148, v155, v157
	v_cvt_pk_bf16_f32 v149, v159, v161
	buffer_store_dwordx4 v[146:149], v164, s[8:11], 0 offen sc1
	v_mov_b32_e32 v163, v12
	s_nop 0
	v_cvt_pk_bf16_f32 v146, v162, v150
	v_cvt_pk_bf16_f32 v147, v152, v154
	v_cvt_pk_bf16_f32 v148, v156, v158
	v_cvt_pk_bf16_f32 v149, v160, v166
	buffer_store_dwordx4 v[146:149], v164, s[8:11], 0 offen offset:128 sc1
	v_mov_b32_e32 v162, v142
	s_nop 0
	v_mul_lo_u32 v146, v162, v140
	v_ashrrev_i32_e32 v147, 31, v146
	v_lshl_add_u64 v[148:149], v[146:147], 3, s[26:27]
	global_load_dwordx2 v[148:149], v[148:149], off
	v_add_u32_e32 v146, v146, v162
	v_ashrrev_i32_e32 v147, 31, v146
	v_lshl_add_u64 v[150:151], v[146:147], 3, s[26:27]
	global_load_dwordx2 v[150:151], v[150:151], off
	v_add_u32_e32 v146, v146, v162
	v_ashrrev_i32_e32 v147, 31, v146
	v_lshl_add_u64 v[152:153], v[146:147], 3, s[26:27]
	global_load_dwordx2 v[152:153], v[152:153], off
	v_add_u32_e32 v146, v146, v162
	v_ashrrev_i32_e32 v147, 31, v146
	v_lshl_add_u64 v[154:155], v[146:147], 3, s[26:27]
	global_load_dwordx2 v[154:155], v[154:155], off
	v_add_u32_e32 v146, v146, v162
	v_ashrrev_i32_e32 v147, 31, v146
	v_lshl_add_u64 v[156:157], v[146:147], 3, s[26:27]
	global_load_dwordx2 v[156:157], v[156:157], off
	v_add_u32_e32 v146, v146, v162
	v_ashrrev_i32_e32 v147, 31, v146
	v_lshl_add_u64 v[158:159], v[146:147], 3, s[26:27]
	global_load_dwordx2 v[158:159], v[158:159], off
	v_add_u32_e32 v146, v146, v162
	v_ashrrev_i32_e32 v147, 31, v146
	v_lshl_add_u64 v[160:161], v[146:147], 3, s[26:27]
	global_load_dwordx2 v[160:161], v[160:161], off
	v_add_u32_e32 v146, v146, v162
	v_ashrrev_i32_e32 v147, 31, v146
	v_lshl_add_u64 v[146:147], v[146:147], 3, s[26:27]
	global_load_dwordx2 v[146:147], v[146:147], off
	v_mov_b32_e32 v162, v76
	s_waitcnt vmcnt(7)
	v_pk_mul_f32 v[162:163], v[162:163], v[148:149]
	s_nop 0
	v_add_f32_e32 v164, v162, v163
	v_mov_b32_e32 v162, v12
	v_mov_b32_e32 v163, v76
	v_pk_mul_f32 v[148:149], v[162:163], v[148:149]
	s_nop 0
	v_sub_f32_e32 v162, v148, v149
	v_mov_b32_e32 v148, v77
	v_mov_b32_e32 v149, v13
	s_waitcnt vmcnt(6)
	v_pk_mul_f32 v[148:149], v[148:149], v[150:151]
	s_nop 0
	v_add_f32_e32 v163, v148, v149
	v_mov_b32_e32 v148, v13
	v_mov_b32_e32 v149, v77
	v_pk_mul_f32 v[148:149], v[148:149], v[150:151]
	s_nop 0
	v_sub_f32_e32 v150, v148, v149
	v_mov_b32_e32 v148, v78
	v_mov_b32_e32 v149, v14
	s_waitcnt vmcnt(5)
	v_pk_mul_f32 v[148:149], v[148:149], v[152:153]
	s_nop 0
	v_add_f32_e32 v151, v148, v149
	v_mov_b32_e32 v148, v14
	v_mov_b32_e32 v149, v78
	v_pk_mul_f32 v[148:149], v[148:149], v[152:153]
	s_nop 0
	v_sub_f32_e32 v152, v148, v149
	v_mov_b32_e32 v148, v79
	v_mov_b32_e32 v149, v15
	s_waitcnt vmcnt(4)
	v_pk_mul_f32 v[148:149], v[148:149], v[154:155]
	s_nop 0
	v_add_f32_e32 v153, v148, v149
	v_mov_b32_e32 v148, v15
	v_mov_b32_e32 v149, v79
	v_pk_mul_f32 v[148:149], v[148:149], v[154:155]
	s_nop 0
	v_sub_f32_e32 v154, v148, v149
	v_mov_b32_e32 v148, v72
	v_mov_b32_e32 v149, v8
	s_waitcnt vmcnt(3)
	v_pk_mul_f32 v[148:149], v[148:149], v[156:157]
	s_nop 0
	v_add_f32_e32 v155, v148, v149
	v_mov_b32_e32 v148, v8
	v_mov_b32_e32 v149, v72
	v_pk_mul_f32 v[148:149], v[148:149], v[156:157]
	s_nop 0
	v_sub_f32_e32 v156, v148, v149
	v_mov_b32_e32 v148, v73
	v_mov_b32_e32 v149, v9
	s_waitcnt vmcnt(2)
	v_pk_mul_f32 v[148:149], v[148:149], v[158:159]
	s_nop 0
	v_add_f32_e32 v157, v148, v149
	v_mov_b32_e32 v148, v9
	v_mov_b32_e32 v149, v73
	v_pk_mul_f32 v[148:149], v[148:149], v[158:159]
	s_nop 0
	v_sub_f32_e32 v158, v148, v149
	v_mov_b32_e32 v148, v74
	v_mov_b32_e32 v149, v10
	s_waitcnt vmcnt(1)
	v_pk_mul_f32 v[148:149], v[148:149], v[160:161]
	s_nop 0
	v_add_f32_e32 v159, v148, v149
	v_mov_b32_e32 v148, v10
	v_mov_b32_e32 v149, v74
	v_pk_mul_f32 v[148:149], v[148:149], v[160:161]
	s_nop 0
	v_sub_f32_e32 v160, v148, v149
	v_mov_b32_e32 v148, v75
	v_mov_b32_e32 v149, v11
	s_waitcnt vmcnt(0)
; __device__ __forceinline__ unsigned cvt_pk_bf16(float lo, float hi) { unsigned r; asm volatile("v_cvt_pk_bf16_f32 %0, %1, %2" : "=v"(r) : "v"(lo), "v"(hi)); return r; }
;     __device__ __forceinline__ void operator()(const f32x4 (&acc)[2][2][4][2], const Unit& u, int wr, int wc, int fr, int fq) const {
;     ...
;         for (int m = 0; m < 4; ++m) { const int k1 = 16 * m + fr;
; #pragma unroll
;             for (int bj = 0; bj < 2; ++bj) { const int col = 4 * u.pn + 2 * bj + (wc >> 1), b = col >> 8, ch = col & 255;
;                 const int n2 = 32 * (wc & 1) + 8 * fq;
;                 const unsigned rowo = (unsigned)((((size_t)(b * 64 + k1) * 256 + ch) * 128 + n2) * 2);
;                 int kk = k1; asm volatile("" : "+v"(kk));
;                 f32x4 pr[2], pi[2];
; #pragma unroll
;                 for (int n = 0; n < 2; ++n) { const f32x4 yr = acc[0][bj][m][n], yi = acc[1][bj][m][n];
; #pragma unroll
;                     for (int i = 0; i < 4; ++i) { const f32x2 cs = TW[(n2 + 4 * n + i) * kk]; pr[n][i] = yr[i] * cs.x + yi[i] * cs.y; pi[n][i] = yi[i] * cs.x - yr[i] * cs.y; } }
;                 u32x4 w; w.x = cvt_pk_bf16(pr[0][0], pr[0][1]); w.y = cvt_pk_bf16(pr[0][2], pr[0][3]); w.z = cvt_pk_bf16(pr[1][0], pr[1][1]); w.w = cvt_pk_bf16(pr[1][2], pr[1][3]);
;                 __builtin_amdgcn_raw_buffer_store_b128(w, rsrc, rowo, 0, 16);
;                 w.x = cvt_pk_bf16(pi[0][0], pi[0][1]); w.y = cvt_pk_bf16(pi[0][2], pi[0][3]); w.z = cvt_pk_bf16(pi[1][0], pi[1][1]); w.w = cvt_pk_bf16(pi[1][2], pi[1][3]);
;                 __builtin_amdgcn_raw_buffer_store_b128(w, rsrc, rowo + 128, 0, 16);
;                 asm volatile("" ::: "memory"); } }
	v_pk_mul_f32 v[148:149], v[148:149], v[146:147]
	s_nop 0
	v_add_f32_e32 v161, v148, v149
	v_mov_b32_e32 v148, v11
	v_mov_b32_e32 v149, v75
	v_pk_mul_f32 v[146:147], v[148:149], v[146:147]
	s_nop 0
	v_sub_f32_e32 v165, v146, v147
	v_cvt_pk_bf16_f32 v146, v164, v163
	v_cvt_pk_bf16_f32 v147, v151, v153
	v_cvt_pk_bf16_f32 v148, v155, v157
	v_cvt_pk_bf16_f32 v149, v159, v161
	buffer_store_dwordx4 v[146:149], v145, s[8:11], 0 offen sc1
	v_mov_b32_e32 v163, v36
	s_nop 0
	v_cvt_pk_bf16_f32 v146, v162, v150
	v_cvt_pk_bf16_f32 v147, v152, v154
	v_cvt_pk_bf16_f32 v148, v156, v158
	v_cvt_pk_bf16_f32 v149, v160, v165
	buffer_store_dwordx4 v[146:149], v145, s[8:11], 0 offen offset:128 sc1
	v_mov_b32_e32 v145, v143
	v_mov_b32_e32 v162, v100
	v_mul_lo_u32 v146, v145, v140
	v_ashrrev_i32_e32 v147, 31, v146
	v_lshl_add_u64 v[148:149], v[146:147], 3, s[26:27]
	global_load_dwordx2 v[148:149], v[148:149], off
	v_add_u32_e32 v146, v146, v145
	v_ashrrev_i32_e32 v147, 31, v146
	v_lshl_add_u64 v[150:151], v[146:147], 3, s[26:27]
	global_load_dwordx2 v[150:151], v[150:151], off
	v_add_u32_e32 v146, v146, v145
	v_ashrrev_i32_e32 v147, 31, v146
	v_lshl_add_u64 v[152:153], v[146:147], 3, s[26:27]
	global_load_dwordx2 v[152:153], v[152:153], off
	v_add_u32_e32 v146, v146, v145
	v_ashrrev_i32_e32 v147, 31, v146
	v_lshl_add_u64 v[154:155], v[146:147], 3, s[26:27]
	global_load_dwordx2 v[154:155], v[154:155], off
	v_add_u32_e32 v146, v146, v145
	v_ashrrev_i32_e32 v147, 31, v146
	v_lshl_add_u64 v[156:157], v[146:147], 3, s[26:27]
	global_load_dwordx2 v[156:157], v[156:157], off
	v_add_u32_e32 v146, v146, v145
	v_ashrrev_i32_e32 v147, 31, v146
	v_lshl_add_u64 v[158:159], v[146:147], 3, s[26:27]
	global_load_dwordx2 v[158:159], v[158:159], off
	v_add_u32_e32 v146, v146, v145
	v_ashrrev_i32_e32 v147, 31, v146
	v_lshl_add_u64 v[160:161], v[146:147], 3, s[26:27]
	global_load_dwordx2 v[160:161], v[160:161], off
	v_add_u32_e32 v146, v146, v145
	v_ashrrev_i32_e32 v147, 31, v146
	v_lshl_add_u64 v[146:147], v[146:147], 3, s[26:27]
	global_load_dwordx2 v[146:147], v[146:147], off
	v_or_b32_e32 v145, s2, v143
	v_lshl_or_b32 v145, v145, 15, v140
	v_or_b32_e32 v164, s35, v145
	v_lshlrev_b32_e32 v164, 1, v164
	v_or_b32_e32 v145, s3, v145
	v_lshlrev_b32_e32 v145, 1, v145
	s_waitcnt vmcnt(7)
	v_pk_mul_f32 v[162:163], v[162:163], v[148:149]
	s_nop 0
	v_add_f32_e32 v165, v162, v163
	v_mov_b32_e32 v162, v36
	v_mov_b32_e32 v163, v100
	v_pk_mul_f32 v[148:149], v[162:163], v[148:149]
	s_nop 0
	v_sub_f32_e32 v162, v148, v149
	v_mov_b32_e32 v148, v101
	v_mov_b32_e32 v149, v37
	s_waitcnt vmcnt(6)
	v_pk_mul_f32 v[148:149], v[148:149], v[150:151]
	s_nop 0
	v_add_f32_e32 v163, v148, v149
	v_mov_b32_e32 v148, v37
	v_mov_b32_e32 v149, v101
	v_pk_mul_f32 v[148:149], v[148:149], v[150:151]
	s_nop 0
	v_sub_f32_e32 v150, v148, v149
	v_mov_b32_e32 v148, v102
	v_mov_b32_e32 v149, v38
	s_waitcnt vmcnt(5)
	v_pk_mul_f32 v[148:149], v[148:149], v[152:153]
	s_nop 0
	v_add_f32_e32 v151, v148, v149
	v_mov_b32_e32 v148, v38
	v_mov_b32_e32 v149, v102
	v_pk_mul_f32 v[148:149], v[148:149], v[152:153]
	s_nop 0
	v_sub_f32_e32 v152, v148, v149
	v_mov_b32_e32 v148, v103
	v_mov_b32_e32 v149, v39
	s_waitcnt vmcnt(4)
	v_pk_mul_f32 v[148:149], v[148:149], v[154:155]
	s_nop 0
	v_add_f32_e32 v153, v148, v149
	v_mov_b32_e32 v148, v39
	v_mov_b32_e32 v149, v103
	v_pk_mul_f32 v[148:149], v[148:149], v[154:155]
	s_nop 0
	v_sub_f32_e32 v154, v148, v149
	v_mov_b32_e32 v148, v96
	v_mov_b32_e32 v149, v32
	s_waitcnt vmcnt(3)
	v_pk_mul_f32 v[148:149], v[148:149], v[156:157]
	s_nop 0
	v_add_f32_e32 v155, v148, v149
	v_mov_b32_e32 v148, v32
	v_mov_b32_e32 v149, v96
	v_pk_mul_f32 v[148:149], v[148:149], v[156:157]
	s_nop 0
	v_sub_f32_e32 v156, v148, v149
	v_mov_b32_e32 v148, v97
	v_mov_b32_e32 v149, v33
	s_waitcnt vmcnt(2)
	v_pk_mul_f32 v[148:149], v[148:149], v[158:159]
	s_nop 0
	v_add_f32_e32 v157, v148, v149
	v_mov_b32_e32 v148, v33
	v_mov_b32_e32 v149, v97
	v_pk_mul_f32 v[148:149], v[148:149], v[158:159]
	s_nop 0
	v_sub_f32_e32 v158, v148, v149
	v_mov_b32_e32 v148, v98
	v_mov_b32_e32 v149, v34
	s_waitcnt vmcnt(1)
	v_pk_mul_f32 v[148:149], v[148:149], v[160:161]
	s_nop 0
	v_add_f32_e32 v159, v148, v149
	v_mov_b32_e32 v148, v34
	v_mov_b32_e32 v149, v98
	v_pk_mul_f32 v[148:149], v[148:149], v[160:161]
	s_nop 0
	v_sub_f32_e32 v160, v148, v149
	v_mov_b32_e32 v148, v99
	v_mov_b32_e32 v149, v35
	s_waitcnt vmcnt(0)
; __device__ __forceinline__ unsigned cvt_pk_bf16(float lo, float hi) { unsigned r; asm volatile("v_cvt_pk_bf16_f32 %0, %1, %2" : "=v"(r) : "v"(lo), "v"(hi)); return r; }
; template <class Epi, bool BSEL = false>
; __device__ __forceinline__ void gemm_phase(LAS unsigned char* lds, const Gemm g, const Order& S, const Epi& E, const int tid) {
;     ...
;         if (!has_next) break;
;     __device__ __forceinline__ void operator()(const f32x4 (&acc)[2][2][4][2], const Unit& u, int wr, int wc, int fr, int fq) const {
;     ...
;         for (int m = 0; m < 4; ++m) { const int k1 = 16 * m + fr;
; #pragma unroll
;             for (int bj = 0; bj < 2; ++bj) { const int col = 4 * u.pn + 2 * bj + (wc >> 1), b = col >> 8, ch = col & 255;
;                 const int n2 = 32 * (wc & 1) + 8 * fq;
;                 const unsigned rowo = (unsigned)((((size_t)(b * 64 + k1) * 256 + ch) * 128 + n2) * 2);
;                 int kk = k1; asm volatile("" : "+v"(kk));
;                 f32x4 pr[2], pi[2];
; #pragma unroll
;                 for (int n = 0; n < 2; ++n) { const f32x4 yr = acc[0][bj][m][n], yi = acc[1][bj][m][n];
; #pragma unroll
;                     for (int i = 0; i < 4; ++i) { const f32x2 cs = TW[(n2 + 4 * n + i) * kk]; pr[n][i] = yr[i] * cs.x + yi[i] * cs.y; pi[n][i] = yi[i] * cs.x - yr[i] * cs.y; } }
;                 u32x4 w; w.x = cvt_pk_bf16(pr[0][0], pr[0][1]); w.y = cvt_pk_bf16(pr[0][2], pr[0][3]); w.z = cvt_pk_bf16(pr[1][0], pr[1][1]); w.w = cvt_pk_bf16(pr[1][2], pr[1][3]);
;                 __builtin_amdgcn_raw_buffer_store_b128(w, rsrc, rowo, 0, 16);
;                 w.x = cvt_pk_bf16(pi[0][0], pi[0][1]); w.y = cvt_pk_bf16(pi[0][2], pi[0][3]); w.z = cvt_pk_bf16(pi[1][0], pi[1][1]); w.w = cvt_pk_bf16(pi[1][2], pi[1][3]);
;                 __builtin_amdgcn_raw_buffer_store_b128(w, rsrc, rowo + 128, 0, 16);
;                 asm volatile("" ::: "memory"); } }
	v_pk_mul_f32 v[148:149], v[148:149], v[146:147]
	s_nop 0
	v_add_f32_e32 v161, v148, v149
	v_mov_b32_e32 v148, v35
	v_mov_b32_e32 v149, v99
	v_pk_mul_f32 v[146:147], v[148:149], v[146:147]
	s_nop 0
	v_sub_f32_e32 v166, v146, v147
	v_cvt_pk_bf16_f32 v146, v165, v163
	v_cvt_pk_bf16_f32 v147, v151, v153
	v_cvt_pk_bf16_f32 v148, v155, v157
	v_cvt_pk_bf16_f32 v149, v159, v161
	buffer_store_dwordx4 v[146:149], v164, s[8:11], 0 offen sc1
	v_mov_b32_e32 v163, v4
	s_nop 0
	v_cvt_pk_bf16_f32 v146, v162, v150
	v_cvt_pk_bf16_f32 v147, v152, v154
	v_cvt_pk_bf16_f32 v148, v156, v158
	v_cvt_pk_bf16_f32 v149, v160, v166
	buffer_store_dwordx4 v[146:149], v164, s[8:11], 0 offen offset:128 sc1
	v_mov_b32_e32 v162, v143
	s_nop 0
	v_mul_lo_u32 v146, v162, v140
	v_ashrrev_i32_e32 v147, 31, v146
	v_lshl_add_u64 v[148:149], v[146:147], 3, s[26:27]
	global_load_dwordx2 v[148:149], v[148:149], off
	v_add_u32_e32 v146, v146, v162
	v_ashrrev_i32_e32 v147, 31, v146
	v_lshl_add_u64 v[150:151], v[146:147], 3, s[26:27]
	global_load_dwordx2 v[150:151], v[150:151], off
	v_add_u32_e32 v146, v146, v162
	v_ashrrev_i32_e32 v147, 31, v146
	v_lshl_add_u64 v[152:153], v[146:147], 3, s[26:27]
	global_load_dwordx2 v[152:153], v[152:153], off
	v_add_u32_e32 v146, v146, v162
	v_ashrrev_i32_e32 v147, 31, v146
	v_lshl_add_u64 v[154:155], v[146:147], 3, s[26:27]
	global_load_dwordx2 v[154:155], v[154:155], off
	v_add_u32_e32 v146, v146, v162
	v_ashrrev_i32_e32 v147, 31, v146
	v_lshl_add_u64 v[156:157], v[146:147], 3, s[26:27]
	global_load_dwordx2 v[156:157], v[156:157], off
	v_add_u32_e32 v146, v146, v162
	v_ashrrev_i32_e32 v147, 31, v146
	v_lshl_add_u64 v[158:159], v[146:147], 3, s[26:27]
	global_load_dwordx2 v[158:159], v[158:159], off
	v_add_u32_e32 v146, v146, v162
	v_ashrrev_i32_e32 v147, 31, v146
	v_lshl_add_u64 v[160:161], v[146:147], 3, s[26:27]
	global_load_dwordx2 v[160:161], v[160:161], off
	v_add_u32_e32 v146, v146, v162
	v_ashrrev_i32_e32 v147, 31, v146
	v_lshl_add_u64 v[146:147], v[146:147], 3, s[26:27]
	global_load_dwordx2 v[146:147], v[146:147], off
	v_mov_b32_e32 v162, v68
	s_waitcnt vmcnt(7)
	v_pk_mul_f32 v[162:163], v[162:163], v[148:149]
	s_nop 0
	v_add_f32_e32 v164, v162, v163
	v_mov_b32_e32 v162, v4
	v_mov_b32_e32 v163, v68
	v_pk_mul_f32 v[148:149], v[162:163], v[148:149]
	s_nop 0
	v_sub_f32_e32 v162, v148, v149
	v_mov_b32_e32 v148, v69
	v_mov_b32_e32 v149, v5
	s_waitcnt vmcnt(6)
	v_pk_mul_f32 v[148:149], v[148:149], v[150:151]
	s_nop 0
	v_add_f32_e32 v163, v148, v149
	v_mov_b32_e32 v148, v5
	v_mov_b32_e32 v149, v69
	v_pk_mul_f32 v[148:149], v[148:149], v[150:151]
	s_nop 0
	v_sub_f32_e32 v150, v148, v149
	v_mov_b32_e32 v148, v70
	v_mov_b32_e32 v149, v6
	s_waitcnt vmcnt(5)
	v_pk_mul_f32 v[148:149], v[148:149], v[152:153]
	s_nop 0
	v_add_f32_e32 v151, v148, v149
	v_mov_b32_e32 v148, v6
	v_mov_b32_e32 v149, v70
	v_pk_mul_f32 v[148:149], v[148:149], v[152:153]
	s_nop 0
	v_sub_f32_e32 v152, v148, v149
	v_mov_b32_e32 v148, v71
	v_mov_b32_e32 v149, v7
	s_waitcnt vmcnt(4)
	v_pk_mul_f32 v[148:149], v[148:149], v[154:155]
	s_nop 0
	v_add_f32_e32 v153, v148, v149
	v_mov_b32_e32 v148, v7
	v_mov_b32_e32 v149, v71
	v_pk_mul_f32 v[148:149], v[148:149], v[154:155]
	s_nop 0
	v_sub_f32_e32 v154, v148, v149
	v_mov_b32_e32 v148, v64
	v_mov_b32_e32 v149, v0
	s_waitcnt vmcnt(3)
	v_pk_mul_f32 v[148:149], v[148:149], v[156:157]
	s_nop 0
	v_add_f32_e32 v155, v148, v149
	v_mov_b32_e32 v148, v0
	v_mov_b32_e32 v149, v64
	v_pk_mul_f32 v[148:149], v[148:149], v[156:157]
	s_nop 0
	v_sub_f32_e32 v156, v148, v149
	v_mov_b32_e32 v148, v65
	v_mov_b32_e32 v149, v1
	s_waitcnt vmcnt(2)
	v_pk_mul_f32 v[148:149], v[148:149], v[158:159]
	s_nop 0
	v_add_f32_e32 v157, v148, v149
	v_mov_b32_e32 v148, v1
	v_mov_b32_e32 v149, v65
	v_pk_mul_f32 v[148:149], v[148:149], v[158:159]
	s_nop 0
	v_sub_f32_e32 v158, v148, v149
	v_mov_b32_e32 v148, v66
	v_mov_b32_e32 v149, v2
	s_waitcnt vmcnt(1)
	v_pk_mul_f32 v[148:149], v[148:149], v[160:161]
	s_nop 0
	v_add_f32_e32 v159, v148, v149
	v_mov_b32_e32 v148, v2
	v_mov_b32_e32 v149, v66
	v_pk_mul_f32 v[148:149], v[148:149], v[160:161]
	s_nop 0
	v_sub_f32_e32 v160, v148, v149
	v_mov_b32_e32 v148, v67
	v_mov_b32_e32 v149, v3
	s_waitcnt vmcnt(0)
	v_pk_mul_f32 v[148:149], v[148:149], v[146:147]
	s_nop 0
	v_add_f32_e32 v161, v148, v149
	v_mov_b32_e32 v148, v3
	v_mov_b32_e32 v149, v67
	v_pk_mul_f32 v[146:147], v[148:149], v[146:147]
	s_nop 0
	v_sub_f32_e32 v165, v146, v147
	v_cvt_pk_bf16_f32 v146, v164, v163
	v_cvt_pk_bf16_f32 v147, v151, v153
	v_cvt_pk_bf16_f32 v148, v155, v157
	v_cvt_pk_bf16_f32 v149, v159, v161
	buffer_store_dwordx4 v[146:149], v145, s[8:11], 0 offen sc1
	s_nop 1
	v_cvt_pk_bf16_f32 v146, v162, v150
	v_cvt_pk_bf16_f32 v147, v152, v154
	v_cvt_pk_bf16_f32 v148, v156, v158
	v_cvt_pk_bf16_f32 v149, v160, v165
	buffer_store_dwordx4 v[146:149], v145, s[8:11], 0 offen offset:128 sc1
	s_andn2_b64 vcc, exec, s[40:41]
	s_cbranch_vccnz .LBB0_820
	s_branch .LBB0_829

; #define PG8_STAGE(bufoff, gbase, voff) do { _Pragma("unroll") for (int _i = 0; _i < 2; ++_i) \
;         __builtin_amdgcn_global_load_lds((const unsigned*)((const char*)(gbase) + (voff)[_i]), (LAS unsigned*)(lds + (bufoff) + ldsw + _i * 8192), 16, 0, 0); } while (0)
; #define PG8_STAGEB(bufoff, gbase, perm) do { _Pragma("unroll") for (int _i = 0; _i < 2; ++_i) \
;         __builtin_amdgcn_global_load_lds((const unsigned*)((const char*)(gbase) + ((BSEL && (perm)) ? voffBp[_i] : voffB[_i])), (LAS unsigned*)(lds + (bufoff) + ldsw + _i * 8192), 16, 0, 0); } while (0)
; #define PG8_LDA(dst, b, h) do { _Pragma("unroll") for (int m = 0; m < 4; ++m) _Pragma("unroll") for (int k = 0; k < 2; ++k) dst[m][k] = *(const LAS bf16x8*)(lds + PG8_SA(b, h) + aoff + m * 2048 + k * 1024); } while (0)
; #define PG8_LDB(dst, b, h) do { _Pragma("unroll") for (int n = 0; n < 2; ++n) _Pragma("unroll") for (int k = 0; k < 2; ++k) dst[n][k] = *(const LAS bf16x8*)(lds + PG8_SB(b, h) + boff + n * 2048 + k * 1024); } while (0)
; template <class Epi, bool BSEL = false>
; __device__ __forceinline__ void gemm_phase(LAS unsigned char* lds, const Gemm g, const Order& S, const Epi& E, const int tid) {
;     ...
;         for (int t = 0; t < nt; t += 2) {
;             const bool last = (t == nt - 2);
;             const char* a1 = cA + (size_t)(t + 1) * kstep;
;             const char* a2 = last ? nA : cA + (size_t)(t + 2) * kstep; const char* b2 = last ? nB : cB + (size_t)(t + 2) * kstep;
;             const char* a3 = a2 + kstep; const char* b3 = b2 + kstep;
;             const bool p2 = last ? nP : cP; const size_t h2 = last ? nhB : chB;
;             PG8_LDB(B0, 0, 0); PG8_LDB(B1, 0, 1); PG8_SCHED; PG8_LDA(At, 0, 0); PG8_STAGE(PG8_SA(1, 1), a1 + hstepA, voffA);
;             PG8_WAIT_V(8); PG8_WAIT_L(0); PG8_BAR; PG8_MMA(0, 0, At, B0); PG8_MMA(0, 1, At, B1); PG8_BAR; PG8_SCHED;
;             PG8_LDA(At, 0, 1); PG8_STAGEB(PG8_SB(0, 0), b2, p2); PG8_STAGEB(PG8_SB(0, 1), b2 + h2, p2); PG8_STAGE(PG8_SA(0, 0), a2, voffA);
;             PG8_WAIT_V(8); PG8_WAIT_L(0); PG8_BAR; PG8_MMA(1, 0, At, B0); PG8_MMA(1, 1, At, B1); PG8_BAR; PG8_SCHED;
;             PG8_LDB(B0, 1, 0); PG8_LDB(B1, 1, 1); PG8_SCHED; PG8_LDA(At, 1, 0); PG8_STAGE(PG8_SA(0, 1), a2 + hstepA, voffA);
;             PG8_WAIT_V(8); PG8_WAIT_L(0); PG8_BAR; PG8_MMA(0, 0, At, B0); PG8_MMA(0, 1, At, B1); PG8_BAR; PG8_SCHED;
.LBB0_998:
	s_xor_b64 s[2:3], s[34:35], -1
	v_add_u32_e32 v79, s44, v77
	s_and_b64 s[36:37], s[34:35], exec
	ds_read_b128 v[80:83], v79
	ds_read_b128 v[84:87], v79 offset:1024
	ds_read_b128 v[88:91], v79 offset:2048
	ds_read_b128 v[92:95], v79 offset:3072
	v_add_u32_e32 v79, s45, v77
	s_cselect_b32 s41, s1, s1
	s_cselect_b32 s40, s0, s0
	s_add_u32 s48, s0, 0x8080
	ds_read_b128 v[96:99], v79
	ds_read_b128 v[100:103], v79 offset:1024
	ds_read_b128 v[104:107], v79 offset:2048
	ds_read_b128 v[108:111], v79 offset:3072
	s_addc_u32 s49, s1, 0
	s_add_u32 s38, s40, 0x8000
	s_addc_u32 s39, s41, 0
	s_and_b64 s[36:37], s[34:35], exec
	s_cselect_b32 s36, s30, s4
	s_cselect_b32 s37, s31, s5
	s_add_u32 s52, s36, 0x8000
	s_addc_u32 s53, s37, 0
	v_lshl_add_u64 v[144:145], s[48:49], 0, v[64:65]
	s_add_i32 m0, s13, 0xc000
	ds_read_b128 v[112:115], v78
	ds_read_b128 v[116:119], v78 offset:1024
	ds_read_b128 v[120:123], v78 offset:2048
	ds_read_b128 v[124:127], v78 offset:3072
	ds_read_b128 v[128:131], v78 offset:4096
	ds_read_b128 v[132:135], v78 offset:5120
	ds_read_b128 v[136:139], v78 offset:6144
	ds_read_b128 v[140:143], v78 offset:7168
	global_load_lds_dwordx4 v[144:145], off
	v_lshl_add_u64 v[144:145], s[48:49], 0, v[68:69]
	s_add_i32 m0, s13, 0xe000
	s_nop 0
	global_load_lds_dwordx4 v[144:145], off
	s_waitcnt vmcnt(8)
	s_waitcnt lgkmcnt(0)
	s_barrier
	v_mfma_f32_16x16x32_bf16 v[60:63], v[80:83], v[112:115], v[60:63]
	v_mfma_f32_16x16x32_bf16 v[56:59], v[88:91], v[112:115], v[56:59]
	v_mfma_f32_16x16x32_bf16 v[52:55], v[80:83], v[120:123], v[52:55]
	v_mfma_f32_16x16x32_bf16 v[48:51], v[88:91], v[120:123], v[48:51]
	v_mfma_f32_16x16x32_bf16 v[44:47], v[80:83], v[128:131], v[44:47]
	v_mfma_f32_16x16x32_bf16 v[40:43], v[88:91], v[128:131], v[40:43]
	v_mfma_f32_16x16x32_bf16 v[36:39], v[80:83], v[136:139], v[36:39]
	v_mfma_f32_16x16x32_bf16 v[32:35], v[88:91], v[136:139], v[32:35]
	v_mfma_f32_16x16x32_bf16 v[60:63], v[84:87], v[116:119], v[60:63]
	v_mfma_f32_16x16x32_bf16 v[56:59], v[92:95], v[116:119], v[56:59]
	v_mfma_f32_16x16x32_bf16 v[52:55], v[84:87], v[124:127], v[52:55]
	v_mfma_f32_16x16x32_bf16 v[48:51], v[92:95], v[124:127], v[48:51]
	v_mfma_f32_16x16x32_bf16 v[44:47], v[84:87], v[132:135], v[44:47]
	v_mfma_f32_16x16x32_bf16 v[40:43], v[92:95], v[132:135], v[40:43]
	v_mfma_f32_16x16x32_bf16 v[36:39], v[84:87], v[140:143], v[36:39]
	v_mfma_f32_16x16x32_bf16 v[32:35], v[92:95], v[140:143], v[32:35]
	v_mfma_f32_16x16x32_bf16 v[28:31], v[96:99], v[112:115], v[28:31]
	v_mfma_f32_16x16x32_bf16 v[24:27], v[104:107], v[112:115], v[24:27]
	v_mfma_f32_16x16x32_bf16 v[20:23], v[96:99], v[120:123], v[20:23]
	v_mfma_f32_16x16x32_bf16 v[16:19], v[104:107], v[120:123], v[16:19]
	v_mfma_f32_16x16x32_bf16 v[12:15], v[96:99], v[128:131], v[12:15]
	v_mfma_f32_16x16x32_bf16 v[8:11], v[104:107], v[128:131], v[8:11]
	v_mfma_f32_16x16x32_bf16 v[4:7], v[96:99], v[136:139], v[4:7]
	v_mfma_f32_16x16x32_bf16 v[0:3], v[104:107], v[136:139], v[0:3]
	v_mfma_f32_16x16x32_bf16 v[28:31], v[100:103], v[116:119], v[28:31]
	v_mfma_f32_16x16x32_bf16 v[24:27], v[108:111], v[116:119], v[24:27]
	v_mfma_f32_16x16x32_bf16 v[20:23], v[100:103], v[124:127], v[20:23]
	v_mfma_f32_16x16x32_bf16 v[16:19], v[108:111], v[124:127], v[16:19]
	v_mfma_f32_16x16x32_bf16 v[12:15], v[100:103], v[132:135], v[12:15]
	v_mfma_f32_16x16x32_bf16 v[8:11], v[108:111], v[132:135], v[8:11]
	v_mfma_f32_16x16x32_bf16 v[4:7], v[100:103], v[140:143], v[4:7]
	v_mfma_f32_16x16x32_bf16 v[0:3], v[108:111], v[140:143], v[0:3]
	s_barrier
	s_add_i32 s29, s44, s12
	v_lshl_add_u64 v[144:145], s[36:37], 0, v[66:67]
	s_mov_b32 m0, s29
	v_lshl_add_u64 v[146:147], s[36:37], 0, v[70:71]
	global_load_lds_dwordx4 v[144:145], off
	s_add_i32 m0, s29, 0x2000
	s_add_i32 s29, s45, s12
	global_load_lds_dwordx4 v[146:147], off
	v_lshl_add_u64 v[80:81], s[52:53], 0, v[66:67]
	s_mov_b32 m0, s29
	v_lshl_add_u64 v[148:149], s[40:41], 0, v[64:65]
	global_load_lds_dwordx4 v[80:81], off
	v_lshl_add_u64 v[80:81], s[52:53], 0, v[70:71]
	s_add_i32 m0, s29, 0x2000
	v_lshl_add_u64 v[150:151], s[40:41], 0, v[68:69]
	global_load_lds_dwordx4 v[80:81], off
	s_mov_b32 m0, s13
	s_nop 0
	global_load_lds_dwordx4 v[148:149], off
	s_mov_b32 m0, s14
	s_nop 0
	global_load_lds_dwordx4 v[150:151], off
	s_waitcnt vmcnt(8)
	s_waitcnt lgkmcnt(0)
	s_barrier
	s_setprio 1
	s_setprio 0
	s_setprio 1
	s_setprio 0
	s_barrier
	s_add_i32 s29, 0, 0x18000
	v_add_u32_e32 v79, s29, v77
	s_add_i32 s40, 0, 0x1c000
	ds_read_b128 v[80:83], v79
	ds_read_b128 v[84:87], v79 offset:1024
	ds_read_b128 v[88:91], v79 offset:2048
	ds_read_b128 v[92:95], v79 offset:3072
	v_add_u32_e32 v79, s40, v77
	ds_read_b128 v[96:99], v79
	ds_read_b128 v[100:103], v79 offset:1024
	ds_read_b128 v[104:107], v79 offset:2048
	ds_read_b128 v[108:111], v79 offset:3072
	s_mov_b32 m0, s15
	v_lshl_add_u64 v[152:153], s[38:39], 0, v[64:65]
	ds_read_b128 v[112:115], v78 offset:32768
	ds_read_b128 v[116:119], v78 offset:33792
	ds_read_b128 v[120:123], v78 offset:34816
	ds_read_b128 v[124:127], v78 offset:35840
	ds_read_b128 v[128:131], v78 offset:36864
	ds_read_b128 v[132:135], v78 offset:37888
	ds_read_b128 v[136:139], v78 offset:38912
	ds_read_b128 v[140:143], v78 offset:39936
	global_load_lds_dwordx4 v[152:153], off
	v_lshl_add_u64 v[152:153], s[38:39], 0, v[68:69]
	s_mov_b32 m0, s20
	s_nop 0
	global_load_lds_dwordx4 v[152:153], off
	s_waitcnt vmcnt(8)
	s_waitcnt lgkmcnt(0)
	s_barrier
; #define PG8_STAGE(bufoff, gbase, voff) do { _Pragma("unroll") for (int _i = 0; _i < 2; ++_i) \
;         __builtin_amdgcn_global_load_lds((const unsigned*)((const char*)(gbase) + (voff)[_i]), (LAS unsigned*)(lds + (bufoff) + ldsw + _i * 8192), 16, 0, 0); } while (0)
; #define PG8_STAGEB(bufoff, gbase, perm) do { _Pragma("unroll") for (int _i = 0; _i < 2; ++_i) \
;         __builtin_amdgcn_global_load_lds((const unsigned*)((const char*)(gbase) + ((BSEL && (perm)) ? voffBp[_i] : voffB[_i])), (LAS unsigned*)(lds + (bufoff) + ldsw + _i * 8192), 16, 0, 0); } while (0)
; #define PG8_LDA(dst, b, h) do { _Pragma("unroll") for (int m = 0; m < 4; ++m) _Pragma("unroll") for (int k = 0; k < 2; ++k) dst[m][k] = *(const LAS bf16x8*)(lds + PG8_SA(b, h) + aoff + m * 2048 + k * 1024); } while (0)
; #define PG8_MMA(ai, bj, At, Bt) do { __builtin_amdgcn_s_setprio(1); _Pragma("unroll") for (int m = 0; m < 4; ++m) _Pragma("unroll") for (int n = 0; n < 2; ++n) _Pragma("unroll") for (int k = 0; k < 2; ++k) \
;         acc[ai][bj][m][n] = __builtin_amdgcn_mfma_f32_16x16x32_bf16(Bt[n][k], At[m][k], acc[ai][bj][m][n], 0, 0, 0); __builtin_amdgcn_s_setprio(0); } while (0)
; #define PG8_WAIT_V(n) asm volatile("s_waitcnt vmcnt(" #n ")" ::: "memory")
; #define PG8_WAIT_L(n) asm volatile("s_waitcnt lgkmcnt(" #n ")" ::: "memory")
; template <class Epi, bool BSEL = false>
; __device__ __forceinline__ void gemm_phase(LAS unsigned char* lds, const Gemm g, const Order& S, const Epi& E, const int tid) {
;     ...
;             PG8_WAIT_V(8); PG8_WAIT_L(0); PG8_BAR; PG8_MMA(0, 0, At, B0); PG8_MMA(0, 1, At, B1); PG8_BAR; PG8_SCHED;
;             PG8_LDA(At, 1, 1); PG8_STAGEB(PG8_SB(1, 0), b3, p2); PG8_STAGEB(PG8_SB(1, 1), b3 + h2, p2); PG8_STAGE(PG8_SA(1, 0), a3, voffA);
;             PG8_WAIT_V(8); PG8_WAIT_L(0); PG8_BAR; PG8_MMA(1, 0, At, B0); PG8_MMA(1, 1, At, B1); PG8_BAR; PG8_SCHED;
;         }
;         if constexpr (ALIGN_EPI) { if (wr == 0) PG8_BAR; }
;     __device__ __forceinline__ void operator()(const f32x4 (&acc)[2][2][4][2], const Unit& u, int wr, int wc, int fr, int fq) const {
;         if (wr != 0) return;
;         const float sc = 1.0f / 512.0f; const int b = u.pn >> 6, k1 = u.pn & 63;
; #pragma unroll
;         for (int m = 0; m < 4; ++m) { const int k2 = 16 * m + fr; bf16_t* rowp = AO + (size_t)(b * SEQ + 64 * k2 + k1) * DM + DQK + wc * 32 + 8 * fq;
	v_mfma_f32_16x16x32_bf16 v[60:63], v[80:83], v[112:115], v[60:63]
	v_mfma_f32_16x16x32_bf16 v[56:59], v[88:91], v[112:115], v[56:59]
	v_mfma_f32_16x16x32_bf16 v[52:55], v[80:83], v[120:123], v[52:55]
	v_mfma_f32_16x16x32_bf16 v[48:51], v[88:91], v[120:123], v[48:51]
	v_mfma_f32_16x16x32_bf16 v[44:47], v[80:83], v[128:131], v[44:47]
	v_mfma_f32_16x16x32_bf16 v[40:43], v[88:91], v[128:131], v[40:43]
	v_mfma_f32_16x16x32_bf16 v[36:39], v[80:83], v[136:139], v[36:39]
	v_mfma_f32_16x16x32_bf16 v[32:35], v[88:91], v[136:139], v[32:35]
	v_mfma_f32_16x16x32_bf16 v[60:63], v[84:87], v[116:119], v[60:63]
	v_mfma_f32_16x16x32_bf16 v[56:59], v[92:95], v[116:119], v[56:59]
	v_mfma_f32_16x16x32_bf16 v[52:55], v[84:87], v[124:127], v[52:55]
	v_mfma_f32_16x16x32_bf16 v[48:51], v[92:95], v[124:127], v[48:51]
	v_mfma_f32_16x16x32_bf16 v[44:47], v[84:87], v[132:135], v[44:47]
	v_mfma_f32_16x16x32_bf16 v[40:43], v[92:95], v[132:135], v[40:43]
	v_mfma_f32_16x16x32_bf16 v[36:39], v[84:87], v[140:143], v[36:39]
	v_mfma_f32_16x16x32_bf16 v[32:35], v[92:95], v[140:143], v[32:35]
	v_mfma_f32_16x16x32_bf16 v[28:31], v[96:99], v[112:115], v[28:31]
	v_mfma_f32_16x16x32_bf16 v[24:27], v[104:107], v[112:115], v[24:27]
	v_mfma_f32_16x16x32_bf16 v[20:23], v[96:99], v[120:123], v[20:23]
	v_mfma_f32_16x16x32_bf16 v[16:19], v[104:107], v[120:123], v[16:19]
	v_mfma_f32_16x16x32_bf16 v[12:15], v[96:99], v[128:131], v[12:15]
	v_mfma_f32_16x16x32_bf16 v[8:11], v[104:107], v[128:131], v[8:11]
	v_mfma_f32_16x16x32_bf16 v[4:7], v[96:99], v[136:139], v[4:7]
	v_mfma_f32_16x16x32_bf16 v[0:3], v[104:107], v[136:139], v[0:3]
	v_mfma_f32_16x16x32_bf16 v[28:31], v[100:103], v[116:119], v[28:31]
	v_mfma_f32_16x16x32_bf16 v[24:27], v[108:111], v[116:119], v[24:27]
	v_mfma_f32_16x16x32_bf16 v[20:23], v[100:103], v[124:127], v[20:23]
	v_mfma_f32_16x16x32_bf16 v[16:19], v[108:111], v[124:127], v[16:19]
	v_mfma_f32_16x16x32_bf16 v[12:15], v[100:103], v[132:135], v[12:15]
	v_mfma_f32_16x16x32_bf16 v[8:11], v[108:111], v[132:135], v[8:11]
	v_mfma_f32_16x16x32_bf16 v[4:7], v[100:103], v[140:143], v[4:7]
	v_mfma_f32_16x16x32_bf16 v[0:3], v[108:111], v[140:143], v[0:3]
	s_barrier
	s_add_i32 s29, s29, s12
	v_lshl_add_u64 v[80:81], v[144:145], 0, s[10:11]
	s_mov_b32 m0, s29
	s_nop 0
	global_load_lds_dwordx4 v[80:81], off
	s_add_i32 m0, s29, 0x2000
	s_add_u32 s36, s36, 0x8080
	v_lshl_add_u64 v[80:81], v[146:147], 0, s[10:11]
	s_addc_u32 s37, s37, 0
	s_add_i32 s29, s40, s12
	global_load_lds_dwordx4 v[80:81], off
	v_lshl_add_u64 v[80:81], s[36:37], 0, v[66:67]
	s_mov_b32 m0, s29
	s_nop 0
	global_load_lds_dwordx4 v[80:81], off
	v_lshl_add_u64 v[80:81], s[36:37], 0, v[70:71]
	s_add_i32 m0, s29, 0x2000
	s_nop 0
	global_load_lds_dwordx4 v[80:81], off
	v_lshl_add_u64 v[80:81], v[148:149], 0, s[10:11]
	s_mov_b32 m0, s27
	s_nop 0
	global_load_lds_dwordx4 v[80:81], off
	v_lshl_add_u64 v[80:81], v[150:151], 0, s[10:11]
	s_mov_b32 m0, s42
	s_nop 0
	global_load_lds_dwordx4 v[80:81], off
	s_waitcnt vmcnt(8)
	s_waitcnt lgkmcnt(0)
	s_barrier
	s_setprio 1
	s_setprio 0
	s_setprio 1
	s_setprio 0
	s_barrier
	s_andn2_b64 vcc, exec, s[24:25]
	s_cbranch_vccnz .LBB0_1000
	s_and_b32 s36, s21, 0x3ffffc0
	s_and_b32 s29, s21, 63
	v_or_b32_e32 v79, s36, v76
	v_lshl_or_b32 v84, v79, 6, s29
	v_ashrrev_i32_e32 v85, 31, v84
	v_lshlrev_b64 v[80:81], 11, v[84:85]
	v_lshl_add_u64 v[86:87], v[72:73], 0, v[80:81]
	v_pk_mul_f32 v[80:81], v[60:61], s[26:27] op_sel_hi:[1,0]
	s_barrier
; __device__ __forceinline__ unsigned cvt_pk_bf16(float lo, float hi) { unsigned r; asm volatile("v_cvt_pk_bf16_f32 %0, %1, %2" : "=v"(r) : "v"(lo), "v"(hi)); return r; }
; template <class Epi, bool BSEL = false>
; __device__ __forceinline__ void gemm_phase(LAS unsigned char* lds, const Gemm g, const Order& S, const Epi& E, const int tid) {
;     ...
;         if (!has_next) break;
;     __device__ __forceinline__ void operator()(const f32x4 (&acc)[2][2][4][2], const Unit& u, int wr, int wc, int fr, int fq) const {
;     ...
;         for (int m = 0; m < 4; ++m) { const int k2 = 16 * m + fr; bf16_t* rowp = AO + (size_t)(b * SEQ + 64 * k2 + k1) * DM + DQK + wc * 32 + 8 * fq;
; #pragma unroll
;             for (int bj = 0; bj < 2; ++bj) { const f32x4 v0 = acc[0][bj][m][0] * sc, v1 = acc[0][bj][m][1] * sc;
;                 u32x4 w; w.x = cvt_pk_bf16(v0[0], v0[1]); w.y = cvt_pk_bf16(v0[2], v0[3]); w.z = cvt_pk_bf16(v1[0], v1[1]); w.w = cvt_pk_bf16(v1[2], v1[3]);
;                 *(u32x4*)(rowp + bj * HALF) = w; } }
	v_pk_mul_f32 v[82:83], v[62:63], s[26:27] op_sel_hi:[1,0]
	v_cvt_pk_bf16_f32 v80, v80, v81
	v_pk_mul_f32 v[88:89], v[58:59], s[26:27] op_sel_hi:[1,0]
	v_cvt_pk_bf16_f32 v81, v82, v83
	v_pk_mul_f32 v[90:91], v[56:57], s[26:27] op_sel_hi:[1,0]
	s_nop 0
	v_cvt_pk_bf16_f32 v82, v90, v91
	v_cvt_pk_bf16_f32 v83, v88, v89
	global_store_dwordx4 v[86:87], v[80:83], off offset:1536
	v_pk_mul_f32 v[88:89], v[26:27], s[26:27] op_sel_hi:[1,0]
	v_pk_mul_f32 v[90:91], v[24:25], s[26:27] op_sel_hi:[1,0]
	v_pk_mul_f32 v[80:81], v[28:29], s[26:27] op_sel_hi:[1,0]
	v_pk_mul_f32 v[82:83], v[30:31], s[26:27] op_sel_hi:[1,0]
	v_cvt_pk_bf16_f32 v80, v80, v81
	s_nop 0
	v_cvt_pk_bf16_f32 v81, v82, v83
	v_cvt_pk_bf16_f32 v82, v90, v91
	v_cvt_pk_bf16_f32 v83, v88, v89
	global_store_dwordx4 v[86:87], v[80:83], off offset:1792
	v_pk_mul_f32 v[88:89], v[50:51], s[26:27] op_sel_hi:[1,0]
	v_pk_mul_f32 v[90:91], v[48:49], s[26:27] op_sel_hi:[1,0]
	v_or_b32_e32 v80, 0x400, v84
	v_ashrrev_i32_e32 v81, 31, v80
	v_lshlrev_b64 v[80:81], 11, v[80:81]
	v_lshl_add_u64 v[86:87], v[72:73], 0, v[80:81]
	v_pk_mul_f32 v[80:81], v[52:53], s[26:27] op_sel_hi:[1,0]
	v_pk_mul_f32 v[82:83], v[54:55], s[26:27] op_sel_hi:[1,0]
	v_cvt_pk_bf16_f32 v80, v80, v81
	s_nop 0
	v_cvt_pk_bf16_f32 v81, v82, v83
	v_cvt_pk_bf16_f32 v82, v90, v91
	v_cvt_pk_bf16_f32 v83, v88, v89
	global_store_dwordx4 v[86:87], v[80:83], off offset:1536
	v_pk_mul_f32 v[88:89], v[18:19], s[26:27] op_sel_hi:[1,0]
	v_pk_mul_f32 v[90:91], v[16:17], s[26:27] op_sel_hi:[1,0]
	v_pk_mul_f32 v[80:81], v[20:21], s[26:27] op_sel_hi:[1,0]
	v_pk_mul_f32 v[82:83], v[22:23], s[26:27] op_sel_hi:[1,0]
	v_cvt_pk_bf16_f32 v80, v80, v81
	s_nop 0
	v_cvt_pk_bf16_f32 v81, v82, v83
	v_cvt_pk_bf16_f32 v82, v90, v91
	v_cvt_pk_bf16_f32 v83, v88, v89
	global_store_dwordx4 v[86:87], v[80:83], off offset:1792
	v_pk_mul_f32 v[88:89], v[42:43], s[26:27] op_sel_hi:[1,0]
	v_pk_mul_f32 v[90:91], v[40:41], s[26:27] op_sel_hi:[1,0]
	v_or_b32_e32 v80, 0x800, v84
	v_ashrrev_i32_e32 v81, 31, v80
	v_lshlrev_b64 v[80:81], 11, v[80:81]
	v_lshl_add_u64 v[86:87], v[72:73], 0, v[80:81]
	v_pk_mul_f32 v[80:81], v[44:45], s[26:27] op_sel_hi:[1,0]
	v_pk_mul_f32 v[82:83], v[46:47], s[26:27] op_sel_hi:[1,0]
	v_cvt_pk_bf16_f32 v80, v80, v81
	s_nop 0
	v_cvt_pk_bf16_f32 v81, v82, v83
	v_cvt_pk_bf16_f32 v82, v90, v91
	v_cvt_pk_bf16_f32 v83, v88, v89
	global_store_dwordx4 v[86:87], v[80:83], off offset:1536
	v_pk_mul_f32 v[88:89], v[10:11], s[26:27] op_sel_hi:[1,0]
	v_pk_mul_f32 v[90:91], v[8:9], s[26:27] op_sel_hi:[1,0]
	v_pk_mul_f32 v[80:81], v[12:13], s[26:27] op_sel_hi:[1,0]
	v_pk_mul_f32 v[82:83], v[14:15], s[26:27] op_sel_hi:[1,0]
	v_cvt_pk_bf16_f32 v80, v80, v81
	s_nop 0
	v_cvt_pk_bf16_f32 v81, v82, v83
	v_cvt_pk_bf16_f32 v82, v90, v91
	v_cvt_pk_bf16_f32 v83, v88, v89
	global_store_dwordx4 v[86:87], v[80:83], off offset:1792
	v_pk_mul_f32 v[86:87], v[34:35], s[26:27] op_sel_hi:[1,0]
	v_pk_mul_f32 v[88:89], v[32:33], s[26:27] op_sel_hi:[1,0]
	v_or_b32_e32 v80, 0xc00, v84
	v_ashrrev_i32_e32 v81, 31, v80
	v_lshlrev_b64 v[80:81], 11, v[80:81]
	v_lshl_add_u64 v[84:85], v[72:73], 0, v[80:81]
	v_pk_mul_f32 v[82:83], v[38:39], s[26:27] op_sel_hi:[1,0]
	v_pk_mul_f32 v[80:81], v[36:37], s[26:27] op_sel_hi:[1,0]
	s_nop 0
	v_cvt_pk_bf16_f32 v80, v80, v81
	v_cvt_pk_bf16_f32 v81, v82, v83
	v_cvt_pk_bf16_f32 v82, v88, v89
	v_cvt_pk_bf16_f32 v83, v86, v87
	global_store_dwordx4 v[84:85], v[80:83], off offset:1536
	v_pk_mul_f32 v[86:87], v[2:3], s[26:27] op_sel_hi:[1,0]
	v_pk_mul_f32 v[88:89], v[0:1], s[26:27] op_sel_hi:[1,0]
	v_pk_mul_f32 v[82:83], v[6:7], s[26:27] op_sel_hi:[1,0]
	v_pk_mul_f32 v[80:81], v[4:5], s[26:27] op_sel_hi:[1,0]
	s_nop 0
	v_cvt_pk_bf16_f32 v80, v80, v81
	v_cvt_pk_bf16_f32 v81, v82, v83
	v_cvt_pk_bf16_f32 v82, v88, v89
	v_cvt_pk_bf16_f32 v83, v86, v87
	global_store_dwordx4 v[84:85], v[80:83], off offset:1792
	s_andn2_b64 vcc, exec, s[34:35]
	s_cbranch_vccnz .LBB0_990
	s_branch .LBB0_1001

; #define PG8_STAGE(bufoff, gbase, voff) do { _Pragma("unroll") for (int _i = 0; _i < 2; ++_i) \
;         __builtin_amdgcn_global_load_lds((const unsigned*)((const char*)(gbase) + (voff)[_i]), (LAS unsigned*)(lds + (bufoff) + ldsw + _i * 8192), 16, 0, 0); } while (0)
; #define PG8_STAGEB(bufoff, gbase, perm) do { _Pragma("unroll") for (int _i = 0; _i < 2; ++_i) \
;         __builtin_amdgcn_global_load_lds((const unsigned*)((const char*)(gbase) + ((BSEL && (perm)) ? voffBp[_i] : voffB[_i])), (LAS unsigned*)(lds + (bufoff) + ldsw + _i * 8192), 16, 0, 0); } while (0)
; #define PG8_LDA(dst, b, h) do { _Pragma("unroll") for (int m = 0; m < 4; ++m) _Pragma("unroll") for (int k = 0; k < 2; ++k) dst[m][k] = *(const LAS bf16x8*)(lds + PG8_SA(b, h) + aoff + m * 2048 + k * 1024); } while (0)
; #define PG8_LDB(dst, b, h) do { _Pragma("unroll") for (int n = 0; n < 2; ++n) _Pragma("unroll") for (int k = 0; k < 2; ++k) dst[n][k] = *(const LAS bf16x8*)(lds + PG8_SB(b, h) + boff + n * 2048 + k * 1024); } while (0)
; #define PG8_WAIT_V(n) asm volatile("s_waitcnt vmcnt(" #n ")" ::: "memory")
; #define PG8_WAIT_L(n) asm volatile("s_waitcnt lgkmcnt(" #n ")" ::: "memory")
; #define PG8_BAR __builtin_amdgcn_s_barrier()
; #define PG8_SCHED __builtin_amdgcn_sched_barrier(0)
; template <class Epi, bool BSEL = false>
; __device__ __forceinline__ void gemm_phase(LAS unsigned char* lds, const Gemm g, const Order& S, const Epi& E, const int tid) {
;     ...
;         for (int t = 0; t < nt; t += 2) {
;             const bool last = (t == nt - 2);
;             const char* a1 = cA + (size_t)(t + 1) * kstep;
;             const char* a2 = last ? nA : cA + (size_t)(t + 2) * kstep; const char* b2 = last ? nB : cB + (size_t)(t + 2) * kstep;
;             const char* a3 = a2 + kstep; const char* b3 = b2 + kstep;
;             const bool p2 = last ? nP : cP; const size_t h2 = last ? nhB : chB;
;             PG8_LDB(B0, 0, 0); PG8_LDB(B1, 0, 1); PG8_SCHED; PG8_LDA(At, 0, 0); PG8_STAGE(PG8_SA(1, 1), a1 + hstepA, voffA);
;             PG8_WAIT_V(8); PG8_WAIT_L(0); PG8_BAR; PG8_MMA(0, 0, At, B0); PG8_MMA(0, 1, At, B1); PG8_BAR; PG8_SCHED;
;             PG8_LDA(At, 0, 1); PG8_STAGEB(PG8_SB(0, 0), b2, p2); PG8_STAGEB(PG8_SB(0, 1), b2 + h2, p2); PG8_STAGE(PG8_SA(0, 0), a2, voffA);
;             PG8_WAIT_V(8); PG8_WAIT_L(0); PG8_BAR; PG8_MMA(1, 0, At, B0); PG8_MMA(1, 1, At, B1); PG8_BAR; PG8_SCHED;
.LBB0_1072:
	v_add_u32_e32 v172, s47, v145
	ds_read_b128 v[132:135], v172
	ds_read_b128 v[136:139], v172 offset:1024
	ds_read_b128 v[140:143], v172 offset:2048
	ds_read_b128 v[176:179], v172 offset:3072
	v_add_u32_e32 v172, s48, v145
	s_add_u32 s34, s6, s2
	ds_read_b128 v[180:183], v172
	ds_read_b128 v[184:187], v172 offset:1024
	ds_read_b128 v[188:191], v172 offset:2048
	ds_read_b128 v[192:195], v172 offset:3072
	s_addc_u32 s35, s7, s3
	s_add_u32 s34, s34, 0x100
	s_addc_u32 s35, s35, 0
	s_add_u32 s57, s1, s2
	s_addc_u32 s58, s25, s3
	s_cmpk_eq_i32 s2, 0x700
	s_cselect_b32 s39, s52, s35
	s_cselect_b32 s38, s53, s34
	s_cselect_b32 s35, s54, s58
	s_cselect_b32 s34, s55, s57
	v_lshl_add_u64 v[172:173], v[128:129], 0, s[2:3]
	s_add_i32 m0, s20, 0xc000
	ds_read_b128 v[196:199], v175
	ds_read_b128 v[202:205], v175 offset:1024
	ds_read_b128 v[206:209], v175 offset:2048
	ds_read_b128 v[210:213], v175 offset:3072
	ds_read_b128 v[214:217], v175 offset:4096
	ds_read_b128 v[218:221], v175 offset:5120
	ds_read_b128 v[222:225], v175 offset:6144
	ds_read_b128 v[226:229], v175 offset:7168
	global_load_lds_dwordx4 v[172:173], off
	v_lshl_add_u64 v[172:173], v[130:131], 0, s[2:3]
	s_add_i32 m0, s20, 0xe000
	s_nop 0
	global_load_lds_dwordx4 v[172:173], off
	s_waitcnt vmcnt(8)
	s_waitcnt lgkmcnt(0)
	s_barrier
	v_mfma_f32_16x16x32_bf16 v[124:127], v[132:135], v[196:199], v[124:127]
	v_mfma_f32_16x16x32_bf16 v[120:123], v[140:143], v[196:199], v[120:123]
	v_mfma_f32_16x16x32_bf16 v[116:119], v[132:135], v[206:209], v[116:119]
	v_mfma_f32_16x16x32_bf16 v[112:115], v[140:143], v[206:209], v[112:115]
	v_mfma_f32_16x16x32_bf16 v[108:111], v[132:135], v[214:217], v[108:111]
	v_mfma_f32_16x16x32_bf16 v[104:107], v[140:143], v[214:217], v[104:107]
	v_mfma_f32_16x16x32_bf16 v[100:103], v[132:135], v[222:225], v[100:103]
	v_mfma_f32_16x16x32_bf16 v[96:99], v[140:143], v[222:225], v[96:99]
	v_mfma_f32_16x16x32_bf16 v[124:127], v[136:139], v[202:205], v[124:127]
	v_mfma_f32_16x16x32_bf16 v[120:123], v[176:179], v[202:205], v[120:123]
	v_mfma_f32_16x16x32_bf16 v[116:119], v[136:139], v[210:213], v[116:119]
	v_mfma_f32_16x16x32_bf16 v[112:115], v[176:179], v[210:213], v[112:115]
	v_mfma_f32_16x16x32_bf16 v[108:111], v[136:139], v[218:221], v[108:111]
	v_mfma_f32_16x16x32_bf16 v[104:107], v[176:179], v[218:221], v[104:107]
	v_mfma_f32_16x16x32_bf16 v[100:103], v[136:139], v[226:229], v[100:103]
	v_mfma_f32_16x16x32_bf16 v[96:99], v[176:179], v[226:229], v[96:99]
	v_mfma_f32_16x16x32_bf16 v[92:95], v[180:183], v[196:199], v[92:95]
	v_mfma_f32_16x16x32_bf16 v[88:91], v[188:191], v[196:199], v[88:91]
	v_mfma_f32_16x16x32_bf16 v[84:87], v[180:183], v[206:209], v[84:87]
	v_mfma_f32_16x16x32_bf16 v[80:83], v[188:191], v[206:209], v[80:83]
	v_mfma_f32_16x16x32_bf16 v[76:79], v[180:183], v[214:217], v[76:79]
	v_mfma_f32_16x16x32_bf16 v[72:75], v[188:191], v[214:217], v[72:75]
	v_mfma_f32_16x16x32_bf16 v[68:71], v[180:183], v[222:225], v[68:71]
	v_mfma_f32_16x16x32_bf16 v[64:67], v[188:191], v[222:225], v[64:67]
	v_mfma_f32_16x16x32_bf16 v[92:95], v[184:187], v[202:205], v[92:95]
	v_mfma_f32_16x16x32_bf16 v[88:91], v[192:195], v[202:205], v[88:91]
	v_mfma_f32_16x16x32_bf16 v[84:87], v[184:187], v[210:213], v[84:87]
	v_mfma_f32_16x16x32_bf16 v[80:83], v[192:195], v[210:213], v[80:83]
	v_mfma_f32_16x16x32_bf16 v[76:79], v[184:187], v[218:221], v[76:79]
	v_mfma_f32_16x16x32_bf16 v[72:75], v[192:195], v[218:221], v[72:75]
	v_mfma_f32_16x16x32_bf16 v[68:71], v[184:187], v[226:229], v[68:71]
	v_mfma_f32_16x16x32_bf16 v[64:67], v[192:195], v[226:229], v[64:67]
	s_barrier
	s_add_i32 s57, s47, s15
	v_lshl_add_u64 v[172:173], s[34:35], 0, v[146:147]
	s_mov_b32 m0, s57
	ds_read_b128 v[196:199], v175 offset:16384
	ds_read_b128 v[202:205], v175 offset:17408
	ds_read_b128 v[206:209], v175 offset:18432
	ds_read_b128 v[210:213], v175 offset:19456
	ds_read_b128 v[214:217], v175 offset:20480
	ds_read_b128 v[218:221], v175 offset:21504
	ds_read_b128 v[222:225], v175 offset:22528
	ds_read_b128 v[226:229], v175 offset:23552
	global_load_lds_dwordx4 v[172:173], off
	s_add_i32 m0, s57, 0x2000
	s_add_u32 s58, s34, 0x40000
	v_lshl_add_u64 v[230:231], s[34:35], 0, v[148:149]
	s_addc_u32 s59, s35, 0
	s_add_i32 s57, s48, s15
	global_load_lds_dwordx4 v[230:231], off
	v_lshl_add_u64 v[232:233], s[58:59], 0, v[146:147]
	s_mov_b32 m0, s57
	v_lshl_add_u64 v[234:235], s[38:39], 0, v[148:149]
	global_load_lds_dwordx4 v[232:233], off
	v_lshl_add_u64 v[232:233], s[58:59], 0, v[148:149]
	s_add_i32 m0, s57, 0x2000
	s_nop 0
	global_load_lds_dwordx4 v[232:233], off
	v_lshl_add_u64 v[232:233], s[38:39], 0, v[146:147]
	s_mov_b32 m0, s20
	s_nop 0
	global_load_lds_dwordx4 v[232:233], off
	s_mov_b32 m0, s21
	s_nop 0
	global_load_lds_dwordx4 v[234:235], off
	s_waitcnt vmcnt(8)
	s_waitcnt lgkmcnt(0)
	s_barrier
; #define PG8_STAGE(bufoff, gbase, voff) do { _Pragma("unroll") for (int _i = 0; _i < 2; ++_i) \
;         __builtin_amdgcn_global_load_lds((const unsigned*)((const char*)(gbase) + (voff)[_i]), (LAS unsigned*)(lds + (bufoff) + ldsw + _i * 8192), 16, 0, 0); } while (0)
; #define PG8_LDA(dst, b, h) do { _Pragma("unroll") for (int m = 0; m < 4; ++m) _Pragma("unroll") for (int k = 0; k < 2; ++k) dst[m][k] = *(const LAS bf16x8*)(lds + PG8_SA(b, h) + aoff + m * 2048 + k * 1024); } while (0)
; #define PG8_LDB(dst, b, h) do { _Pragma("unroll") for (int n = 0; n < 2; ++n) _Pragma("unroll") for (int k = 0; k < 2; ++k) dst[n][k] = *(const LAS bf16x8*)(lds + PG8_SB(b, h) + boff + n * 2048 + k * 1024); } while (0)
; #define PG8_MMA(ai, bj, At, Bt) do { __builtin_amdgcn_s_setprio(1); _Pragma("unroll") for (int m = 0; m < 4; ++m) _Pragma("unroll") for (int n = 0; n < 2; ++n) _Pragma("unroll") for (int k = 0; k < 2; ++k) \
;         acc[ai][bj][m][n] = __builtin_amdgcn_mfma_f32_16x16x32_bf16(Bt[n][k], At[m][k], acc[ai][bj][m][n], 0, 0, 0); __builtin_amdgcn_s_setprio(0); } while (0)
; #define PG8_WAIT_V(n) asm volatile("s_waitcnt vmcnt(" #n ")" ::: "memory")
; #define PG8_WAIT_L(n) asm volatile("s_waitcnt lgkmcnt(" #n ")" ::: "memory")
; #define PG8_BAR __builtin_amdgcn_s_barrier()
; #define PG8_SCHED __builtin_amdgcn_sched_barrier(0)
; template <class Epi, bool BSEL = false>
; __device__ __forceinline__ void gemm_phase(LAS unsigned char* lds, const Gemm g, const Order& S, const Epi& E, const int tid) {
;     ...
;             PG8_WAIT_V(8); PG8_WAIT_L(0); PG8_BAR; PG8_MMA(1, 0, At, B0); PG8_MMA(1, 1, At, B1); PG8_BAR; PG8_SCHED;
;             PG8_LDB(B0, 1, 0); PG8_LDB(B1, 1, 1); PG8_SCHED; PG8_LDA(At, 1, 0); PG8_STAGE(PG8_SA(0, 1), a2 + hstepA, voffA);
;             PG8_WAIT_V(8); PG8_WAIT_L(0); PG8_BAR; PG8_MMA(0, 0, At, B0); PG8_MMA(0, 1, At, B1); PG8_BAR; PG8_SCHED;
	v_mfma_f32_16x16x32_bf16 v[60:63], v[132:135], v[196:199], v[60:63]
	v_mfma_f32_16x16x32_bf16 v[56:59], v[140:143], v[196:199], v[56:59]
	v_mfma_f32_16x16x32_bf16 v[52:55], v[132:135], v[206:209], v[52:55]
	v_mfma_f32_16x16x32_bf16 v[48:51], v[140:143], v[206:209], v[48:51]
	v_mfma_f32_16x16x32_bf16 v[44:47], v[132:135], v[214:217], v[44:47]
	v_mfma_f32_16x16x32_bf16 v[40:43], v[140:143], v[214:217], v[40:43]
	v_mfma_f32_16x16x32_bf16 v[36:39], v[132:135], v[222:225], v[36:39]
	v_mfma_f32_16x16x32_bf16 v[32:35], v[140:143], v[222:225], v[32:35]
	v_mfma_f32_16x16x32_bf16 v[60:63], v[136:139], v[202:205], v[60:63]
	v_mfma_f32_16x16x32_bf16 v[56:59], v[176:179], v[202:205], v[56:59]
	v_mfma_f32_16x16x32_bf16 v[52:55], v[136:139], v[210:213], v[52:55]
	v_mfma_f32_16x16x32_bf16 v[48:51], v[176:179], v[210:213], v[48:51]
	v_mfma_f32_16x16x32_bf16 v[44:47], v[136:139], v[218:221], v[44:47]
	v_mfma_f32_16x16x32_bf16 v[40:43], v[176:179], v[218:221], v[40:43]
	v_mfma_f32_16x16x32_bf16 v[36:39], v[136:139], v[226:229], v[36:39]
	v_mfma_f32_16x16x32_bf16 v[32:35], v[176:179], v[226:229], v[32:35]
	v_mfma_f32_16x16x32_bf16 v[28:31], v[180:183], v[196:199], v[28:31]
	v_mfma_f32_16x16x32_bf16 v[24:27], v[188:191], v[196:199], v[24:27]
	v_mfma_f32_16x16x32_bf16 v[20:23], v[180:183], v[206:209], v[20:23]
	v_mfma_f32_16x16x32_bf16 v[16:19], v[188:191], v[206:209], v[16:19]
	v_mfma_f32_16x16x32_bf16 v[12:15], v[180:183], v[214:217], v[12:15]
	v_mfma_f32_16x16x32_bf16 v[8:11], v[188:191], v[214:217], v[8:11]
	v_mfma_f32_16x16x32_bf16 v[4:7], v[180:183], v[222:225], v[4:7]
	v_mfma_f32_16x16x32_bf16 v[0:3], v[188:191], v[222:225], v[0:3]
	v_mfma_f32_16x16x32_bf16 v[28:31], v[184:187], v[202:205], v[28:31]
	v_mfma_f32_16x16x32_bf16 v[24:27], v[192:195], v[202:205], v[24:27]
	v_mfma_f32_16x16x32_bf16 v[20:23], v[184:187], v[210:213], v[20:23]
	v_mfma_f32_16x16x32_bf16 v[16:19], v[192:195], v[210:213], v[16:19]
	v_mfma_f32_16x16x32_bf16 v[12:15], v[184:187], v[218:221], v[12:15]
	v_mfma_f32_16x16x32_bf16 v[8:11], v[192:195], v[218:221], v[8:11]
	v_mfma_f32_16x16x32_bf16 v[4:7], v[184:187], v[226:229], v[4:7]
	v_mfma_f32_16x16x32_bf16 v[0:3], v[192:195], v[226:229], v[0:3]
	s_barrier
	s_add_i32 s57, 0, 0x18000
	s_add_i32 s58, 0, 0x1c000
	v_add_u32_e32 v176, s57, v145
	v_add_u32_e32 v192, s58, v145
	ds_read_b128 v[132:135], v176
	ds_read_b128 v[136:139], v176 offset:1024
	ds_read_b128 v[140:143], v176 offset:2048
	ds_read_b128 v[176:179], v176 offset:3072
	ds_read_b128 v[180:183], v192
	ds_read_b128 v[184:187], v192 offset:1024
	ds_read_b128 v[188:191], v192 offset:2048
	ds_read_b128 v[192:195], v192 offset:3072
	s_add_u32 s38, s38, 0x40000
	s_addc_u32 s39, s39, 0
	s_mov_b32 m0, s40
	v_lshl_add_u64 v[236:237], s[38:39], 0, v[146:147]
	ds_read_b128 v[196:199], v175 offset:32768
	ds_read_b128 v[202:205], v175 offset:33792
	ds_read_b128 v[206:209], v175 offset:34816
	ds_read_b128 v[210:213], v175 offset:35840
	ds_read_b128 v[214:217], v175 offset:36864
	ds_read_b128 v[218:221], v175 offset:37888
	ds_read_b128 v[222:225], v175 offset:38912
	ds_read_b128 v[226:229], v175 offset:39936
	global_load_lds_dwordx4 v[236:237], off
	v_lshl_add_u64 v[236:237], s[38:39], 0, v[148:149]
	s_mov_b32 m0, s41
	s_nop 0
	global_load_lds_dwordx4 v[236:237], off
	s_waitcnt vmcnt(8)
	s_waitcnt lgkmcnt(0)
	s_barrier
	v_mfma_f32_16x16x32_bf16 v[124:127], v[132:135], v[196:199], v[124:127]
	v_mfma_f32_16x16x32_bf16 v[120:123], v[140:143], v[196:199], v[120:123]
	v_mfma_f32_16x16x32_bf16 v[116:119], v[132:135], v[206:209], v[116:119]
	v_mfma_f32_16x16x32_bf16 v[112:115], v[140:143], v[206:209], v[112:115]
	v_mfma_f32_16x16x32_bf16 v[108:111], v[132:135], v[214:217], v[108:111]
	v_mfma_f32_16x16x32_bf16 v[104:107], v[140:143], v[214:217], v[104:107]
	v_mfma_f32_16x16x32_bf16 v[100:103], v[132:135], v[222:225], v[100:103]
	v_mfma_f32_16x16x32_bf16 v[96:99], v[140:143], v[222:225], v[96:99]
	v_mfma_f32_16x16x32_bf16 v[124:127], v[136:139], v[202:205], v[124:127]
	v_mfma_f32_16x16x32_bf16 v[120:123], v[176:179], v[202:205], v[120:123]
	v_mfma_f32_16x16x32_bf16 v[116:119], v[136:139], v[210:213], v[116:119]
	v_mfma_f32_16x16x32_bf16 v[112:115], v[176:179], v[210:213], v[112:115]
	v_mfma_f32_16x16x32_bf16 v[108:111], v[136:139], v[218:221], v[108:111]
	v_mfma_f32_16x16x32_bf16 v[104:107], v[176:179], v[218:221], v[104:107]
	v_mfma_f32_16x16x32_bf16 v[100:103], v[136:139], v[226:229], v[100:103]
	v_mfma_f32_16x16x32_bf16 v[96:99], v[176:179], v[226:229], v[96:99]
	v_mfma_f32_16x16x32_bf16 v[92:95], v[180:183], v[196:199], v[92:95]
	v_mfma_f32_16x16x32_bf16 v[88:91], v[188:191], v[196:199], v[88:91]
	v_mfma_f32_16x16x32_bf16 v[84:87], v[180:183], v[206:209], v[84:87]
	v_mfma_f32_16x16x32_bf16 v[80:83], v[188:191], v[206:209], v[80:83]
	v_mfma_f32_16x16x32_bf16 v[76:79], v[180:183], v[214:217], v[76:79]
	v_mfma_f32_16x16x32_bf16 v[72:75], v[188:191], v[214:217], v[72:75]
	v_mfma_f32_16x16x32_bf16 v[68:71], v[180:183], v[222:225], v[68:71]
	v_mfma_f32_16x16x32_bf16 v[64:67], v[188:191], v[222:225], v[64:67]
	v_mfma_f32_16x16x32_bf16 v[92:95], v[184:187], v[202:205], v[92:95]
	v_mfma_f32_16x16x32_bf16 v[88:91], v[192:195], v[202:205], v[88:91]
	v_mfma_f32_16x16x32_bf16 v[84:87], v[184:187], v[210:213], v[84:87]
	v_mfma_f32_16x16x32_bf16 v[80:83], v[192:195], v[210:213], v[80:83]
	v_mfma_f32_16x16x32_bf16 v[76:79], v[184:187], v[218:221], v[76:79]
	v_mfma_f32_16x16x32_bf16 v[72:75], v[192:195], v[218:221], v[72:75]
	v_mfma_f32_16x16x32_bf16 v[68:71], v[184:187], v[226:229], v[68:71]
	v_mfma_f32_16x16x32_bf16 v[64:67], v[192:195], v[226:229], v[64:67]
	s_barrier
; #define PG8_STAGE(bufoff, gbase, voff) do { _Pragma("unroll") for (int _i = 0; _i < 2; ++_i) \
;         __builtin_amdgcn_global_load_lds((const unsigned*)((const char*)(gbase) + (voff)[_i]), (LAS unsigned*)(lds + (bufoff) + ldsw + _i * 8192), 16, 0, 0); } while (0)
; #define PG8_STAGEB(bufoff, gbase, perm) do { _Pragma("unroll") for (int _i = 0; _i < 2; ++_i) \
;         __builtin_amdgcn_global_load_lds((const unsigned*)((const char*)(gbase) + ((BSEL && (perm)) ? voffBp[_i] : voffB[_i])), (LAS unsigned*)(lds + (bufoff) + ldsw + _i * 8192), 16, 0, 0); } while (0)
; #define PG8_LDA(dst, b, h) do { _Pragma("unroll") for (int m = 0; m < 4; ++m) _Pragma("unroll") for (int k = 0; k < 2; ++k) dst[m][k] = *(const LAS bf16x8*)(lds + PG8_SA(b, h) + aoff + m * 2048 + k * 1024); } while (0)
; #define PG8_MMA(ai, bj, At, Bt) do { __builtin_amdgcn_s_setprio(1); _Pragma("unroll") for (int m = 0; m < 4; ++m) _Pragma("unroll") for (int n = 0; n < 2; ++n) _Pragma("unroll") for (int k = 0; k < 2; ++k) \
;         acc[ai][bj][m][n] = __builtin_amdgcn_mfma_f32_16x16x32_bf16(Bt[n][k], At[m][k], acc[ai][bj][m][n], 0, 0, 0); __builtin_amdgcn_s_setprio(0); } while (0)
; #define PG8_WAIT_V(n) asm volatile("s_waitcnt vmcnt(" #n ")" ::: "memory")
; #define PG8_WAIT_L(n) asm volatile("s_waitcnt lgkmcnt(" #n ")" ::: "memory")
; #define PG8_BAR __builtin_amdgcn_s_barrier()
; #define PG8_SCHED __builtin_amdgcn_sched_barrier(0)
; template <class Epi, bool BSEL = false>
; __device__ __forceinline__ void gemm_phase(LAS unsigned char* lds, const Gemm g, const Order& S, const Epi& E, const int tid) {
;     ...
;             PG8_LDA(At, 1, 1); PG8_STAGEB(PG8_SB(1, 0), b3, p2); PG8_STAGEB(PG8_SB(1, 1), b3 + h2, p2); PG8_STAGE(PG8_SA(1, 0), a3, voffA);
;             PG8_WAIT_V(8); PG8_WAIT_L(0); PG8_BAR; PG8_MMA(1, 0, At, B0); PG8_MMA(1, 1, At, B1); PG8_BAR; PG8_SCHED;
;         }
	s_add_i32 s38, s57, s15
	v_lshl_add_u64 v[172:173], v[172:173], 0, s[10:11]
	s_mov_b32 m0, s38
	ds_read_b128 v[196:199], v175 offset:49152
	ds_read_b128 v[202:205], v175 offset:50176
	ds_read_b128 v[206:209], v175 offset:51200
	ds_read_b128 v[210:213], v175 offset:52224
	ds_read_b128 v[214:217], v175 offset:53248
	ds_read_b128 v[218:221], v175 offset:54272
	ds_read_b128 v[222:225], v175 offset:55296
	ds_read_b128 v[226:229], v175 offset:56320
	global_load_lds_dwordx4 v[172:173], off
	s_add_i32 m0, s38, 0x2000
	s_add_u32 s34, s34, 0x40080
	v_lshl_add_u64 v[172:173], v[230:231], 0, s[10:11]
	s_addc_u32 s35, s35, 0
	s_add_i32 s38, s58, s15
	global_load_lds_dwordx4 v[172:173], off
	v_lshl_add_u64 v[172:173], s[34:35], 0, v[146:147]
	s_mov_b32 m0, s38
	s_nop 0
	global_load_lds_dwordx4 v[172:173], off
	v_lshl_add_u64 v[172:173], s[34:35], 0, v[148:149]
	s_add_i32 m0, s38, 0x2000
	s_nop 0
	global_load_lds_dwordx4 v[172:173], off
	v_lshl_add_u64 v[172:173], v[232:233], 0, s[10:11]
	s_mov_b32 m0, s45
	s_nop 0
	global_load_lds_dwordx4 v[172:173], off
	v_lshl_add_u64 v[172:173], v[234:235], 0, s[10:11]
	s_mov_b32 m0, s46
	s_nop 0
	global_load_lds_dwordx4 v[172:173], off
	s_waitcnt vmcnt(8)
	s_waitcnt lgkmcnt(0)
	s_barrier
	v_mfma_f32_16x16x32_bf16 v[60:63], v[132:135], v[196:199], v[60:63]
	v_mfma_f32_16x16x32_bf16 v[56:59], v[140:143], v[196:199], v[56:59]
	v_mfma_f32_16x16x32_bf16 v[52:55], v[132:135], v[206:209], v[52:55]
	v_mfma_f32_16x16x32_bf16 v[48:51], v[140:143], v[206:209], v[48:51]
	v_mfma_f32_16x16x32_bf16 v[44:47], v[132:135], v[214:217], v[44:47]
	v_mfma_f32_16x16x32_bf16 v[40:43], v[140:143], v[214:217], v[40:43]
	v_mfma_f32_16x16x32_bf16 v[36:39], v[132:135], v[222:225], v[36:39]
	v_mfma_f32_16x16x32_bf16 v[32:35], v[140:143], v[222:225], v[32:35]
	v_mfma_f32_16x16x32_bf16 v[60:63], v[136:139], v[202:205], v[60:63]
	v_mfma_f32_16x16x32_bf16 v[56:59], v[176:179], v[202:205], v[56:59]
	v_mfma_f32_16x16x32_bf16 v[52:55], v[136:139], v[210:213], v[52:55]
	v_mfma_f32_16x16x32_bf16 v[48:51], v[176:179], v[210:213], v[48:51]
	v_mfma_f32_16x16x32_bf16 v[44:47], v[136:139], v[218:221], v[44:47]
	v_mfma_f32_16x16x32_bf16 v[40:43], v[176:179], v[218:221], v[40:43]
	v_mfma_f32_16x16x32_bf16 v[36:39], v[136:139], v[226:229], v[36:39]
	v_mfma_f32_16x16x32_bf16 v[32:35], v[176:179], v[226:229], v[32:35]
	v_mfma_f32_16x16x32_bf16 v[28:31], v[180:183], v[196:199], v[28:31]
	v_mfma_f32_16x16x32_bf16 v[24:27], v[188:191], v[196:199], v[24:27]
	v_mfma_f32_16x16x32_bf16 v[20:23], v[180:183], v[206:209], v[20:23]
	v_mfma_f32_16x16x32_bf16 v[16:19], v[188:191], v[206:209], v[16:19]
	v_mfma_f32_16x16x32_bf16 v[12:15], v[180:183], v[214:217], v[12:15]
	v_mfma_f32_16x16x32_bf16 v[8:11], v[188:191], v[214:217], v[8:11]
	v_mfma_f32_16x16x32_bf16 v[4:7], v[180:183], v[222:225], v[4:7]
	v_mfma_f32_16x16x32_bf16 v[0:3], v[188:191], v[222:225], v[0:3]
	v_mfma_f32_16x16x32_bf16 v[28:31], v[184:187], v[202:205], v[28:31]
	v_mfma_f32_16x16x32_bf16 v[24:27], v[192:195], v[202:205], v[24:27]
	v_mfma_f32_16x16x32_bf16 v[20:23], v[184:187], v[210:213], v[20:23]
	v_mfma_f32_16x16x32_bf16 v[16:19], v[192:195], v[210:213], v[16:19]
	v_mfma_f32_16x16x32_bf16 v[12:15], v[184:187], v[218:221], v[12:15]
	v_mfma_f32_16x16x32_bf16 v[8:11], v[192:195], v[218:221], v[8:11]
	v_mfma_f32_16x16x32_bf16 v[4:7], v[184:187], v[226:229], v[4:7]
	v_mfma_f32_16x16x32_bf16 v[0:3], v[192:195], v[226:229], v[0:3]
	s_barrier
	s_add_i32 s56, s56, 2
	s_add_u32 s2, s2, 0x100
	s_addc_u32 s3, s3, 0
	s_cmp_gt_u32 s56, 13
	s_cbranch_scc0 .LBB0_1072
	s_and_b64 vcc, exec, s[22:23]
	s_cbranch_vccz .LBB0_1075
	s_barrier

; #define PG8_STAGE(bufoff, gbase, voff) do { _Pragma("unroll") for (int _i = 0; _i < 2; ++_i) \
;         __builtin_amdgcn_global_load_lds((const unsigned*)((const char*)(gbase) + (voff)[_i]), (LAS unsigned*)(lds + (bufoff) + ldsw + _i * 8192), 16, 0, 0); } while (0)
; #define PG8_STAGEB(bufoff, gbase, perm) do { _Pragma("unroll") for (int _i = 0; _i < 2; ++_i) \
;         __builtin_amdgcn_global_load_lds((const unsigned*)((const char*)(gbase) + ((BSEL && (perm)) ? voffBp[_i] : voffB[_i])), (LAS unsigned*)(lds + (bufoff) + ldsw + _i * 8192), 16, 0, 0); } while (0)
; #define PG8_LDA(dst, b, h) do { _Pragma("unroll") for (int m = 0; m < 4; ++m) _Pragma("unroll") for (int k = 0; k < 2; ++k) dst[m][k] = *(const LAS bf16x8*)(lds + PG8_SA(b, h) + aoff + m * 2048 + k * 1024); } while (0)
; #define PG8_LDB(dst, b, h) do { _Pragma("unroll") for (int n = 0; n < 2; ++n) _Pragma("unroll") for (int k = 0; k < 2; ++k) dst[n][k] = *(const LAS bf16x8*)(lds + PG8_SB(b, h) + boff + n * 2048 + k * 1024); } while (0)
; #define PG8_WAIT_V(n) asm volatile("s_waitcnt vmcnt(" #n ")" ::: "memory")
; #define PG8_WAIT_L(n) asm volatile("s_waitcnt lgkmcnt(" #n ")" ::: "memory")
; #define PG8_BAR __builtin_amdgcn_s_barrier()
; #define PG8_SCHED __builtin_amdgcn_sched_barrier(0)
; template <class Epi, bool BSEL = false>
; __device__ __forceinline__ void gemm_phase(LAS unsigned char* lds, const Gemm g, const Order& S, const Epi& E, const int tid) {
;     ...
;         for (int t = 0; t < nt; t += 2) {
;             const bool last = (t == nt - 2);
;             const char* a1 = cA + (size_t)(t + 1) * kstep;
;             const char* a2 = last ? nA : cA + (size_t)(t + 2) * kstep; const char* b2 = last ? nB : cB + (size_t)(t + 2) * kstep;
;             const char* a3 = a2 + kstep; const char* b3 = b2 + kstep;
;             const bool p2 = last ? nP : cP; const size_t h2 = last ? nhB : chB;
;             PG8_LDB(B0, 0, 0); PG8_LDB(B1, 0, 1); PG8_SCHED; PG8_LDA(At, 0, 0); PG8_STAGE(PG8_SA(1, 1), a1 + hstepA, voffA);
;             PG8_WAIT_V(8); PG8_WAIT_L(0); PG8_BAR; PG8_MMA(0, 0, At, B0); PG8_MMA(0, 1, At, B1); PG8_BAR; PG8_SCHED;
;             PG8_LDA(At, 0, 1); PG8_STAGEB(PG8_SB(0, 0), b2, p2); PG8_STAGEB(PG8_SB(0, 1), b2 + h2, p2); PG8_STAGE(PG8_SA(0, 0), a2, voffA);
;             PG8_WAIT_V(8); PG8_WAIT_L(0); PG8_BAR; PG8_MMA(1, 0, At, B0); PG8_MMA(1, 1, At, B1); PG8_BAR; PG8_SCHED;
.LBB0_1101:
	v_add_u32_e32 v164, s47, v129
	v_add_u32_e32 v180, s48, v129
	s_add_u32 s40, s8, s38
	ds_read_b128 v[152:155], v164
	ds_read_b128 v[156:159], v164 offset:1024
	ds_read_b128 v[160:163], v164 offset:2048
	ds_read_b128 v[164:167], v164 offset:3072
	ds_read_b128 v[168:171], v180
	ds_read_b128 v[172:175], v180 offset:1024
	ds_read_b128 v[176:179], v180 offset:2048
	ds_read_b128 v[180:183], v180 offset:3072
	s_addc_u32 s41, s9, s39
	s_add_u32 s40, s40, 0x100
	s_addc_u32 s41, s41, 0
	s_add_u32 s56, s27, s38
	s_addc_u32 s57, s35, s39
	s_cmpk_eq_i32 s38, 0x700
	s_cselect_b32 s43, s51, s41
	s_cselect_b32 s42, s52, s40
	s_cselect_b32 s41, s53, s57
	s_cselect_b32 s40, s54, s56
	v_lshl_add_u64 v[188:189], v[146:147], 0, s[38:39]
	s_add_i32 m0, s7, 0xc000
	ds_read_b128 v[184:187], v151
	ds_read_b128 v[192:195], v151 offset:1024
	ds_read_b128 v[196:199], v151 offset:2048
	ds_read_b128 v[202:205], v151 offset:3072
	ds_read_b128 v[206:209], v151 offset:4096
	ds_read_b128 v[210:213], v151 offset:5120
	ds_read_b128 v[214:217], v151 offset:6144
	ds_read_b128 v[218:221], v151 offset:7168
	global_load_lds_dwordx4 v[188:189], off
	v_lshl_add_u64 v[188:189], v[148:149], 0, s[38:39]
	s_add_i32 m0, s7, 0xe000
	s_nop 0
	global_load_lds_dwordx4 v[188:189], off
	s_waitcnt vmcnt(8)
	s_waitcnt lgkmcnt(0)
	s_barrier
	v_mfma_f32_16x16x32_bf16 v[124:127], v[152:155], v[184:187], v[124:127]
	v_mfma_f32_16x16x32_bf16 v[120:123], v[160:163], v[184:187], v[120:123]
	v_mfma_f32_16x16x32_bf16 v[108:111], v[152:155], v[196:199], v[108:111]
	v_mfma_f32_16x16x32_bf16 v[104:107], v[160:163], v[196:199], v[104:107]
	v_mfma_f32_16x16x32_bf16 v[92:95], v[152:155], v[206:209], v[92:95]
	v_mfma_f32_16x16x32_bf16 v[88:91], v[160:163], v[206:209], v[88:91]
	v_mfma_f32_16x16x32_bf16 v[76:79], v[152:155], v[214:217], v[76:79]
	v_mfma_f32_16x16x32_bf16 v[72:75], v[160:163], v[214:217], v[72:75]
	v_mfma_f32_16x16x32_bf16 v[124:127], v[156:159], v[192:195], v[124:127]
	v_mfma_f32_16x16x32_bf16 v[120:123], v[164:167], v[192:195], v[120:123]
	v_mfma_f32_16x16x32_bf16 v[108:111], v[156:159], v[202:205], v[108:111]
	v_mfma_f32_16x16x32_bf16 v[104:107], v[164:167], v[202:205], v[104:107]
	v_mfma_f32_16x16x32_bf16 v[92:95], v[156:159], v[210:213], v[92:95]
	v_mfma_f32_16x16x32_bf16 v[88:91], v[164:167], v[210:213], v[88:91]
	v_mfma_f32_16x16x32_bf16 v[76:79], v[156:159], v[218:221], v[76:79]
	v_mfma_f32_16x16x32_bf16 v[72:75], v[164:167], v[218:221], v[72:75]
	v_mfma_f32_16x16x32_bf16 v[116:119], v[168:171], v[184:187], v[116:119]
	v_mfma_f32_16x16x32_bf16 v[112:115], v[176:179], v[184:187], v[112:115]
	v_mfma_f32_16x16x32_bf16 v[100:103], v[168:171], v[196:199], v[100:103]
	v_mfma_f32_16x16x32_bf16 v[96:99], v[176:179], v[196:199], v[96:99]
	v_mfma_f32_16x16x32_bf16 v[84:87], v[168:171], v[206:209], v[84:87]
	v_mfma_f32_16x16x32_bf16 v[80:83], v[176:179], v[206:209], v[80:83]
	v_mfma_f32_16x16x32_bf16 v[68:71], v[168:171], v[214:217], v[68:71]
	v_mfma_f32_16x16x32_bf16 v[64:67], v[176:179], v[214:217], v[64:67]
	v_mfma_f32_16x16x32_bf16 v[116:119], v[172:175], v[192:195], v[116:119]
	v_mfma_f32_16x16x32_bf16 v[112:115], v[180:183], v[192:195], v[112:115]
	v_mfma_f32_16x16x32_bf16 v[100:103], v[172:175], v[202:205], v[100:103]
	v_mfma_f32_16x16x32_bf16 v[96:99], v[180:183], v[202:205], v[96:99]
	v_mfma_f32_16x16x32_bf16 v[84:87], v[172:175], v[210:213], v[84:87]
	v_mfma_f32_16x16x32_bf16 v[80:83], v[180:183], v[210:213], v[80:83]
	v_mfma_f32_16x16x32_bf16 v[68:71], v[172:175], v[218:221], v[68:71]
	v_mfma_f32_16x16x32_bf16 v[64:67], v[180:183], v[218:221], v[64:67]
	s_barrier
	s_add_i32 s56, s47, s15
	v_lshl_add_u64 v[188:189], s[40:41], 0, v[132:133]
	s_mov_b32 m0, s56
	ds_read_b128 v[184:187], v151 offset:16384
	ds_read_b128 v[192:195], v151 offset:17408
	ds_read_b128 v[196:199], v151 offset:18432
	ds_read_b128 v[202:205], v151 offset:19456
	ds_read_b128 v[206:209], v151 offset:20480
	ds_read_b128 v[210:213], v151 offset:21504
	ds_read_b128 v[214:217], v151 offset:22528
	ds_read_b128 v[218:221], v151 offset:23552
	global_load_lds_dwordx4 v[188:189], off
	s_add_i32 m0, s56, 0x2000
	s_add_u32 s56, s40, 0x40000
	v_lshl_add_u64 v[222:223], s[40:41], 0, v[136:137]
	s_addc_u32 s57, s41, 0
	s_add_i32 s58, s48, s15
	global_load_lds_dwordx4 v[222:223], off
	v_lshl_add_u64 v[224:225], s[56:57], 0, v[132:133]
	s_mov_b32 m0, s58
	v_lshl_add_u64 v[226:227], s[42:43], 0, v[134:135]
	global_load_lds_dwordx4 v[224:225], off
	v_lshl_add_u64 v[224:225], s[56:57], 0, v[136:137]
	s_add_i32 m0, s58, 0x2000
	s_nop 0
	global_load_lds_dwordx4 v[224:225], off
	v_lshl_add_u64 v[224:225], s[42:43], 0, v[130:131]
	s_mov_b32 m0, s7
	s_nop 0
	global_load_lds_dwordx4 v[224:225], off
	s_mov_b32 m0, s20
	s_nop 0
	global_load_lds_dwordx4 v[226:227], off
	s_waitcnt vmcnt(8)
	s_waitcnt lgkmcnt(0)
	s_barrier
; #define PG8_STAGE(bufoff, gbase, voff) do { _Pragma("unroll") for (int _i = 0; _i < 2; ++_i) \
;         __builtin_amdgcn_global_load_lds((const unsigned*)((const char*)(gbase) + (voff)[_i]), (LAS unsigned*)(lds + (bufoff) + ldsw + _i * 8192), 16, 0, 0); } while (0)
; #define PG8_LDA(dst, b, h) do { _Pragma("unroll") for (int m = 0; m < 4; ++m) _Pragma("unroll") for (int k = 0; k < 2; ++k) dst[m][k] = *(const LAS bf16x8*)(lds + PG8_SA(b, h) + aoff + m * 2048 + k * 1024); } while (0)
; #define PG8_LDB(dst, b, h) do { _Pragma("unroll") for (int n = 0; n < 2; ++n) _Pragma("unroll") for (int k = 0; k < 2; ++k) dst[n][k] = *(const LAS bf16x8*)(lds + PG8_SB(b, h) + boff + n * 2048 + k * 1024); } while (0)
; #define PG8_MMA(ai, bj, At, Bt) do { __builtin_amdgcn_s_setprio(1); _Pragma("unroll") for (int m = 0; m < 4; ++m) _Pragma("unroll") for (int n = 0; n < 2; ++n) _Pragma("unroll") for (int k = 0; k < 2; ++k) \
;         acc[ai][bj][m][n] = __builtin_amdgcn_mfma_f32_16x16x32_bf16(Bt[n][k], At[m][k], acc[ai][bj][m][n], 0, 0, 0); __builtin_amdgcn_s_setprio(0); } while (0)
; #define PG8_WAIT_V(n) asm volatile("s_waitcnt vmcnt(" #n ")" ::: "memory")
; #define PG8_WAIT_L(n) asm volatile("s_waitcnt lgkmcnt(" #n ")" ::: "memory")
; #define PG8_BAR __builtin_amdgcn_s_barrier()
; #define PG8_SCHED __builtin_amdgcn_sched_barrier(0)
; template <class Epi, bool BSEL = false>
; __device__ __forceinline__ void gemm_phase(LAS unsigned char* lds, const Gemm g, const Order& S, const Epi& E, const int tid) {
;     ...
;             PG8_WAIT_V(8); PG8_WAIT_L(0); PG8_BAR; PG8_MMA(1, 0, At, B0); PG8_MMA(1, 1, At, B1); PG8_BAR; PG8_SCHED;
;             PG8_LDB(B0, 1, 0); PG8_LDB(B1, 1, 1); PG8_SCHED; PG8_LDA(At, 1, 0); PG8_STAGE(PG8_SA(0, 1), a2 + hstepA, voffA);
;             PG8_WAIT_V(8); PG8_WAIT_L(0); PG8_BAR; PG8_MMA(0, 0, At, B0); PG8_MMA(0, 1, At, B1); PG8_BAR; PG8_SCHED;
	v_mfma_f32_16x16x32_bf16 v[60:63], v[152:155], v[184:187], v[60:63]
	v_mfma_f32_16x16x32_bf16 v[56:59], v[160:163], v[184:187], v[56:59]
	v_mfma_f32_16x16x32_bf16 v[44:47], v[152:155], v[196:199], v[44:47]
	v_mfma_f32_16x16x32_bf16 v[40:43], v[160:163], v[196:199], v[40:43]
	v_mfma_f32_16x16x32_bf16 v[28:31], v[152:155], v[206:209], v[28:31]
	v_mfma_f32_16x16x32_bf16 v[24:27], v[160:163], v[206:209], v[24:27]
	v_mfma_f32_16x16x32_bf16 v[12:15], v[152:155], v[214:217], v[12:15]
	v_mfma_f32_16x16x32_bf16 v[8:11], v[160:163], v[214:217], v[8:11]
	v_mfma_f32_16x16x32_bf16 v[60:63], v[156:159], v[192:195], v[60:63]
	v_mfma_f32_16x16x32_bf16 v[56:59], v[164:167], v[192:195], v[56:59]
	v_mfma_f32_16x16x32_bf16 v[44:47], v[156:159], v[202:205], v[44:47]
	v_mfma_f32_16x16x32_bf16 v[40:43], v[164:167], v[202:205], v[40:43]
	v_mfma_f32_16x16x32_bf16 v[28:31], v[156:159], v[210:213], v[28:31]
	v_mfma_f32_16x16x32_bf16 v[24:27], v[164:167], v[210:213], v[24:27]
	v_mfma_f32_16x16x32_bf16 v[12:15], v[156:159], v[218:221], v[12:15]
	v_mfma_f32_16x16x32_bf16 v[8:11], v[164:167], v[218:221], v[8:11]
	v_mfma_f32_16x16x32_bf16 v[52:55], v[168:171], v[184:187], v[52:55]
	v_mfma_f32_16x16x32_bf16 v[48:51], v[176:179], v[184:187], v[48:51]
	v_mfma_f32_16x16x32_bf16 v[36:39], v[168:171], v[196:199], v[36:39]
	v_mfma_f32_16x16x32_bf16 v[32:35], v[176:179], v[196:199], v[32:35]
	v_mfma_f32_16x16x32_bf16 v[20:23], v[168:171], v[206:209], v[20:23]
	v_mfma_f32_16x16x32_bf16 v[16:19], v[176:179], v[206:209], v[16:19]
	v_mfma_f32_16x16x32_bf16 v[4:7], v[168:171], v[214:217], v[4:7]
	v_mfma_f32_16x16x32_bf16 v[0:3], v[176:179], v[214:217], v[0:3]
	v_mfma_f32_16x16x32_bf16 v[52:55], v[172:175], v[192:195], v[52:55]
	v_mfma_f32_16x16x32_bf16 v[48:51], v[180:183], v[192:195], v[48:51]
	v_mfma_f32_16x16x32_bf16 v[36:39], v[172:175], v[202:205], v[36:39]
	v_mfma_f32_16x16x32_bf16 v[32:35], v[180:183], v[202:205], v[32:35]
	v_mfma_f32_16x16x32_bf16 v[20:23], v[172:175], v[210:213], v[20:23]
	v_mfma_f32_16x16x32_bf16 v[16:19], v[180:183], v[210:213], v[16:19]
	v_mfma_f32_16x16x32_bf16 v[4:7], v[172:175], v[218:221], v[4:7]
	v_mfma_f32_16x16x32_bf16 v[0:3], v[180:183], v[218:221], v[0:3]
	s_barrier
	s_add_i32 s56, 0, 0x18000
	s_add_i32 s57, 0, 0x1c000
	v_add_u32_e32 v164, s56, v129
	v_add_u32_e32 v180, s57, v129
	ds_read_b128 v[152:155], v164
	ds_read_b128 v[156:159], v164 offset:1024
	ds_read_b128 v[160:163], v164 offset:2048
	ds_read_b128 v[164:167], v164 offset:3072
	ds_read_b128 v[168:171], v180
	ds_read_b128 v[172:175], v180 offset:1024
	ds_read_b128 v[176:179], v180 offset:2048
	ds_read_b128 v[180:183], v180 offset:3072
	s_add_u32 s42, s42, 0x40000
	s_addc_u32 s43, s43, 0
	s_mov_b32 m0, s21
	v_lshl_add_u64 v[228:229], s[42:43], 0, v[130:131]
	ds_read_b128 v[184:187], v151 offset:32768
	ds_read_b128 v[192:195], v151 offset:33792
	ds_read_b128 v[196:199], v151 offset:34816
	ds_read_b128 v[202:205], v151 offset:35840
	ds_read_b128 v[206:209], v151 offset:36864
	ds_read_b128 v[210:213], v151 offset:37888
	ds_read_b128 v[214:217], v151 offset:38912
	ds_read_b128 v[218:221], v151 offset:39936
	global_load_lds_dwordx4 v[228:229], off
	v_lshl_add_u64 v[228:229], s[42:43], 0, v[134:135]
	s_mov_b32 m0, s44
	s_nop 0
	global_load_lds_dwordx4 v[228:229], off
	s_waitcnt vmcnt(8)
	s_waitcnt lgkmcnt(0)
	s_barrier
	v_mfma_f32_16x16x32_bf16 v[124:127], v[152:155], v[184:187], v[124:127]
	v_mfma_f32_16x16x32_bf16 v[120:123], v[160:163], v[184:187], v[120:123]
	v_mfma_f32_16x16x32_bf16 v[108:111], v[152:155], v[196:199], v[108:111]
	v_mfma_f32_16x16x32_bf16 v[104:107], v[160:163], v[196:199], v[104:107]
	v_mfma_f32_16x16x32_bf16 v[92:95], v[152:155], v[206:209], v[92:95]
	v_mfma_f32_16x16x32_bf16 v[88:91], v[160:163], v[206:209], v[88:91]
	v_mfma_f32_16x16x32_bf16 v[76:79], v[152:155], v[214:217], v[76:79]
	v_mfma_f32_16x16x32_bf16 v[72:75], v[160:163], v[214:217], v[72:75]
	v_mfma_f32_16x16x32_bf16 v[124:127], v[156:159], v[192:195], v[124:127]
	v_mfma_f32_16x16x32_bf16 v[120:123], v[164:167], v[192:195], v[120:123]
	v_mfma_f32_16x16x32_bf16 v[108:111], v[156:159], v[202:205], v[108:111]
	v_mfma_f32_16x16x32_bf16 v[104:107], v[164:167], v[202:205], v[104:107]
	v_mfma_f32_16x16x32_bf16 v[92:95], v[156:159], v[210:213], v[92:95]
	v_mfma_f32_16x16x32_bf16 v[88:91], v[164:167], v[210:213], v[88:91]
	v_mfma_f32_16x16x32_bf16 v[76:79], v[156:159], v[218:221], v[76:79]
	v_mfma_f32_16x16x32_bf16 v[72:75], v[164:167], v[218:221], v[72:75]
	v_mfma_f32_16x16x32_bf16 v[116:119], v[168:171], v[184:187], v[116:119]
	v_mfma_f32_16x16x32_bf16 v[112:115], v[176:179], v[184:187], v[112:115]
	v_mfma_f32_16x16x32_bf16 v[100:103], v[168:171], v[196:199], v[100:103]
	v_mfma_f32_16x16x32_bf16 v[96:99], v[176:179], v[196:199], v[96:99]
	v_mfma_f32_16x16x32_bf16 v[84:87], v[168:171], v[206:209], v[84:87]
	v_mfma_f32_16x16x32_bf16 v[80:83], v[176:179], v[206:209], v[80:83]
	v_mfma_f32_16x16x32_bf16 v[68:71], v[168:171], v[214:217], v[68:71]
	v_mfma_f32_16x16x32_bf16 v[64:67], v[176:179], v[214:217], v[64:67]
	v_mfma_f32_16x16x32_bf16 v[116:119], v[172:175], v[192:195], v[116:119]
	v_mfma_f32_16x16x32_bf16 v[112:115], v[180:183], v[192:195], v[112:115]
	v_mfma_f32_16x16x32_bf16 v[100:103], v[172:175], v[202:205], v[100:103]
	v_mfma_f32_16x16x32_bf16 v[96:99], v[180:183], v[202:205], v[96:99]
	v_mfma_f32_16x16x32_bf16 v[84:87], v[172:175], v[210:213], v[84:87]
	v_mfma_f32_16x16x32_bf16 v[80:83], v[180:183], v[210:213], v[80:83]
	v_mfma_f32_16x16x32_bf16 v[68:71], v[172:175], v[218:221], v[68:71]
	v_mfma_f32_16x16x32_bf16 v[64:67], v[180:183], v[218:221], v[64:67]
	s_barrier
; #define PG8_STAGE(bufoff, gbase, voff) do { _Pragma("unroll") for (int _i = 0; _i < 2; ++_i) \
;         __builtin_amdgcn_global_load_lds((const unsigned*)((const char*)(gbase) + (voff)[_i]), (LAS unsigned*)(lds + (bufoff) + ldsw + _i * 8192), 16, 0, 0); } while (0)
; #define PG8_STAGEB(bufoff, gbase, perm) do { _Pragma("unroll") for (int _i = 0; _i < 2; ++_i) \
;         __builtin_amdgcn_global_load_lds((const unsigned*)((const char*)(gbase) + ((BSEL && (perm)) ? voffBp[_i] : voffB[_i])), (LAS unsigned*)(lds + (bufoff) + ldsw + _i * 8192), 16, 0, 0); } while (0)
; #define PG8_LDA(dst, b, h) do { _Pragma("unroll") for (int m = 0; m < 4; ++m) _Pragma("unroll") for (int k = 0; k < 2; ++k) dst[m][k] = *(const LAS bf16x8*)(lds + PG8_SA(b, h) + aoff + m * 2048 + k * 1024); } while (0)
; #define PG8_MMA(ai, bj, At, Bt) do { __builtin_amdgcn_s_setprio(1); _Pragma("unroll") for (int m = 0; m < 4; ++m) _Pragma("unroll") for (int n = 0; n < 2; ++n) _Pragma("unroll") for (int k = 0; k < 2; ++k) \
;         acc[ai][bj][m][n] = __builtin_amdgcn_mfma_f32_16x16x32_bf16(Bt[n][k], At[m][k], acc[ai][bj][m][n], 0, 0, 0); __builtin_amdgcn_s_setprio(0); } while (0)
; #define PG8_WAIT_V(n) asm volatile("s_waitcnt vmcnt(" #n ")" ::: "memory")
; #define PG8_WAIT_L(n) asm volatile("s_waitcnt lgkmcnt(" #n ")" ::: "memory")
; #define PG8_BAR __builtin_amdgcn_s_barrier()
; #define PG8_SCHED __builtin_amdgcn_sched_barrier(0)
; template <class Epi, bool BSEL = false>
; __device__ __forceinline__ void gemm_phase(LAS unsigned char* lds, const Gemm g, const Order& S, const Epi& E, const int tid) {
;     ...
;             PG8_LDA(At, 1, 1); PG8_STAGEB(PG8_SB(1, 0), b3, p2); PG8_STAGEB(PG8_SB(1, 1), b3 + h2, p2); PG8_STAGE(PG8_SA(1, 0), a3, voffA);
;             PG8_WAIT_V(8); PG8_WAIT_L(0); PG8_BAR; PG8_MMA(1, 0, At, B0); PG8_MMA(1, 1, At, B1); PG8_BAR; PG8_SCHED;
;         }
;         if constexpr (ALIGN_EPI) { if (wr == 0) PG8_BAR; }
	s_add_i32 s42, s56, s15
	v_lshl_add_u64 v[188:189], v[188:189], 0, s[22:23]
	s_mov_b32 m0, s42
	ds_read_b128 v[184:187], v151 offset:49152
	ds_read_b128 v[192:195], v151 offset:50176
	ds_read_b128 v[196:199], v151 offset:51200
	ds_read_b128 v[202:205], v151 offset:52224
	ds_read_b128 v[206:209], v151 offset:53248
	ds_read_b128 v[210:213], v151 offset:54272
	ds_read_b128 v[214:217], v151 offset:55296
	ds_read_b128 v[218:221], v151 offset:56320
	global_load_lds_dwordx4 v[188:189], off
	s_add_i32 m0, s42, 0x2000
	s_add_u32 s40, s40, 0x40080
	v_lshl_add_u64 v[188:189], v[222:223], 0, s[22:23]
	s_addc_u32 s41, s41, 0
	s_add_i32 s42, s57, s15
	global_load_lds_dwordx4 v[188:189], off
	v_lshl_add_u64 v[188:189], s[40:41], 0, v[132:133]
	s_mov_b32 m0, s42
	s_nop 0
	global_load_lds_dwordx4 v[188:189], off
	v_lshl_add_u64 v[188:189], s[40:41], 0, v[136:137]
	s_add_i32 m0, s42, 0x2000
	s_nop 0
	global_load_lds_dwordx4 v[188:189], off
	v_lshl_add_u64 v[188:189], v[224:225], 0, s[22:23]
	s_mov_b32 m0, s45
	s_nop 0
	global_load_lds_dwordx4 v[188:189], off
	v_lshl_add_u64 v[188:189], v[226:227], 0, s[22:23]
	s_mov_b32 m0, s46
	s_nop 0
	global_load_lds_dwordx4 v[188:189], off
	s_waitcnt vmcnt(8)
	s_waitcnt lgkmcnt(0)
	s_barrier
	v_mfma_f32_16x16x32_bf16 v[60:63], v[152:155], v[184:187], v[60:63]
	v_mfma_f32_16x16x32_bf16 v[56:59], v[160:163], v[184:187], v[56:59]
	v_mfma_f32_16x16x32_bf16 v[44:47], v[152:155], v[196:199], v[44:47]
	v_mfma_f32_16x16x32_bf16 v[40:43], v[160:163], v[196:199], v[40:43]
	v_mfma_f32_16x16x32_bf16 v[28:31], v[152:155], v[206:209], v[28:31]
	v_mfma_f32_16x16x32_bf16 v[24:27], v[160:163], v[206:209], v[24:27]
	v_mfma_f32_16x16x32_bf16 v[12:15], v[152:155], v[214:217], v[12:15]
	v_mfma_f32_16x16x32_bf16 v[8:11], v[160:163], v[214:217], v[8:11]
	v_mfma_f32_16x16x32_bf16 v[60:63], v[156:159], v[192:195], v[60:63]
	v_mfma_f32_16x16x32_bf16 v[56:59], v[164:167], v[192:195], v[56:59]
	v_mfma_f32_16x16x32_bf16 v[44:47], v[156:159], v[202:205], v[44:47]
	v_mfma_f32_16x16x32_bf16 v[40:43], v[164:167], v[202:205], v[40:43]
	v_mfma_f32_16x16x32_bf16 v[28:31], v[156:159], v[210:213], v[28:31]
	v_mfma_f32_16x16x32_bf16 v[24:27], v[164:167], v[210:213], v[24:27]
	v_mfma_f32_16x16x32_bf16 v[12:15], v[156:159], v[218:221], v[12:15]
	v_mfma_f32_16x16x32_bf16 v[8:11], v[164:167], v[218:221], v[8:11]
	v_mfma_f32_16x16x32_bf16 v[52:55], v[168:171], v[184:187], v[52:55]
	v_mfma_f32_16x16x32_bf16 v[48:51], v[176:179], v[184:187], v[48:51]
	v_mfma_f32_16x16x32_bf16 v[36:39], v[168:171], v[196:199], v[36:39]
	v_mfma_f32_16x16x32_bf16 v[32:35], v[176:179], v[196:199], v[32:35]
	v_mfma_f32_16x16x32_bf16 v[20:23], v[168:171], v[206:209], v[20:23]
	v_mfma_f32_16x16x32_bf16 v[16:19], v[176:179], v[206:209], v[16:19]
	v_mfma_f32_16x16x32_bf16 v[4:7], v[168:171], v[214:217], v[4:7]
	v_mfma_f32_16x16x32_bf16 v[0:3], v[176:179], v[214:217], v[0:3]
	v_mfma_f32_16x16x32_bf16 v[52:55], v[172:175], v[192:195], v[52:55]
	v_mfma_f32_16x16x32_bf16 v[48:51], v[180:183], v[192:195], v[48:51]
	v_mfma_f32_16x16x32_bf16 v[36:39], v[172:175], v[202:205], v[36:39]
	v_mfma_f32_16x16x32_bf16 v[32:35], v[180:183], v[202:205], v[32:35]
	v_mfma_f32_16x16x32_bf16 v[20:23], v[172:175], v[210:213], v[20:23]
	v_mfma_f32_16x16x32_bf16 v[16:19], v[180:183], v[210:213], v[16:19]
	v_mfma_f32_16x16x32_bf16 v[4:7], v[172:175], v[218:221], v[4:7]
	v_mfma_f32_16x16x32_bf16 v[0:3], v[180:183], v[218:221], v[0:3]
	s_barrier
	s_add_i32 s55, s55, 2
	s_add_u32 s38, s38, 0x100
	s_addc_u32 s39, s39, 0
	s_cmp_gt_u32 s55, 13
	s_cbranch_scc0 .LBB0_1101
	s_and_b64 vcc, exec, s[24:25]
	s_cbranch_vccz .LBB0_1104
	s_barrier

; #define PG8_STAGE(bufoff, gbase, voff) do { _Pragma("unroll") for (int _i = 0; _i < 2; ++_i) \
;         __builtin_amdgcn_global_load_lds((const unsigned*)((const char*)(gbase) + (voff)[_i]), (LAS unsigned*)(lds + (bufoff) + ldsw + _i * 8192), 16, 0, 0); } while (0)
; #define PG8_STAGEB(bufoff, gbase, perm) do { _Pragma("unroll") for (int _i = 0; _i < 2; ++_i) \
;         __builtin_amdgcn_global_load_lds((const unsigned*)((const char*)(gbase) + ((BSEL && (perm)) ? voffBp[_i] : voffB[_i])), (LAS unsigned*)(lds + (bufoff) + ldsw + _i * 8192), 16, 0, 0); } while (0)
; #define PG8_LDA(dst, b, h) do { _Pragma("unroll") for (int m = 0; m < 4; ++m) _Pragma("unroll") for (int k = 0; k < 2; ++k) dst[m][k] = *(const LAS bf16x8*)(lds + PG8_SA(b, h) + aoff + m * 2048 + k * 1024); } while (0)
; #define PG8_LDB(dst, b, h) do { _Pragma("unroll") for (int n = 0; n < 2; ++n) _Pragma("unroll") for (int k = 0; k < 2; ++k) dst[n][k] = *(const LAS bf16x8*)(lds + PG8_SB(b, h) + boff + n * 2048 + k * 1024); } while (0)
; template <class Epi, bool BSEL = false>
; __device__ __forceinline__ void gemm_phase(LAS unsigned char* lds, const Gemm g, const Order& S, const Epi& E, const int tid) {
;     ...
;         for (int t = 0; t < nt; t += 2) {
;             const bool last = (t == nt - 2);
;             const char* a1 = cA + (size_t)(t + 1) * kstep;
;             const char* a2 = last ? nA : cA + (size_t)(t + 2) * kstep; const char* b2 = last ? nB : cB + (size_t)(t + 2) * kstep;
;             const char* a3 = a2 + kstep; const char* b3 = b2 + kstep;
;             const bool p2 = last ? nP : cP; const size_t h2 = last ? nhB : chB;
;             PG8_LDB(B0, 0, 0); PG8_LDB(B1, 0, 1); PG8_SCHED; PG8_LDA(At, 0, 0); PG8_STAGE(PG8_SA(1, 1), a1 + hstepA, voffA);
;             PG8_WAIT_V(8); PG8_WAIT_L(0); PG8_BAR; PG8_MMA(0, 0, At, B0); PG8_MMA(0, 1, At, B1); PG8_BAR; PG8_SCHED;
;             PG8_LDA(At, 0, 1); PG8_STAGEB(PG8_SB(0, 0), b2, p2); PG8_STAGEB(PG8_SB(0, 1), b2 + h2, p2); PG8_STAGE(PG8_SA(0, 0), a2, voffA);
;             PG8_WAIT_V(8); PG8_WAIT_L(0); PG8_BAR; PG8_MMA(1, 0, At, B0); PG8_MMA(1, 1, At, B1); PG8_BAR; PG8_SCHED;
;             PG8_LDB(B0, 1, 0); PG8_LDB(B1, 1, 1); PG8_SCHED; PG8_LDA(At, 1, 0); PG8_STAGE(PG8_SA(0, 1), a2 + hstepA, voffA);
;             PG8_WAIT_V(8); PG8_WAIT_L(0); PG8_BAR; PG8_MMA(0, 0, At, B0); PG8_MMA(0, 1, At, B1); PG8_BAR; PG8_SCHED;
.LBB0_1271:
	v_add_u32_e32 v162, s45, v147
	v_add_u32_e32 v178, s46, v147
	s_add_u32 s2, s8, s40
	ds_read_b128 v[150:153], v162
	ds_read_b128 v[154:157], v162 offset:1024
	ds_read_b128 v[158:161], v162 offset:2048
	ds_read_b128 v[162:165], v162 offset:3072
	ds_read_b128 v[166:169], v178
	ds_read_b128 v[170:173], v178 offset:1024
	ds_read_b128 v[174:177], v178 offset:2048
	ds_read_b128 v[178:181], v178 offset:3072
	s_addc_u32 s3, s9, s41
	s_add_u32 s2, s2, 0x100
	s_addc_u32 s3, s3, 0
	s_add_u32 s57, s27, s40
	s_addc_u32 s58, s51, s41
	s_cmpk_eq_i32 s40, 0x700
	s_cselect_b32 s37, s52, s3
	s_cselect_b32 s36, s53, s2
	s_cselect_b32 s3, s54, s58
	s_cselect_b32 s2, s55, s57
	v_lshl_add_u64 v[198:199], v[142:143], 0, s[40:41]
	s_add_i32 m0, s7, 0xc000
	ds_read_b128 v[182:185], v149
	ds_read_b128 v[186:189], v149 offset:1024
	ds_read_b128 v[190:193], v149 offset:2048
	ds_read_b128 v[194:197], v149 offset:3072
	ds_read_b128 v[202:205], v149 offset:4096
	ds_read_b128 v[206:209], v149 offset:5120
	ds_read_b128 v[210:213], v149 offset:6144
	ds_read_b128 v[214:217], v149 offset:7168
	global_load_lds_dwordx4 v[198:199], off
	v_lshl_add_u64 v[198:199], v[144:145], 0, s[40:41]
	s_add_i32 m0, s7, 0xe000
	s_nop 0
	global_load_lds_dwordx4 v[198:199], off
	s_waitcnt vmcnt(8)
	s_waitcnt lgkmcnt(0)
	s_barrier
	v_mfma_f32_16x16x32_bf16 v[124:127], v[150:153], v[182:185], v[124:127]
	v_mfma_f32_16x16x32_bf16 v[120:123], v[158:161], v[182:185], v[120:123]
	v_mfma_f32_16x16x32_bf16 v[116:119], v[150:153], v[190:193], v[116:119]
	v_mfma_f32_16x16x32_bf16 v[112:115], v[158:161], v[190:193], v[112:115]
	v_mfma_f32_16x16x32_bf16 v[108:111], v[150:153], v[202:205], v[108:111]
	v_mfma_f32_16x16x32_bf16 v[104:107], v[158:161], v[202:205], v[104:107]
	v_mfma_f32_16x16x32_bf16 v[100:103], v[150:153], v[210:213], v[100:103]
	v_mfma_f32_16x16x32_bf16 v[96:99], v[158:161], v[210:213], v[96:99]
	v_mfma_f32_16x16x32_bf16 v[124:127], v[154:157], v[186:189], v[124:127]
	v_mfma_f32_16x16x32_bf16 v[120:123], v[162:165], v[186:189], v[120:123]
	v_mfma_f32_16x16x32_bf16 v[116:119], v[154:157], v[194:197], v[116:119]
	v_mfma_f32_16x16x32_bf16 v[112:115], v[162:165], v[194:197], v[112:115]
	v_mfma_f32_16x16x32_bf16 v[108:111], v[154:157], v[206:209], v[108:111]
	v_mfma_f32_16x16x32_bf16 v[104:107], v[162:165], v[206:209], v[104:107]
	v_mfma_f32_16x16x32_bf16 v[100:103], v[154:157], v[214:217], v[100:103]
	v_mfma_f32_16x16x32_bf16 v[96:99], v[162:165], v[214:217], v[96:99]
	v_mfma_f32_16x16x32_bf16 v[92:95], v[166:169], v[182:185], v[92:95]
	v_mfma_f32_16x16x32_bf16 v[88:91], v[174:177], v[182:185], v[88:91]
	v_mfma_f32_16x16x32_bf16 v[84:87], v[166:169], v[190:193], v[84:87]
	v_mfma_f32_16x16x32_bf16 v[80:83], v[174:177], v[190:193], v[80:83]
	v_mfma_f32_16x16x32_bf16 v[76:79], v[166:169], v[202:205], v[76:79]
	v_mfma_f32_16x16x32_bf16 v[72:75], v[174:177], v[202:205], v[72:75]
	v_mfma_f32_16x16x32_bf16 v[68:71], v[166:169], v[210:213], v[68:71]
	v_mfma_f32_16x16x32_bf16 v[64:67], v[174:177], v[210:213], v[64:67]
	v_mfma_f32_16x16x32_bf16 v[92:95], v[170:173], v[186:189], v[92:95]
	v_mfma_f32_16x16x32_bf16 v[88:91], v[178:181], v[186:189], v[88:91]
	v_mfma_f32_16x16x32_bf16 v[84:87], v[170:173], v[194:197], v[84:87]
	v_mfma_f32_16x16x32_bf16 v[80:83], v[178:181], v[194:197], v[80:83]
	v_mfma_f32_16x16x32_bf16 v[76:79], v[170:173], v[206:209], v[76:79]
	v_mfma_f32_16x16x32_bf16 v[72:75], v[178:181], v[206:209], v[72:75]
	v_mfma_f32_16x16x32_bf16 v[68:71], v[170:173], v[214:217], v[68:71]
	v_mfma_f32_16x16x32_bf16 v[64:67], v[178:181], v[214:217], v[64:67]
	s_barrier
	s_add_i32 s57, s45, s12
	v_lshl_add_u64 v[198:199], s[2:3], 0, v[132:133]
	s_mov_b32 m0, s57
	ds_read_b128 v[182:185], v149 offset:16384
	ds_read_b128 v[186:189], v149 offset:17408
	ds_read_b128 v[190:193], v149 offset:18432
	ds_read_b128 v[194:197], v149 offset:19456
	ds_read_b128 v[202:205], v149 offset:20480
	ds_read_b128 v[206:209], v149 offset:21504
	ds_read_b128 v[210:213], v149 offset:22528
	ds_read_b128 v[214:217], v149 offset:23552
	global_load_lds_dwordx4 v[198:199], off
	s_add_i32 m0, s57, 0x2000
	s_add_u32 s58, s2, 0x40000
	v_lshl_add_u64 v[218:219], s[2:3], 0, v[128:129]
	s_addc_u32 s59, s3, 0
	s_add_i32 s57, s46, s12
	global_load_lds_dwordx4 v[218:219], off
	v_lshl_add_u64 v[220:221], s[58:59], 0, v[132:133]
	s_mov_b32 m0, s57
	v_lshl_add_u64 v[222:223], s[36:37], 0, v[130:131]
	global_load_lds_dwordx4 v[220:221], off
	v_lshl_add_u64 v[220:221], s[58:59], 0, v[128:129]
	s_add_i32 m0, s57, 0x2000
	s_nop 0
	global_load_lds_dwordx4 v[220:221], off
	v_lshl_add_u64 v[220:221], s[36:37], 0, v[134:135]
	s_mov_b32 m0, s7
	s_nop 0
	global_load_lds_dwordx4 v[220:221], off
	s_mov_b32 m0, s15
	s_nop 0
	global_load_lds_dwordx4 v[222:223], off
	s_waitcnt vmcnt(8)
	s_waitcnt lgkmcnt(0)
	s_barrier
; #define PG8_STAGE(bufoff, gbase, voff) do { _Pragma("unroll") for (int _i = 0; _i < 2; ++_i) \
;         __builtin_amdgcn_global_load_lds((const unsigned*)((const char*)(gbase) + (voff)[_i]), (LAS unsigned*)(lds + (bufoff) + ldsw + _i * 8192), 16, 0, 0); } while (0)
; #define PG8_STAGEB(bufoff, gbase, perm) do { _Pragma("unroll") for (int _i = 0; _i < 2; ++_i) \
;         __builtin_amdgcn_global_load_lds((const unsigned*)((const char*)(gbase) + ((BSEL && (perm)) ? voffBp[_i] : voffB[_i])), (LAS unsigned*)(lds + (bufoff) + ldsw + _i * 8192), 16, 0, 0); } while (0)
; #define PG8_LDA(dst, b, h) do { _Pragma("unroll") for (int m = 0; m < 4; ++m) _Pragma("unroll") for (int k = 0; k < 2; ++k) dst[m][k] = *(const LAS bf16x8*)(lds + PG8_SA(b, h) + aoff + m * 2048 + k * 1024); } while (0)
; #define PG8_LDB(dst, b, h) do { _Pragma("unroll") for (int n = 0; n < 2; ++n) _Pragma("unroll") for (int k = 0; k < 2; ++k) dst[n][k] = *(const LAS bf16x8*)(lds + PG8_SB(b, h) + boff + n * 2048 + k * 1024); } while (0)
; #define PG8_MMA(ai, bj, At, Bt) do { __builtin_amdgcn_s_setprio(1); _Pragma("unroll") for (int m = 0; m < 4; ++m) _Pragma("unroll") for (int n = 0; n < 2; ++n) _Pragma("unroll") for (int k = 0; k < 2; ++k) \
;         acc[ai][bj][m][n] = __builtin_amdgcn_mfma_f32_16x16x32_bf16(Bt[n][k], At[m][k], acc[ai][bj][m][n], 0, 0, 0); __builtin_amdgcn_s_setprio(0); } while (0)
; #define PG8_WAIT_V(n) asm volatile("s_waitcnt vmcnt(" #n ")" ::: "memory")
; #define PG8_WAIT_L(n) asm volatile("s_waitcnt lgkmcnt(" #n ")" ::: "memory")
; #define PG8_BAR __builtin_amdgcn_s_barrier()
; template <class Epi, bool BSEL = false>
; __device__ __forceinline__ void gemm_phase(LAS unsigned char* lds, const Gemm g, const Order& S, const Epi& E, const int tid) {
;     ...
;             PG8_WAIT_V(8); PG8_WAIT_L(0); PG8_BAR; PG8_MMA(1, 0, At, B0); PG8_MMA(1, 1, At, B1); PG8_BAR; PG8_SCHED;
;             PG8_LDB(B0, 1, 0); PG8_LDB(B1, 1, 1); PG8_SCHED; PG8_LDA(At, 1, 0); PG8_STAGE(PG8_SA(0, 1), a2 + hstepA, voffA);
;             PG8_WAIT_V(8); PG8_WAIT_L(0); PG8_BAR; PG8_MMA(0, 0, At, B0); PG8_MMA(0, 1, At, B1); PG8_BAR; PG8_SCHED;
;             PG8_LDA(At, 1, 1); PG8_STAGEB(PG8_SB(1, 0), b3, p2); PG8_STAGEB(PG8_SB(1, 1), b3 + h2, p2); PG8_STAGE(PG8_SA(1, 0), a3, voffA);
;             PG8_WAIT_V(8); PG8_WAIT_L(0); PG8_BAR; PG8_MMA(1, 0, At, B0); PG8_MMA(1, 1, At, B1); PG8_BAR; PG8_SCHED;
	v_mfma_f32_16x16x32_bf16 v[60:63], v[150:153], v[182:185], v[60:63]
	v_mfma_f32_16x16x32_bf16 v[56:59], v[158:161], v[182:185], v[56:59]
	v_mfma_f32_16x16x32_bf16 v[52:55], v[150:153], v[190:193], v[52:55]
	v_mfma_f32_16x16x32_bf16 v[48:51], v[158:161], v[190:193], v[48:51]
	v_mfma_f32_16x16x32_bf16 v[44:47], v[150:153], v[202:205], v[44:47]
	v_mfma_f32_16x16x32_bf16 v[40:43], v[158:161], v[202:205], v[40:43]
	v_mfma_f32_16x16x32_bf16 v[36:39], v[150:153], v[210:213], v[36:39]
	v_mfma_f32_16x16x32_bf16 v[32:35], v[158:161], v[210:213], v[32:35]
	v_mfma_f32_16x16x32_bf16 v[60:63], v[154:157], v[186:189], v[60:63]
	v_mfma_f32_16x16x32_bf16 v[56:59], v[162:165], v[186:189], v[56:59]
	v_mfma_f32_16x16x32_bf16 v[52:55], v[154:157], v[194:197], v[52:55]
	v_mfma_f32_16x16x32_bf16 v[48:51], v[162:165], v[194:197], v[48:51]
	v_mfma_f32_16x16x32_bf16 v[44:47], v[154:157], v[206:209], v[44:47]
	v_mfma_f32_16x16x32_bf16 v[40:43], v[162:165], v[206:209], v[40:43]
	v_mfma_f32_16x16x32_bf16 v[36:39], v[154:157], v[214:217], v[36:39]
	v_mfma_f32_16x16x32_bf16 v[32:35], v[162:165], v[214:217], v[32:35]
	v_mfma_f32_16x16x32_bf16 v[28:31], v[166:169], v[182:185], v[28:31]
	v_mfma_f32_16x16x32_bf16 v[24:27], v[174:177], v[182:185], v[24:27]
	v_mfma_f32_16x16x32_bf16 v[20:23], v[166:169], v[190:193], v[20:23]
	v_mfma_f32_16x16x32_bf16 v[16:19], v[174:177], v[190:193], v[16:19]
	v_mfma_f32_16x16x32_bf16 v[12:15], v[166:169], v[202:205], v[12:15]
	v_mfma_f32_16x16x32_bf16 v[8:11], v[174:177], v[202:205], v[8:11]
	v_mfma_f32_16x16x32_bf16 v[4:7], v[166:169], v[210:213], v[4:7]
	v_mfma_f32_16x16x32_bf16 v[0:3], v[174:177], v[210:213], v[0:3]
	v_mfma_f32_16x16x32_bf16 v[28:31], v[170:173], v[186:189], v[28:31]
	v_mfma_f32_16x16x32_bf16 v[24:27], v[178:181], v[186:189], v[24:27]
	v_mfma_f32_16x16x32_bf16 v[20:23], v[170:173], v[194:197], v[20:23]
	v_mfma_f32_16x16x32_bf16 v[16:19], v[178:181], v[194:197], v[16:19]
	v_mfma_f32_16x16x32_bf16 v[12:15], v[170:173], v[206:209], v[12:15]
	v_mfma_f32_16x16x32_bf16 v[8:11], v[178:181], v[206:209], v[8:11]
	v_mfma_f32_16x16x32_bf16 v[4:7], v[170:173], v[214:217], v[4:7]
	v_mfma_f32_16x16x32_bf16 v[0:3], v[178:181], v[214:217], v[0:3]
	s_barrier
	s_add_i32 s57, 0, 0x18000
	s_add_i32 s58, 0, 0x1c000
	v_add_u32_e32 v162, s57, v147
	v_add_u32_e32 v178, s58, v147
	ds_read_b128 v[150:153], v162
	ds_read_b128 v[154:157], v162 offset:1024
	ds_read_b128 v[158:161], v162 offset:2048
	ds_read_b128 v[162:165], v162 offset:3072
	ds_read_b128 v[166:169], v178
	ds_read_b128 v[170:173], v178 offset:1024
	ds_read_b128 v[174:177], v178 offset:2048
	ds_read_b128 v[178:181], v178 offset:3072
	s_add_u32 s36, s36, 0x40000
	s_addc_u32 s37, s37, 0
	s_mov_b32 m0, s20
	v_lshl_add_u64 v[224:225], s[36:37], 0, v[134:135]
	ds_read_b128 v[182:185], v149 offset:32768
	ds_read_b128 v[186:189], v149 offset:33792
	ds_read_b128 v[190:193], v149 offset:34816
	ds_read_b128 v[194:197], v149 offset:35840
	ds_read_b128 v[202:205], v149 offset:36864
	ds_read_b128 v[206:209], v149 offset:37888
	ds_read_b128 v[210:213], v149 offset:38912
	ds_read_b128 v[214:217], v149 offset:39936
	global_load_lds_dwordx4 v[224:225], off
	v_lshl_add_u64 v[224:225], s[36:37], 0, v[130:131]
	s_mov_b32 m0, s21
	s_nop 0
	global_load_lds_dwordx4 v[224:225], off
	s_waitcnt vmcnt(8)
	s_waitcnt lgkmcnt(0)
	s_barrier
	v_mfma_f32_16x16x32_bf16 v[124:127], v[150:153], v[182:185], v[124:127]
	v_mfma_f32_16x16x32_bf16 v[120:123], v[158:161], v[182:185], v[120:123]
	v_mfma_f32_16x16x32_bf16 v[116:119], v[150:153], v[190:193], v[116:119]
	v_mfma_f32_16x16x32_bf16 v[112:115], v[158:161], v[190:193], v[112:115]
	v_mfma_f32_16x16x32_bf16 v[108:111], v[150:153], v[202:205], v[108:111]
	v_mfma_f32_16x16x32_bf16 v[104:107], v[158:161], v[202:205], v[104:107]
	v_mfma_f32_16x16x32_bf16 v[100:103], v[150:153], v[210:213], v[100:103]
	v_mfma_f32_16x16x32_bf16 v[96:99], v[158:161], v[210:213], v[96:99]
	v_mfma_f32_16x16x32_bf16 v[124:127], v[154:157], v[186:189], v[124:127]
	v_mfma_f32_16x16x32_bf16 v[120:123], v[162:165], v[186:189], v[120:123]
	v_mfma_f32_16x16x32_bf16 v[116:119], v[154:157], v[194:197], v[116:119]
	v_mfma_f32_16x16x32_bf16 v[112:115], v[162:165], v[194:197], v[112:115]
	v_mfma_f32_16x16x32_bf16 v[108:111], v[154:157], v[206:209], v[108:111]
	v_mfma_f32_16x16x32_bf16 v[104:107], v[162:165], v[206:209], v[104:107]
	v_mfma_f32_16x16x32_bf16 v[100:103], v[154:157], v[214:217], v[100:103]
	v_mfma_f32_16x16x32_bf16 v[96:99], v[162:165], v[214:217], v[96:99]
	v_mfma_f32_16x16x32_bf16 v[92:95], v[166:169], v[182:185], v[92:95]
	v_mfma_f32_16x16x32_bf16 v[88:91], v[174:177], v[182:185], v[88:91]
	v_mfma_f32_16x16x32_bf16 v[84:87], v[166:169], v[190:193], v[84:87]
	v_mfma_f32_16x16x32_bf16 v[80:83], v[174:177], v[190:193], v[80:83]
	v_mfma_f32_16x16x32_bf16 v[76:79], v[166:169], v[202:205], v[76:79]
	v_mfma_f32_16x16x32_bf16 v[72:75], v[174:177], v[202:205], v[72:75]
	v_mfma_f32_16x16x32_bf16 v[68:71], v[166:169], v[210:213], v[68:71]
	v_mfma_f32_16x16x32_bf16 v[64:67], v[174:177], v[210:213], v[64:67]
	v_mfma_f32_16x16x32_bf16 v[92:95], v[170:173], v[186:189], v[92:95]
	v_mfma_f32_16x16x32_bf16 v[88:91], v[178:181], v[186:189], v[88:91]
	v_mfma_f32_16x16x32_bf16 v[84:87], v[170:173], v[194:197], v[84:87]
	v_mfma_f32_16x16x32_bf16 v[80:83], v[178:181], v[194:197], v[80:83]
	v_mfma_f32_16x16x32_bf16 v[76:79], v[170:173], v[206:209], v[76:79]
	v_mfma_f32_16x16x32_bf16 v[72:75], v[178:181], v[206:209], v[72:75]
	v_mfma_f32_16x16x32_bf16 v[68:71], v[170:173], v[214:217], v[68:71]
	v_mfma_f32_16x16x32_bf16 v[64:67], v[178:181], v[214:217], v[64:67]
	s_barrier
; #define PG8_STAGE(bufoff, gbase, voff) do { _Pragma("unroll") for (int _i = 0; _i < 2; ++_i) \
;         __builtin_amdgcn_global_load_lds((const unsigned*)((const char*)(gbase) + (voff)[_i]), (LAS unsigned*)(lds + (bufoff) + ldsw + _i * 8192), 16, 0, 0); } while (0)
; #define PG8_STAGEB(bufoff, gbase, perm) do { _Pragma("unroll") for (int _i = 0; _i < 2; ++_i) \
;         __builtin_amdgcn_global_load_lds((const unsigned*)((const char*)(gbase) + ((BSEL && (perm)) ? voffBp[_i] : voffB[_i])), (LAS unsigned*)(lds + (bufoff) + ldsw + _i * 8192), 16, 0, 0); } while (0)
; #define PG8_LDA(dst, b, h) do { _Pragma("unroll") for (int m = 0; m < 4; ++m) _Pragma("unroll") for (int k = 0; k < 2; ++k) dst[m][k] = *(const LAS bf16x8*)(lds + PG8_SA(b, h) + aoff + m * 2048 + k * 1024); } while (0)
; #define PG8_MMA(ai, bj, At, Bt) do { __builtin_amdgcn_s_setprio(1); _Pragma("unroll") for (int m = 0; m < 4; ++m) _Pragma("unroll") for (int n = 0; n < 2; ++n) _Pragma("unroll") for (int k = 0; k < 2; ++k) \
;         acc[ai][bj][m][n] = __builtin_amdgcn_mfma_f32_16x16x32_bf16(Bt[n][k], At[m][k], acc[ai][bj][m][n], 0, 0, 0); __builtin_amdgcn_s_setprio(0); } while (0)
; #define PG8_WAIT_V(n) asm volatile("s_waitcnt vmcnt(" #n ")" ::: "memory")
; #define PG8_WAIT_L(n) asm volatile("s_waitcnt lgkmcnt(" #n ")" ::: "memory")
; #define PG8_BAR __builtin_amdgcn_s_barrier()
; #define PG8_SCHED __builtin_amdgcn_sched_barrier(0)
; template <class Epi, bool BSEL = false>
; __device__ __forceinline__ void gemm_phase(LAS unsigned char* lds, const Gemm g, const Order& S, const Epi& E, const int tid) {
;     ...
;             PG8_LDA(At, 1, 1); PG8_STAGEB(PG8_SB(1, 0), b3, p2); PG8_STAGEB(PG8_SB(1, 1), b3 + h2, p2); PG8_STAGE(PG8_SA(1, 0), a3, voffA);
;             PG8_WAIT_V(8); PG8_WAIT_L(0); PG8_BAR; PG8_MMA(1, 0, At, B0); PG8_MMA(1, 1, At, B1); PG8_BAR; PG8_SCHED;
;         }
;         if constexpr (ALIGN_EPI) { if (wr == 0) PG8_BAR; }
	s_add_i32 s36, s57, s12
	v_lshl_add_u64 v[198:199], v[198:199], 0, s[22:23]
	s_mov_b32 m0, s36
	ds_read_b128 v[182:185], v149 offset:49152
	ds_read_b128 v[186:189], v149 offset:50176
	ds_read_b128 v[190:193], v149 offset:51200
	ds_read_b128 v[194:197], v149 offset:52224
	ds_read_b128 v[202:205], v149 offset:53248
	ds_read_b128 v[206:209], v149 offset:54272
	ds_read_b128 v[210:213], v149 offset:55296
	ds_read_b128 v[214:217], v149 offset:56320
	global_load_lds_dwordx4 v[198:199], off
	s_add_i32 m0, s36, 0x2000
	s_add_u32 s2, s2, 0x40080
	v_lshl_add_u64 v[198:199], v[218:219], 0, s[22:23]
	s_addc_u32 s3, s3, 0
	s_add_i32 s36, s58, s12
	global_load_lds_dwordx4 v[198:199], off
	v_lshl_add_u64 v[198:199], s[2:3], 0, v[132:133]
	s_mov_b32 m0, s36
	s_nop 0
	global_load_lds_dwordx4 v[198:199], off
	v_lshl_add_u64 v[198:199], s[2:3], 0, v[128:129]
	s_add_i32 m0, s36, 0x2000
	s_nop 0
	global_load_lds_dwordx4 v[198:199], off
	v_lshl_add_u64 v[198:199], v[220:221], 0, s[22:23]
	s_mov_b32 m0, s43
	s_nop 0
	global_load_lds_dwordx4 v[198:199], off
	v_lshl_add_u64 v[198:199], v[222:223], 0, s[22:23]
	s_mov_b32 m0, s44
	s_nop 0
	global_load_lds_dwordx4 v[198:199], off
	s_waitcnt vmcnt(8)
	s_waitcnt lgkmcnt(0)
	s_barrier
	v_mfma_f32_16x16x32_bf16 v[60:63], v[150:153], v[182:185], v[60:63]
	v_mfma_f32_16x16x32_bf16 v[56:59], v[158:161], v[182:185], v[56:59]
	v_mfma_f32_16x16x32_bf16 v[52:55], v[150:153], v[190:193], v[52:55]
	v_mfma_f32_16x16x32_bf16 v[48:51], v[158:161], v[190:193], v[48:51]
	v_mfma_f32_16x16x32_bf16 v[44:47], v[150:153], v[202:205], v[44:47]
	v_mfma_f32_16x16x32_bf16 v[40:43], v[158:161], v[202:205], v[40:43]
	v_mfma_f32_16x16x32_bf16 v[36:39], v[150:153], v[210:213], v[36:39]
	v_mfma_f32_16x16x32_bf16 v[32:35], v[158:161], v[210:213], v[32:35]
	v_mfma_f32_16x16x32_bf16 v[60:63], v[154:157], v[186:189], v[60:63]
	v_mfma_f32_16x16x32_bf16 v[56:59], v[162:165], v[186:189], v[56:59]
	v_mfma_f32_16x16x32_bf16 v[52:55], v[154:157], v[194:197], v[52:55]
	v_mfma_f32_16x16x32_bf16 v[48:51], v[162:165], v[194:197], v[48:51]
	v_mfma_f32_16x16x32_bf16 v[44:47], v[154:157], v[206:209], v[44:47]
	v_mfma_f32_16x16x32_bf16 v[40:43], v[162:165], v[206:209], v[40:43]
	v_mfma_f32_16x16x32_bf16 v[36:39], v[154:157], v[214:217], v[36:39]
	v_mfma_f32_16x16x32_bf16 v[32:35], v[162:165], v[214:217], v[32:35]
	v_mfma_f32_16x16x32_bf16 v[28:31], v[166:169], v[182:185], v[28:31]
	v_mfma_f32_16x16x32_bf16 v[24:27], v[174:177], v[182:185], v[24:27]
	v_mfma_f32_16x16x32_bf16 v[20:23], v[166:169], v[190:193], v[20:23]
	v_mfma_f32_16x16x32_bf16 v[16:19], v[174:177], v[190:193], v[16:19]
	v_mfma_f32_16x16x32_bf16 v[12:15], v[166:169], v[202:205], v[12:15]
	v_mfma_f32_16x16x32_bf16 v[8:11], v[174:177], v[202:205], v[8:11]
	v_mfma_f32_16x16x32_bf16 v[4:7], v[166:169], v[210:213], v[4:7]
	v_mfma_f32_16x16x32_bf16 v[0:3], v[174:177], v[210:213], v[0:3]
	v_mfma_f32_16x16x32_bf16 v[28:31], v[170:173], v[186:189], v[28:31]
	v_mfma_f32_16x16x32_bf16 v[24:27], v[178:181], v[186:189], v[24:27]
	v_mfma_f32_16x16x32_bf16 v[20:23], v[170:173], v[194:197], v[20:23]
	v_mfma_f32_16x16x32_bf16 v[16:19], v[178:181], v[194:197], v[16:19]
	v_mfma_f32_16x16x32_bf16 v[12:15], v[170:173], v[206:209], v[12:15]
	v_mfma_f32_16x16x32_bf16 v[8:11], v[178:181], v[206:209], v[8:11]
	v_mfma_f32_16x16x32_bf16 v[4:7], v[170:173], v[214:217], v[4:7]
	v_mfma_f32_16x16x32_bf16 v[0:3], v[178:181], v[214:217], v[0:3]
	s_barrier
	s_add_i32 s56, s56, 2
	s_add_u32 s40, s40, 0x100
	s_addc_u32 s41, s41, 0
	s_cmp_gt_u32 s56, 13
	s_cbranch_scc0 .LBB0_1271
	s_and_b64 vcc, exec, s[24:25]
	s_cbranch_vccz .LBB0_1274
	s_barrier

; #define PG8_STAGE(bufoff, gbase, voff) do { _Pragma("unroll") for (int _i = 0; _i < 2; ++_i) \
;         __builtin_amdgcn_global_load_lds((const unsigned*)((const char*)(gbase) + (voff)[_i]), (LAS unsigned*)(lds + (bufoff) + ldsw + _i * 8192), 16, 0, 0); } while (0)
; #define PG8_STAGEB(bufoff, gbase, perm) do { _Pragma("unroll") for (int _i = 0; _i < 2; ++_i) \
;         __builtin_amdgcn_global_load_lds((const unsigned*)((const char*)(gbase) + ((BSEL && (perm)) ? voffBp[_i] : voffB[_i])), (LAS unsigned*)(lds + (bufoff) + ldsw + _i * 8192), 16, 0, 0); } while (0)
; #define PG8_LDA(dst, b, h) do { _Pragma("unroll") for (int m = 0; m < 4; ++m) _Pragma("unroll") for (int k = 0; k < 2; ++k) dst[m][k] = *(const LAS bf16x8*)(lds + PG8_SA(b, h) + aoff + m * 2048 + k * 1024); } while (0)
; #define PG8_LDB(dst, b, h) do { _Pragma("unroll") for (int n = 0; n < 2; ++n) _Pragma("unroll") for (int k = 0; k < 2; ++k) dst[n][k] = *(const LAS bf16x8*)(lds + PG8_SB(b, h) + boff + n * 2048 + k * 1024); } while (0)
; template <class Epi, bool BSEL = false>
; __device__ __forceinline__ void gemm_phase(LAS unsigned char* lds, const Gemm g, const Order& S, const Epi& E, const int tid) {
;     ...
;         for (int t = 0; t < nt; t += 2) {
;             const bool last = (t == nt - 2);
;             const char* a1 = cA + (size_t)(t + 1) * kstep;
;             const char* a2 = last ? nA : cA + (size_t)(t + 2) * kstep; const char* b2 = last ? nB : cB + (size_t)(t + 2) * kstep;
;             const char* a3 = a2 + kstep; const char* b3 = b2 + kstep;
;             const bool p2 = last ? nP : cP; const size_t h2 = last ? nhB : chB;
;             PG8_LDB(B0, 0, 0); PG8_LDB(B1, 0, 1); PG8_SCHED; PG8_LDA(At, 0, 0); PG8_STAGE(PG8_SA(1, 1), a1 + hstepA, voffA);
;             PG8_WAIT_V(8); PG8_WAIT_L(0); PG8_BAR; PG8_MMA(0, 0, At, B0); PG8_MMA(0, 1, At, B1); PG8_BAR; PG8_SCHED;
;             PG8_LDA(At, 0, 1); PG8_STAGEB(PG8_SB(0, 0), b2, p2); PG8_STAGEB(PG8_SB(0, 1), b2 + h2, p2); PG8_STAGE(PG8_SA(0, 0), a2, voffA);
;             PG8_WAIT_V(8); PG8_WAIT_L(0); PG8_BAR; PG8_MMA(1, 0, At, B0); PG8_MMA(1, 1, At, B1); PG8_BAR; PG8_SCHED;
;             PG8_LDB(B0, 1, 0); PG8_LDB(B1, 1, 1); PG8_SCHED; PG8_LDA(At, 1, 0); PG8_STAGE(PG8_SA(0, 1), a2 + hstepA, voffA);
;             PG8_WAIT_V(8); PG8_WAIT_L(0); PG8_BAR; PG8_MMA(0, 0, At, B0); PG8_MMA(0, 1, At, B1); PG8_BAR; PG8_SCHED;
.LBB0_1364:
	v_add_u32_e32 v172, s43, v129
	ds_read_b128 v[160:163], v172
	ds_read_b128 v[164:167], v172 offset:1024
	ds_read_b128 v[168:171], v172 offset:2048
	ds_read_b128 v[176:179], v172 offset:3072
	v_add_u32_e32 v172, s44, v129
	s_add_u32 s28, s6, s2
	ds_read_b128 v[180:183], v172
	ds_read_b128 v[184:187], v172 offset:1024
	ds_read_b128 v[188:191], v172 offset:2048
	ds_read_b128 v[192:195], v172 offset:3072
	s_addc_u32 s29, s7, s3
	s_add_u32 s28, s28, 0x100
	s_addc_u32 s29, s29, 0
	s_add_u32 s55, s1, s2
	s_addc_u32 s56, s49, s3
	s_cmpk_eq_i32 s2, 0x1500
	s_cselect_b32 s35, s50, s29
	s_cselect_b32 s34, s51, s28
	s_cselect_b32 s29, s52, s56
	s_cselect_b32 s28, s53, s55
	v_lshl_add_u64 v[172:173], v[156:157], 0, s[2:3]
	s_add_i32 m0, s20, 0xc000
	ds_read_b128 v[196:199], v175
	ds_read_b128 v[202:205], v175 offset:1024
	ds_read_b128 v[206:209], v175 offset:2048
	ds_read_b128 v[210:213], v175 offset:3072
	ds_read_b128 v[214:217], v175 offset:4096
	ds_read_b128 v[218:221], v175 offset:5120
	ds_read_b128 v[222:225], v175 offset:6144
	ds_read_b128 v[226:229], v175 offset:7168
	global_load_lds_dwordx4 v[172:173], off
	v_lshl_add_u64 v[172:173], v[158:159], 0, s[2:3]
	s_add_i32 m0, s20, 0xe000
	s_nop 0
	global_load_lds_dwordx4 v[172:173], off
	s_waitcnt vmcnt(8)
	s_waitcnt lgkmcnt(0)
	s_barrier
	v_mfma_f32_16x16x32_bf16 v[124:127], v[160:163], v[196:199], v[124:127]
	v_mfma_f32_16x16x32_bf16 v[120:123], v[168:171], v[196:199], v[120:123]
	v_mfma_f32_16x16x32_bf16 v[116:119], v[160:163], v[206:209], v[116:119]
	v_mfma_f32_16x16x32_bf16 v[112:115], v[168:171], v[206:209], v[112:115]
	v_mfma_f32_16x16x32_bf16 v[108:111], v[160:163], v[214:217], v[108:111]
	v_mfma_f32_16x16x32_bf16 v[104:107], v[168:171], v[214:217], v[104:107]
	v_mfma_f32_16x16x32_bf16 v[100:103], v[160:163], v[222:225], v[100:103]
	v_mfma_f32_16x16x32_bf16 v[96:99], v[168:171], v[222:225], v[96:99]
	v_mfma_f32_16x16x32_bf16 v[124:127], v[164:167], v[202:205], v[124:127]
	v_mfma_f32_16x16x32_bf16 v[120:123], v[176:179], v[202:205], v[120:123]
	v_mfma_f32_16x16x32_bf16 v[116:119], v[164:167], v[210:213], v[116:119]
	v_mfma_f32_16x16x32_bf16 v[112:115], v[176:179], v[210:213], v[112:115]
	v_mfma_f32_16x16x32_bf16 v[108:111], v[164:167], v[218:221], v[108:111]
	v_mfma_f32_16x16x32_bf16 v[104:107], v[176:179], v[218:221], v[104:107]
	v_mfma_f32_16x16x32_bf16 v[100:103], v[164:167], v[226:229], v[100:103]
	v_mfma_f32_16x16x32_bf16 v[96:99], v[176:179], v[226:229], v[96:99]
	v_mfma_f32_16x16x32_bf16 v[92:95], v[180:183], v[196:199], v[92:95]
	v_mfma_f32_16x16x32_bf16 v[88:91], v[188:191], v[196:199], v[88:91]
	v_mfma_f32_16x16x32_bf16 v[84:87], v[180:183], v[206:209], v[84:87]
	v_mfma_f32_16x16x32_bf16 v[80:83], v[188:191], v[206:209], v[80:83]
	v_mfma_f32_16x16x32_bf16 v[76:79], v[180:183], v[214:217], v[76:79]
	v_mfma_f32_16x16x32_bf16 v[72:75], v[188:191], v[214:217], v[72:75]
	v_mfma_f32_16x16x32_bf16 v[68:71], v[180:183], v[222:225], v[68:71]
	v_mfma_f32_16x16x32_bf16 v[64:67], v[188:191], v[222:225], v[64:67]
	v_mfma_f32_16x16x32_bf16 v[92:95], v[184:187], v[202:205], v[92:95]
	v_mfma_f32_16x16x32_bf16 v[88:91], v[192:195], v[202:205], v[88:91]
	v_mfma_f32_16x16x32_bf16 v[84:87], v[184:187], v[210:213], v[84:87]
	v_mfma_f32_16x16x32_bf16 v[80:83], v[192:195], v[210:213], v[80:83]
	v_mfma_f32_16x16x32_bf16 v[76:79], v[184:187], v[218:221], v[76:79]
	v_mfma_f32_16x16x32_bf16 v[72:75], v[192:195], v[218:221], v[72:75]
	v_mfma_f32_16x16x32_bf16 v[68:71], v[184:187], v[226:229], v[68:71]
	v_mfma_f32_16x16x32_bf16 v[64:67], v[192:195], v[226:229], v[64:67]
	s_barrier
	s_add_i32 s55, s43, s15
	v_lshl_add_u64 v[172:173], s[28:29], 0, v[130:131]
	s_mov_b32 m0, s55
	ds_read_b128 v[196:199], v175 offset:16384
	ds_read_b128 v[202:205], v175 offset:17408
	ds_read_b128 v[206:209], v175 offset:18432
	ds_read_b128 v[210:213], v175 offset:19456
	ds_read_b128 v[214:217], v175 offset:20480
	ds_read_b128 v[218:221], v175 offset:21504
	ds_read_b128 v[222:225], v175 offset:22528
	ds_read_b128 v[226:229], v175 offset:23552
	global_load_lds_dwordx4 v[172:173], off
	s_add_i32 m0, s55, 0x2000
	s_add_u32 s56, s28, 0xb0000
	v_lshl_add_u64 v[230:231], s[28:29], 0, v[132:133]
	s_addc_u32 s57, s29, 0
	s_add_i32 s55, s44, s15
	global_load_lds_dwordx4 v[230:231], off
	v_lshl_add_u64 v[232:233], s[56:57], 0, v[130:131]
	s_mov_b32 m0, s55
	v_lshl_add_u64 v[234:235], s[34:35], 0, v[132:133]
	global_load_lds_dwordx4 v[232:233], off
	v_lshl_add_u64 v[232:233], s[56:57], 0, v[132:133]
	s_add_i32 m0, s55, 0x2000
	s_nop 0
	global_load_lds_dwordx4 v[232:233], off
	v_lshl_add_u64 v[232:233], s[34:35], 0, v[130:131]
	s_mov_b32 m0, s20
	s_nop 0
	global_load_lds_dwordx4 v[232:233], off
	s_mov_b32 m0, s21
	s_nop 0
	global_load_lds_dwordx4 v[234:235], off
	s_waitcnt vmcnt(8)
	s_waitcnt lgkmcnt(0)
	s_barrier
; #define PG8_STAGE(bufoff, gbase, voff) do { _Pragma("unroll") for (int _i = 0; _i < 2; ++_i) \
;         __builtin_amdgcn_global_load_lds((const unsigned*)((const char*)(gbase) + (voff)[_i]), (LAS unsigned*)(lds + (bufoff) + ldsw + _i * 8192), 16, 0, 0); } while (0)
; #define PG8_STAGEB(bufoff, gbase, perm) do { _Pragma("unroll") for (int _i = 0; _i < 2; ++_i) \
;         __builtin_amdgcn_global_load_lds((const unsigned*)((const char*)(gbase) + ((BSEL && (perm)) ? voffBp[_i] : voffB[_i])), (LAS unsigned*)(lds + (bufoff) + ldsw + _i * 8192), 16, 0, 0); } while (0)
; #define PG8_LDA(dst, b, h) do { _Pragma("unroll") for (int m = 0; m < 4; ++m) _Pragma("unroll") for (int k = 0; k < 2; ++k) dst[m][k] = *(const LAS bf16x8*)(lds + PG8_SA(b, h) + aoff + m * 2048 + k * 1024); } while (0)
; #define PG8_LDB(dst, b, h) do { _Pragma("unroll") for (int n = 0; n < 2; ++n) _Pragma("unroll") for (int k = 0; k < 2; ++k) dst[n][k] = *(const LAS bf16x8*)(lds + PG8_SB(b, h) + boff + n * 2048 + k * 1024); } while (0)
; #define PG8_MMA(ai, bj, At, Bt) do { __builtin_amdgcn_s_setprio(1); _Pragma("unroll") for (int m = 0; m < 4; ++m) _Pragma("unroll") for (int n = 0; n < 2; ++n) _Pragma("unroll") for (int k = 0; k < 2; ++k) \
;         acc[ai][bj][m][n] = __builtin_amdgcn_mfma_f32_16x16x32_bf16(Bt[n][k], At[m][k], acc[ai][bj][m][n], 0, 0, 0); __builtin_amdgcn_s_setprio(0); } while (0)
; #define PG8_WAIT_V(n) asm volatile("s_waitcnt vmcnt(" #n ")" ::: "memory")
; #define PG8_WAIT_L(n) asm volatile("s_waitcnt lgkmcnt(" #n ")" ::: "memory")
; #define PG8_BAR __builtin_amdgcn_s_barrier()
; template <class Epi, bool BSEL = false>
; __device__ __forceinline__ void gemm_phase(LAS unsigned char* lds, const Gemm g, const Order& S, const Epi& E, const int tid) {
;     ...
;             PG8_WAIT_V(8); PG8_WAIT_L(0); PG8_BAR; PG8_MMA(1, 0, At, B0); PG8_MMA(1, 1, At, B1); PG8_BAR; PG8_SCHED;
;             PG8_LDB(B0, 1, 0); PG8_LDB(B1, 1, 1); PG8_SCHED; PG8_LDA(At, 1, 0); PG8_STAGE(PG8_SA(0, 1), a2 + hstepA, voffA);
;             PG8_WAIT_V(8); PG8_WAIT_L(0); PG8_BAR; PG8_MMA(0, 0, At, B0); PG8_MMA(0, 1, At, B1); PG8_BAR; PG8_SCHED;
;             PG8_LDA(At, 1, 1); PG8_STAGEB(PG8_SB(1, 0), b3, p2); PG8_STAGEB(PG8_SB(1, 1), b3 + h2, p2); PG8_STAGE(PG8_SA(1, 0), a3, voffA);
;             PG8_WAIT_V(8); PG8_WAIT_L(0); PG8_BAR; PG8_MMA(1, 0, At, B0); PG8_MMA(1, 1, At, B1); PG8_BAR; PG8_SCHED;
	v_mfma_f32_16x16x32_bf16 v[60:63], v[160:163], v[196:199], v[60:63]
	v_mfma_f32_16x16x32_bf16 v[56:59], v[168:171], v[196:199], v[56:59]
	v_mfma_f32_16x16x32_bf16 v[52:55], v[160:163], v[206:209], v[52:55]
	v_mfma_f32_16x16x32_bf16 v[48:51], v[168:171], v[206:209], v[48:51]
	v_mfma_f32_16x16x32_bf16 v[44:47], v[160:163], v[214:217], v[44:47]
	v_mfma_f32_16x16x32_bf16 v[40:43], v[168:171], v[214:217], v[40:43]
	v_mfma_f32_16x16x32_bf16 v[36:39], v[160:163], v[222:225], v[36:39]
	v_mfma_f32_16x16x32_bf16 v[32:35], v[168:171], v[222:225], v[32:35]
	v_mfma_f32_16x16x32_bf16 v[60:63], v[164:167], v[202:205], v[60:63]
	v_mfma_f32_16x16x32_bf16 v[56:59], v[176:179], v[202:205], v[56:59]
	v_mfma_f32_16x16x32_bf16 v[52:55], v[164:167], v[210:213], v[52:55]
	v_mfma_f32_16x16x32_bf16 v[48:51], v[176:179], v[210:213], v[48:51]
	v_mfma_f32_16x16x32_bf16 v[44:47], v[164:167], v[218:221], v[44:47]
	v_mfma_f32_16x16x32_bf16 v[40:43], v[176:179], v[218:221], v[40:43]
	v_mfma_f32_16x16x32_bf16 v[36:39], v[164:167], v[226:229], v[36:39]
	v_mfma_f32_16x16x32_bf16 v[32:35], v[176:179], v[226:229], v[32:35]
	v_mfma_f32_16x16x32_bf16 v[28:31], v[180:183], v[196:199], v[28:31]
	v_mfma_f32_16x16x32_bf16 v[24:27], v[188:191], v[196:199], v[24:27]
	v_mfma_f32_16x16x32_bf16 v[20:23], v[180:183], v[206:209], v[20:23]
	v_mfma_f32_16x16x32_bf16 v[16:19], v[188:191], v[206:209], v[16:19]
	v_mfma_f32_16x16x32_bf16 v[12:15], v[180:183], v[214:217], v[12:15]
	v_mfma_f32_16x16x32_bf16 v[8:11], v[188:191], v[214:217], v[8:11]
	v_mfma_f32_16x16x32_bf16 v[4:7], v[180:183], v[222:225], v[4:7]
	v_mfma_f32_16x16x32_bf16 v[0:3], v[188:191], v[222:225], v[0:3]
	v_mfma_f32_16x16x32_bf16 v[28:31], v[184:187], v[202:205], v[28:31]
	v_mfma_f32_16x16x32_bf16 v[24:27], v[192:195], v[202:205], v[24:27]
	v_mfma_f32_16x16x32_bf16 v[20:23], v[184:187], v[210:213], v[20:23]
	v_mfma_f32_16x16x32_bf16 v[16:19], v[192:195], v[210:213], v[16:19]
	v_mfma_f32_16x16x32_bf16 v[12:15], v[184:187], v[218:221], v[12:15]
	v_mfma_f32_16x16x32_bf16 v[8:11], v[192:195], v[218:221], v[8:11]
	v_mfma_f32_16x16x32_bf16 v[4:7], v[184:187], v[226:229], v[4:7]
	v_mfma_f32_16x16x32_bf16 v[0:3], v[192:195], v[226:229], v[0:3]
	s_barrier
	s_add_i32 s55, 0, 0x18000
	s_add_i32 s56, 0, 0x1c000
	v_add_u32_e32 v176, s55, v129
	v_add_u32_e32 v192, s56, v129
	ds_read_b128 v[160:163], v176
	ds_read_b128 v[164:167], v176 offset:1024
	ds_read_b128 v[168:171], v176 offset:2048
	ds_read_b128 v[176:179], v176 offset:3072
	ds_read_b128 v[180:183], v192
	ds_read_b128 v[184:187], v192 offset:1024
	ds_read_b128 v[188:191], v192 offset:2048
	ds_read_b128 v[192:195], v192 offset:3072
	s_add_u32 s34, s34, 0xb0000
	s_addc_u32 s35, s35, 0
	s_mov_b32 m0, s36
	v_lshl_add_u64 v[236:237], s[34:35], 0, v[130:131]
	ds_read_b128 v[196:199], v175 offset:32768
	ds_read_b128 v[202:205], v175 offset:33792
	ds_read_b128 v[206:209], v175 offset:34816
	ds_read_b128 v[210:213], v175 offset:35840
	ds_read_b128 v[214:217], v175 offset:36864
	ds_read_b128 v[218:221], v175 offset:37888
	ds_read_b128 v[222:225], v175 offset:38912
	ds_read_b128 v[226:229], v175 offset:39936
	global_load_lds_dwordx4 v[236:237], off
	v_lshl_add_u64 v[236:237], s[34:35], 0, v[132:133]
	s_mov_b32 m0, s37
	s_nop 0
	global_load_lds_dwordx4 v[236:237], off
	s_waitcnt vmcnt(8)
	s_waitcnt lgkmcnt(0)
	s_barrier
	v_mfma_f32_16x16x32_bf16 v[124:127], v[160:163], v[196:199], v[124:127]
	v_mfma_f32_16x16x32_bf16 v[120:123], v[168:171], v[196:199], v[120:123]
	v_mfma_f32_16x16x32_bf16 v[116:119], v[160:163], v[206:209], v[116:119]
	v_mfma_f32_16x16x32_bf16 v[112:115], v[168:171], v[206:209], v[112:115]
	v_mfma_f32_16x16x32_bf16 v[108:111], v[160:163], v[214:217], v[108:111]
	v_mfma_f32_16x16x32_bf16 v[104:107], v[168:171], v[214:217], v[104:107]
	v_mfma_f32_16x16x32_bf16 v[100:103], v[160:163], v[222:225], v[100:103]
	v_mfma_f32_16x16x32_bf16 v[96:99], v[168:171], v[222:225], v[96:99]
	v_mfma_f32_16x16x32_bf16 v[124:127], v[164:167], v[202:205], v[124:127]
	v_mfma_f32_16x16x32_bf16 v[120:123], v[176:179], v[202:205], v[120:123]
	v_mfma_f32_16x16x32_bf16 v[116:119], v[164:167], v[210:213], v[116:119]
	v_mfma_f32_16x16x32_bf16 v[112:115], v[176:179], v[210:213], v[112:115]
	v_mfma_f32_16x16x32_bf16 v[108:111], v[164:167], v[218:221], v[108:111]
	v_mfma_f32_16x16x32_bf16 v[104:107], v[176:179], v[218:221], v[104:107]
	v_mfma_f32_16x16x32_bf16 v[100:103], v[164:167], v[226:229], v[100:103]
	v_mfma_f32_16x16x32_bf16 v[96:99], v[176:179], v[226:229], v[96:99]
	v_mfma_f32_16x16x32_bf16 v[92:95], v[180:183], v[196:199], v[92:95]
	v_mfma_f32_16x16x32_bf16 v[88:91], v[188:191], v[196:199], v[88:91]
	v_mfma_f32_16x16x32_bf16 v[84:87], v[180:183], v[206:209], v[84:87]
	v_mfma_f32_16x16x32_bf16 v[80:83], v[188:191], v[206:209], v[80:83]
	v_mfma_f32_16x16x32_bf16 v[76:79], v[180:183], v[214:217], v[76:79]
	v_mfma_f32_16x16x32_bf16 v[72:75], v[188:191], v[214:217], v[72:75]
	v_mfma_f32_16x16x32_bf16 v[68:71], v[180:183], v[222:225], v[68:71]
	v_mfma_f32_16x16x32_bf16 v[64:67], v[188:191], v[222:225], v[64:67]
	v_mfma_f32_16x16x32_bf16 v[92:95], v[184:187], v[202:205], v[92:95]
	v_mfma_f32_16x16x32_bf16 v[88:91], v[192:195], v[202:205], v[88:91]
	v_mfma_f32_16x16x32_bf16 v[84:87], v[184:187], v[210:213], v[84:87]
	v_mfma_f32_16x16x32_bf16 v[80:83], v[192:195], v[210:213], v[80:83]
	v_mfma_f32_16x16x32_bf16 v[76:79], v[184:187], v[218:221], v[76:79]
	v_mfma_f32_16x16x32_bf16 v[72:75], v[192:195], v[218:221], v[72:75]
	v_mfma_f32_16x16x32_bf16 v[68:71], v[184:187], v[226:229], v[68:71]
	v_mfma_f32_16x16x32_bf16 v[64:67], v[192:195], v[226:229], v[64:67]
	s_barrier
; #define PG8_STAGE(bufoff, gbase, voff) do { _Pragma("unroll") for (int _i = 0; _i < 2; ++_i) \
;         __builtin_amdgcn_global_load_lds((const unsigned*)((const char*)(gbase) + (voff)[_i]), (LAS unsigned*)(lds + (bufoff) + ldsw + _i * 8192), 16, 0, 0); } while (0)
; #define PG8_STAGEB(bufoff, gbase, perm) do { _Pragma("unroll") for (int _i = 0; _i < 2; ++_i) \
;         __builtin_amdgcn_global_load_lds((const unsigned*)((const char*)(gbase) + ((BSEL && (perm)) ? voffBp[_i] : voffB[_i])), (LAS unsigned*)(lds + (bufoff) + ldsw + _i * 8192), 16, 0, 0); } while (0)
; #define PG8_LDA(dst, b, h) do { _Pragma("unroll") for (int m = 0; m < 4; ++m) _Pragma("unroll") for (int k = 0; k < 2; ++k) dst[m][k] = *(const LAS bf16x8*)(lds + PG8_SA(b, h) + aoff + m * 2048 + k * 1024); } while (0)
; #define PG8_MMA(ai, bj, At, Bt) do { __builtin_amdgcn_s_setprio(1); _Pragma("unroll") for (int m = 0; m < 4; ++m) _Pragma("unroll") for (int n = 0; n < 2; ++n) _Pragma("unroll") for (int k = 0; k < 2; ++k) \
;         acc[ai][bj][m][n] = __builtin_amdgcn_mfma_f32_16x16x32_bf16(Bt[n][k], At[m][k], acc[ai][bj][m][n], 0, 0, 0); __builtin_amdgcn_s_setprio(0); } while (0)
; #define PG8_WAIT_V(n) asm volatile("s_waitcnt vmcnt(" #n ")" ::: "memory")
; #define PG8_WAIT_L(n) asm volatile("s_waitcnt lgkmcnt(" #n ")" ::: "memory")
; #define PG8_BAR __builtin_amdgcn_s_barrier()
; #define PG8_SCHED __builtin_amdgcn_sched_barrier(0)
; template <class Epi, bool BSEL = false>
; __device__ __forceinline__ void gemm_phase(LAS unsigned char* lds, const Gemm g, const Order& S, const Epi& E, const int tid) {
;     ...
;             PG8_LDA(At, 1, 1); PG8_STAGEB(PG8_SB(1, 0), b3, p2); PG8_STAGEB(PG8_SB(1, 1), b3 + h2, p2); PG8_STAGE(PG8_SA(1, 0), a3, voffA);
;             PG8_WAIT_V(8); PG8_WAIT_L(0); PG8_BAR; PG8_MMA(1, 0, At, B0); PG8_MMA(1, 1, At, B1); PG8_BAR; PG8_SCHED;
;         }
;         if constexpr (ALIGN_EPI) { if (wr == 0) PG8_BAR; }
	s_add_i32 s34, s55, s15
	v_lshl_add_u64 v[172:173], v[172:173], 0, s[10:11]
	s_mov_b32 m0, s34
	ds_read_b128 v[196:199], v175 offset:49152
	ds_read_b128 v[202:205], v175 offset:50176
	ds_read_b128 v[206:209], v175 offset:51200
	ds_read_b128 v[210:213], v175 offset:52224
	ds_read_b128 v[214:217], v175 offset:53248
	ds_read_b128 v[218:221], v175 offset:54272
	ds_read_b128 v[222:225], v175 offset:55296
	ds_read_b128 v[226:229], v175 offset:56320
	global_load_lds_dwordx4 v[172:173], off
	s_add_i32 m0, s34, 0x2000
	s_add_u32 s28, s28, 0xb0080
	v_lshl_add_u64 v[172:173], v[230:231], 0, s[10:11]
	s_addc_u32 s29, s29, 0
	s_add_i32 s34, s56, s15
	global_load_lds_dwordx4 v[172:173], off
	v_lshl_add_u64 v[172:173], s[28:29], 0, v[130:131]
	s_mov_b32 m0, s34
	s_nop 0
	global_load_lds_dwordx4 v[172:173], off
	v_lshl_add_u64 v[172:173], s[28:29], 0, v[132:133]
	s_add_i32 m0, s34, 0x2000
	s_nop 0
	global_load_lds_dwordx4 v[172:173], off
	v_lshl_add_u64 v[172:173], v[232:233], 0, s[10:11]
	s_mov_b32 m0, s41
	s_nop 0
	global_load_lds_dwordx4 v[172:173], off
	v_lshl_add_u64 v[172:173], v[234:235], 0, s[10:11]
	s_mov_b32 m0, s42
	s_nop 0
	global_load_lds_dwordx4 v[172:173], off
	s_waitcnt vmcnt(8)
	s_waitcnt lgkmcnt(0)
	s_barrier
	v_mfma_f32_16x16x32_bf16 v[60:63], v[160:163], v[196:199], v[60:63]
	v_mfma_f32_16x16x32_bf16 v[56:59], v[168:171], v[196:199], v[56:59]
	v_mfma_f32_16x16x32_bf16 v[52:55], v[160:163], v[206:209], v[52:55]
	v_mfma_f32_16x16x32_bf16 v[48:51], v[168:171], v[206:209], v[48:51]
	v_mfma_f32_16x16x32_bf16 v[44:47], v[160:163], v[214:217], v[44:47]
	v_mfma_f32_16x16x32_bf16 v[40:43], v[168:171], v[214:217], v[40:43]
	v_mfma_f32_16x16x32_bf16 v[36:39], v[160:163], v[222:225], v[36:39]
	v_mfma_f32_16x16x32_bf16 v[32:35], v[168:171], v[222:225], v[32:35]
	v_mfma_f32_16x16x32_bf16 v[60:63], v[164:167], v[202:205], v[60:63]
	v_mfma_f32_16x16x32_bf16 v[56:59], v[176:179], v[202:205], v[56:59]
	v_mfma_f32_16x16x32_bf16 v[52:55], v[164:167], v[210:213], v[52:55]
	v_mfma_f32_16x16x32_bf16 v[48:51], v[176:179], v[210:213], v[48:51]
	v_mfma_f32_16x16x32_bf16 v[44:47], v[164:167], v[218:221], v[44:47]
	v_mfma_f32_16x16x32_bf16 v[40:43], v[176:179], v[218:221], v[40:43]
	v_mfma_f32_16x16x32_bf16 v[36:39], v[164:167], v[226:229], v[36:39]
	v_mfma_f32_16x16x32_bf16 v[32:35], v[176:179], v[226:229], v[32:35]
	v_mfma_f32_16x16x32_bf16 v[28:31], v[180:183], v[196:199], v[28:31]
	v_mfma_f32_16x16x32_bf16 v[24:27], v[188:191], v[196:199], v[24:27]
	v_mfma_f32_16x16x32_bf16 v[20:23], v[180:183], v[206:209], v[20:23]
	v_mfma_f32_16x16x32_bf16 v[16:19], v[188:191], v[206:209], v[16:19]
	v_mfma_f32_16x16x32_bf16 v[12:15], v[180:183], v[214:217], v[12:15]
	v_mfma_f32_16x16x32_bf16 v[8:11], v[188:191], v[214:217], v[8:11]
	v_mfma_f32_16x16x32_bf16 v[4:7], v[180:183], v[222:225], v[4:7]
	v_mfma_f32_16x16x32_bf16 v[0:3], v[188:191], v[222:225], v[0:3]
	v_mfma_f32_16x16x32_bf16 v[28:31], v[184:187], v[202:205], v[28:31]
	v_mfma_f32_16x16x32_bf16 v[24:27], v[192:195], v[202:205], v[24:27]
	v_mfma_f32_16x16x32_bf16 v[20:23], v[184:187], v[210:213], v[20:23]
	v_mfma_f32_16x16x32_bf16 v[16:19], v[192:195], v[210:213], v[16:19]
	v_mfma_f32_16x16x32_bf16 v[12:15], v[184:187], v[218:221], v[12:15]
	v_mfma_f32_16x16x32_bf16 v[8:11], v[192:195], v[218:221], v[8:11]
	v_mfma_f32_16x16x32_bf16 v[4:7], v[184:187], v[226:229], v[4:7]
	v_mfma_f32_16x16x32_bf16 v[0:3], v[192:195], v[226:229], v[0:3]
	s_barrier
	s_add_i32 s54, s54, 2
	s_add_u32 s2, s2, 0x100
	s_addc_u32 s3, s3, 0
	s_cmp_gt_u32 s54, 41
	s_cbranch_scc0 .LBB0_1364
	s_and_b64 vcc, exec, s[18:19]
	s_cbranch_vccz .LBB0_1367
	s_barrier

; #define PG8_STAGE(bufoff, gbase, voff) do { _Pragma("unroll") for (int _i = 0; _i < 2; ++_i) \
;         __builtin_amdgcn_global_load_lds((const unsigned*)((const char*)(gbase) + (voff)[_i]), (LAS unsigned*)(lds + (bufoff) + ldsw + _i * 8192), 16, 0, 0); } while (0)
; #define PG8_STAGEB(bufoff, gbase, perm) do { _Pragma("unroll") for (int _i = 0; _i < 2; ++_i) \
;         __builtin_amdgcn_global_load_lds((const unsigned*)((const char*)(gbase) + ((BSEL && (perm)) ? voffBp[_i] : voffB[_i])), (LAS unsigned*)(lds + (bufoff) + ldsw + _i * 8192), 16, 0, 0); } while (0)
; #define PG8_LDA(dst, b, h) do { _Pragma("unroll") for (int m = 0; m < 4; ++m) _Pragma("unroll") for (int k = 0; k < 2; ++k) dst[m][k] = *(const LAS bf16x8*)(lds + PG8_SA(b, h) + aoff + m * 2048 + k * 1024); } while (0)
; #define PG8_LDB(dst, b, h) do { _Pragma("unroll") for (int n = 0; n < 2; ++n) _Pragma("unroll") for (int k = 0; k < 2; ++k) dst[n][k] = *(const LAS bf16x8*)(lds + PG8_SB(b, h) + boff + n * 2048 + k * 1024); } while (0)
; template <class Epi, bool BSEL = false>
; __device__ __forceinline__ void gemm_phase(LAS unsigned char* lds, const Gemm g, const Order& S, const Epi& E, const int tid) {
;     ...
;         for (int t = 0; t < nt; t += 2) {
;             const bool last = (t == nt - 2);
;             const char* a1 = cA + (size_t)(t + 1) * kstep;
;             const char* a2 = last ? nA : cA + (size_t)(t + 2) * kstep; const char* b2 = last ? nB : cB + (size_t)(t + 2) * kstep;
;             const char* a3 = a2 + kstep; const char* b3 = b2 + kstep;
;             const bool p2 = last ? nP : cP; const size_t h2 = last ? nhB : chB;
;             PG8_LDB(B0, 0, 0); PG8_LDB(B1, 0, 1); PG8_SCHED; PG8_LDA(At, 0, 0); PG8_STAGE(PG8_SA(1, 1), a1 + hstepA, voffA);
;             PG8_WAIT_V(8); PG8_WAIT_L(0); PG8_BAR; PG8_MMA(0, 0, At, B0); PG8_MMA(0, 1, At, B1); PG8_BAR; PG8_SCHED;
;             PG8_LDA(At, 0, 1); PG8_STAGEB(PG8_SB(0, 0), b2, p2); PG8_STAGEB(PG8_SB(0, 1), b2 + h2, p2); PG8_STAGE(PG8_SA(0, 0), a2, voffA);
;             PG8_WAIT_V(8); PG8_WAIT_L(0); PG8_BAR; PG8_MMA(1, 0, At, B0); PG8_MMA(1, 1, At, B1); PG8_BAR; PG8_SCHED;
;             PG8_LDB(B0, 1, 0); PG8_LDB(B1, 1, 1); PG8_SCHED; PG8_LDA(At, 1, 0); PG8_STAGE(PG8_SA(0, 1), a2 + hstepA, voffA);
;             PG8_WAIT_V(8); PG8_WAIT_L(0); PG8_BAR; PG8_MMA(0, 0, At, B0); PG8_MMA(0, 1, At, B1); PG8_BAR; PG8_SCHED;
.LBB0_1393:
	v_add_u32_e32 v151, s43, v131
	ds_read_b128 v[152:155], v151
	ds_read_b128 v[156:159], v151 offset:1024
	ds_read_b128 v[168:171], v151 offset:2048
	ds_read_b128 v[172:175], v151 offset:3072
	v_add_u32_e32 v151, s44, v131
	s_add_u32 s36, s8, s34
	ds_read_b128 v[176:179], v151
	ds_read_b128 v[180:183], v151 offset:1024
	ds_read_b128 v[184:187], v151 offset:2048
	ds_read_b128 v[188:191], v151 offset:3072
	s_addc_u32 s37, s9, s35
	s_add_u32 s36, s36, 0x100
	s_addc_u32 s37, s37, 0
	s_add_u32 s54, s29, s34
	s_addc_u32 s55, s48, s35
	s_cmpk_eq_i32 s34, 0x1500
	s_cselect_b32 s39, s49, s37
	s_cselect_b32 s38, s50, s36
	s_cselect_b32 s37, s51, s55
	s_cselect_b32 s36, s52, s54
	v_lshl_add_u64 v[160:161], v[146:147], 0, s[34:35]
	s_add_i32 m0, s15, 0xc000
	ds_read_b128 v[192:195], v150
	ds_read_b128 v[196:199], v150 offset:1024
	ds_read_b128 v[202:205], v150 offset:2048
	ds_read_b128 v[206:209], v150 offset:3072
	ds_read_b128 v[210:213], v150 offset:4096
	ds_read_b128 v[214:217], v150 offset:5120
	ds_read_b128 v[218:221], v150 offset:6144
	ds_read_b128 v[222:225], v150 offset:7168
	global_load_lds_dwordx4 v[160:161], off
	v_lshl_add_u64 v[160:161], v[148:149], 0, s[34:35]
	s_add_i32 m0, s15, 0xe000
	s_nop 0
	global_load_lds_dwordx4 v[160:161], off
	s_waitcnt vmcnt(8)
	s_waitcnt lgkmcnt(0)
	s_barrier
	v_mfma_f32_16x16x32_bf16 v[124:127], v[152:155], v[192:195], v[124:127]
	v_mfma_f32_16x16x32_bf16 v[120:123], v[168:171], v[192:195], v[120:123]
	v_mfma_f32_16x16x32_bf16 v[108:111], v[152:155], v[202:205], v[108:111]
	v_mfma_f32_16x16x32_bf16 v[104:107], v[168:171], v[202:205], v[104:107]
	v_mfma_f32_16x16x32_bf16 v[92:95], v[152:155], v[210:213], v[92:95]
	v_mfma_f32_16x16x32_bf16 v[88:91], v[168:171], v[210:213], v[88:91]
	v_mfma_f32_16x16x32_bf16 v[76:79], v[152:155], v[218:221], v[76:79]
	v_mfma_f32_16x16x32_bf16 v[72:75], v[168:171], v[218:221], v[72:75]
	v_mfma_f32_16x16x32_bf16 v[124:127], v[156:159], v[196:199], v[124:127]
	v_mfma_f32_16x16x32_bf16 v[120:123], v[172:175], v[196:199], v[120:123]
	v_mfma_f32_16x16x32_bf16 v[108:111], v[156:159], v[206:209], v[108:111]
	v_mfma_f32_16x16x32_bf16 v[104:107], v[172:175], v[206:209], v[104:107]
	v_mfma_f32_16x16x32_bf16 v[92:95], v[156:159], v[214:217], v[92:95]
	v_mfma_f32_16x16x32_bf16 v[88:91], v[172:175], v[214:217], v[88:91]
	v_mfma_f32_16x16x32_bf16 v[76:79], v[156:159], v[222:225], v[76:79]
	v_mfma_f32_16x16x32_bf16 v[72:75], v[172:175], v[222:225], v[72:75]
	v_mfma_f32_16x16x32_bf16 v[116:119], v[176:179], v[192:195], v[116:119]
	v_mfma_f32_16x16x32_bf16 v[112:115], v[184:187], v[192:195], v[112:115]
	v_mfma_f32_16x16x32_bf16 v[100:103], v[176:179], v[202:205], v[100:103]
	v_mfma_f32_16x16x32_bf16 v[96:99], v[184:187], v[202:205], v[96:99]
	v_mfma_f32_16x16x32_bf16 v[84:87], v[176:179], v[210:213], v[84:87]
	v_mfma_f32_16x16x32_bf16 v[80:83], v[184:187], v[210:213], v[80:83]
	v_mfma_f32_16x16x32_bf16 v[68:71], v[176:179], v[218:221], v[68:71]
	v_mfma_f32_16x16x32_bf16 v[64:67], v[184:187], v[218:221], v[64:67]
	v_mfma_f32_16x16x32_bf16 v[116:119], v[180:183], v[196:199], v[116:119]
	v_mfma_f32_16x16x32_bf16 v[112:115], v[188:191], v[196:199], v[112:115]
	v_mfma_f32_16x16x32_bf16 v[100:103], v[180:183], v[206:209], v[100:103]
	v_mfma_f32_16x16x32_bf16 v[96:99], v[188:191], v[206:209], v[96:99]
	v_mfma_f32_16x16x32_bf16 v[84:87], v[180:183], v[214:217], v[84:87]
	v_mfma_f32_16x16x32_bf16 v[80:83], v[188:191], v[214:217], v[80:83]
	v_mfma_f32_16x16x32_bf16 v[68:71], v[180:183], v[222:225], v[68:71]
	v_mfma_f32_16x16x32_bf16 v[64:67], v[188:191], v[222:225], v[64:67]
	s_barrier
	s_add_i32 s54, s43, s14
	v_lshl_add_u64 v[160:161], s[36:37], 0, v[134:135]
	s_mov_b32 m0, s54
	ds_read_b128 v[192:195], v150 offset:16384
	ds_read_b128 v[196:199], v150 offset:17408
	ds_read_b128 v[202:205], v150 offset:18432
	ds_read_b128 v[206:209], v150 offset:19456
	ds_read_b128 v[210:213], v150 offset:20480
	ds_read_b128 v[214:217], v150 offset:21504
	ds_read_b128 v[218:221], v150 offset:22528
	ds_read_b128 v[222:225], v150 offset:23552
	global_load_lds_dwordx4 v[160:161], off
	s_add_i32 m0, s54, 0x2000
	s_add_u32 s54, s36, 0xb0000
	v_lshl_add_u64 v[164:165], s[36:37], 0, v[138:139]
	s_addc_u32 s55, s37, 0
	s_add_i32 s56, s44, s14
	global_load_lds_dwordx4 v[164:165], off
	v_lshl_add_u64 v[226:227], s[54:55], 0, v[134:135]
	s_mov_b32 m0, s56
	v_lshl_add_u64 v[228:229], s[38:39], 0, v[136:137]
	global_load_lds_dwordx4 v[226:227], off
	v_lshl_add_u64 v[226:227], s[54:55], 0, v[138:139]
	s_add_i32 m0, s56, 0x2000
	s_nop 0
	global_load_lds_dwordx4 v[226:227], off
	v_lshl_add_u64 v[226:227], s[38:39], 0, v[132:133]
	s_mov_b32 m0, s15
	s_nop 0
	global_load_lds_dwordx4 v[226:227], off
	s_mov_b32 m0, s20
	s_nop 0
	global_load_lds_dwordx4 v[228:229], off
	s_waitcnt vmcnt(8)
	s_waitcnt lgkmcnt(0)
	s_barrier
; #define PG8_STAGE(bufoff, gbase, voff) do { _Pragma("unroll") for (int _i = 0; _i < 2; ++_i) \
;         __builtin_amdgcn_global_load_lds((const unsigned*)((const char*)(gbase) + (voff)[_i]), (LAS unsigned*)(lds + (bufoff) + ldsw + _i * 8192), 16, 0, 0); } while (0)
; #define PG8_STAGEB(bufoff, gbase, perm) do { _Pragma("unroll") for (int _i = 0; _i < 2; ++_i) \
;         __builtin_amdgcn_global_load_lds((const unsigned*)((const char*)(gbase) + ((BSEL && (perm)) ? voffBp[_i] : voffB[_i])), (LAS unsigned*)(lds + (bufoff) + ldsw + _i * 8192), 16, 0, 0); } while (0)
; #define PG8_LDA(dst, b, h) do { _Pragma("unroll") for (int m = 0; m < 4; ++m) _Pragma("unroll") for (int k = 0; k < 2; ++k) dst[m][k] = *(const LAS bf16x8*)(lds + PG8_SA(b, h) + aoff + m * 2048 + k * 1024); } while (0)
; #define PG8_LDB(dst, b, h) do { _Pragma("unroll") for (int n = 0; n < 2; ++n) _Pragma("unroll") for (int k = 0; k < 2; ++k) dst[n][k] = *(const LAS bf16x8*)(lds + PG8_SB(b, h) + boff + n * 2048 + k * 1024); } while (0)
; #define PG8_MMA(ai, bj, At, Bt) do { __builtin_amdgcn_s_setprio(1); _Pragma("unroll") for (int m = 0; m < 4; ++m) _Pragma("unroll") for (int n = 0; n < 2; ++n) _Pragma("unroll") for (int k = 0; k < 2; ++k) \
;         acc[ai][bj][m][n] = __builtin_amdgcn_mfma_f32_16x16x32_bf16(Bt[n][k], At[m][k], acc[ai][bj][m][n], 0, 0, 0); __builtin_amdgcn_s_setprio(0); } while (0)
; #define PG8_WAIT_V(n) asm volatile("s_waitcnt vmcnt(" #n ")" ::: "memory")
; #define PG8_WAIT_L(n) asm volatile("s_waitcnt lgkmcnt(" #n ")" ::: "memory")
; #define PG8_BAR __builtin_amdgcn_s_barrier()
; template <class Epi, bool BSEL = false>
; __device__ __forceinline__ void gemm_phase(LAS unsigned char* lds, const Gemm g, const Order& S, const Epi& E, const int tid) {
;     ...
;             PG8_WAIT_V(8); PG8_WAIT_L(0); PG8_BAR; PG8_MMA(1, 0, At, B0); PG8_MMA(1, 1, At, B1); PG8_BAR; PG8_SCHED;
;             PG8_LDB(B0, 1, 0); PG8_LDB(B1, 1, 1); PG8_SCHED; PG8_LDA(At, 1, 0); PG8_STAGE(PG8_SA(0, 1), a2 + hstepA, voffA);
;             PG8_WAIT_V(8); PG8_WAIT_L(0); PG8_BAR; PG8_MMA(0, 0, At, B0); PG8_MMA(0, 1, At, B1); PG8_BAR; PG8_SCHED;
;             PG8_LDA(At, 1, 1); PG8_STAGEB(PG8_SB(1, 0), b3, p2); PG8_STAGEB(PG8_SB(1, 1), b3 + h2, p2); PG8_STAGE(PG8_SA(1, 0), a3, voffA);
;             PG8_WAIT_V(8); PG8_WAIT_L(0); PG8_BAR; PG8_MMA(1, 0, At, B0); PG8_MMA(1, 1, At, B1); PG8_BAR; PG8_SCHED;
	v_mfma_f32_16x16x32_bf16 v[60:63], v[152:155], v[192:195], v[60:63]
	v_mfma_f32_16x16x32_bf16 v[56:59], v[168:171], v[192:195], v[56:59]
	v_mfma_f32_16x16x32_bf16 v[44:47], v[152:155], v[202:205], v[44:47]
	v_mfma_f32_16x16x32_bf16 v[40:43], v[168:171], v[202:205], v[40:43]
	v_mfma_f32_16x16x32_bf16 v[28:31], v[152:155], v[210:213], v[28:31]
	v_mfma_f32_16x16x32_bf16 v[24:27], v[168:171], v[210:213], v[24:27]
	v_mfma_f32_16x16x32_bf16 v[12:15], v[152:155], v[218:221], v[12:15]
	v_mfma_f32_16x16x32_bf16 v[8:11], v[168:171], v[218:221], v[8:11]
	v_mfma_f32_16x16x32_bf16 v[60:63], v[156:159], v[196:199], v[60:63]
	v_mfma_f32_16x16x32_bf16 v[56:59], v[172:175], v[196:199], v[56:59]
	v_mfma_f32_16x16x32_bf16 v[44:47], v[156:159], v[206:209], v[44:47]
	v_mfma_f32_16x16x32_bf16 v[40:43], v[172:175], v[206:209], v[40:43]
	v_mfma_f32_16x16x32_bf16 v[28:31], v[156:159], v[214:217], v[28:31]
	v_mfma_f32_16x16x32_bf16 v[24:27], v[172:175], v[214:217], v[24:27]
	v_mfma_f32_16x16x32_bf16 v[12:15], v[156:159], v[222:225], v[12:15]
	v_mfma_f32_16x16x32_bf16 v[8:11], v[172:175], v[222:225], v[8:11]
	v_mfma_f32_16x16x32_bf16 v[52:55], v[176:179], v[192:195], v[52:55]
	v_mfma_f32_16x16x32_bf16 v[48:51], v[184:187], v[192:195], v[48:51]
	v_mfma_f32_16x16x32_bf16 v[36:39], v[176:179], v[202:205], v[36:39]
	v_mfma_f32_16x16x32_bf16 v[32:35], v[184:187], v[202:205], v[32:35]
	v_mfma_f32_16x16x32_bf16 v[20:23], v[176:179], v[210:213], v[20:23]
	v_mfma_f32_16x16x32_bf16 v[16:19], v[184:187], v[210:213], v[16:19]
	v_mfma_f32_16x16x32_bf16 v[4:7], v[176:179], v[218:221], v[4:7]
	v_mfma_f32_16x16x32_bf16 v[0:3], v[184:187], v[218:221], v[0:3]
	v_mfma_f32_16x16x32_bf16 v[52:55], v[180:183], v[196:199], v[52:55]
	v_mfma_f32_16x16x32_bf16 v[48:51], v[188:191], v[196:199], v[48:51]
	v_mfma_f32_16x16x32_bf16 v[36:39], v[180:183], v[206:209], v[36:39]
	v_mfma_f32_16x16x32_bf16 v[32:35], v[188:191], v[206:209], v[32:35]
	v_mfma_f32_16x16x32_bf16 v[20:23], v[180:183], v[214:217], v[20:23]
	v_mfma_f32_16x16x32_bf16 v[16:19], v[188:191], v[214:217], v[16:19]
	v_mfma_f32_16x16x32_bf16 v[4:7], v[180:183], v[222:225], v[4:7]
	v_mfma_f32_16x16x32_bf16 v[0:3], v[188:191], v[222:225], v[0:3]
	s_barrier
	s_add_i32 s54, 0, 0x18000
	v_add_u32_e32 v151, s54, v131
	s_add_i32 s55, 0, 0x1c000
	ds_read_b128 v[152:155], v151
	ds_read_b128 v[156:159], v151 offset:1024
	ds_read_b128 v[168:171], v151 offset:2048
	ds_read_b128 v[172:175], v151 offset:3072
	v_add_u32_e32 v151, s55, v131
	ds_read_b128 v[176:179], v151
	ds_read_b128 v[180:183], v151 offset:1024
	ds_read_b128 v[184:187], v151 offset:2048
	ds_read_b128 v[188:191], v151 offset:3072
	s_add_u32 s38, s38, 0xb0000
	s_addc_u32 s39, s39, 0
	s_mov_b32 m0, s21
	v_lshl_add_u64 v[230:231], s[38:39], 0, v[132:133]
	ds_read_b128 v[192:195], v150 offset:32768
	ds_read_b128 v[196:199], v150 offset:33792
	ds_read_b128 v[202:205], v150 offset:34816
	ds_read_b128 v[206:209], v150 offset:35840
	ds_read_b128 v[210:213], v150 offset:36864
	ds_read_b128 v[214:217], v150 offset:37888
	ds_read_b128 v[218:221], v150 offset:38912
	ds_read_b128 v[222:225], v150 offset:39936
	global_load_lds_dwordx4 v[230:231], off
	v_lshl_add_u64 v[230:231], s[38:39], 0, v[136:137]
	s_mov_b32 m0, s40
	s_nop 0
	global_load_lds_dwordx4 v[230:231], off
	s_waitcnt vmcnt(8)
	s_waitcnt lgkmcnt(0)
	s_barrier
	v_mfma_f32_16x16x32_bf16 v[124:127], v[152:155], v[192:195], v[124:127]
	v_mfma_f32_16x16x32_bf16 v[120:123], v[168:171], v[192:195], v[120:123]
	v_mfma_f32_16x16x32_bf16 v[108:111], v[152:155], v[202:205], v[108:111]
	v_mfma_f32_16x16x32_bf16 v[104:107], v[168:171], v[202:205], v[104:107]
	v_mfma_f32_16x16x32_bf16 v[92:95], v[152:155], v[210:213], v[92:95]
	v_mfma_f32_16x16x32_bf16 v[88:91], v[168:171], v[210:213], v[88:91]
	v_mfma_f32_16x16x32_bf16 v[76:79], v[152:155], v[218:221], v[76:79]
	v_mfma_f32_16x16x32_bf16 v[72:75], v[168:171], v[218:221], v[72:75]
	v_mfma_f32_16x16x32_bf16 v[124:127], v[156:159], v[196:199], v[124:127]
	v_mfma_f32_16x16x32_bf16 v[120:123], v[172:175], v[196:199], v[120:123]
	v_mfma_f32_16x16x32_bf16 v[108:111], v[156:159], v[206:209], v[108:111]
	v_mfma_f32_16x16x32_bf16 v[104:107], v[172:175], v[206:209], v[104:107]
	v_mfma_f32_16x16x32_bf16 v[92:95], v[156:159], v[214:217], v[92:95]
	v_mfma_f32_16x16x32_bf16 v[88:91], v[172:175], v[214:217], v[88:91]
	v_mfma_f32_16x16x32_bf16 v[76:79], v[156:159], v[222:225], v[76:79]
	v_mfma_f32_16x16x32_bf16 v[72:75], v[172:175], v[222:225], v[72:75]
	v_mfma_f32_16x16x32_bf16 v[116:119], v[176:179], v[192:195], v[116:119]
	v_mfma_f32_16x16x32_bf16 v[112:115], v[184:187], v[192:195], v[112:115]
	v_mfma_f32_16x16x32_bf16 v[100:103], v[176:179], v[202:205], v[100:103]
	v_mfma_f32_16x16x32_bf16 v[96:99], v[184:187], v[202:205], v[96:99]
	v_mfma_f32_16x16x32_bf16 v[84:87], v[176:179], v[210:213], v[84:87]
	v_mfma_f32_16x16x32_bf16 v[80:83], v[184:187], v[210:213], v[80:83]
	v_mfma_f32_16x16x32_bf16 v[68:71], v[176:179], v[218:221], v[68:71]
	v_mfma_f32_16x16x32_bf16 v[64:67], v[184:187], v[218:221], v[64:67]
	v_mfma_f32_16x16x32_bf16 v[116:119], v[180:183], v[196:199], v[116:119]
	v_mfma_f32_16x16x32_bf16 v[112:115], v[188:191], v[196:199], v[112:115]
	v_mfma_f32_16x16x32_bf16 v[100:103], v[180:183], v[206:209], v[100:103]
	v_mfma_f32_16x16x32_bf16 v[96:99], v[188:191], v[206:209], v[96:99]
	v_mfma_f32_16x16x32_bf16 v[84:87], v[180:183], v[214:217], v[84:87]
	v_mfma_f32_16x16x32_bf16 v[80:83], v[188:191], v[214:217], v[80:83]
	v_mfma_f32_16x16x32_bf16 v[68:71], v[180:183], v[222:225], v[68:71]
	v_mfma_f32_16x16x32_bf16 v[64:67], v[188:191], v[222:225], v[64:67]
	s_barrier
; #define PG8_STAGE(bufoff, gbase, voff) do { _Pragma("unroll") for (int _i = 0; _i < 2; ++_i) \
;         __builtin_amdgcn_global_load_lds((const unsigned*)((const char*)(gbase) + (voff)[_i]), (LAS unsigned*)(lds + (bufoff) + ldsw + _i * 8192), 16, 0, 0); } while (0)
; #define PG8_STAGEB(bufoff, gbase, perm) do { _Pragma("unroll") for (int _i = 0; _i < 2; ++_i) \
;         __builtin_amdgcn_global_load_lds((const unsigned*)((const char*)(gbase) + ((BSEL && (perm)) ? voffBp[_i] : voffB[_i])), (LAS unsigned*)(lds + (bufoff) + ldsw + _i * 8192), 16, 0, 0); } while (0)
; #define PG8_LDA(dst, b, h) do { _Pragma("unroll") for (int m = 0; m < 4; ++m) _Pragma("unroll") for (int k = 0; k < 2; ++k) dst[m][k] = *(const LAS bf16x8*)(lds + PG8_SA(b, h) + aoff + m * 2048 + k * 1024); } while (0)
; #define PG8_MMA(ai, bj, At, Bt) do { __builtin_amdgcn_s_setprio(1); _Pragma("unroll") for (int m = 0; m < 4; ++m) _Pragma("unroll") for (int n = 0; n < 2; ++n) _Pragma("unroll") for (int k = 0; k < 2; ++k) \
;         acc[ai][bj][m][n] = __builtin_amdgcn_mfma_f32_16x16x32_bf16(Bt[n][k], At[m][k], acc[ai][bj][m][n], 0, 0, 0); __builtin_amdgcn_s_setprio(0); } while (0)
; #define PG8_WAIT_V(n) asm volatile("s_waitcnt vmcnt(" #n ")" ::: "memory")
; #define PG8_WAIT_L(n) asm volatile("s_waitcnt lgkmcnt(" #n ")" ::: "memory")
; #define PG8_BAR __builtin_amdgcn_s_barrier()
; #define PG8_SCHED __builtin_amdgcn_sched_barrier(0)
; template <class Epi, bool BSEL = false>
; __device__ __forceinline__ void gemm_phase(LAS unsigned char* lds, const Gemm g, const Order& S, const Epi& E, const int tid) {
;     ...
;             PG8_LDA(At, 1, 1); PG8_STAGEB(PG8_SB(1, 0), b3, p2); PG8_STAGEB(PG8_SB(1, 1), b3 + h2, p2); PG8_STAGE(PG8_SA(1, 0), a3, voffA);
;             PG8_WAIT_V(8); PG8_WAIT_L(0); PG8_BAR; PG8_MMA(1, 0, At, B0); PG8_MMA(1, 1, At, B1); PG8_BAR; PG8_SCHED;
;         }
;         if constexpr (ALIGN_EPI) { if (wr == 0) PG8_BAR; }
	s_add_i32 s38, s54, s14
	v_lshl_add_u64 v[160:161], v[160:161], 0, s[18:19]
	s_mov_b32 m0, s38
	ds_read_b128 v[192:195], v150 offset:49152
	ds_read_b128 v[196:199], v150 offset:50176
	ds_read_b128 v[202:205], v150 offset:51200
	ds_read_b128 v[206:209], v150 offset:52224
	ds_read_b128 v[210:213], v150 offset:53248
	ds_read_b128 v[214:217], v150 offset:54272
	ds_read_b128 v[218:221], v150 offset:55296
	ds_read_b128 v[222:225], v150 offset:56320
	global_load_lds_dwordx4 v[160:161], off
	s_add_i32 m0, s38, 0x2000
	s_add_u32 s36, s36, 0xb0080
	v_lshl_add_u64 v[160:161], v[164:165], 0, s[18:19]
	s_addc_u32 s37, s37, 0
	s_add_i32 s38, s55, s14
	global_load_lds_dwordx4 v[160:161], off
	v_lshl_add_u64 v[160:161], s[36:37], 0, v[134:135]
	s_mov_b32 m0, s38
	s_nop 0
	global_load_lds_dwordx4 v[160:161], off
	v_lshl_add_u64 v[160:161], s[36:37], 0, v[138:139]
	s_add_i32 m0, s38, 0x2000
	s_nop 0
	global_load_lds_dwordx4 v[160:161], off
	v_lshl_add_u64 v[160:161], v[226:227], 0, s[18:19]
	s_mov_b32 m0, s41
	s_nop 0
	global_load_lds_dwordx4 v[160:161], off
	v_lshl_add_u64 v[160:161], v[228:229], 0, s[18:19]
	s_mov_b32 m0, s42
	s_nop 0
	global_load_lds_dwordx4 v[160:161], off
	s_waitcnt vmcnt(8)
	s_waitcnt lgkmcnt(0)
	s_barrier
	v_mfma_f32_16x16x32_bf16 v[60:63], v[152:155], v[192:195], v[60:63]
	v_mfma_f32_16x16x32_bf16 v[56:59], v[168:171], v[192:195], v[56:59]
	v_mfma_f32_16x16x32_bf16 v[44:47], v[152:155], v[202:205], v[44:47]
	v_mfma_f32_16x16x32_bf16 v[40:43], v[168:171], v[202:205], v[40:43]
	v_mfma_f32_16x16x32_bf16 v[28:31], v[152:155], v[210:213], v[28:31]
	v_mfma_f32_16x16x32_bf16 v[24:27], v[168:171], v[210:213], v[24:27]
	v_mfma_f32_16x16x32_bf16 v[12:15], v[152:155], v[218:221], v[12:15]
	v_mfma_f32_16x16x32_bf16 v[8:11], v[168:171], v[218:221], v[8:11]
	v_mfma_f32_16x16x32_bf16 v[60:63], v[156:159], v[196:199], v[60:63]
	v_mfma_f32_16x16x32_bf16 v[56:59], v[172:175], v[196:199], v[56:59]
	v_mfma_f32_16x16x32_bf16 v[44:47], v[156:159], v[206:209], v[44:47]
	v_mfma_f32_16x16x32_bf16 v[40:43], v[172:175], v[206:209], v[40:43]
	v_mfma_f32_16x16x32_bf16 v[28:31], v[156:159], v[214:217], v[28:31]
	v_mfma_f32_16x16x32_bf16 v[24:27], v[172:175], v[214:217], v[24:27]
	v_mfma_f32_16x16x32_bf16 v[12:15], v[156:159], v[222:225], v[12:15]
	v_mfma_f32_16x16x32_bf16 v[8:11], v[172:175], v[222:225], v[8:11]
	v_mfma_f32_16x16x32_bf16 v[52:55], v[176:179], v[192:195], v[52:55]
	v_mfma_f32_16x16x32_bf16 v[48:51], v[184:187], v[192:195], v[48:51]
	v_mfma_f32_16x16x32_bf16 v[36:39], v[176:179], v[202:205], v[36:39]
	v_mfma_f32_16x16x32_bf16 v[32:35], v[184:187], v[202:205], v[32:35]
	v_mfma_f32_16x16x32_bf16 v[20:23], v[176:179], v[210:213], v[20:23]
	v_mfma_f32_16x16x32_bf16 v[16:19], v[184:187], v[210:213], v[16:19]
	v_mfma_f32_16x16x32_bf16 v[4:7], v[176:179], v[218:221], v[4:7]
	v_mfma_f32_16x16x32_bf16 v[0:3], v[184:187], v[218:221], v[0:3]
	v_mfma_f32_16x16x32_bf16 v[52:55], v[180:183], v[196:199], v[52:55]
	v_mfma_f32_16x16x32_bf16 v[48:51], v[188:191], v[196:199], v[48:51]
	v_mfma_f32_16x16x32_bf16 v[36:39], v[180:183], v[206:209], v[36:39]
	v_mfma_f32_16x16x32_bf16 v[32:35], v[188:191], v[206:209], v[32:35]
	v_mfma_f32_16x16x32_bf16 v[20:23], v[180:183], v[214:217], v[20:23]
	v_mfma_f32_16x16x32_bf16 v[16:19], v[188:191], v[214:217], v[16:19]
	v_mfma_f32_16x16x32_bf16 v[4:7], v[180:183], v[222:225], v[4:7]
	v_mfma_f32_16x16x32_bf16 v[0:3], v[188:191], v[222:225], v[0:3]
	s_barrier
	s_add_i32 s53, s53, 2
	s_add_u32 s34, s34, 0x100
	s_addc_u32 s35, s35, 0
	s_cmp_gt_u32 s53, 41
	s_cbranch_scc0 .LBB0_1393
	s_and_b64 vcc, exec, s[22:23]
	s_cbranch_vccz .LBB0_1396
	s_barrier
